# rg gates: max(0, 1-a^2) folded into the fma's clamp (value never exceeds 1), one VALU less per token
# baseline (speedup 1.0000x reference)
; #define LAS __attribute__((address_space(3)))
; template <bool FINAL>
; __device__ __forceinline__ void rg_item(PREF p, int l, int item, LAS unsigned char* wl, int lane) {
;     const bf16_t* __restrict__ P = (const bf16_t*)(p.ws + WS_GP);
;     const int h = item & 7, rest = item >> 3;
;     const int ci = rest < 512 ? 4 + (rest & 255) : ((rest - 512) & 3), b = rest < 512 ? (rest >> 8) : ((rest - 512) >> 2);
;     const int seq_row0 = ci < 4 ? TL + b * 256 : b * 16384;
;     const int t0 = ci < 4 ? ci * 64 : (ci - 4) * 64;
;     const int seqlen = ci < 4 ? 256 : 16384;
;     const int ch = h * 64 + lane;
;     LAS bf16_t* sXc = (LAS bf16_t*)wl;
;     LAS float* stg = (LAS float*)(wl + 9216);
;     {
;         const float cw0 = p.conv_w[(l * 4 + 0) * 512 + ch], cw1 = p.conv_w[(l * 4 + 1) * 512 + ch], cw2 = p.conv_w[(l * 4 + 2) * 512 + ch], cw3 = p.conv_w[(l * 4 + 3) * 512 + ch];
;         const float cb = p.conv_b[l * 512 + ch];
;         float xv[67]; unsigned xr_[67];
; #pragma unroll
;         for (int i = 0; i < 67; ++i) { const int t = t0 - 2 + i; const int tc = t < 0 ? 0 : (t >= seqlen ? seqlen - 1 : t);
;             xr_[i] = P[(size_t)(seq_row0 + tc) * PW + ch]; }
.Lrg7_dec:
	s_add_i32 s15, s11, s10
	s_mul_i32 s36, s9, 0x104
	s_add_i32 s36, s36, s8
	s_lshl_b32 s36, s36, 12
	s_cmp_eq_u32 s10, 0
	s_cselect_b32 s37, 0, -1
	s_add_i32 s38, s10, 64
	s_cmp_eq_u32 s38, s14
	s_cselect_b32 s38, 0, -1
	s_bfe_u32 s44, s44, 0x30006
	s_mul_i32 s44, s44, 0x4800
	v_lshl_or_b32 v234, s7, 6, v233
	v_lshlrev_b32_e32 v235, 2, v234
	v_lshlrev_b32_e32 v234, 1, v234
	v_and_b32_e32 v236, 15, v233
	v_lshrrev_b32_e32 v241, 4, v233
	s_movk_i32 s39, 0x90
	v_mul_u32_u24_e32 v237, 0x90, v236
	v_lshl_add_u32 v237, v241, 4, v237
	v_lshlrev_b32_e32 v238, 7, v236
	v_lshl_add_u32 v238, v241, 4, v238
	v_lshlrev_b32_e32 v239, 10, v241
	v_lshl_add_u32 v239, v236, 2, v239
	v_mov_b32_e32 v241, v238
	v_add_u32_e32 v236, s44, v237
	s_add_i32 s39, s44, 0x2400
	v_add_u32_e32 v237, s39, v239
	v_add_u32_e32 v238, 0x1000, v237
	v_lshl_add_u32 v239, v233, 2, s44
	v_lshl_add_u32 v240, v233, 1, s44
	s_add_i32 s39, s15, -2
	s_mul_hi_i32 s83, s39, 0x1600
	s_mul_i32 s82, s39, 0x1600
	s_waitcnt lgkmcnt(0)
	s_add_u32 s82, s82, s0
	s_addc_u32 s83, s83, s1
	s_add_u32 s82, s82, 0xbc00000
	s_addc_u32 s83, s83, 0
	global_load_ushort v158, v234, s[82:83]
	s_add_u32 s82, s82, 0x1600
	s_addc_u32 s83, s83, 0
	global_load_ushort v159, v234, s[82:83]
	s_add_u32 s82, s82, 0x1600
	s_addc_u32 s83, s83, 0
	global_load_ushort v160, v234, s[82:83]
	s_add_u32 s82, s82, 0x1600
	s_addc_u32 s83, s83, 0
	global_load_ushort v161, v234, s[82:83]
	s_add_u32 s82, s82, 0x1600
	s_addc_u32 s83, s83, 0
	global_load_ushort v162, v234, s[82:83]
	s_add_u32 s82, s82, 0x1600
	s_addc_u32 s83, s83, 0
	global_load_ushort v163, v234, s[82:83]
	s_add_u32 s82, s82, 0x1600
	s_addc_u32 s83, s83, 0
	global_load_ushort v164, v234, s[82:83]
	s_add_u32 s82, s82, 0x1600
	s_addc_u32 s83, s83, 0
	global_load_ushort v165, v234, s[82:83]
	s_add_u32 s82, s82, 0x1600
	s_addc_u32 s83, s83, 0
	global_load_ushort v166, v234, s[82:83]
	s_add_u32 s82, s82, 0x1600
	s_addc_u32 s83, s83, 0
	global_load_ushort v167, v234, s[82:83]
	s_add_u32 s82, s82, 0x1600
	s_addc_u32 s83, s83, 0
	global_load_ushort v168, v234, s[82:83]
	s_add_u32 s82, s82, 0x1600
	s_addc_u32 s83, s83, 0
	global_load_ushort v169, v234, s[82:83]
	s_add_u32 s82, s82, 0x1600
	s_addc_u32 s83, s83, 0
	global_load_ushort v170, v234, s[82:83]
	s_add_u32 s82, s82, 0x1600
	s_addc_u32 s83, s83, 0
	global_load_ushort v171, v234, s[82:83]
	s_add_u32 s82, s82, 0x1600
	s_addc_u32 s83, s83, 0
	global_load_ushort v172, v234, s[82:83]
	s_add_u32 s82, s82, 0x1600
	s_addc_u32 s83, s83, 0
	global_load_ushort v173, v234, s[82:83]
	s_add_u32 s82, s82, 0x1600
	s_addc_u32 s83, s83, 0
	global_load_ushort v174, v234, s[82:83]
	s_add_u32 s82, s82, 0x1600
	s_addc_u32 s83, s83, 0
	global_load_ushort v175, v234, s[82:83]
	s_add_u32 s82, s82, 0x1600
	s_addc_u32 s83, s83, 0
	global_load_ushort v176, v234, s[82:83]
	s_add_u32 s82, s82, 0x1600
	s_addc_u32 s83, s83, 0
	global_load_ushort v177, v234, s[82:83]
	s_add_u32 s82, s82, 0x1600
	s_addc_u32 s83, s83, 0
	global_load_ushort v178, v234, s[82:83]
	s_add_u32 s82, s82, 0x1600
	s_addc_u32 s83, s83, 0
	global_load_ushort v179, v234, s[82:83]
	s_add_u32 s82, s82, 0x1600
	s_addc_u32 s83, s83, 0
	global_load_ushort v180, v234, s[82:83]
	s_add_u32 s82, s82, 0x1600
	s_addc_u32 s83, s83, 0
	global_load_ushort v181, v234, s[82:83]
	s_add_u32 s82, s82, 0x1600
	s_addc_u32 s83, s83, 0
	global_load_ushort v182, v234, s[82:83]
	s_add_u32 s82, s82, 0x1600
	s_addc_u32 s83, s83, 0
	global_load_ushort v183, v234, s[82:83]
	s_add_u32 s82, s82, 0x1600
	s_addc_u32 s83, s83, 0
	global_load_ushort v184, v234, s[82:83]
	s_add_u32 s82, s82, 0x1600
	s_addc_u32 s83, s83, 0
	global_load_ushort v185, v234, s[82:83]
	s_add_u32 s82, s82, 0x1600
	s_addc_u32 s83, s83, 0
	global_load_ushort v186, v234, s[82:83]
	s_add_u32 s82, s82, 0x1600
	s_addc_u32 s83, s83, 0
	global_load_ushort v187, v234, s[82:83]
	s_add_u32 s82, s82, 0x1600
	s_addc_u32 s83, s83, 0
	global_load_ushort v188, v234, s[82:83]
	s_add_u32 s82, s82, 0x1600
	s_addc_u32 s83, s83, 0
	global_load_ushort v189, v234, s[82:83]
	s_add_u32 s82, s82, 0x1600
	s_addc_u32 s83, s83, 0
	global_load_ushort v190, v234, s[82:83]
	s_add_u32 s82, s82, 0x1600
	s_addc_u32 s83, s83, 0
	global_load_ushort v191, v234, s[82:83]
	s_add_u32 s82, s82, 0x1600
	s_addc_u32 s83, s83, 0
	global_load_ushort v192, v234, s[82:83]
	s_add_u32 s82, s82, 0x1600
	s_addc_u32 s83, s83, 0
	global_load_ushort v193, v234, s[82:83]
	s_add_u32 s82, s82, 0x1600
	s_addc_u32 s83, s83, 0
	global_load_ushort v194, v234, s[82:83]
	s_add_u32 s82, s82, 0x1600
	s_addc_u32 s83, s83, 0
	global_load_ushort v195, v234, s[82:83]
	s_add_u32 s82, s82, 0x1600
	s_addc_u32 s83, s83, 0
	global_load_ushort v196, v234, s[82:83]
	s_add_u32 s82, s82, 0x1600
	s_addc_u32 s83, s83, 0
	global_load_ushort v197, v234, s[82:83]
	s_add_u32 s82, s82, 0x1600
	s_addc_u32 s83, s83, 0
	global_load_ushort v198, v234, s[82:83]
	s_add_u32 s82, s82, 0x1600
	s_addc_u32 s83, s83, 0
	global_load_ushort v199, v234, s[82:83]
	s_add_u32 s82, s82, 0x1600
	s_addc_u32 s83, s83, 0
	global_load_ushort v200, v234, s[82:83]
	s_add_u32 s82, s82, 0x1600
	s_addc_u32 s83, s83, 0
	global_load_ushort v201, v234, s[82:83]
	s_add_u32 s82, s82, 0x1600
	s_addc_u32 s83, s83, 0
	global_load_ushort v202, v234, s[82:83]
	s_add_u32 s82, s82, 0x1600
	s_addc_u32 s83, s83, 0
	global_load_ushort v203, v234, s[82:83]
	s_add_u32 s82, s82, 0x1600
	s_addc_u32 s83, s83, 0
	global_load_ushort v204, v234, s[82:83]
	s_add_u32 s82, s82, 0x1600
	s_addc_u32 s83, s83, 0
	global_load_ushort v205, v234, s[82:83]
	s_add_u32 s82, s82, 0x1600
	s_addc_u32 s83, s83, 0
	global_load_ushort v206, v234, s[82:83]
	s_add_u32 s82, s82, 0x1600
; __device__ __forceinline__ float rcpf_(float x) { return __builtin_amdgcn_rcpf(x); }
; template <bool FINAL, int D>
; __device__ __forceinline__ void rg_dir(PREF p, int l, int h, int ch, int sidx, int rowbase  , LAS bf16_t* sXc, LAS float* stg, int lane) {
;     ...
;     const float ba = p.rg_ba[(l * 2 + D) * 512 + ch], bi = p.rg_bi[(l * 2 + D) * 512 + ch], lam = p.rg_lam[(l * 2 + D) * 512 + ch];
;     const float e_ = __expf(-lam), u_ = 1.f + e_;
;     const float l1p = (u_ == 1.f) ? e_ : __logf(u_) * e_ * rcpf_(u_ - 1.f);
;     const float sp8 = -8.f * 1.4426950408889634f * l1p;
;     float hc = FINAL ? RGC[sidx] : 0.f, Ap = 1.f;
;     bf16x8 Br[4][2], Bi[4][2];
; #pragma unroll
;     for (int nt = 0; nt < 4; ++nt) { const int o0 = (nt * 16 + (lane & 15)) * 64 + (lane >> 4) * 8;
;         Br[nt][0] = *(const bf16x8*)(wr_ + o0); Br[nt][1] = *(const bf16x8*)(wr_ + o0 + 32); Bi[nt][0] = *(const bf16x8*)(wi_ + o0); Bi[nt][1] = *(const bf16x8*)(wi_ + o0 + 32); }
; template <bool FINAL>
; __device__ __forceinline__ void rg_item(PREF p, int l, int item, LAS unsigned char* wl, int lane) {
;     ...
;         const float cw0 = p.conv_w[(l * 4 + 0) * 512 + ch], cw1 = p.conv_w[(l * 4 + 1) * 512 + ch], cw2 = p.conv_w[(l * 4 + 2) * 512 + ch], cw3 = p.conv_w[(l * 4 + 3) * 512 + ch];
;         const float cb = p.conv_b[l * 512 + ch];
;         float xv[67]; unsigned xr_[67];
; #pragma unroll
;         for (int i = 0; i < 67; ++i) { const int t = t0 - 2 + i; const int tc = t < 0 ? 0 : (t >= seqlen ? seqlen - 1 : t);
;             xr_[i] = P[(size_t)(seq_row0 + tc) * PW + ch]; }
;         __builtin_amdgcn_sched_barrier(0);
; #pragma unroll
;         for (int i = 0; i < 67; ++i) { const int t = t0 - 2 + i; const int tc = t < 0 ? 0 : (t >= seqlen ? seqlen - 1 : t); xv[i] = (t == tc) ? bf2f(xr_[i]) : 0.f; }
	s_addc_u32 s83, s83, 0
	global_load_ushort v207, v234, s[82:83]
	s_add_u32 s82, s82, 0x1600
	s_addc_u32 s83, s83, 0
	global_load_ushort v208, v234, s[82:83]
	s_add_u32 s82, s82, 0x1600
	s_addc_u32 s83, s83, 0
	global_load_ushort v209, v234, s[82:83]
	s_add_u32 s82, s82, 0x1600
	s_addc_u32 s83, s83, 0
	global_load_ushort v210, v234, s[82:83]
	s_add_u32 s82, s82, 0x1600
	s_addc_u32 s83, s83, 0
	global_load_ushort v211, v234, s[82:83]
	s_add_u32 s82, s82, 0x1600
	s_addc_u32 s83, s83, 0
	global_load_ushort v212, v234, s[82:83]
	s_add_u32 s82, s82, 0x1600
	s_addc_u32 s83, s83, 0
	global_load_ushort v213, v234, s[82:83]
	s_add_u32 s82, s82, 0x1600
	s_addc_u32 s83, s83, 0
	global_load_ushort v214, v234, s[82:83]
	s_add_u32 s82, s82, 0x1600
	s_addc_u32 s83, s83, 0
	global_load_ushort v215, v234, s[82:83]
	s_add_u32 s82, s82, 0x1600
	s_addc_u32 s83, s83, 0
	global_load_ushort v216, v234, s[82:83]
	s_add_u32 s82, s82, 0x1600
	s_addc_u32 s83, s83, 0
	global_load_ushort v217, v234, s[82:83]
	s_add_u32 s82, s82, 0x1600
	s_addc_u32 s83, s83, 0
	global_load_ushort v218, v234, s[82:83]
	s_add_u32 s82, s82, 0x1600
	s_addc_u32 s83, s83, 0
	global_load_ushort v219, v234, s[82:83]
	s_add_u32 s82, s82, 0x1600
	s_addc_u32 s83, s83, 0
	global_load_ushort v222, v234, s[82:83]
	s_add_u32 s82, s82, 0x1600
	s_addc_u32 s83, s83, 0
	global_load_ushort v223, v234, s[82:83]
	s_add_u32 s82, s82, 0x1600
	s_addc_u32 s83, s83, 0
	global_load_ushort v140, v234, s[82:83]
	s_add_u32 s82, s82, 0x1600
	s_addc_u32 s83, s83, 0
	global_load_ushort v141, v234, s[82:83]
	s_add_u32 s82, s82, 0x1600
	s_addc_u32 s83, s83, 0
	global_load_ushort v232, v234, s[82:83]
	s_lshl_b32 s39, s47, 13
	s_add_u32 s72, s72, s39
	s_addc_u32 s73, s73, 0
	global_load_dword v40, v235, s[72:73]
	global_load_dword v41, v235, s[72:73] offset:2048
	s_add_u32 s72, s72, 0x1000
	s_addc_u32 s73, s73, 0
	global_load_dword v42, v235, s[72:73]
	global_load_dword v43, v235, s[72:73] offset:2048
	s_lshl_b32 s39, s47, 11
	s_add_u32 s74, s74, s39
	s_addc_u32 s75, s75, 0
	global_load_dword v44, v235, s[74:75]
	s_lshl_b32 s39, s47, 12
	s_add_u32 s76, s76, s39
	s_addc_u32 s77, s77, 0
	s_add_u32 s78, s78, s39
	s_addc_u32 s79, s79, 0
	s_add_u32 s80, s80, s39
	s_addc_u32 s81, s81, 0
	s_add_u32 s96, s0, 0xa00000
	s_addc_u32 s97, s1, 0
	s_add_u32 s96, s96, s36
	s_addc_u32 s97, s97, 0
	s_lshl_b32 s39, s47, 5
	s_add_i32 s39, s39, s7
	s_lshl_b32 s39, s39, 13
	s_add_u32 s92, s0, 0x300000
	s_addc_u32 s93, s1, 0
	s_add_u32 s92, s92, s39
	s_addc_u32 s93, s93, 0
	global_load_dword v45, v235, s[76:77]
	global_load_dword v46, v235, s[78:79]
	global_load_dword v47, v235, s[80:81]
	global_load_dword v250, v235, s[96:97]
	s_add_u32 s90, s92, 0x0
	s_addc_u32 s91, s93, 0
	global_load_dwordx4 v[80:83], v241, s[90:91]
	global_load_dwordx4 v[84:87], v241, s[90:91] offset:64
	global_load_dwordx4 v[88:91], v241, s[90:91] offset:2048
	global_load_dwordx4 v[92:95], v241, s[90:91] offset:2112
	s_add_u32 s90, s92, 0x1000
	s_addc_u32 s91, s93, 0
	global_load_dwordx4 v[96:99], v241, s[90:91]
	global_load_dwordx4 v[100:103], v241, s[90:91] offset:64
	global_load_dwordx4 v[104:107], v241, s[90:91] offset:2048
	global_load_dwordx4 v[108:111], v241, s[90:91] offset:2112
	s_add_u32 s90, s92, 0x10000
	s_addc_u32 s91, s93, 0
	global_load_dwordx4 v[112:115], v241, s[90:91]
	global_load_dwordx4 v[116:119], v241, s[90:91] offset:64
	global_load_dwordx4 v[120:123], v241, s[90:91] offset:2048
	global_load_dwordx4 v[124:127], v241, s[90:91] offset:2112
	s_add_u32 s90, s92, 0x11000
	s_addc_u32 s91, s93, 0
	global_load_dwordx4 v[128:131], v241, s[90:91]
	global_load_dwordx4 v[132:135], v241, s[90:91] offset:64
	global_load_dwordx4 v[136:139], v241, s[90:91] offset:2048
	global_load_dwordx4 v[228:231], v241, s[90:91] offset:2112
	s_waitcnt vmcnt(20)
	v_lshlrev_b32_e32 v158, 16, v158
	v_lshlrev_b32_e32 v159, 16, v159
	v_lshlrev_b32_e32 v160, 16, v160
	v_lshlrev_b32_e32 v161, 16, v161
	v_lshlrev_b32_e32 v162, 16, v162
	v_lshlrev_b32_e32 v163, 16, v163
	v_lshlrev_b32_e32 v164, 16, v164
	v_lshlrev_b32_e32 v165, 16, v165
	v_lshlrev_b32_e32 v166, 16, v166
	v_lshlrev_b32_e32 v167, 16, v167
	v_lshlrev_b32_e32 v168, 16, v168
	v_lshlrev_b32_e32 v169, 16, v169
	v_lshlrev_b32_e32 v170, 16, v170
	v_lshlrev_b32_e32 v171, 16, v171
	v_lshlrev_b32_e32 v172, 16, v172
	v_lshlrev_b32_e32 v173, 16, v173
	v_lshlrev_b32_e32 v174, 16, v174
	v_lshlrev_b32_e32 v175, 16, v175
	v_lshlrev_b32_e32 v176, 16, v176
	v_lshlrev_b32_e32 v177, 16, v177
	v_lshlrev_b32_e32 v178, 16, v178
	v_lshlrev_b32_e32 v179, 16, v179
	v_lshlrev_b32_e32 v180, 16, v180
	v_lshlrev_b32_e32 v181, 16, v181
	v_lshlrev_b32_e32 v182, 16, v182
	v_lshlrev_b32_e32 v183, 16, v183
	v_lshlrev_b32_e32 v184, 16, v184
	v_lshlrev_b32_e32 v185, 16, v185
	v_lshlrev_b32_e32 v186, 16, v186
	v_lshlrev_b32_e32 v187, 16, v187
	v_lshlrev_b32_e32 v188, 16, v188
	v_lshlrev_b32_e32 v189, 16, v189
	v_lshlrev_b32_e32 v190, 16, v190
	v_lshlrev_b32_e32 v191, 16, v191
	v_lshlrev_b32_e32 v192, 16, v192
	v_lshlrev_b32_e32 v193, 16, v193
	v_lshlrev_b32_e32 v194, 16, v194
	v_lshlrev_b32_e32 v195, 16, v195
	v_lshlrev_b32_e32 v196, 16, v196
	v_lshlrev_b32_e32 v197, 16, v197
	v_lshlrev_b32_e32 v198, 16, v198
	v_lshlrev_b32_e32 v199, 16, v199
	v_lshlrev_b32_e32 v200, 16, v200
	v_lshlrev_b32_e32 v201, 16, v201
	v_lshlrev_b32_e32 v202, 16, v202
	v_lshlrev_b32_e32 v203, 16, v203
	v_lshlrev_b32_e32 v204, 16, v204
	v_lshlrev_b32_e32 v205, 16, v205
	v_lshlrev_b32_e32 v206, 16, v206
	v_lshlrev_b32_e32 v207, 16, v207
	v_lshlrev_b32_e32 v208, 16, v208
	v_lshlrev_b32_e32 v209, 16, v209
	v_lshlrev_b32_e32 v210, 16, v210
	v_lshlrev_b32_e32 v211, 16, v211
; __device__ __forceinline__ unsigned f2bf(float f) { unsigned r; asm("v_cvt_pk_bf16_f32 %0, %1, %1" : "=v"(r) : "v"(f)); return r & 0xffffu; }
; template <bool FINAL>
; __device__ __forceinline__ void rg_item(PREF p, int l, int item, LAS unsigned char* wl, int lane) {
;     ...
;         for (int i = 0; i < 67; ++i) { const int t = t0 - 2 + i; const int tc = t < 0 ? 0 : (t >= seqlen ? seqlen - 1 : t); xv[i] = (t == tc) ? bf2f(xr_[i]) : 0.f; }
; #pragma unroll
;         for (int tt = 0; tt < 64; ++tt) { const float xc = xv[tt] * cw0 + xv[tt + 1] * cw1 + xv[tt + 2] * cw2 + xv[tt + 3] * cw3 + cb; sXc[tt * 72 + lane] = (bf16_t)f2bf(xc); }
	v_lshlrev_b32_e32 v212, 16, v212
	v_lshlrev_b32_e32 v213, 16, v213
	v_lshlrev_b32_e32 v214, 16, v214
	v_lshlrev_b32_e32 v215, 16, v215
	v_lshlrev_b32_e32 v216, 16, v216
	v_lshlrev_b32_e32 v217, 16, v217
	v_lshlrev_b32_e32 v218, 16, v218
	v_lshlrev_b32_e32 v219, 16, v219
	v_lshlrev_b32_e32 v222, 16, v222
	v_lshlrev_b32_e32 v223, 16, v223
	v_lshlrev_b32_e32 v140, 16, v140
	v_lshlrev_b32_e32 v141, 16, v141
	v_lshlrev_b32_e32 v232, 16, v232
	v_and_b32_e32 v158, s37, v158
	v_and_b32_e32 v159, s37, v159
	v_and_b32_e32 v232, s38, v232
	v_mul_f32_e32 v32, v41, v159
	v_mul_f32_e32 v33, v41, v160
	v_mul_f32_e32 v34, v41, v161
	v_mul_f32_e32 v35, v41, v162
	v_mul_f32_e32 v36, v41, v163
	v_mul_f32_e32 v37, v41, v164
	v_mul_f32_e32 v38, v41, v165
	v_mul_f32_e32 v39, v41, v166
	v_fmac_f32_e32 v32, v40, v158
	v_fmac_f32_e32 v33, v40, v159
	v_fmac_f32_e32 v34, v40, v160
	v_fmac_f32_e32 v35, v40, v161
	v_fmac_f32_e32 v36, v40, v162
	v_fmac_f32_e32 v37, v40, v163
	v_fmac_f32_e32 v38, v40, v164
	v_fmac_f32_e32 v39, v40, v165
	v_fmac_f32_e32 v32, v42, v160
	v_fmac_f32_e32 v33, v42, v161
	v_fmac_f32_e32 v34, v42, v162
	v_fmac_f32_e32 v35, v42, v163
	v_fmac_f32_e32 v36, v42, v164
	v_fmac_f32_e32 v37, v42, v165
	v_fmac_f32_e32 v38, v42, v166
	v_fmac_f32_e32 v39, v42, v167
	v_fmac_f32_e32 v32, v43, v161
	v_fmac_f32_e32 v33, v43, v162
	v_fmac_f32_e32 v34, v43, v163
	v_fmac_f32_e32 v35, v43, v164
	v_fmac_f32_e32 v36, v43, v165
	v_fmac_f32_e32 v37, v43, v166
	v_fmac_f32_e32 v38, v43, v167
	v_fmac_f32_e32 v39, v43, v168
	v_add_f32_e32 v32, v44, v32
	v_add_f32_e32 v33, v44, v33
	v_add_f32_e32 v34, v44, v34
	v_add_f32_e32 v35, v44, v35
	v_add_f32_e32 v36, v44, v36
	v_add_f32_e32 v37, v44, v37
	v_add_f32_e32 v38, v44, v38
	v_add_f32_e32 v39, v44, v39
	v_cvt_pk_bf16_f32 v32, v32, v33
	v_cvt_pk_bf16_f32 v34, v34, v35
	v_cvt_pk_bf16_f32 v36, v36, v37
	v_cvt_pk_bf16_f32 v38, v38, v39
	ds_write_b16 v240, v32 offset:0
	ds_write_b16_d16_hi v240, v32 offset:144
	ds_write_b16 v240, v34 offset:288
	ds_write_b16_d16_hi v240, v34 offset:432
	ds_write_b16 v240, v36 offset:576
	ds_write_b16_d16_hi v240, v36 offset:720
	ds_write_b16 v240, v38 offset:864
	ds_write_b16_d16_hi v240, v38 offset:1008
	v_mul_f32_e32 v32, v41, v167
	v_mul_f32_e32 v33, v41, v168
	v_mul_f32_e32 v34, v41, v169
	v_mul_f32_e32 v35, v41, v170
	v_mul_f32_e32 v36, v41, v171
	v_mul_f32_e32 v37, v41, v172
	v_mul_f32_e32 v38, v41, v173
	v_mul_f32_e32 v39, v41, v174
	v_fmac_f32_e32 v32, v40, v166
	v_fmac_f32_e32 v33, v40, v167
	v_fmac_f32_e32 v34, v40, v168
	v_fmac_f32_e32 v35, v40, v169
	v_fmac_f32_e32 v36, v40, v170
	v_fmac_f32_e32 v37, v40, v171
	v_fmac_f32_e32 v38, v40, v172
	v_fmac_f32_e32 v39, v40, v173
	v_fmac_f32_e32 v32, v42, v168
	v_fmac_f32_e32 v33, v42, v169
	v_fmac_f32_e32 v34, v42, v170
	v_fmac_f32_e32 v35, v42, v171
	v_fmac_f32_e32 v36, v42, v172
	v_fmac_f32_e32 v37, v42, v173
	v_fmac_f32_e32 v38, v42, v174
	v_fmac_f32_e32 v39, v42, v175
	v_fmac_f32_e32 v32, v43, v169
	v_fmac_f32_e32 v33, v43, v170
	v_fmac_f32_e32 v34, v43, v171
	v_fmac_f32_e32 v35, v43, v172
	v_fmac_f32_e32 v36, v43, v173
	v_fmac_f32_e32 v37, v43, v174
	v_fmac_f32_e32 v38, v43, v175
	v_fmac_f32_e32 v39, v43, v176
	v_add_f32_e32 v32, v44, v32
	v_add_f32_e32 v33, v44, v33
	v_add_f32_e32 v34, v44, v34
	v_add_f32_e32 v35, v44, v35
	v_add_f32_e32 v36, v44, v36
	v_add_f32_e32 v37, v44, v37
	v_add_f32_e32 v38, v44, v38
	v_add_f32_e32 v39, v44, v39
	v_cvt_pk_bf16_f32 v32, v32, v33
	v_cvt_pk_bf16_f32 v34, v34, v35
	v_cvt_pk_bf16_f32 v36, v36, v37
	v_cvt_pk_bf16_f32 v38, v38, v39
	ds_write_b16 v240, v32 offset:1152
	ds_write_b16_d16_hi v240, v32 offset:1296
	ds_write_b16 v240, v34 offset:1440
	ds_write_b16_d16_hi v240, v34 offset:1584
	ds_write_b16 v240, v36 offset:1728
	ds_write_b16_d16_hi v240, v36 offset:1872
	ds_write_b16 v240, v38 offset:2016
	ds_write_b16_d16_hi v240, v38 offset:2160
	v_mul_f32_e32 v32, v41, v175
	v_mul_f32_e32 v33, v41, v176
	v_mul_f32_e32 v34, v41, v177
	v_mul_f32_e32 v35, v41, v178
	v_mul_f32_e32 v36, v41, v179
	v_mul_f32_e32 v37, v41, v180
	v_mul_f32_e32 v38, v41, v181
	v_mul_f32_e32 v39, v41, v182
	v_fmac_f32_e32 v32, v40, v174
	v_fmac_f32_e32 v33, v40, v175
	v_fmac_f32_e32 v34, v40, v176
	v_fmac_f32_e32 v35, v40, v177
	v_fmac_f32_e32 v36, v40, v178
	v_fmac_f32_e32 v37, v40, v179
	v_fmac_f32_e32 v38, v40, v180
	v_fmac_f32_e32 v39, v40, v181
	v_fmac_f32_e32 v32, v42, v176
	v_fmac_f32_e32 v33, v42, v177
	v_fmac_f32_e32 v34, v42, v178
	v_fmac_f32_e32 v35, v42, v179
	v_fmac_f32_e32 v36, v42, v180
	v_fmac_f32_e32 v37, v42, v181
	v_fmac_f32_e32 v38, v42, v182
	v_fmac_f32_e32 v39, v42, v183
	v_fmac_f32_e32 v32, v43, v177
	v_fmac_f32_e32 v33, v43, v178
	v_fmac_f32_e32 v34, v43, v179
	v_fmac_f32_e32 v35, v43, v180
	v_fmac_f32_e32 v36, v43, v181
	v_fmac_f32_e32 v37, v43, v182
	v_fmac_f32_e32 v38, v43, v183
	v_fmac_f32_e32 v39, v43, v184
	v_add_f32_e32 v32, v44, v32
	v_add_f32_e32 v33, v44, v33
	v_add_f32_e32 v34, v44, v34
	v_add_f32_e32 v35, v44, v35
	v_add_f32_e32 v36, v44, v36
	v_add_f32_e32 v37, v44, v37
	v_add_f32_e32 v38, v44, v38
	v_add_f32_e32 v39, v44, v39
	v_cvt_pk_bf16_f32 v32, v32, v33
	v_cvt_pk_bf16_f32 v34, v34, v35
	v_cvt_pk_bf16_f32 v36, v36, v37
	v_cvt_pk_bf16_f32 v38, v38, v39
	ds_write_b16 v240, v32 offset:2304
	ds_write_b16_d16_hi v240, v32 offset:2448
	ds_write_b16 v240, v34 offset:2592
	ds_write_b16_d16_hi v240, v34 offset:2736
	ds_write_b16 v240, v36 offset:2880
	ds_write_b16_d16_hi v240, v36 offset:3024
	ds_write_b16 v240, v38 offset:3168
	ds_write_b16_d16_hi v240, v38 offset:3312
	v_mul_f32_e32 v32, v41, v183
	v_mul_f32_e32 v33, v41, v184
	v_mul_f32_e32 v34, v41, v185
	v_mul_f32_e32 v35, v41, v186
; __device__ __forceinline__ unsigned f2bf(float f) { unsigned r; asm("v_cvt_pk_bf16_f32 %0, %1, %1" : "=v"(r) : "v"(f)); return r & 0xffffu; }
; template <bool FINAL>
; __device__ __forceinline__ void rg_item(PREF p, int l, int item, LAS unsigned char* wl, int lane) {
;     ...
;         for (int i = 0; i < 67; ++i) { const int t = t0 - 2 + i; const int tc = t < 0 ? 0 : (t >= seqlen ? seqlen - 1 : t); xv[i] = (t == tc) ? bf2f(xr_[i]) : 0.f; }
; #pragma unroll
;         for (int tt = 0; tt < 64; ++tt) { const float xc = xv[tt] * cw0 + xv[tt + 1] * cw1 + xv[tt + 2] * cw2 + xv[tt + 3] * cw3 + cb; sXc[tt * 72 + lane] = (bf16_t)f2bf(xc); }
	v_mul_f32_e32 v36, v41, v187
	v_mul_f32_e32 v37, v41, v188
	v_mul_f32_e32 v38, v41, v189
	v_mul_f32_e32 v39, v41, v190
	v_fmac_f32_e32 v32, v40, v182
	v_fmac_f32_e32 v33, v40, v183
	v_fmac_f32_e32 v34, v40, v184
	v_fmac_f32_e32 v35, v40, v185
	v_fmac_f32_e32 v36, v40, v186
	v_fmac_f32_e32 v37, v40, v187
	v_fmac_f32_e32 v38, v40, v188
	v_fmac_f32_e32 v39, v40, v189
	v_fmac_f32_e32 v32, v42, v184
	v_fmac_f32_e32 v33, v42, v185
	v_fmac_f32_e32 v34, v42, v186
	v_fmac_f32_e32 v35, v42, v187
	v_fmac_f32_e32 v36, v42, v188
	v_fmac_f32_e32 v37, v42, v189
	v_fmac_f32_e32 v38, v42, v190
	v_fmac_f32_e32 v39, v42, v191
	v_fmac_f32_e32 v32, v43, v185
	v_fmac_f32_e32 v33, v43, v186
	v_fmac_f32_e32 v34, v43, v187
	v_fmac_f32_e32 v35, v43, v188
	v_fmac_f32_e32 v36, v43, v189
	v_fmac_f32_e32 v37, v43, v190
	v_fmac_f32_e32 v38, v43, v191
	v_fmac_f32_e32 v39, v43, v192
	v_add_f32_e32 v32, v44, v32
	v_add_f32_e32 v33, v44, v33
	v_add_f32_e32 v34, v44, v34
	v_add_f32_e32 v35, v44, v35
	v_add_f32_e32 v36, v44, v36
	v_add_f32_e32 v37, v44, v37
	v_add_f32_e32 v38, v44, v38
	v_add_f32_e32 v39, v44, v39
	v_cvt_pk_bf16_f32 v32, v32, v33
	v_cvt_pk_bf16_f32 v34, v34, v35
	v_cvt_pk_bf16_f32 v36, v36, v37
	v_cvt_pk_bf16_f32 v38, v38, v39
	ds_write_b16 v240, v32 offset:3456
	ds_write_b16_d16_hi v240, v32 offset:3600
	ds_write_b16 v240, v34 offset:3744
	ds_write_b16_d16_hi v240, v34 offset:3888
	ds_write_b16 v240, v36 offset:4032
	ds_write_b16_d16_hi v240, v36 offset:4176
	ds_write_b16 v240, v38 offset:4320
	ds_write_b16_d16_hi v240, v38 offset:4464
	v_mul_f32_e32 v32, v41, v191
	v_mul_f32_e32 v33, v41, v192
	v_mul_f32_e32 v34, v41, v193
	v_mul_f32_e32 v35, v41, v194
	v_mul_f32_e32 v36, v41, v195
	v_mul_f32_e32 v37, v41, v196
	v_mul_f32_e32 v38, v41, v197
	v_mul_f32_e32 v39, v41, v198
	v_fmac_f32_e32 v32, v40, v190
	v_fmac_f32_e32 v33, v40, v191
	v_fmac_f32_e32 v34, v40, v192
	v_fmac_f32_e32 v35, v40, v193
	v_fmac_f32_e32 v36, v40, v194
	v_fmac_f32_e32 v37, v40, v195
	v_fmac_f32_e32 v38, v40, v196
	v_fmac_f32_e32 v39, v40, v197
	v_fmac_f32_e32 v32, v42, v192
	v_fmac_f32_e32 v33, v42, v193
	v_fmac_f32_e32 v34, v42, v194
	v_fmac_f32_e32 v35, v42, v195
	v_fmac_f32_e32 v36, v42, v196
	v_fmac_f32_e32 v37, v42, v197
	v_fmac_f32_e32 v38, v42, v198
	v_fmac_f32_e32 v39, v42, v199
	v_fmac_f32_e32 v32, v43, v193
	v_fmac_f32_e32 v33, v43, v194
	v_fmac_f32_e32 v34, v43, v195
	v_fmac_f32_e32 v35, v43, v196
	v_fmac_f32_e32 v36, v43, v197
	v_fmac_f32_e32 v37, v43, v198
	v_fmac_f32_e32 v38, v43, v199
	v_fmac_f32_e32 v39, v43, v200
	v_add_f32_e32 v32, v44, v32
	v_add_f32_e32 v33, v44, v33
	v_add_f32_e32 v34, v44, v34
	v_add_f32_e32 v35, v44, v35
	v_add_f32_e32 v36, v44, v36
	v_add_f32_e32 v37, v44, v37
	v_add_f32_e32 v38, v44, v38
	v_add_f32_e32 v39, v44, v39
	v_cvt_pk_bf16_f32 v32, v32, v33
	v_cvt_pk_bf16_f32 v34, v34, v35
	v_cvt_pk_bf16_f32 v36, v36, v37
	v_cvt_pk_bf16_f32 v38, v38, v39
	ds_write_b16 v240, v32 offset:4608
	ds_write_b16_d16_hi v240, v32 offset:4752
	ds_write_b16 v240, v34 offset:4896
	ds_write_b16_d16_hi v240, v34 offset:5040
	ds_write_b16 v240, v36 offset:5184
	ds_write_b16_d16_hi v240, v36 offset:5328
	ds_write_b16 v240, v38 offset:5472
	ds_write_b16_d16_hi v240, v38 offset:5616
	v_mul_f32_e32 v32, v41, v199
	v_mul_f32_e32 v33, v41, v200
	v_mul_f32_e32 v34, v41, v201
	v_mul_f32_e32 v35, v41, v202
	v_mul_f32_e32 v36, v41, v203
	v_mul_f32_e32 v37, v41, v204
	v_mul_f32_e32 v38, v41, v205
	v_mul_f32_e32 v39, v41, v206
	v_fmac_f32_e32 v32, v40, v198
	v_fmac_f32_e32 v33, v40, v199
	v_fmac_f32_e32 v34, v40, v200
	v_fmac_f32_e32 v35, v40, v201
	v_fmac_f32_e32 v36, v40, v202
	v_fmac_f32_e32 v37, v40, v203
	v_fmac_f32_e32 v38, v40, v204
	v_fmac_f32_e32 v39, v40, v205
	v_fmac_f32_e32 v32, v42, v200
	v_fmac_f32_e32 v33, v42, v201
	v_fmac_f32_e32 v34, v42, v202
	v_fmac_f32_e32 v35, v42, v203
	v_fmac_f32_e32 v36, v42, v204
	v_fmac_f32_e32 v37, v42, v205
	v_fmac_f32_e32 v38, v42, v206
	v_fmac_f32_e32 v39, v42, v207
	v_fmac_f32_e32 v32, v43, v201
	v_fmac_f32_e32 v33, v43, v202
	v_fmac_f32_e32 v34, v43, v203
	v_fmac_f32_e32 v35, v43, v204
	v_fmac_f32_e32 v36, v43, v205
	v_fmac_f32_e32 v37, v43, v206
	v_fmac_f32_e32 v38, v43, v207
	v_fmac_f32_e32 v39, v43, v208
	v_add_f32_e32 v32, v44, v32
	v_add_f32_e32 v33, v44, v33
	v_add_f32_e32 v34, v44, v34
	v_add_f32_e32 v35, v44, v35
	v_add_f32_e32 v36, v44, v36
	v_add_f32_e32 v37, v44, v37
	v_add_f32_e32 v38, v44, v38
	v_add_f32_e32 v39, v44, v39
	v_cvt_pk_bf16_f32 v32, v32, v33
	v_cvt_pk_bf16_f32 v34, v34, v35
	v_cvt_pk_bf16_f32 v36, v36, v37
	v_cvt_pk_bf16_f32 v38, v38, v39
	ds_write_b16 v240, v32 offset:5760
	ds_write_b16_d16_hi v240, v32 offset:5904
	ds_write_b16 v240, v34 offset:6048
	ds_write_b16_d16_hi v240, v34 offset:6192
	ds_write_b16 v240, v36 offset:6336
	ds_write_b16_d16_hi v240, v36 offset:6480
	ds_write_b16 v240, v38 offset:6624
	ds_write_b16_d16_hi v240, v38 offset:6768
	v_mul_f32_e32 v32, v41, v207
	v_mul_f32_e32 v33, v41, v208
	v_mul_f32_e32 v34, v41, v209
	v_mul_f32_e32 v35, v41, v210
	v_mul_f32_e32 v36, v41, v211
	v_mul_f32_e32 v37, v41, v212
	v_mul_f32_e32 v38, v41, v213
	v_mul_f32_e32 v39, v41, v214
	v_fmac_f32_e32 v32, v40, v206
	v_fmac_f32_e32 v33, v40, v207
	v_fmac_f32_e32 v34, v40, v208
	v_fmac_f32_e32 v35, v40, v209
	v_fmac_f32_e32 v36, v40, v210
	v_fmac_f32_e32 v37, v40, v211
	v_fmac_f32_e32 v38, v40, v212
	v_fmac_f32_e32 v39, v40, v213
	v_fmac_f32_e32 v32, v42, v208
	v_fmac_f32_e32 v33, v42, v209
	v_fmac_f32_e32 v34, v42, v210
	v_fmac_f32_e32 v35, v42, v211
	v_fmac_f32_e32 v36, v42, v212
	v_fmac_f32_e32 v37, v42, v213
	v_fmac_f32_e32 v38, v42, v214
	v_fmac_f32_e32 v39, v42, v215
	v_fmac_f32_e32 v32, v43, v209
; __device__ __forceinline__ unsigned f2bf(float f) { unsigned r; asm("v_cvt_pk_bf16_f32 %0, %1, %1" : "=v"(r) : "v"(f)); return r & 0xffffu; }
; __device__ __forceinline__ float rcpf_(float x) { return __builtin_amdgcn_rcpf(x); }
; template <bool FINAL, int D>
; __device__ __forceinline__ void rg_dir(PREF p, int l, int h, int ch, int sidx, int rowbase  , LAS bf16_t* sXc, LAS float* stg, int lane) {
;     ...
;     const float ba = p.rg_ba[(l * 2 + D) * 512 + ch], bi = p.rg_bi[(l * 2 + D) * 512 + ch], lam = p.rg_lam[(l * 2 + D) * 512 + ch];
;     const float e_ = __expf(-lam), u_ = 1.f + e_;
;     const float l1p = (u_ == 1.f) ? e_ : __logf(u_) * e_ * rcpf_(u_ - 1.f);
;     const float sp8 = -8.f * 1.4426950408889634f * l1p;
;     float hc = FINAL ? RGC[sidx] : 0.f, Ap = 1.f;
;     bf16x8 Br[4][2], Bi[4][2];
; #pragma unroll
;     for (int nt = 0; nt < 4; ++nt) { const int o0 = (nt * 16 + (lane & 15)) * 64 + (lane >> 4) * 8;
;         Br[nt][0] = *(const bf16x8*)(wr_ + o0); Br[nt][1] = *(const bf16x8*)(wr_ + o0 + 32); Bi[nt][0] = *(const bf16x8*)(wi_ + o0); Bi[nt][1] = *(const bf16x8*)(wi_ + o0 + 32); }
;     if (FINAL && D == 1) asm volatile("s_waitcnt vmcnt(0)" ::: "memory");
; #pragma unroll 1
;     for (int mi = 0; mi < 4; ++mi) { const int mt = D ? 3 - mi : mi;
;         float grv[16], hfv[16];
;         if (FINAL && D == 1) {
; #pragma unroll
;             for (int ti = 0; ti < 16; ++ti) { const size_t row = (size_t)(rowbase + mt * 16 + 15 - ti); grv[ti] = __builtin_bit_cast(float, (unsigned)P[row * PW + 512 + ch]); hfv[ti] = __builtin_bit_cast(float, (unsigned)TMP[row * 512 + ch]); }
; template <bool FINAL>
; __device__ __forceinline__ void rg_item(PREF p, int l, int item, LAS unsigned char* wl, int lane) {
;     ...
;         for (int tt = 0; tt < 64; ++tt) { const float xc = xv[tt] * cw0 + xv[tt + 1] * cw1 + xv[tt + 2] * cw2 + xv[tt + 3] * cw3 + cb; sXc[tt * 72 + lane] = (bf16_t)f2bf(xc); }
	v_fmac_f32_e32 v33, v43, v210
	v_fmac_f32_e32 v34, v43, v211
	v_fmac_f32_e32 v35, v43, v212
	v_fmac_f32_e32 v36, v43, v213
	v_fmac_f32_e32 v37, v43, v214
	v_fmac_f32_e32 v38, v43, v215
	v_fmac_f32_e32 v39, v43, v216
	v_add_f32_e32 v32, v44, v32
	v_add_f32_e32 v33, v44, v33
	v_add_f32_e32 v34, v44, v34
	v_add_f32_e32 v35, v44, v35
	v_add_f32_e32 v36, v44, v36
	v_add_f32_e32 v37, v44, v37
	v_add_f32_e32 v38, v44, v38
	v_add_f32_e32 v39, v44, v39
	v_cvt_pk_bf16_f32 v32, v32, v33
	v_cvt_pk_bf16_f32 v34, v34, v35
	v_cvt_pk_bf16_f32 v36, v36, v37
	v_cvt_pk_bf16_f32 v38, v38, v39
	ds_write_b16 v240, v32 offset:6912
	ds_write_b16_d16_hi v240, v32 offset:7056
	ds_write_b16 v240, v34 offset:7200
	ds_write_b16_d16_hi v240, v34 offset:7344
	ds_write_b16 v240, v36 offset:7488
	ds_write_b16_d16_hi v240, v36 offset:7632
	ds_write_b16 v240, v38 offset:7776
	ds_write_b16_d16_hi v240, v38 offset:7920
	v_mul_f32_e32 v32, v41, v215
	v_mul_f32_e32 v33, v41, v216
	v_mul_f32_e32 v34, v41, v217
	v_mul_f32_e32 v35, v41, v218
	v_mul_f32_e32 v36, v41, v219
	v_mul_f32_e32 v37, v41, v222
	v_mul_f32_e32 v38, v41, v223
	v_mul_f32_e32 v39, v41, v140
	v_fmac_f32_e32 v32, v40, v214
	v_fmac_f32_e32 v33, v40, v215
	v_fmac_f32_e32 v34, v40, v216
	v_fmac_f32_e32 v35, v40, v217
	v_fmac_f32_e32 v36, v40, v218
	v_fmac_f32_e32 v37, v40, v219
	v_fmac_f32_e32 v38, v40, v222
	v_fmac_f32_e32 v39, v40, v223
	v_fmac_f32_e32 v32, v42, v216
	v_fmac_f32_e32 v33, v42, v217
	v_fmac_f32_e32 v34, v42, v218
	v_fmac_f32_e32 v35, v42, v219
	v_fmac_f32_e32 v36, v42, v222
	v_fmac_f32_e32 v37, v42, v223
	v_fmac_f32_e32 v38, v42, v140
	v_fmac_f32_e32 v39, v42, v141
	v_fmac_f32_e32 v32, v43, v217
	v_fmac_f32_e32 v33, v43, v218
	v_fmac_f32_e32 v34, v43, v219
	v_fmac_f32_e32 v35, v43, v222
	v_fmac_f32_e32 v36, v43, v223
	v_fmac_f32_e32 v37, v43, v140
	v_fmac_f32_e32 v38, v43, v141
	v_fmac_f32_e32 v39, v43, v232
	v_add_f32_e32 v32, v44, v32
	v_add_f32_e32 v33, v44, v33
	v_add_f32_e32 v34, v44, v34
	v_add_f32_e32 v35, v44, v35
	v_add_f32_e32 v36, v44, v36
	v_add_f32_e32 v37, v44, v37
	v_add_f32_e32 v38, v44, v38
	v_add_f32_e32 v39, v44, v39
	v_cvt_pk_bf16_f32 v32, v32, v33
	v_cvt_pk_bf16_f32 v34, v34, v35
	v_cvt_pk_bf16_f32 v36, v36, v37
	v_cvt_pk_bf16_f32 v38, v38, v39
	ds_write_b16 v240, v32 offset:8064
	ds_write_b16_d16_hi v240, v32 offset:8208
	ds_write_b16 v240, v34 offset:8352
	ds_write_b16_d16_hi v240, v34 offset:8496
	ds_write_b16 v240, v36 offset:8640
	ds_write_b16_d16_hi v240, v36 offset:8784
	ds_write_b16 v240, v38 offset:8928
	ds_write_b16_d16_hi v240, v38 offset:9072
	v_mov_b32_e32 v248, 0xbfb8aa3b
	v_mov_b32_e32 v249, 0xbfb8aa3b
	v_mov_b32_e32 v140, 0x3d372713
	v_mov_b32_e32 v141, 0x3d372713
	s_waitcnt vmcnt(16)
	s_mov_b32 s8, 0x800000
	s_mov_b32 s9, 0x3f317217
	s_mov_b32 s14, 0x7f800000
	v_mul_f32_e32 v32, 0xbfb8aa3b, v45
	v_exp_f32_e32 v32, v32
	s_nop 0
	v_add_f32_e32 v33, 1.0, v32
	v_cmp_gt_f32_e32 vcc, s8, v33
	s_nop 1
	v_cndmask_b32_e64 v34, 0, 32, vcc
	v_ldexp_f32 v34, v33, v34
	v_log_f32_e32 v34, v34
	v_cndmask_b32_e32 v36, 0, v226, vcc
	v_cmp_eq_f32_e32 vcc, 1.0, v33
	v_mul_f32_e32 v35, 0x3f317217, v34
	v_fma_f32 v35, v34, s9, -v35
	v_fmac_f32_e32 v35, 0x3377d1cf, v34
	v_fmac_f32_e32 v35, 0x3f317217, v34
	v_cmp_lt_f32_e64 s[10:11], |v34|, s14
	s_nop 1
	v_cndmask_b32_e64 v34, v34, v35, s[10:11]
	v_add_f32_e32 v35, -1.0, v33
	v_rcp_f32_e32 v35, v35
	v_sub_f32_e32 v34, v34, v36
	v_mul_f32_e32 v34, v32, v34
	v_mul_f32_e32 v34, v34, v35
	v_cndmask_b32_e32 v32, v34, v32, vcc
	v_mul_f32_e32 v246, 0xc138aa3b, v32
	v_mov_b32_e32 v247, v246
	v_mul_f32_e32 v242, 0xbfb8aa3b, v46
	v_mul_f32_e32 v244, 0xbfb8aa3b, v47
	v_mov_b32_e32 v243, v242
	v_mov_b32_e32 v245, v244
	s_waitcnt vmcnt(0)
	s_add_i32 s39, s15, 48
	s_mul_hi_u32 s83, s39, 0x1600
	s_mul_i32 s82, s39, 0x1600
	s_add_u32 s82, s82, s0
	s_addc_u32 s83, s83, s1
	s_add_u32 s82, s82, 0xbc00400
	s_addc_u32 s83, s83, 0
	global_load_ushort v190, v234, s[82:83]
	s_add_u32 s82, s82, 0x1600
	s_addc_u32 s83, s83, 0
	global_load_ushort v191, v234, s[82:83]
	s_add_u32 s82, s82, 0x1600
	s_addc_u32 s83, s83, 0
	global_load_ushort v192, v234, s[82:83]
	s_add_u32 s82, s82, 0x1600
	s_addc_u32 s83, s83, 0
	global_load_ushort v193, v234, s[82:83]
	s_add_u32 s82, s82, 0x1600
	s_addc_u32 s83, s83, 0
	global_load_ushort v194, v234, s[82:83]
	s_add_u32 s82, s82, 0x1600
	s_addc_u32 s83, s83, 0
	global_load_ushort v195, v234, s[82:83]
	s_add_u32 s82, s82, 0x1600
	s_addc_u32 s83, s83, 0
	global_load_ushort v196, v234, s[82:83]
	s_add_u32 s82, s82, 0x1600
	s_addc_u32 s83, s83, 0
	global_load_ushort v197, v234, s[82:83]
	s_add_u32 s82, s82, 0x1600
	s_addc_u32 s83, s83, 0
	global_load_ushort v198, v234, s[82:83]
	s_add_u32 s82, s82, 0x1600
	s_addc_u32 s83, s83, 0
	global_load_ushort v199, v234, s[82:83]
	s_add_u32 s82, s82, 0x1600
	s_addc_u32 s83, s83, 0
	global_load_ushort v200, v234, s[82:83]
	s_add_u32 s82, s82, 0x1600
	s_addc_u32 s83, s83, 0
	global_load_ushort v201, v234, s[82:83]
	s_add_u32 s82, s82, 0x1600
	s_addc_u32 s83, s83, 0
	global_load_ushort v202, v234, s[82:83]
	s_add_u32 s82, s82, 0x1600
	s_addc_u32 s83, s83, 0
	global_load_ushort v203, v234, s[82:83]
	s_add_u32 s82, s82, 0x1600
	s_addc_u32 s83, s83, 0
	global_load_ushort v204, v234, s[82:83]
	s_add_u32 s82, s82, 0x1600
	s_addc_u32 s83, s83, 0
	global_load_ushort v205, v234, s[82:83]
	ds_read_b128 v[32:35], v236 offset:0
	ds_read_b128 v[36:39], v236 offset:64
	s_waitcnt lgkmcnt(0)
; #define LAS __attribute__((address_space(3)))
; #define WAVE_SYNC() asm volatile("s_waitcnt lgkmcnt(0)" ::: "memory")
; __device__ __forceinline__ float sigmoid_f(float x) { return rcpf_(1.f + __expf(-x)); }
; __device__ __forceinline__ f32x4 mfma16(bf16x8 a, bf16x8 b, f32x4 c) { return __builtin_amdgcn_mfma_f32_16x16x32_bf16(a, b, c, 0, 0, 0); }
; template <bool FINAL, int D>
; __device__ __forceinline__ void rg_dir(PREF p, int l, int h, int ch, int sidx, int rowbase  , LAS bf16_t* sXc, LAS float* stg, int lane) {
;     ...
;         const bf16x8 A0 = *(const LAS bf16x8*)(sXc + (mt * 16 + (lane & 15)) * 72 + (lane >> 4) * 8), A1 = *(const LAS bf16x8*)(sXc + (mt * 16 + (lane & 15)) * 72 + 32 + (lane >> 4) * 8);
;         f32x4 ar[4], ai[4];
; #pragma unroll
;         for (int nt = 0; nt < 4; ++nt) { const f32x4 z = {0.f, 0.f, 0.f, 0.f};
;             ar[nt] = mfma16(A0, Br[nt][0], z); ar[nt] = mfma16(A1, Br[nt][1], ar[nt]); ai[nt] = mfma16(A0, Bi[nt][0], z); ai[nt] = mfma16(A1, Bi[nt][1], ai[nt]); }
;         WAVE_SYNC();
; #pragma unroll
;         for (int nt = 0; nt < 4; ++nt)
; #pragma unroll
;             for (int j = 0; j < 4; ++j) { const int o = ((lane >> 4) * 4 + j) * 64 + nt * 16 + (lane & 15); stg[o] = ar[nt][j]; stg[1024 + o] = ai[nt][j]; }
;         WAVE_SYNC();
;         float av[16], iv[16];
; #pragma unroll
;         for (int ti = 0; ti < 16; ++ti) { const int tk = D ? 15 - ti : ti;
;             const float zr = stg[tk * 64 + lane] + ba, zi = stg[1024 + tk * 64 + lane] + bi;
;             const float r = sigmoid_f(zr), ig = sigmoid_f(zi);
;             const float a = __builtin_amdgcn_exp2f(r * sp8);
;             const float xc = bf2f(sXc[(mt * 16 + tk) * 72 + lane]);
	v_mfma_f32_16x16x32_bf16 v[0:3], v[32:35], v[80:83], 0
	v_mfma_f32_16x16x32_bf16 v[4:7], v[32:35], v[88:91], 0
	v_mfma_f32_16x16x32_bf16 v[8:11], v[32:35], v[96:99], 0
	v_mfma_f32_16x16x32_bf16 v[12:15], v[32:35], v[104:107], 0
	v_mfma_f32_16x16x32_bf16 v[16:19], v[32:35], v[112:115], 0
	v_mfma_f32_16x16x32_bf16 v[20:23], v[32:35], v[120:123], 0
	v_mfma_f32_16x16x32_bf16 v[24:27], v[32:35], v[128:131], 0
	v_mfma_f32_16x16x32_bf16 v[28:31], v[32:35], v[136:139], 0
	v_mfma_f32_16x16x32_bf16 v[0:3], v[36:39], v[84:87], v[0:3]
	v_mfma_f32_16x16x32_bf16 v[4:7], v[36:39], v[92:95], v[4:7]
	v_mfma_f32_16x16x32_bf16 v[8:11], v[36:39], v[100:103], v[8:11]
	v_mfma_f32_16x16x32_bf16 v[12:15], v[36:39], v[108:111], v[12:15]
	v_mfma_f32_16x16x32_bf16 v[16:19], v[36:39], v[116:119], v[16:19]
	v_mfma_f32_16x16x32_bf16 v[20:23], v[36:39], v[124:127], v[20:23]
	v_mfma_f32_16x16x32_bf16 v[24:27], v[36:39], v[132:135], v[24:27]
	v_mfma_f32_16x16x32_bf16 v[28:31], v[36:39], v[228:231], v[28:31]
	s_nop 3
	ds_write2_b32 v237, v0, v4 offset0:0 offset1:16
	ds_write2_b32 v237, v8, v12 offset0:32 offset1:48
	ds_write2_b32 v237, v1, v5 offset0:64 offset1:80
	ds_write2_b32 v237, v9, v13 offset0:96 offset1:112
	ds_write2_b32 v237, v2, v6 offset0:128 offset1:144
	ds_write2_b32 v237, v10, v14 offset0:160 offset1:176
	ds_write2_b32 v237, v3, v7 offset0:192 offset1:208
	ds_write2_b32 v237, v11, v15 offset0:224 offset1:240
	ds_write2_b32 v238, v16, v20 offset0:0 offset1:16
	ds_write2_b32 v238, v24, v28 offset0:32 offset1:48
	ds_write2_b32 v238, v17, v21 offset0:64 offset1:80
	ds_write2_b32 v238, v25, v29 offset0:96 offset1:112
	ds_write2_b32 v238, v18, v22 offset0:128 offset1:144
	ds_write2_b32 v238, v26, v30 offset0:160 offset1:176
	ds_write2_b32 v238, v19, v23 offset0:192 offset1:208
	ds_write2_b32 v238, v27, v31 offset0:224 offset1:240
	s_waitcnt lgkmcnt(0)
	ds_read2st64_b32 v[0:1], v239 offset0:36 offset1:37
	ds_read2st64_b32 v[2:3], v239 offset0:38 offset1:39
	ds_read2st64_b32 v[4:5], v239 offset0:40 offset1:41
	ds_read2st64_b32 v[6:7], v239 offset0:42 offset1:43
	ds_read2st64_b32 v[8:9], v239 offset0:44 offset1:45
	ds_read2st64_b32 v[10:11], v239 offset0:46 offset1:47
	ds_read2st64_b32 v[12:13], v239 offset0:48 offset1:49
	ds_read2st64_b32 v[14:15], v239 offset0:50 offset1:51
	ds_read2st64_b32 v[16:17], v239 offset0:52 offset1:53
	ds_read2st64_b32 v[18:19], v239 offset0:54 offset1:55
	ds_read2st64_b32 v[20:21], v239 offset0:56 offset1:57
	ds_read2st64_b32 v[22:23], v239 offset0:58 offset1:59
	ds_read2st64_b32 v[24:25], v239 offset0:60 offset1:61
	ds_read2st64_b32 v[26:27], v239 offset0:62 offset1:63
	ds_read2st64_b32 v[28:29], v239 offset0:64 offset1:65
	ds_read2st64_b32 v[30:31], v239 offset0:66 offset1:67
	ds_read_u16 v48, v240 offset:0
	ds_read_u16 v49, v240 offset:144
	ds_read_u16 v50, v240 offset:288
	ds_read_u16 v51, v240 offset:432
	ds_read_u16 v52, v240 offset:576
	ds_read_u16 v53, v240 offset:720
	ds_read_u16 v54, v240 offset:864
	ds_read_u16 v55, v240 offset:1008
	ds_read_u16 v56, v240 offset:1152
	ds_read_u16 v57, v240 offset:1296
	ds_read_u16 v58, v240 offset:1440
	ds_read_u16 v59, v240 offset:1584
	ds_read_u16 v60, v240 offset:1728
	ds_read_u16 v61, v240 offset:1872
	ds_read_u16 v62, v240 offset:2016
	ds_read_u16 v63, v240 offset:2160
	s_waitcnt lgkmcnt(0)
	v_pk_fma_f32 v[0:1], v[0:1], v[248:249], v[242:243]
	v_pk_fma_f32 v[2:3], v[2:3], v[248:249], v[242:243]
	v_pk_fma_f32 v[4:5], v[4:5], v[248:249], v[242:243]
	v_pk_fma_f32 v[6:7], v[6:7], v[248:249], v[242:243]
	v_pk_fma_f32 v[8:9], v[8:9], v[248:249], v[242:243]
	v_pk_fma_f32 v[10:11], v[10:11], v[248:249], v[242:243]
	v_pk_fma_f32 v[12:13], v[12:13], v[248:249], v[242:243]
	v_pk_fma_f32 v[14:15], v[14:15], v[248:249], v[242:243]
	v_pk_fma_f32 v[16:17], v[16:17], v[248:249], v[244:245]
	v_pk_fma_f32 v[18:19], v[18:19], v[248:249], v[244:245]
	v_pk_fma_f32 v[20:21], v[20:21], v[248:249], v[244:245]
	v_pk_fma_f32 v[22:23], v[22:23], v[248:249], v[244:245]
	v_pk_fma_f32 v[24:25], v[24:25], v[248:249], v[244:245]
	v_pk_fma_f32 v[26:27], v[26:27], v[248:249], v[244:245]
	v_pk_fma_f32 v[28:29], v[28:29], v[248:249], v[244:245]
	v_pk_fma_f32 v[30:31], v[30:31], v[248:249], v[244:245]
	v_exp_f32_e32 v0, v0
	v_exp_f32_e32 v1, v1
	v_exp_f32_e32 v2, v2
	v_exp_f32_e32 v3, v3
	v_exp_f32_e32 v4, v4
	v_exp_f32_e32 v5, v5
	v_exp_f32_e32 v6, v6
	v_exp_f32_e32 v7, v7
	v_exp_f32_e32 v8, v8
	v_exp_f32_e32 v9, v9
	v_exp_f32_e32 v10, v10
	v_exp_f32_e32 v11, v11
	v_exp_f32_e32 v12, v12
	v_exp_f32_e32 v13, v13
	v_exp_f32_e32 v14, v14
	v_exp_f32_e32 v15, v15
	v_exp_f32_e32 v16, v16
	v_exp_f32_e32 v17, v17
	v_exp_f32_e32 v18, v18
	v_exp_f32_e32 v19, v19
	v_exp_f32_e32 v20, v20
	v_exp_f32_e32 v21, v21
	v_exp_f32_e32 v22, v22
	v_exp_f32_e32 v23, v23
	v_exp_f32_e32 v24, v24
	v_exp_f32_e32 v25, v25
	v_exp_f32_e32 v26, v26
	v_exp_f32_e32 v27, v27
	v_exp_f32_e32 v28, v28
	v_exp_f32_e32 v29, v29
	v_exp_f32_e32 v30, v30
	v_exp_f32_e32 v31, v31
	v_pk_add_f32 v[0:1], v[0:1], 1.0 op_sel_hi:[1,0]
	v_pk_add_f32 v[2:3], v[2:3], 1.0 op_sel_hi:[1,0]
	v_pk_add_f32 v[4:5], v[4:5], 1.0 op_sel_hi:[1,0]
	v_pk_add_f32 v[6:7], v[6:7], 1.0 op_sel_hi:[1,0]
	v_pk_add_f32 v[8:9], v[8:9], 1.0 op_sel_hi:[1,0]
	v_pk_add_f32 v[10:11], v[10:11], 1.0 op_sel_hi:[1,0]
	v_pk_add_f32 v[12:13], v[12:13], 1.0 op_sel_hi:[1,0]
	v_pk_add_f32 v[14:15], v[14:15], 1.0 op_sel_hi:[1,0]
	v_pk_add_f32 v[16:17], v[16:17], 1.0 op_sel_hi:[1,0]
	v_pk_add_f32 v[18:19], v[18:19], 1.0 op_sel_hi:[1,0]
	v_pk_add_f32 v[20:21], v[20:21], 1.0 op_sel_hi:[1,0]
	v_pk_add_f32 v[22:23], v[22:23], 1.0 op_sel_hi:[1,0]
	v_pk_add_f32 v[24:25], v[24:25], 1.0 op_sel_hi:[1,0]
; #define LAS __attribute__((address_space(3)))
; #define WAVE_SYNC() asm volatile("s_waitcnt lgkmcnt(0)" ::: "memory")
; __device__ __forceinline__ unsigned f2bf(float f) { unsigned r; asm("v_cvt_pk_bf16_f32 %0, %1, %1" : "=v"(r) : "v"(f)); return r & 0xffffu; }
; __device__ __forceinline__ float sigmoid_f(float x) { return rcpf_(1.f + __expf(-x)); }
; template <bool FINAL, int D>
; __device__ __forceinline__ void rg_dir(PREF p, int l, int h, int ch, int sidx, int rowbase  , LAS bf16_t* sXc, LAS float* stg, int lane) {
;     ...
;         const bf16x8 A0 = *(const LAS bf16x8*)(sXc + (mt * 16 + (lane & 15)) * 72 + (lane >> 4) * 8), A1 = *(const LAS bf16x8*)(sXc + (mt * 16 + (lane & 15)) * 72 + 32 + (lane >> 4) * 8);
;         f32x4 ar[4], ai[4];
; #pragma unroll
;         for (int nt = 0; nt < 4; ++nt) { const f32x4 z = {0.f, 0.f, 0.f, 0.f};
;             ar[nt] = mfma16(A0, Br[nt][0], z); ar[nt] = mfma16(A1, Br[nt][1], ar[nt]); ai[nt] = mfma16(A0, Bi[nt][0], z); ai[nt] = mfma16(A1, Bi[nt][1], ai[nt]); }
;         WAVE_SYNC();
; #pragma unroll
;         for (int nt = 0; nt < 4; ++nt)
; #pragma unroll
;             for (int j = 0; j < 4; ++j) { const int o = ((lane >> 4) * 4 + j) * 64 + nt * 16 + (lane & 15); stg[o] = ar[nt][j]; stg[1024 + o] = ai[nt][j]; }
;         WAVE_SYNC();
;         float av[16], iv[16];
; #pragma unroll
;         for (int ti = 0; ti < 16; ++ti) { const int tk = D ? 15 - ti : ti;
;             const float zr = stg[tk * 64 + lane] + ba, zi = stg[1024 + tk * 64 + lane] + bi;
;             const float r = sigmoid_f(zr), ig = sigmoid_f(zi);
;             const float a = __builtin_amdgcn_exp2f(r * sp8);
;             const float xc = bf2f(sXc[(mt * 16 + tk) * 72 + lane]);
;             av[ti] = a; iv[ti] = __builtin_amdgcn_sqrtf(fmaxf(1.f - a * a, 0.f)) * ig * xc;
;             if (FINAL && D == 1) grv[ti] = gelu_tanh_f(grv[ti]);
;         }
; #pragma unroll
;         for (int ti = 0; ti < 16; ++ti) { const int tk = D ? 15 - ti : ti;
;             hc = av[ti] * hc + iv[ti]; Ap *= av[ti];
;             if (FINAL) { const size_t row = (size_t)(rowbase + mt * 16 + tk);
;                 if (D == 0) TMP[row * 512 + ch] = (bf16_t)f2bf(hc);
;                 else MIX[row * DM + ch] = (bf16_t)f2bf(grv[ti] * (hfv[ti] + hc)); }
;         }
	v_pk_add_f32 v[26:27], v[26:27], 1.0 op_sel_hi:[1,0]
	v_pk_add_f32 v[28:29], v[28:29], 1.0 op_sel_hi:[1,0]
	v_pk_add_f32 v[30:31], v[30:31], 1.0 op_sel_hi:[1,0]
	v_rcp_f32_e32 v0, v0
	v_rcp_f32_e32 v1, v1
	v_rcp_f32_e32 v2, v2
	v_rcp_f32_e32 v3, v3
	v_rcp_f32_e32 v4, v4
	v_rcp_f32_e32 v5, v5
	v_rcp_f32_e32 v6, v6
	v_rcp_f32_e32 v7, v7
	v_rcp_f32_e32 v8, v8
	v_rcp_f32_e32 v9, v9
	v_rcp_f32_e32 v10, v10
	v_rcp_f32_e32 v11, v11
	v_rcp_f32_e32 v12, v12
	v_rcp_f32_e32 v13, v13
	v_rcp_f32_e32 v14, v14
	v_rcp_f32_e32 v15, v15
	v_rcp_f32_e32 v16, v16
	v_rcp_f32_e32 v17, v17
	v_rcp_f32_e32 v18, v18
	v_rcp_f32_e32 v19, v19
	v_rcp_f32_e32 v20, v20
	v_rcp_f32_e32 v21, v21
	v_rcp_f32_e32 v22, v22
	v_rcp_f32_e32 v23, v23
	v_rcp_f32_e32 v24, v24
	v_rcp_f32_e32 v25, v25
	v_rcp_f32_e32 v26, v26
	v_rcp_f32_e32 v27, v27
	v_rcp_f32_e32 v28, v28
	v_rcp_f32_e32 v29, v29
	v_rcp_f32_e32 v30, v30
	v_rcp_f32_e32 v31, v31
	v_pk_mul_f32 v[0:1], v[246:247], v[0:1]
	v_pk_mul_f32 v[2:3], v[246:247], v[2:3]
	v_pk_mul_f32 v[4:5], v[246:247], v[4:5]
	v_pk_mul_f32 v[6:7], v[246:247], v[6:7]
	v_pk_mul_f32 v[8:9], v[246:247], v[8:9]
	v_pk_mul_f32 v[10:11], v[246:247], v[10:11]
	v_pk_mul_f32 v[12:13], v[246:247], v[12:13]
	v_pk_mul_f32 v[14:15], v[246:247], v[14:15]
	v_lshlrev_b32_e32 v48, 16, v48
	v_lshlrev_b32_e32 v49, 16, v49
	v_lshlrev_b32_e32 v50, 16, v50
	v_lshlrev_b32_e32 v51, 16, v51
	v_lshlrev_b32_e32 v52, 16, v52
	v_lshlrev_b32_e32 v53, 16, v53
	v_lshlrev_b32_e32 v54, 16, v54
	v_lshlrev_b32_e32 v55, 16, v55
	v_lshlrev_b32_e32 v56, 16, v56
	v_lshlrev_b32_e32 v57, 16, v57
	v_lshlrev_b32_e32 v58, 16, v58
	v_lshlrev_b32_e32 v59, 16, v59
	v_lshlrev_b32_e32 v60, 16, v60
	v_lshlrev_b32_e32 v61, 16, v61
	v_lshlrev_b32_e32 v62, 16, v62
	v_lshlrev_b32_e32 v63, 16, v63
	v_exp_f32_e32 v0, v0
	v_exp_f32_e32 v1, v1
	v_exp_f32_e32 v2, v2
	v_exp_f32_e32 v3, v3
	v_exp_f32_e32 v4, v4
	v_exp_f32_e32 v5, v5
	v_exp_f32_e32 v6, v6
	v_exp_f32_e32 v7, v7
	v_exp_f32_e32 v8, v8
	v_exp_f32_e32 v9, v9
	v_exp_f32_e32 v10, v10
	v_exp_f32_e32 v11, v11
	v_exp_f32_e32 v12, v12
	v_exp_f32_e32 v13, v13
	v_exp_f32_e32 v14, v14
	v_exp_f32_e32 v15, v15
	v_fma_f32 v32, -v0, v0, 1.0 clamp
	v_fma_f32 v33, -v1, v1, 1.0 clamp
	v_fma_f32 v34, -v2, v2, 1.0 clamp
	v_fma_f32 v35, -v3, v3, 1.0 clamp
	v_fma_f32 v36, -v4, v4, 1.0 clamp
	v_fma_f32 v37, -v5, v5, 1.0 clamp
	v_fma_f32 v38, -v6, v6, 1.0 clamp
	v_fma_f32 v39, -v7, v7, 1.0 clamp
	v_fma_f32 v40, -v8, v8, 1.0 clamp
	v_fma_f32 v41, -v9, v9, 1.0 clamp
	v_fma_f32 v42, -v10, v10, 1.0 clamp
	v_fma_f32 v43, -v11, v11, 1.0 clamp
	v_fma_f32 v44, -v12, v12, 1.0 clamp
	v_fma_f32 v45, -v13, v13, 1.0 clamp
	v_fma_f32 v46, -v14, v14, 1.0 clamp
	v_fma_f32 v47, -v15, v15, 1.0 clamp
	v_sqrt_f32_e32 v32, v32
	v_sqrt_f32_e32 v33, v33
	v_sqrt_f32_e32 v34, v34
	v_sqrt_f32_e32 v35, v35
	v_sqrt_f32_e32 v36, v36
	v_sqrt_f32_e32 v37, v37
	v_sqrt_f32_e32 v38, v38
	v_sqrt_f32_e32 v39, v39
	v_sqrt_f32_e32 v40, v40
	v_sqrt_f32_e32 v41, v41
	v_sqrt_f32_e32 v42, v42
	v_sqrt_f32_e32 v43, v43
	v_sqrt_f32_e32 v44, v44
	v_sqrt_f32_e32 v45, v45
	v_sqrt_f32_e32 v46, v46
	v_sqrt_f32_e32 v47, v47
	s_nop 0
	v_pk_mul_f32 v[16:17], v[16:17], v[32:33]
	v_pk_mul_f32 v[18:19], v[18:19], v[34:35]
	v_pk_mul_f32 v[20:21], v[20:21], v[36:37]
	v_pk_mul_f32 v[22:23], v[22:23], v[38:39]
	v_pk_mul_f32 v[24:25], v[24:25], v[40:41]
	v_pk_mul_f32 v[26:27], v[26:27], v[42:43]
	v_pk_mul_f32 v[28:29], v[28:29], v[44:45]
	v_pk_mul_f32 v[30:31], v[30:31], v[46:47]
	v_pk_mul_f32 v[16:17], v[16:17], v[48:49]
	v_pk_mul_f32 v[18:19], v[18:19], v[50:51]
	v_pk_mul_f32 v[20:21], v[20:21], v[52:53]
	v_pk_mul_f32 v[22:23], v[22:23], v[54:55]
	v_pk_mul_f32 v[24:25], v[24:25], v[56:57]
	v_pk_mul_f32 v[26:27], v[26:27], v[58:59]
	v_pk_mul_f32 v[28:29], v[28:29], v[60:61]
	v_pk_mul_f32 v[30:31], v[30:31], v[62:63]
	v_fma_f32 v32, v0, v250, v16
	v_fma_f32 v250, v1, v32, v17
	v_cvt_pk_bf16_f32 v158, v32, v250
	v_fma_f32 v32, v2, v250, v18
	v_fma_f32 v250, v3, v32, v19
	v_cvt_pk_bf16_f32 v159, v32, v250
	v_fma_f32 v32, v4, v250, v20
	v_fma_f32 v250, v5, v32, v21
	v_cvt_pk_bf16_f32 v160, v32, v250
	v_fma_f32 v32, v6, v250, v22
	v_fma_f32 v250, v7, v32, v23
	v_cvt_pk_bf16_f32 v161, v32, v250
	v_fma_f32 v32, v8, v250, v24
	v_fma_f32 v250, v9, v32, v25
	v_cvt_pk_bf16_f32 v162, v32, v250
	v_fma_f32 v32, v10, v250, v26
	v_fma_f32 v250, v11, v32, v27
	v_cvt_pk_bf16_f32 v163, v32, v250
	v_fma_f32 v32, v12, v250, v28
	v_fma_f32 v250, v13, v32, v29
	v_cvt_pk_bf16_f32 v164, v32, v250
	v_fma_f32 v32, v14, v250, v30
	v_fma_f32 v250, v15, v32, v31
	v_cvt_pk_bf16_f32 v165, v32, v250
	ds_read_b128 v[32:35], v236 offset:2304
	ds_read_b128 v[36:39], v236 offset:2368
	s_waitcnt lgkmcnt(0)
	v_mfma_f32_16x16x32_bf16 v[0:3], v[32:35], v[80:83], 0
	v_mfma_f32_16x16x32_bf16 v[4:7], v[32:35], v[88:91], 0
	v_mfma_f32_16x16x32_bf16 v[8:11], v[32:35], v[96:99], 0
	v_mfma_f32_16x16x32_bf16 v[12:15], v[32:35], v[104:107], 0
	v_mfma_f32_16x16x32_bf16 v[16:19], v[32:35], v[112:115], 0
	v_mfma_f32_16x16x32_bf16 v[20:23], v[32:35], v[120:123], 0
	v_mfma_f32_16x16x32_bf16 v[24:27], v[32:35], v[128:131], 0
	v_mfma_f32_16x16x32_bf16 v[28:31], v[32:35], v[136:139], 0
	v_mfma_f32_16x16x32_bf16 v[0:3], v[36:39], v[84:87], v[0:3]
	v_mfma_f32_16x16x32_bf16 v[4:7], v[36:39], v[92:95], v[4:7]
	v_mfma_f32_16x16x32_bf16 v[8:11], v[36:39], v[100:103], v[8:11]
	v_mfma_f32_16x16x32_bf16 v[12:15], v[36:39], v[108:111], v[12:15]
	v_mfma_f32_16x16x32_bf16 v[16:19], v[36:39], v[116:119], v[16:19]
	v_mfma_f32_16x16x32_bf16 v[20:23], v[36:39], v[124:127], v[20:23]
	v_mfma_f32_16x16x32_bf16 v[24:27], v[36:39], v[132:135], v[24:27]
	v_mfma_f32_16x16x32_bf16 v[28:31], v[36:39], v[228:231], v[28:31]
	s_nop 3
	ds_write2_b32 v237, v0, v4 offset0:0 offset1:16
	ds_write2_b32 v237, v8, v12 offset0:32 offset1:48
	ds_write2_b32 v237, v1, v5 offset0:64 offset1:80
	ds_write2_b32 v237, v9, v13 offset0:96 offset1:112
	ds_write2_b32 v237, v2, v6 offset0:128 offset1:144
	ds_write2_b32 v237, v10, v14 offset0:160 offset1:176
	ds_write2_b32 v237, v3, v7 offset0:192 offset1:208
	ds_write2_b32 v237, v11, v15 offset0:224 offset1:240
	ds_write2_b32 v238, v16, v20 offset0:0 offset1:16
	ds_write2_b32 v238, v24, v28 offset0:32 offset1:48
	ds_write2_b32 v238, v17, v21 offset0:64 offset1:80
	ds_write2_b32 v238, v25, v29 offset0:96 offset1:112
	ds_write2_b32 v238, v18, v22 offset0:128 offset1:144
	ds_write2_b32 v238, v26, v30 offset0:160 offset1:176
	ds_write2_b32 v238, v19, v23 offset0:192 offset1:208
	ds_write2_b32 v238, v27, v31 offset0:224 offset1:240
	s_waitcnt lgkmcnt(0)
; #define WAVE_SYNC() asm volatile("s_waitcnt lgkmcnt(0)" ::: "memory")
; __device__ __forceinline__ float sigmoid_f(float x) { return rcpf_(1.f + __expf(-x)); }
; __device__ __forceinline__ float gelu_tanh_f(float x) { const float y = 0.7978845608028654f * (x + 0.044715f * x * x * x); return x * sigmoid_f(2.f * y); }
; template <bool FINAL, int D>
; __device__ __forceinline__ void rg_dir(PREF p, int l, int h, int ch, int sidx, int rowbase  , LAS bf16_t* sXc, LAS float* stg, int lane) {
;     ...
;             for (int j = 0; j < 4; ++j) { const int o = ((lane >> 4) * 4 + j) * 64 + nt * 16 + (lane & 15); stg[o] = ar[nt][j]; stg[1024 + o] = ai[nt][j]; }
;         WAVE_SYNC();
;         float av[16], iv[16];
; #pragma unroll
;         for (int ti = 0; ti < 16; ++ti) { const int tk = D ? 15 - ti : ti;
;             const float zr = stg[tk * 64 + lane] + ba, zi = stg[1024 + tk * 64 + lane] + bi;
;             const float r = sigmoid_f(zr), ig = sigmoid_f(zi);
;             const float a = __builtin_amdgcn_exp2f(r * sp8);
;             const float xc = bf2f(sXc[(mt * 16 + tk) * 72 + lane]);
;             av[ti] = a; iv[ti] = __builtin_amdgcn_sqrtf(fmaxf(1.f - a * a, 0.f)) * ig * xc;
;             if (FINAL && D == 1) grv[ti] = gelu_tanh_f(grv[ti]);
;         }
	ds_read2st64_b32 v[0:1], v239 offset0:36 offset1:37
	ds_read2st64_b32 v[2:3], v239 offset0:38 offset1:39
	ds_read2st64_b32 v[4:5], v239 offset0:40 offset1:41
	ds_read2st64_b32 v[6:7], v239 offset0:42 offset1:43
	ds_read2st64_b32 v[8:9], v239 offset0:44 offset1:45
	ds_read2st64_b32 v[10:11], v239 offset0:46 offset1:47
	ds_read2st64_b32 v[12:13], v239 offset0:48 offset1:49
	ds_read2st64_b32 v[14:15], v239 offset0:50 offset1:51
	ds_read2st64_b32 v[16:17], v239 offset0:52 offset1:53
	ds_read2st64_b32 v[18:19], v239 offset0:54 offset1:55
	ds_read2st64_b32 v[20:21], v239 offset0:56 offset1:57
	ds_read2st64_b32 v[22:23], v239 offset0:58 offset1:59
	ds_read2st64_b32 v[24:25], v239 offset0:60 offset1:61
	ds_read2st64_b32 v[26:27], v239 offset0:62 offset1:63
	ds_read2st64_b32 v[28:29], v239 offset0:64 offset1:65
	ds_read2st64_b32 v[30:31], v239 offset0:66 offset1:67
	ds_read_u16 v48, v240 offset:2304
	ds_read_u16 v49, v240 offset:2448
	ds_read_u16 v50, v240 offset:2592
	ds_read_u16 v51, v240 offset:2736
	ds_read_u16 v52, v240 offset:2880
	ds_read_u16 v53, v240 offset:3024
	ds_read_u16 v54, v240 offset:3168
	ds_read_u16 v55, v240 offset:3312
	ds_read_u16 v56, v240 offset:3456
	ds_read_u16 v57, v240 offset:3600
	ds_read_u16 v58, v240 offset:3744
	ds_read_u16 v59, v240 offset:3888
	ds_read_u16 v60, v240 offset:4032
	ds_read_u16 v61, v240 offset:4176
	ds_read_u16 v62, v240 offset:4320
	ds_read_u16 v63, v240 offset:4464
	s_waitcnt lgkmcnt(0)
	v_pk_fma_f32 v[0:1], v[0:1], v[248:249], v[242:243]
	v_pk_fma_f32 v[2:3], v[2:3], v[248:249], v[242:243]
	v_pk_fma_f32 v[4:5], v[4:5], v[248:249], v[242:243]
	v_pk_fma_f32 v[6:7], v[6:7], v[248:249], v[242:243]
	v_pk_fma_f32 v[8:9], v[8:9], v[248:249], v[242:243]
	v_pk_fma_f32 v[10:11], v[10:11], v[248:249], v[242:243]
	v_pk_fma_f32 v[12:13], v[12:13], v[248:249], v[242:243]
	v_pk_fma_f32 v[14:15], v[14:15], v[248:249], v[242:243]
	v_pk_fma_f32 v[16:17], v[16:17], v[248:249], v[244:245]
	v_pk_fma_f32 v[18:19], v[18:19], v[248:249], v[244:245]
	v_pk_fma_f32 v[20:21], v[20:21], v[248:249], v[244:245]
	v_pk_fma_f32 v[22:23], v[22:23], v[248:249], v[244:245]
	v_pk_fma_f32 v[24:25], v[24:25], v[248:249], v[244:245]
	v_pk_fma_f32 v[26:27], v[26:27], v[248:249], v[244:245]
	v_pk_fma_f32 v[28:29], v[28:29], v[248:249], v[244:245]
	v_pk_fma_f32 v[30:31], v[30:31], v[248:249], v[244:245]
	v_exp_f32_e32 v0, v0
	v_exp_f32_e32 v1, v1
	v_exp_f32_e32 v2, v2
	v_exp_f32_e32 v3, v3
	v_exp_f32_e32 v4, v4
	v_exp_f32_e32 v5, v5
	v_exp_f32_e32 v6, v6
	v_exp_f32_e32 v7, v7
	v_exp_f32_e32 v8, v8
	v_exp_f32_e32 v9, v9
	v_exp_f32_e32 v10, v10
	v_exp_f32_e32 v11, v11
	v_exp_f32_e32 v12, v12
	v_exp_f32_e32 v13, v13
	v_exp_f32_e32 v14, v14
	v_exp_f32_e32 v15, v15
	v_exp_f32_e32 v16, v16
	v_exp_f32_e32 v17, v17
	v_exp_f32_e32 v18, v18
	v_exp_f32_e32 v19, v19
	v_exp_f32_e32 v20, v20
	v_exp_f32_e32 v21, v21
	v_exp_f32_e32 v22, v22
	v_exp_f32_e32 v23, v23
	v_exp_f32_e32 v24, v24
	v_exp_f32_e32 v25, v25
	v_exp_f32_e32 v26, v26
	v_exp_f32_e32 v27, v27
	v_exp_f32_e32 v28, v28
	v_exp_f32_e32 v29, v29
	v_exp_f32_e32 v30, v30
	v_exp_f32_e32 v31, v31
	v_pk_add_f32 v[0:1], v[0:1], 1.0 op_sel_hi:[1,0]
	v_pk_add_f32 v[2:3], v[2:3], 1.0 op_sel_hi:[1,0]
	v_pk_add_f32 v[4:5], v[4:5], 1.0 op_sel_hi:[1,0]
	v_pk_add_f32 v[6:7], v[6:7], 1.0 op_sel_hi:[1,0]
	v_pk_add_f32 v[8:9], v[8:9], 1.0 op_sel_hi:[1,0]
	v_pk_add_f32 v[10:11], v[10:11], 1.0 op_sel_hi:[1,0]
	v_pk_add_f32 v[12:13], v[12:13], 1.0 op_sel_hi:[1,0]
	v_pk_add_f32 v[14:15], v[14:15], 1.0 op_sel_hi:[1,0]
	v_pk_add_f32 v[16:17], v[16:17], 1.0 op_sel_hi:[1,0]
	v_pk_add_f32 v[18:19], v[18:19], 1.0 op_sel_hi:[1,0]
	v_pk_add_f32 v[20:21], v[20:21], 1.0 op_sel_hi:[1,0]
	v_pk_add_f32 v[22:23], v[22:23], 1.0 op_sel_hi:[1,0]
	v_pk_add_f32 v[24:25], v[24:25], 1.0 op_sel_hi:[1,0]
	v_pk_add_f32 v[26:27], v[26:27], 1.0 op_sel_hi:[1,0]
	v_pk_add_f32 v[28:29], v[28:29], 1.0 op_sel_hi:[1,0]
	v_pk_add_f32 v[30:31], v[30:31], 1.0 op_sel_hi:[1,0]
	v_rcp_f32_e32 v0, v0
	v_rcp_f32_e32 v1, v1
	v_rcp_f32_e32 v2, v2
	v_rcp_f32_e32 v3, v3
	v_rcp_f32_e32 v4, v4
	v_rcp_f32_e32 v5, v5
	v_rcp_f32_e32 v6, v6
	v_rcp_f32_e32 v7, v7
	v_rcp_f32_e32 v8, v8
	v_rcp_f32_e32 v9, v9
	v_rcp_f32_e32 v10, v10
	v_rcp_f32_e32 v11, v11
	v_rcp_f32_e32 v12, v12
	v_rcp_f32_e32 v13, v13
	v_rcp_f32_e32 v14, v14
	v_rcp_f32_e32 v15, v15
	v_rcp_f32_e32 v16, v16
	v_rcp_f32_e32 v17, v17
	v_rcp_f32_e32 v18, v18
	v_rcp_f32_e32 v19, v19
	v_rcp_f32_e32 v20, v20
	v_rcp_f32_e32 v21, v21
	v_rcp_f32_e32 v22, v22
	v_rcp_f32_e32 v23, v23
	v_rcp_f32_e32 v24, v24
	v_rcp_f32_e32 v25, v25
	v_rcp_f32_e32 v26, v26
	v_rcp_f32_e32 v27, v27
	v_rcp_f32_e32 v28, v28
	v_rcp_f32_e32 v29, v29
	v_rcp_f32_e32 v30, v30
	v_rcp_f32_e32 v31, v31
	v_pk_mul_f32 v[0:1], v[246:247], v[0:1]
	v_pk_mul_f32 v[2:3], v[246:247], v[2:3]
	v_pk_mul_f32 v[4:5], v[246:247], v[4:5]
	v_pk_mul_f32 v[6:7], v[246:247], v[6:7]
	v_pk_mul_f32 v[8:9], v[246:247], v[8:9]
	v_pk_mul_f32 v[10:11], v[246:247], v[10:11]
	v_pk_mul_f32 v[12:13], v[246:247], v[12:13]
	v_pk_mul_f32 v[14:15], v[246:247], v[14:15]
	v_lshlrev_b32_e32 v48, 16, v48
	v_lshlrev_b32_e32 v49, 16, v49
	v_lshlrev_b32_e32 v50, 16, v50
	v_lshlrev_b32_e32 v51, 16, v51
	v_lshlrev_b32_e32 v52, 16, v52
	v_lshlrev_b32_e32 v53, 16, v53
	v_lshlrev_b32_e32 v54, 16, v54
	v_lshlrev_b32_e32 v55, 16, v55
	v_lshlrev_b32_e32 v56, 16, v56
	v_lshlrev_b32_e32 v57, 16, v57
	v_lshlrev_b32_e32 v58, 16, v58
	v_lshlrev_b32_e32 v59, 16, v59
	v_lshlrev_b32_e32 v60, 16, v60
	v_lshlrev_b32_e32 v61, 16, v61
	v_lshlrev_b32_e32 v62, 16, v62
	v_lshlrev_b32_e32 v63, 16, v63
	v_exp_f32_e32 v0, v0
	v_exp_f32_e32 v1, v1
	v_exp_f32_e32 v2, v2
	v_exp_f32_e32 v3, v3
	v_exp_f32_e32 v4, v4
; #define LAS __attribute__((address_space(3)))
; #define WAVE_SYNC() asm volatile("s_waitcnt lgkmcnt(0)" ::: "memory")
; __device__ __forceinline__ unsigned f2bf(float f) { unsigned r; asm("v_cvt_pk_bf16_f32 %0, %1, %1" : "=v"(r) : "v"(f)); return r & 0xffffu; }
; __device__ __forceinline__ float sigmoid_f(float x) { return rcpf_(1.f + __expf(-x)); }
; template <bool FINAL, int D>
; __device__ __forceinline__ void rg_dir(PREF p, int l, int h, int ch, int sidx, int rowbase  , LAS bf16_t* sXc, LAS float* stg, int lane) {
;     ...
;         const bf16x8 A0 = *(const LAS bf16x8*)(sXc + (mt * 16 + (lane & 15)) * 72 + (lane >> 4) * 8), A1 = *(const LAS bf16x8*)(sXc + (mt * 16 + (lane & 15)) * 72 + 32 + (lane >> 4) * 8);
;         f32x4 ar[4], ai[4];
; #pragma unroll
;         for (int nt = 0; nt < 4; ++nt) { const f32x4 z = {0.f, 0.f, 0.f, 0.f};
;             ar[nt] = mfma16(A0, Br[nt][0], z); ar[nt] = mfma16(A1, Br[nt][1], ar[nt]); ai[nt] = mfma16(A0, Bi[nt][0], z); ai[nt] = mfma16(A1, Bi[nt][1], ai[nt]); }
;         WAVE_SYNC();
; #pragma unroll
;         for (int nt = 0; nt < 4; ++nt)
; #pragma unroll
;             for (int j = 0; j < 4; ++j) { const int o = ((lane >> 4) * 4 + j) * 64 + nt * 16 + (lane & 15); stg[o] = ar[nt][j]; stg[1024 + o] = ai[nt][j]; }
;         WAVE_SYNC();
;         float av[16], iv[16];
; #pragma unroll
;         for (int ti = 0; ti < 16; ++ti) { const int tk = D ? 15 - ti : ti;
;             const float zr = stg[tk * 64 + lane] + ba, zi = stg[1024 + tk * 64 + lane] + bi;
;             const float r = sigmoid_f(zr), ig = sigmoid_f(zi);
;             const float a = __builtin_amdgcn_exp2f(r * sp8);
;             const float xc = bf2f(sXc[(mt * 16 + tk) * 72 + lane]);
;             av[ti] = a; iv[ti] = __builtin_amdgcn_sqrtf(fmaxf(1.f - a * a, 0.f)) * ig * xc;
;             if (FINAL && D == 1) grv[ti] = gelu_tanh_f(grv[ti]);
;         }
; #pragma unroll
;         for (int ti = 0; ti < 16; ++ti) { const int tk = D ? 15 - ti : ti;
;             hc = av[ti] * hc + iv[ti]; Ap *= av[ti];
;             if (FINAL) { const size_t row = (size_t)(rowbase + mt * 16 + tk);
;                 if (D == 0) TMP[row * 512 + ch] = (bf16_t)f2bf(hc);
;                 else MIX[row * DM + ch] = (bf16_t)f2bf(grv[ti] * (hfv[ti] + hc)); }
;         }
	v_exp_f32_e32 v5, v5
	v_exp_f32_e32 v6, v6
	v_exp_f32_e32 v7, v7
	v_exp_f32_e32 v8, v8
	v_exp_f32_e32 v9, v9
	v_exp_f32_e32 v10, v10
	v_exp_f32_e32 v11, v11
	v_exp_f32_e32 v12, v12
	v_exp_f32_e32 v13, v13
	v_exp_f32_e32 v14, v14
	v_exp_f32_e32 v15, v15
	v_fma_f32 v32, -v0, v0, 1.0 clamp
	v_fma_f32 v33, -v1, v1, 1.0 clamp
	v_fma_f32 v34, -v2, v2, 1.0 clamp
	v_fma_f32 v35, -v3, v3, 1.0 clamp
	v_fma_f32 v36, -v4, v4, 1.0 clamp
	v_fma_f32 v37, -v5, v5, 1.0 clamp
	v_fma_f32 v38, -v6, v6, 1.0 clamp
	v_fma_f32 v39, -v7, v7, 1.0 clamp
	v_fma_f32 v40, -v8, v8, 1.0 clamp
	v_fma_f32 v41, -v9, v9, 1.0 clamp
	v_fma_f32 v42, -v10, v10, 1.0 clamp
	v_fma_f32 v43, -v11, v11, 1.0 clamp
	v_fma_f32 v44, -v12, v12, 1.0 clamp
	v_fma_f32 v45, -v13, v13, 1.0 clamp
	v_fma_f32 v46, -v14, v14, 1.0 clamp
	v_fma_f32 v47, -v15, v15, 1.0 clamp
	v_sqrt_f32_e32 v32, v32
	v_sqrt_f32_e32 v33, v33
	v_sqrt_f32_e32 v34, v34
	v_sqrt_f32_e32 v35, v35
	v_sqrt_f32_e32 v36, v36
	v_sqrt_f32_e32 v37, v37
	v_sqrt_f32_e32 v38, v38
	v_sqrt_f32_e32 v39, v39
	v_sqrt_f32_e32 v40, v40
	v_sqrt_f32_e32 v41, v41
	v_sqrt_f32_e32 v42, v42
	v_sqrt_f32_e32 v43, v43
	v_sqrt_f32_e32 v44, v44
	v_sqrt_f32_e32 v45, v45
	v_sqrt_f32_e32 v46, v46
	v_sqrt_f32_e32 v47, v47
	s_nop 0
	v_pk_mul_f32 v[16:17], v[16:17], v[32:33]
	v_pk_mul_f32 v[18:19], v[18:19], v[34:35]
	v_pk_mul_f32 v[20:21], v[20:21], v[36:37]
	v_pk_mul_f32 v[22:23], v[22:23], v[38:39]
	v_pk_mul_f32 v[24:25], v[24:25], v[40:41]
	v_pk_mul_f32 v[26:27], v[26:27], v[42:43]
	v_pk_mul_f32 v[28:29], v[28:29], v[44:45]
	v_pk_mul_f32 v[30:31], v[30:31], v[46:47]
	v_pk_mul_f32 v[16:17], v[16:17], v[48:49]
	v_pk_mul_f32 v[18:19], v[18:19], v[50:51]
	v_pk_mul_f32 v[20:21], v[20:21], v[52:53]
	v_pk_mul_f32 v[22:23], v[22:23], v[54:55]
	v_pk_mul_f32 v[24:25], v[24:25], v[56:57]
	v_pk_mul_f32 v[26:27], v[26:27], v[58:59]
	v_pk_mul_f32 v[28:29], v[28:29], v[60:61]
	v_pk_mul_f32 v[30:31], v[30:31], v[62:63]
	v_fma_f32 v32, v0, v250, v16
	v_fma_f32 v250, v1, v32, v17
	v_cvt_pk_bf16_f32 v166, v32, v250
	v_fma_f32 v32, v2, v250, v18
	v_fma_f32 v250, v3, v32, v19
	v_cvt_pk_bf16_f32 v167, v32, v250
	v_fma_f32 v32, v4, v250, v20
	v_fma_f32 v250, v5, v32, v21
	v_cvt_pk_bf16_f32 v168, v32, v250
	v_fma_f32 v32, v6, v250, v22
	v_fma_f32 v250, v7, v32, v23
	v_cvt_pk_bf16_f32 v169, v32, v250
	v_fma_f32 v32, v8, v250, v24
	v_fma_f32 v250, v9, v32, v25
	v_cvt_pk_bf16_f32 v170, v32, v250
	v_fma_f32 v32, v10, v250, v26
	v_fma_f32 v250, v11, v32, v27
	v_cvt_pk_bf16_f32 v171, v32, v250
	v_fma_f32 v32, v12, v250, v28
	v_fma_f32 v250, v13, v32, v29
	v_cvt_pk_bf16_f32 v172, v32, v250
	v_fma_f32 v32, v14, v250, v30
	v_fma_f32 v250, v15, v32, v31
	v_cvt_pk_bf16_f32 v173, v32, v250
	ds_read_b128 v[32:35], v236 offset:4608
	ds_read_b128 v[36:39], v236 offset:4672
	s_waitcnt lgkmcnt(0)
	v_mfma_f32_16x16x32_bf16 v[0:3], v[32:35], v[80:83], 0
	v_mfma_f32_16x16x32_bf16 v[4:7], v[32:35], v[88:91], 0
	v_mfma_f32_16x16x32_bf16 v[8:11], v[32:35], v[96:99], 0
	v_mfma_f32_16x16x32_bf16 v[12:15], v[32:35], v[104:107], 0
	v_mfma_f32_16x16x32_bf16 v[16:19], v[32:35], v[112:115], 0
	v_mfma_f32_16x16x32_bf16 v[20:23], v[32:35], v[120:123], 0
	v_mfma_f32_16x16x32_bf16 v[24:27], v[32:35], v[128:131], 0
	v_mfma_f32_16x16x32_bf16 v[28:31], v[32:35], v[136:139], 0
	v_mfma_f32_16x16x32_bf16 v[0:3], v[36:39], v[84:87], v[0:3]
	v_mfma_f32_16x16x32_bf16 v[4:7], v[36:39], v[92:95], v[4:7]
	v_mfma_f32_16x16x32_bf16 v[8:11], v[36:39], v[100:103], v[8:11]
	v_mfma_f32_16x16x32_bf16 v[12:15], v[36:39], v[108:111], v[12:15]
	v_mfma_f32_16x16x32_bf16 v[16:19], v[36:39], v[116:119], v[16:19]
	v_mfma_f32_16x16x32_bf16 v[20:23], v[36:39], v[124:127], v[20:23]
	v_mfma_f32_16x16x32_bf16 v[24:27], v[36:39], v[132:135], v[24:27]
	v_mfma_f32_16x16x32_bf16 v[28:31], v[36:39], v[228:231], v[28:31]
	s_nop 3
	ds_write2_b32 v237, v0, v4 offset0:0 offset1:16
	ds_write2_b32 v237, v8, v12 offset0:32 offset1:48
	ds_write2_b32 v237, v1, v5 offset0:64 offset1:80
	ds_write2_b32 v237, v9, v13 offset0:96 offset1:112
	ds_write2_b32 v237, v2, v6 offset0:128 offset1:144
	ds_write2_b32 v237, v10, v14 offset0:160 offset1:176
	ds_write2_b32 v237, v3, v7 offset0:192 offset1:208
	ds_write2_b32 v237, v11, v15 offset0:224 offset1:240
	ds_write2_b32 v238, v16, v20 offset0:0 offset1:16
	ds_write2_b32 v238, v24, v28 offset0:32 offset1:48
	ds_write2_b32 v238, v17, v21 offset0:64 offset1:80
	ds_write2_b32 v238, v25, v29 offset0:96 offset1:112
	ds_write2_b32 v238, v18, v22 offset0:128 offset1:144
	ds_write2_b32 v238, v26, v30 offset0:160 offset1:176
	ds_write2_b32 v238, v19, v23 offset0:192 offset1:208
	ds_write2_b32 v238, v27, v31 offset0:224 offset1:240
	s_waitcnt lgkmcnt(0)
	ds_read2st64_b32 v[0:1], v239 offset0:36 offset1:37
	ds_read2st64_b32 v[2:3], v239 offset0:38 offset1:39
	ds_read2st64_b32 v[4:5], v239 offset0:40 offset1:41
	ds_read2st64_b32 v[6:7], v239 offset0:42 offset1:43
	ds_read2st64_b32 v[8:9], v239 offset0:44 offset1:45
	ds_read2st64_b32 v[10:11], v239 offset0:46 offset1:47
	ds_read2st64_b32 v[12:13], v239 offset0:48 offset1:49
	ds_read2st64_b32 v[14:15], v239 offset0:50 offset1:51
	ds_read2st64_b32 v[16:17], v239 offset0:52 offset1:53
	ds_read2st64_b32 v[18:19], v239 offset0:54 offset1:55
	ds_read2st64_b32 v[20:21], v239 offset0:56 offset1:57
	ds_read2st64_b32 v[22:23], v239 offset0:58 offset1:59
	ds_read2st64_b32 v[24:25], v239 offset0:60 offset1:61
	ds_read2st64_b32 v[26:27], v239 offset0:62 offset1:63
	ds_read2st64_b32 v[28:29], v239 offset0:64 offset1:65
	ds_read2st64_b32 v[30:31], v239 offset0:66 offset1:67
	ds_read_u16 v48, v240 offset:4608
	ds_read_u16 v49, v240 offset:4752
	ds_read_u16 v50, v240 offset:4896
	ds_read_u16 v51, v240 offset:5040
	ds_read_u16 v52, v240 offset:5184
	ds_read_u16 v53, v240 offset:5328
	ds_read_u16 v54, v240 offset:5472
	ds_read_u16 v55, v240 offset:5616
	ds_read_u16 v56, v240 offset:5760
	ds_read_u16 v57, v240 offset:5904
	ds_read_u16 v58, v240 offset:6048
	ds_read_u16 v59, v240 offset:6192
	ds_read_u16 v60, v240 offset:6336
	ds_read_u16 v61, v240 offset:6480
	ds_read_u16 v62, v240 offset:6624
	ds_read_u16 v63, v240 offset:6768
	s_waitcnt lgkmcnt(0)
; __device__ __forceinline__ unsigned f2bf(float f) { unsigned r; asm("v_cvt_pk_bf16_f32 %0, %1, %1" : "=v"(r) : "v"(f)); return r & 0xffffu; }
; __device__ __forceinline__ float sigmoid_f(float x) { return rcpf_(1.f + __expf(-x)); }
; __device__ __forceinline__ float gelu_tanh_f(float x) { const float y = 0.7978845608028654f * (x + 0.044715f * x * x * x); return x * sigmoid_f(2.f * y); }
; template <bool FINAL, int D>
; __device__ __forceinline__ void rg_dir(PREF p, int l, int h, int ch, int sidx, int rowbase  , LAS bf16_t* sXc, LAS float* stg, int lane) {
;     ...
;         for (int ti = 0; ti < 16; ++ti) { const int tk = D ? 15 - ti : ti;
;             const float zr = stg[tk * 64 + lane] + ba, zi = stg[1024 + tk * 64 + lane] + bi;
;             const float r = sigmoid_f(zr), ig = sigmoid_f(zi);
;             const float a = __builtin_amdgcn_exp2f(r * sp8);
;             const float xc = bf2f(sXc[(mt * 16 + tk) * 72 + lane]);
;             av[ti] = a; iv[ti] = __builtin_amdgcn_sqrtf(fmaxf(1.f - a * a, 0.f)) * ig * xc;
;             if (FINAL && D == 1) grv[ti] = gelu_tanh_f(grv[ti]);
;         }
; #pragma unroll
;         for (int ti = 0; ti < 16; ++ti) { const int tk = D ? 15 - ti : ti;
;             hc = av[ti] * hc + iv[ti]; Ap *= av[ti];
;             if (FINAL) { const size_t row = (size_t)(rowbase + mt * 16 + tk);
;                 if (D == 0) TMP[row * 512 + ch] = (bf16_t)f2bf(hc);
;                 else MIX[row * DM + ch] = (bf16_t)f2bf(grv[ti] * (hfv[ti] + hc)); }
;         }
	v_pk_fma_f32 v[0:1], v[0:1], v[248:249], v[242:243]
	v_pk_fma_f32 v[2:3], v[2:3], v[248:249], v[242:243]
	v_pk_fma_f32 v[4:5], v[4:5], v[248:249], v[242:243]
	v_pk_fma_f32 v[6:7], v[6:7], v[248:249], v[242:243]
	v_pk_fma_f32 v[8:9], v[8:9], v[248:249], v[242:243]
	v_pk_fma_f32 v[10:11], v[10:11], v[248:249], v[242:243]
	v_pk_fma_f32 v[12:13], v[12:13], v[248:249], v[242:243]
	v_pk_fma_f32 v[14:15], v[14:15], v[248:249], v[242:243]
	v_pk_fma_f32 v[16:17], v[16:17], v[248:249], v[244:245]
	v_pk_fma_f32 v[18:19], v[18:19], v[248:249], v[244:245]
	v_pk_fma_f32 v[20:21], v[20:21], v[248:249], v[244:245]
	v_pk_fma_f32 v[22:23], v[22:23], v[248:249], v[244:245]
	v_pk_fma_f32 v[24:25], v[24:25], v[248:249], v[244:245]
	v_pk_fma_f32 v[26:27], v[26:27], v[248:249], v[244:245]
	v_pk_fma_f32 v[28:29], v[28:29], v[248:249], v[244:245]
	v_pk_fma_f32 v[30:31], v[30:31], v[248:249], v[244:245]
	v_exp_f32_e32 v0, v0
	v_exp_f32_e32 v1, v1
	v_exp_f32_e32 v2, v2
	v_exp_f32_e32 v3, v3
	v_exp_f32_e32 v4, v4
	v_exp_f32_e32 v5, v5
	v_exp_f32_e32 v6, v6
	v_exp_f32_e32 v7, v7
	v_exp_f32_e32 v8, v8
	v_exp_f32_e32 v9, v9
	v_exp_f32_e32 v10, v10
	v_exp_f32_e32 v11, v11
	v_exp_f32_e32 v12, v12
	v_exp_f32_e32 v13, v13
	v_exp_f32_e32 v14, v14
	v_exp_f32_e32 v15, v15
	v_exp_f32_e32 v16, v16
	v_exp_f32_e32 v17, v17
	v_exp_f32_e32 v18, v18
	v_exp_f32_e32 v19, v19
	v_exp_f32_e32 v20, v20
	v_exp_f32_e32 v21, v21
	v_exp_f32_e32 v22, v22
	v_exp_f32_e32 v23, v23
	v_exp_f32_e32 v24, v24
	v_exp_f32_e32 v25, v25
	v_exp_f32_e32 v26, v26
	v_exp_f32_e32 v27, v27
	v_exp_f32_e32 v28, v28
	v_exp_f32_e32 v29, v29
	v_exp_f32_e32 v30, v30
	v_exp_f32_e32 v31, v31
	v_pk_add_f32 v[0:1], v[0:1], 1.0 op_sel_hi:[1,0]
	v_pk_add_f32 v[2:3], v[2:3], 1.0 op_sel_hi:[1,0]
	v_pk_add_f32 v[4:5], v[4:5], 1.0 op_sel_hi:[1,0]
	v_pk_add_f32 v[6:7], v[6:7], 1.0 op_sel_hi:[1,0]
	v_pk_add_f32 v[8:9], v[8:9], 1.0 op_sel_hi:[1,0]
	v_pk_add_f32 v[10:11], v[10:11], 1.0 op_sel_hi:[1,0]
	v_pk_add_f32 v[12:13], v[12:13], 1.0 op_sel_hi:[1,0]
	v_pk_add_f32 v[14:15], v[14:15], 1.0 op_sel_hi:[1,0]
	v_pk_add_f32 v[16:17], v[16:17], 1.0 op_sel_hi:[1,0]
	v_pk_add_f32 v[18:19], v[18:19], 1.0 op_sel_hi:[1,0]
	v_pk_add_f32 v[20:21], v[20:21], 1.0 op_sel_hi:[1,0]
	v_pk_add_f32 v[22:23], v[22:23], 1.0 op_sel_hi:[1,0]
	v_pk_add_f32 v[24:25], v[24:25], 1.0 op_sel_hi:[1,0]
	v_pk_add_f32 v[26:27], v[26:27], 1.0 op_sel_hi:[1,0]
	v_pk_add_f32 v[28:29], v[28:29], 1.0 op_sel_hi:[1,0]
	v_pk_add_f32 v[30:31], v[30:31], 1.0 op_sel_hi:[1,0]
	v_rcp_f32_e32 v0, v0
	v_rcp_f32_e32 v1, v1
	v_rcp_f32_e32 v2, v2
	v_rcp_f32_e32 v3, v3
	v_rcp_f32_e32 v4, v4
	v_rcp_f32_e32 v5, v5
	v_rcp_f32_e32 v6, v6
	v_rcp_f32_e32 v7, v7
	v_rcp_f32_e32 v8, v8
	v_rcp_f32_e32 v9, v9
	v_rcp_f32_e32 v10, v10
	v_rcp_f32_e32 v11, v11
	v_rcp_f32_e32 v12, v12
	v_rcp_f32_e32 v13, v13
	v_rcp_f32_e32 v14, v14
	v_rcp_f32_e32 v15, v15
	v_rcp_f32_e32 v16, v16
	v_rcp_f32_e32 v17, v17
	v_rcp_f32_e32 v18, v18
	v_rcp_f32_e32 v19, v19
	v_rcp_f32_e32 v20, v20
	v_rcp_f32_e32 v21, v21
	v_rcp_f32_e32 v22, v22
	v_rcp_f32_e32 v23, v23
	v_rcp_f32_e32 v24, v24
	v_rcp_f32_e32 v25, v25
	v_rcp_f32_e32 v26, v26
	v_rcp_f32_e32 v27, v27
	v_rcp_f32_e32 v28, v28
	v_rcp_f32_e32 v29, v29
	v_rcp_f32_e32 v30, v30
	v_rcp_f32_e32 v31, v31
	v_pk_mul_f32 v[0:1], v[246:247], v[0:1]
	v_pk_mul_f32 v[2:3], v[246:247], v[2:3]
	v_pk_mul_f32 v[4:5], v[246:247], v[4:5]
	v_pk_mul_f32 v[6:7], v[246:247], v[6:7]
	v_pk_mul_f32 v[8:9], v[246:247], v[8:9]
	v_pk_mul_f32 v[10:11], v[246:247], v[10:11]
	v_pk_mul_f32 v[12:13], v[246:247], v[12:13]
	v_pk_mul_f32 v[14:15], v[246:247], v[14:15]
	v_lshlrev_b32_e32 v48, 16, v48
	v_lshlrev_b32_e32 v49, 16, v49
	v_lshlrev_b32_e32 v50, 16, v50
	v_lshlrev_b32_e32 v51, 16, v51
	v_lshlrev_b32_e32 v52, 16, v52
	v_lshlrev_b32_e32 v53, 16, v53
	v_lshlrev_b32_e32 v54, 16, v54
	v_lshlrev_b32_e32 v55, 16, v55
	v_lshlrev_b32_e32 v56, 16, v56
	v_lshlrev_b32_e32 v57, 16, v57
	v_lshlrev_b32_e32 v58, 16, v58
	v_lshlrev_b32_e32 v59, 16, v59
	v_lshlrev_b32_e32 v60, 16, v60
	v_lshlrev_b32_e32 v61, 16, v61
	v_lshlrev_b32_e32 v62, 16, v62
	v_lshlrev_b32_e32 v63, 16, v63
	v_exp_f32_e32 v0, v0
	v_exp_f32_e32 v1, v1
	v_exp_f32_e32 v2, v2
	v_exp_f32_e32 v3, v3
	v_exp_f32_e32 v4, v4
	v_exp_f32_e32 v5, v5
	v_exp_f32_e32 v6, v6
	v_exp_f32_e32 v7, v7
	v_exp_f32_e32 v8, v8
	v_exp_f32_e32 v9, v9
	v_exp_f32_e32 v10, v10
	v_exp_f32_e32 v11, v11
	v_exp_f32_e32 v12, v12
	v_exp_f32_e32 v13, v13
	v_exp_f32_e32 v14, v14
	v_exp_f32_e32 v15, v15
	v_fma_f32 v32, -v0, v0, 1.0 clamp
	v_fma_f32 v33, -v1, v1, 1.0 clamp
	v_fma_f32 v34, -v2, v2, 1.0 clamp
	v_fma_f32 v35, -v3, v3, 1.0 clamp
	v_fma_f32 v36, -v4, v4, 1.0 clamp
	v_fma_f32 v37, -v5, v5, 1.0 clamp
	v_fma_f32 v38, -v6, v6, 1.0 clamp
	v_fma_f32 v39, -v7, v7, 1.0 clamp
	v_fma_f32 v40, -v8, v8, 1.0 clamp
	v_fma_f32 v41, -v9, v9, 1.0 clamp
	v_fma_f32 v42, -v10, v10, 1.0 clamp
	v_fma_f32 v43, -v11, v11, 1.0 clamp
	v_fma_f32 v44, -v12, v12, 1.0 clamp
	v_fma_f32 v45, -v13, v13, 1.0 clamp
	v_fma_f32 v46, -v14, v14, 1.0 clamp
	v_fma_f32 v47, -v15, v15, 1.0 clamp
	v_sqrt_f32_e32 v32, v32
	v_sqrt_f32_e32 v33, v33
	v_sqrt_f32_e32 v34, v34
	v_sqrt_f32_e32 v35, v35
	v_sqrt_f32_e32 v36, v36
	v_sqrt_f32_e32 v37, v37
	v_sqrt_f32_e32 v38, v38
	v_sqrt_f32_e32 v39, v39
	v_sqrt_f32_e32 v40, v40
	v_sqrt_f32_e32 v41, v41
	v_sqrt_f32_e32 v42, v42
	v_sqrt_f32_e32 v43, v43
	v_sqrt_f32_e32 v44, v44
	v_sqrt_f32_e32 v45, v45
	v_sqrt_f32_e32 v46, v46
	v_sqrt_f32_e32 v47, v47
	s_nop 0
	v_pk_mul_f32 v[16:17], v[16:17], v[32:33]
	v_pk_mul_f32 v[18:19], v[18:19], v[34:35]
	v_pk_mul_f32 v[20:21], v[20:21], v[36:37]
	v_pk_mul_f32 v[22:23], v[22:23], v[38:39]
	v_pk_mul_f32 v[24:25], v[24:25], v[40:41]
	v_pk_mul_f32 v[26:27], v[26:27], v[42:43]
	v_pk_mul_f32 v[28:29], v[28:29], v[44:45]
	v_pk_mul_f32 v[30:31], v[30:31], v[46:47]
	v_pk_mul_f32 v[16:17], v[16:17], v[48:49]
	v_pk_mul_f32 v[18:19], v[18:19], v[50:51]
	v_pk_mul_f32 v[20:21], v[20:21], v[52:53]
	v_pk_mul_f32 v[22:23], v[22:23], v[54:55]
	v_pk_mul_f32 v[24:25], v[24:25], v[56:57]
	v_pk_mul_f32 v[26:27], v[26:27], v[58:59]
	v_pk_mul_f32 v[28:29], v[28:29], v[60:61]
	v_pk_mul_f32 v[30:31], v[30:31], v[62:63]
	v_fma_f32 v32, v0, v250, v16
	v_fma_f32 v250, v1, v32, v17
	v_cvt_pk_bf16_f32 v174, v32, v250
	v_fma_f32 v32, v2, v250, v18
	v_fma_f32 v250, v3, v32, v19
	v_cvt_pk_bf16_f32 v175, v32, v250
	v_fma_f32 v32, v4, v250, v20
	v_fma_f32 v250, v5, v32, v21
	v_cvt_pk_bf16_f32 v176, v32, v250
	v_fma_f32 v32, v6, v250, v22
	v_fma_f32 v250, v7, v32, v23
	v_cvt_pk_bf16_f32 v177, v32, v250
	v_fma_f32 v32, v8, v250, v24
	v_fma_f32 v250, v9, v32, v25
	v_cvt_pk_bf16_f32 v178, v32, v250
	v_fma_f32 v32, v10, v250, v26
	v_fma_f32 v250, v11, v32, v27
	v_cvt_pk_bf16_f32 v179, v32, v250
	v_fma_f32 v32, v12, v250, v28
	v_fma_f32 v250, v13, v32, v29
	v_cvt_pk_bf16_f32 v180, v32, v250
	v_fma_f32 v32, v14, v250, v30
	v_fma_f32 v250, v15, v32, v31
	v_cvt_pk_bf16_f32 v181, v32, v250
	ds_read_b128 v[32:35], v236 offset:6912
	ds_read_b128 v[36:39], v236 offset:6976
	s_waitcnt lgkmcnt(0)
; #define LAS __attribute__((address_space(3)))
; #define WAVE_SYNC() asm volatile("s_waitcnt lgkmcnt(0)" ::: "memory")
; __device__ __forceinline__ float sigmoid_f(float x) { return rcpf_(1.f + __expf(-x)); }
; __device__ __forceinline__ f32x4 mfma16(bf16x8 a, bf16x8 b, f32x4 c) { return __builtin_amdgcn_mfma_f32_16x16x32_bf16(a, b, c, 0, 0, 0); }
; template <bool FINAL, int D>
; __device__ __forceinline__ void rg_dir(PREF p, int l, int h, int ch, int sidx, int rowbase  , LAS bf16_t* sXc, LAS float* stg, int lane) {
;     ...
;     for (int nt = 0; nt < 4; ++nt) { const int o0 = (nt * 16 + (lane & 15)) * 64 + (lane >> 4) * 8;
;         Br[nt][0] = *(const bf16x8*)(wr_ + o0); Br[nt][1] = *(const bf16x8*)(wr_ + o0 + 32); Bi[nt][0] = *(const bf16x8*)(wi_ + o0); Bi[nt][1] = *(const bf16x8*)(wi_ + o0 + 32); }
;     ...
;         const bf16x8 A0 = *(const LAS bf16x8*)(sXc + (mt * 16 + (lane & 15)) * 72 + (lane >> 4) * 8), A1 = *(const LAS bf16x8*)(sXc + (mt * 16 + (lane & 15)) * 72 + 32 + (lane >> 4) * 8);
;         f32x4 ar[4], ai[4];
; #pragma unroll
;         for (int nt = 0; nt < 4; ++nt) { const f32x4 z = {0.f, 0.f, 0.f, 0.f};
;             ar[nt] = mfma16(A0, Br[nt][0], z); ar[nt] = mfma16(A1, Br[nt][1], ar[nt]); ai[nt] = mfma16(A0, Bi[nt][0], z); ai[nt] = mfma16(A1, Bi[nt][1], ai[nt]); }
;         WAVE_SYNC();
; #pragma unroll
;         for (int nt = 0; nt < 4; ++nt)
; #pragma unroll
;             for (int j = 0; j < 4; ++j) { const int o = ((lane >> 4) * 4 + j) * 64 + nt * 16 + (lane & 15); stg[o] = ar[nt][j]; stg[1024 + o] = ai[nt][j]; }
;         WAVE_SYNC();
;         float av[16], iv[16];
; #pragma unroll
;         for (int ti = 0; ti < 16; ++ti) { const int tk = D ? 15 - ti : ti;
;             const float zr = stg[tk * 64 + lane] + ba, zi = stg[1024 + tk * 64 + lane] + bi;
;             const float r = sigmoid_f(zr), ig = sigmoid_f(zi);
;             const float a = __builtin_amdgcn_exp2f(r * sp8);
;             const float xc = bf2f(sXc[(mt * 16 + tk) * 72 + lane]);
	v_mfma_f32_16x16x32_bf16 v[0:3], v[32:35], v[80:83], 0
	v_mfma_f32_16x16x32_bf16 v[4:7], v[32:35], v[88:91], 0
	v_mfma_f32_16x16x32_bf16 v[8:11], v[32:35], v[96:99], 0
	v_mfma_f32_16x16x32_bf16 v[12:15], v[32:35], v[104:107], 0
	v_mfma_f32_16x16x32_bf16 v[16:19], v[32:35], v[112:115], 0
	v_mfma_f32_16x16x32_bf16 v[20:23], v[32:35], v[120:123], 0
	v_mfma_f32_16x16x32_bf16 v[24:27], v[32:35], v[128:131], 0
	v_mfma_f32_16x16x32_bf16 v[28:31], v[32:35], v[136:139], 0
	v_mfma_f32_16x16x32_bf16 v[0:3], v[36:39], v[84:87], v[0:3]
	v_mfma_f32_16x16x32_bf16 v[4:7], v[36:39], v[92:95], v[4:7]
	v_mfma_f32_16x16x32_bf16 v[8:11], v[36:39], v[100:103], v[8:11]
	v_mfma_f32_16x16x32_bf16 v[12:15], v[36:39], v[108:111], v[12:15]
	v_mfma_f32_16x16x32_bf16 v[16:19], v[36:39], v[116:119], v[16:19]
	v_mfma_f32_16x16x32_bf16 v[20:23], v[36:39], v[124:127], v[20:23]
	v_mfma_f32_16x16x32_bf16 v[24:27], v[36:39], v[132:135], v[24:27]
	v_mfma_f32_16x16x32_bf16 v[28:31], v[36:39], v[228:231], v[28:31]
	s_nop 3
	ds_write2_b32 v237, v0, v4 offset0:0 offset1:16
	ds_write2_b32 v237, v8, v12 offset0:32 offset1:48
	ds_write2_b32 v237, v1, v5 offset0:64 offset1:80
	ds_write2_b32 v237, v9, v13 offset0:96 offset1:112
	ds_write2_b32 v237, v2, v6 offset0:128 offset1:144
	ds_write2_b32 v237, v10, v14 offset0:160 offset1:176
	ds_write2_b32 v237, v3, v7 offset0:192 offset1:208
	ds_write2_b32 v237, v11, v15 offset0:224 offset1:240
	ds_write2_b32 v238, v16, v20 offset0:0 offset1:16
	ds_write2_b32 v238, v24, v28 offset0:32 offset1:48
	ds_write2_b32 v238, v17, v21 offset0:64 offset1:80
	ds_write2_b32 v238, v25, v29 offset0:96 offset1:112
	ds_write2_b32 v238, v18, v22 offset0:128 offset1:144
	ds_write2_b32 v238, v26, v30 offset0:160 offset1:176
	ds_write2_b32 v238, v19, v23 offset0:192 offset1:208
	ds_write2_b32 v238, v27, v31 offset0:224 offset1:240
	s_waitcnt lgkmcnt(0)
	ds_read2st64_b32 v[0:1], v239 offset0:36 offset1:37
	ds_read2st64_b32 v[2:3], v239 offset0:38 offset1:39
	ds_read2st64_b32 v[4:5], v239 offset0:40 offset1:41
	ds_read2st64_b32 v[6:7], v239 offset0:42 offset1:43
	ds_read2st64_b32 v[8:9], v239 offset0:44 offset1:45
	ds_read2st64_b32 v[10:11], v239 offset0:46 offset1:47
	ds_read2st64_b32 v[12:13], v239 offset0:48 offset1:49
	ds_read2st64_b32 v[14:15], v239 offset0:50 offset1:51
	ds_read2st64_b32 v[16:17], v239 offset0:52 offset1:53
	ds_read2st64_b32 v[18:19], v239 offset0:54 offset1:55
	ds_read2st64_b32 v[20:21], v239 offset0:56 offset1:57
	ds_read2st64_b32 v[22:23], v239 offset0:58 offset1:59
	ds_read2st64_b32 v[24:25], v239 offset0:60 offset1:61
	ds_read2st64_b32 v[26:27], v239 offset0:62 offset1:63
	ds_read2st64_b32 v[28:29], v239 offset0:64 offset1:65
	ds_read2st64_b32 v[30:31], v239 offset0:66 offset1:67
	ds_read_u16 v48, v240 offset:6912
	ds_read_u16 v49, v240 offset:7056
	ds_read_u16 v50, v240 offset:7200
	ds_read_u16 v51, v240 offset:7344
	ds_read_u16 v52, v240 offset:7488
	ds_read_u16 v53, v240 offset:7632
	ds_read_u16 v54, v240 offset:7776
	ds_read_u16 v55, v240 offset:7920
	ds_read_u16 v56, v240 offset:8064
	ds_read_u16 v57, v240 offset:8208
	ds_read_u16 v58, v240 offset:8352
	ds_read_u16 v59, v240 offset:8496
	ds_read_u16 v60, v240 offset:8640
	ds_read_u16 v61, v240 offset:8784
	ds_read_u16 v62, v240 offset:8928
	ds_read_u16 v63, v240 offset:9072
	s_add_u32 s90, s92, 0x20000
	s_addc_u32 s91, s93, 0
	global_load_dwordx4 v[80:83], v241, s[90:91]
	global_load_dwordx4 v[84:87], v241, s[90:91] offset:64
	global_load_dwordx4 v[88:91], v241, s[90:91] offset:2048
	global_load_dwordx4 v[92:95], v241, s[90:91] offset:2112
	s_add_u32 s90, s92, 0x21000
	s_addc_u32 s91, s93, 0
	global_load_dwordx4 v[96:99], v241, s[90:91]
	global_load_dwordx4 v[100:103], v241, s[90:91] offset:64
	global_load_dwordx4 v[104:107], v241, s[90:91] offset:2048
	global_load_dwordx4 v[108:111], v241, s[90:91] offset:2112
	s_add_u32 s90, s92, 0x30000
	s_addc_u32 s91, s93, 0
	global_load_dwordx4 v[112:115], v241, s[90:91]
	global_load_dwordx4 v[116:119], v241, s[90:91] offset:64
	global_load_dwordx4 v[120:123], v241, s[90:91] offset:2048
	global_load_dwordx4 v[124:127], v241, s[90:91] offset:2112
	s_add_u32 s90, s92, 0x31000
	s_addc_u32 s91, s93, 0
	global_load_dwordx4 v[128:131], v241, s[90:91]
	global_load_dwordx4 v[132:135], v241, s[90:91] offset:64
	global_load_dwordx4 v[136:139], v241, s[90:91] offset:2048
	global_load_dwordx4 v[228:231], v241, s[90:91] offset:2112
	s_waitcnt lgkmcnt(0)
; __device__ __forceinline__ float sigmoid_f(float x) { return rcpf_(1.f + __expf(-x)); }
; __device__ __forceinline__ float gelu_tanh_f(float x) { const float y = 0.7978845608028654f * (x + 0.044715f * x * x * x); return x * sigmoid_f(2.f * y); }
; template <bool FINAL, int D>
; __device__ __forceinline__ void rg_dir(PREF p, int l, int h, int ch, int sidx, int rowbase  , LAS bf16_t* sXc, LAS float* stg, int lane) {
;     ...
;         for (int ti = 0; ti < 16; ++ti) { const int tk = D ? 15 - ti : ti;
;             const float zr = stg[tk * 64 + lane] + ba, zi = stg[1024 + tk * 64 + lane] + bi;
;             const float r = sigmoid_f(zr), ig = sigmoid_f(zi);
;             const float a = __builtin_amdgcn_exp2f(r * sp8);
;             const float xc = bf2f(sXc[(mt * 16 + tk) * 72 + lane]);
;             av[ti] = a; iv[ti] = __builtin_amdgcn_sqrtf(fmaxf(1.f - a * a, 0.f)) * ig * xc;
;             if (FINAL && D == 1) grv[ti] = gelu_tanh_f(grv[ti]);
;         }
	v_pk_fma_f32 v[0:1], v[0:1], v[248:249], v[242:243]
	v_pk_fma_f32 v[2:3], v[2:3], v[248:249], v[242:243]
	v_pk_fma_f32 v[4:5], v[4:5], v[248:249], v[242:243]
	v_pk_fma_f32 v[6:7], v[6:7], v[248:249], v[242:243]
	v_pk_fma_f32 v[8:9], v[8:9], v[248:249], v[242:243]
	v_pk_fma_f32 v[10:11], v[10:11], v[248:249], v[242:243]
	v_pk_fma_f32 v[12:13], v[12:13], v[248:249], v[242:243]
	v_pk_fma_f32 v[14:15], v[14:15], v[248:249], v[242:243]
	v_pk_fma_f32 v[16:17], v[16:17], v[248:249], v[244:245]
	v_pk_fma_f32 v[18:19], v[18:19], v[248:249], v[244:245]
	v_pk_fma_f32 v[20:21], v[20:21], v[248:249], v[244:245]
	v_pk_fma_f32 v[22:23], v[22:23], v[248:249], v[244:245]
	v_pk_fma_f32 v[24:25], v[24:25], v[248:249], v[244:245]
	v_pk_fma_f32 v[26:27], v[26:27], v[248:249], v[244:245]
	v_pk_fma_f32 v[28:29], v[28:29], v[248:249], v[244:245]
	v_pk_fma_f32 v[30:31], v[30:31], v[248:249], v[244:245]
	v_exp_f32_e32 v0, v0
	v_exp_f32_e32 v1, v1
	v_exp_f32_e32 v2, v2
	v_exp_f32_e32 v3, v3
	v_exp_f32_e32 v4, v4
	v_exp_f32_e32 v5, v5
	v_exp_f32_e32 v6, v6
	v_exp_f32_e32 v7, v7
	v_exp_f32_e32 v8, v8
	v_exp_f32_e32 v9, v9
	v_exp_f32_e32 v10, v10
	v_exp_f32_e32 v11, v11
	v_exp_f32_e32 v12, v12
	v_exp_f32_e32 v13, v13
	v_exp_f32_e32 v14, v14
	v_exp_f32_e32 v15, v15
	v_exp_f32_e32 v16, v16
	v_exp_f32_e32 v17, v17
	v_exp_f32_e32 v18, v18
	v_exp_f32_e32 v19, v19
	v_exp_f32_e32 v20, v20
	v_exp_f32_e32 v21, v21
	v_exp_f32_e32 v22, v22
	v_exp_f32_e32 v23, v23
	v_exp_f32_e32 v24, v24
	v_exp_f32_e32 v25, v25
	v_exp_f32_e32 v26, v26
	v_exp_f32_e32 v27, v27
	v_exp_f32_e32 v28, v28
	v_exp_f32_e32 v29, v29
	v_exp_f32_e32 v30, v30
	v_exp_f32_e32 v31, v31
	v_pk_add_f32 v[0:1], v[0:1], 1.0 op_sel_hi:[1,0]
	v_pk_add_f32 v[2:3], v[2:3], 1.0 op_sel_hi:[1,0]
	v_pk_add_f32 v[4:5], v[4:5], 1.0 op_sel_hi:[1,0]
	v_pk_add_f32 v[6:7], v[6:7], 1.0 op_sel_hi:[1,0]
	v_pk_add_f32 v[8:9], v[8:9], 1.0 op_sel_hi:[1,0]
	v_pk_add_f32 v[10:11], v[10:11], 1.0 op_sel_hi:[1,0]
	v_pk_add_f32 v[12:13], v[12:13], 1.0 op_sel_hi:[1,0]
	v_pk_add_f32 v[14:15], v[14:15], 1.0 op_sel_hi:[1,0]
	v_pk_add_f32 v[16:17], v[16:17], 1.0 op_sel_hi:[1,0]
	v_pk_add_f32 v[18:19], v[18:19], 1.0 op_sel_hi:[1,0]
	v_pk_add_f32 v[20:21], v[20:21], 1.0 op_sel_hi:[1,0]
	v_pk_add_f32 v[22:23], v[22:23], 1.0 op_sel_hi:[1,0]
	v_pk_add_f32 v[24:25], v[24:25], 1.0 op_sel_hi:[1,0]
	v_pk_add_f32 v[26:27], v[26:27], 1.0 op_sel_hi:[1,0]
	v_pk_add_f32 v[28:29], v[28:29], 1.0 op_sel_hi:[1,0]
	v_pk_add_f32 v[30:31], v[30:31], 1.0 op_sel_hi:[1,0]
	v_rcp_f32_e32 v0, v0
	v_rcp_f32_e32 v1, v1
	v_rcp_f32_e32 v2, v2
	v_rcp_f32_e32 v3, v3
	v_rcp_f32_e32 v4, v4
	v_rcp_f32_e32 v5, v5
	v_rcp_f32_e32 v6, v6
	v_rcp_f32_e32 v7, v7
	v_rcp_f32_e32 v8, v8
	v_rcp_f32_e32 v9, v9
	v_rcp_f32_e32 v10, v10
	v_rcp_f32_e32 v11, v11
	v_rcp_f32_e32 v12, v12
	v_rcp_f32_e32 v13, v13
	v_rcp_f32_e32 v14, v14
	v_rcp_f32_e32 v15, v15
	v_rcp_f32_e32 v16, v16
	v_rcp_f32_e32 v17, v17
	v_rcp_f32_e32 v18, v18
	v_rcp_f32_e32 v19, v19
	v_rcp_f32_e32 v20, v20
	v_rcp_f32_e32 v21, v21
	v_rcp_f32_e32 v22, v22
	v_rcp_f32_e32 v23, v23
	v_rcp_f32_e32 v24, v24
	v_rcp_f32_e32 v25, v25
	v_rcp_f32_e32 v26, v26
	v_rcp_f32_e32 v27, v27
	v_rcp_f32_e32 v28, v28
	v_rcp_f32_e32 v29, v29
	v_rcp_f32_e32 v30, v30
	v_rcp_f32_e32 v31, v31
	v_pk_mul_f32 v[0:1], v[246:247], v[0:1]
	v_pk_mul_f32 v[2:3], v[246:247], v[2:3]
	v_pk_mul_f32 v[4:5], v[246:247], v[4:5]
	v_pk_mul_f32 v[6:7], v[246:247], v[6:7]
	v_pk_mul_f32 v[8:9], v[246:247], v[8:9]
	v_pk_mul_f32 v[10:11], v[246:247], v[10:11]
	v_pk_mul_f32 v[12:13], v[246:247], v[12:13]
	v_pk_mul_f32 v[14:15], v[246:247], v[14:15]
	v_lshlrev_b32_e32 v48, 16, v48
	v_lshlrev_b32_e32 v49, 16, v49
	v_lshlrev_b32_e32 v50, 16, v50
	v_lshlrev_b32_e32 v51, 16, v51
	v_lshlrev_b32_e32 v52, 16, v52
	v_lshlrev_b32_e32 v53, 16, v53
	v_lshlrev_b32_e32 v54, 16, v54
	v_lshlrev_b32_e32 v55, 16, v55
	v_lshlrev_b32_e32 v56, 16, v56
	v_lshlrev_b32_e32 v57, 16, v57
	v_lshlrev_b32_e32 v58, 16, v58
	v_lshlrev_b32_e32 v59, 16, v59
	v_lshlrev_b32_e32 v60, 16, v60
	v_lshlrev_b32_e32 v61, 16, v61
	v_lshlrev_b32_e32 v62, 16, v62
	v_lshlrev_b32_e32 v63, 16, v63
	v_exp_f32_e32 v0, v0
	v_exp_f32_e32 v1, v1
	v_exp_f32_e32 v2, v2
	v_exp_f32_e32 v3, v3
	v_exp_f32_e32 v4, v4
	v_exp_f32_e32 v5, v5
	v_exp_f32_e32 v6, v6
	v_exp_f32_e32 v7, v7
	v_exp_f32_e32 v8, v8
	v_exp_f32_e32 v9, v9
	v_exp_f32_e32 v10, v10
	v_exp_f32_e32 v11, v11
	v_exp_f32_e32 v12, v12
	v_exp_f32_e32 v13, v13
	v_exp_f32_e32 v14, v14
	v_exp_f32_e32 v15, v15
	v_fma_f32 v32, -v0, v0, 1.0 clamp
	v_fma_f32 v33, -v1, v1, 1.0 clamp
	v_fma_f32 v34, -v2, v2, 1.0 clamp
	v_fma_f32 v35, -v3, v3, 1.0 clamp
	v_fma_f32 v36, -v4, v4, 1.0 clamp
	v_fma_f32 v37, -v5, v5, 1.0 clamp
	v_fma_f32 v38, -v6, v6, 1.0 clamp
	v_fma_f32 v39, -v7, v7, 1.0 clamp
	v_fma_f32 v40, -v8, v8, 1.0 clamp
	v_fma_f32 v41, -v9, v9, 1.0 clamp
	v_fma_f32 v42, -v10, v10, 1.0 clamp
	v_fma_f32 v43, -v11, v11, 1.0 clamp
	v_fma_f32 v44, -v12, v12, 1.0 clamp
	v_fma_f32 v45, -v13, v13, 1.0 clamp
	v_fma_f32 v46, -v14, v14, 1.0 clamp
	v_fma_f32 v47, -v15, v15, 1.0 clamp
	v_sqrt_f32_e32 v32, v32
	v_sqrt_f32_e32 v33, v33
	v_sqrt_f32_e32 v34, v34
	v_sqrt_f32_e32 v35, v35
	v_sqrt_f32_e32 v36, v36
	v_sqrt_f32_e32 v37, v37
	v_sqrt_f32_e32 v38, v38
	v_sqrt_f32_e32 v39, v39
	v_sqrt_f32_e32 v40, v40
	v_sqrt_f32_e32 v41, v41
	v_sqrt_f32_e32 v42, v42
	v_sqrt_f32_e32 v43, v43
	v_sqrt_f32_e32 v44, v44
	v_sqrt_f32_e32 v45, v45
	v_sqrt_f32_e32 v46, v46
	v_sqrt_f32_e32 v47, v47
	s_nop 0
	v_pk_mul_f32 v[16:17], v[16:17], v[32:33]
	v_pk_mul_f32 v[18:19], v[18:19], v[34:35]
	v_pk_mul_f32 v[20:21], v[20:21], v[36:37]
	v_pk_mul_f32 v[22:23], v[22:23], v[38:39]
	v_pk_mul_f32 v[24:25], v[24:25], v[40:41]
; template <bool FINAL, int D>
; __device__ __forceinline__ void rg_dir(PREF p, int l, int h, int ch, int sidx, int rowbase  , LAS bf16_t* sXc, LAS float* stg, int lane) {
;     ...
;     const float ba = p.rg_ba[(l * 2 + D) * 512 + ch], bi = p.rg_bi[(l * 2 + D) * 512 + ch], lam = p.rg_lam[(l * 2 + D) * 512 + ch];
;     const float e_ = __expf(-lam), u_ = 1.f + e_;
;     const float l1p = (u_ == 1.f) ? e_ : __logf(u_) * e_ * rcpf_(u_ - 1.f);
;     const float sp8 = -8.f * 1.4426950408889634f * l1p;
;     float hc = FINAL ? RGC[sidx] : 0.f, Ap = 1.f;
;     bf16x8 Br[4][2], Bi[4][2];
; #pragma unroll
;     for (int nt = 0; nt < 4; ++nt) { const int o0 = (nt * 16 + (lane & 15)) * 64 + (lane >> 4) * 8;
;         Br[nt][0] = *(const bf16x8*)(wr_ + o0); Br[nt][1] = *(const bf16x8*)(wr_ + o0 + 32); Bi[nt][0] = *(const bf16x8*)(wi_ + o0); Bi[nt][1] = *(const bf16x8*)(wi_ + o0 + 32); }
;     if (FINAL && D == 1) asm volatile("s_waitcnt vmcnt(0)" ::: "memory");
; #pragma unroll 1
;     for (int mi = 0; mi < 4; ++mi) { const int mt = D ? 3 - mi : mi;
;         float grv[16], hfv[16];
;         if (FINAL && D == 1) {
; #pragma unroll
;             for (int ti = 0; ti < 16; ++ti) { const size_t row = (size_t)(rowbase + mt * 16 + 15 - ti); grv[ti] = __builtin_bit_cast(float, (unsigned)P[row * PW + 512 + ch]); hfv[ti] = __builtin_bit_cast(float, (unsigned)TMP[row * 512 + ch]); }
;             __builtin_amdgcn_sched_barrier(0);
; #pragma unroll
;             for (int ti = 0; ti < 16; ++ti) { grv[ti] = bf2f(__builtin_bit_cast(unsigned, grv[ti])); hfv[ti] = bf2f(__builtin_bit_cast(unsigned, hfv[ti])); }
;         }
;         const bf16x8 A0 = *(const LAS bf16x8*)(sXc + (mt * 16 + (lane & 15)) * 72 + (lane >> 4) * 8), A1 = *(const LAS bf16x8*)(sXc + (mt * 16 + (lane & 15)) * 72 + 32 + (lane >> 4) * 8);
;         f32x4 ar[4], ai[4];
; #pragma unroll
;         for (int nt = 0; nt < 4; ++nt) { const f32x4 z = {0.f, 0.f, 0.f, 0.f};
;             ar[nt] = mfma16(A0, Br[nt][0], z); ar[nt] = mfma16(A1, Br[nt][1], ar[nt]); ai[nt] = mfma16(A0, Bi[nt][0], z); ai[nt] = mfma16(A1, Bi[nt][1], ai[nt]); }
;         WAVE_SYNC();
; #pragma unroll
;         for (int nt = 0; nt < 4; ++nt)
; #pragma unroll
;             for (int j = 0; j < 4; ++j) { const int o = ((lane >> 4) * 4 + j) * 64 + nt * 16 + (lane & 15); stg[o] = ar[nt][j]; stg[1024 + o] = ai[nt][j]; }
;         WAVE_SYNC();
	v_pk_mul_f32 v[26:27], v[26:27], v[42:43]
	v_pk_mul_f32 v[28:29], v[28:29], v[44:45]
	v_pk_mul_f32 v[30:31], v[30:31], v[46:47]
	v_pk_mul_f32 v[16:17], v[16:17], v[48:49]
	v_pk_mul_f32 v[18:19], v[18:19], v[50:51]
	v_pk_mul_f32 v[20:21], v[20:21], v[52:53]
	v_pk_mul_f32 v[22:23], v[22:23], v[54:55]
	v_pk_mul_f32 v[24:25], v[24:25], v[56:57]
	v_pk_mul_f32 v[26:27], v[26:27], v[58:59]
	v_pk_mul_f32 v[28:29], v[28:29], v[60:61]
	v_pk_mul_f32 v[30:31], v[30:31], v[62:63]
	global_load_dword v45, v235, s[76:77] offset:2048
	global_load_dword v46, v235, s[78:79] offset:2048
	global_load_dword v47, v235, s[80:81] offset:2048
	global_load_dword v251, v235, s[96:97] offset:2048
	v_fma_f32 v32, v0, v250, v16
	v_fma_f32 v250, v1, v32, v17
	v_cvt_pk_bf16_f32 v182, v32, v250
	v_fma_f32 v32, v2, v250, v18
	v_fma_f32 v250, v3, v32, v19
	v_cvt_pk_bf16_f32 v183, v32, v250
	v_fma_f32 v32, v4, v250, v20
	v_fma_f32 v250, v5, v32, v21
	v_cvt_pk_bf16_f32 v184, v32, v250
	v_fma_f32 v32, v6, v250, v22
	v_fma_f32 v250, v7, v32, v23
	v_cvt_pk_bf16_f32 v185, v32, v250
	v_fma_f32 v32, v8, v250, v24
	v_fma_f32 v250, v9, v32, v25
	v_cvt_pk_bf16_f32 v186, v32, v250
	v_fma_f32 v32, v10, v250, v26
	v_fma_f32 v250, v11, v32, v27
	v_cvt_pk_bf16_f32 v187, v32, v250
	v_fma_f32 v32, v12, v250, v28
	v_fma_f32 v250, v13, v32, v29
	v_cvt_pk_bf16_f32 v188, v32, v250
	v_fma_f32 v32, v14, v250, v30
	v_fma_f32 v250, v15, v32, v31
	v_cvt_pk_bf16_f32 v189, v32, v250
	s_waitcnt vmcnt(0)
	s_mov_b32 s8, 0x800000
	s_mov_b32 s9, 0x3f317217
	s_mov_b32 s14, 0x7f800000
	v_mul_f32_e32 v32, 0xbfb8aa3b, v45
	v_exp_f32_e32 v32, v32
	s_nop 0
	v_add_f32_e32 v33, 1.0, v32
	v_cmp_gt_f32_e32 vcc, s8, v33
	s_nop 1
	v_cndmask_b32_e64 v34, 0, 32, vcc
	v_ldexp_f32 v34, v33, v34
	v_log_f32_e32 v34, v34
	v_cndmask_b32_e32 v36, 0, v226, vcc
	v_cmp_eq_f32_e32 vcc, 1.0, v33
	v_mul_f32_e32 v35, 0x3f317217, v34
	v_fma_f32 v35, v34, s9, -v35
	v_fmac_f32_e32 v35, 0x3377d1cf, v34
	v_fmac_f32_e32 v35, 0x3f317217, v34
	v_cmp_lt_f32_e64 s[10:11], |v34|, s14
	s_nop 1
	v_cndmask_b32_e64 v34, v34, v35, s[10:11]
	v_add_f32_e32 v35, -1.0, v33
	v_rcp_f32_e32 v35, v35
	v_sub_f32_e32 v34, v34, v36
	v_mul_f32_e32 v34, v32, v34
	v_mul_f32_e32 v34, v34, v35
	v_cndmask_b32_e32 v32, v34, v32, vcc
	v_mul_f32_e32 v246, 0xc138aa3b, v32
	v_mov_b32_e32 v247, v246
	v_mul_f32_e32 v242, 0xbfb8aa3b, v46
	v_mul_f32_e32 v244, 0xbfb8aa3b, v47
	v_mov_b32_e32 v243, v242
	v_mov_b32_e32 v245, v244
	v_mov_b32_e32 v250, v251
	ds_read_b128 v[32:35], v236 offset:6912
	ds_read_b128 v[36:39], v236 offset:6976
	s_waitcnt lgkmcnt(0)
	v_mfma_f32_16x16x32_bf16 v[0:3], v[32:35], v[80:83], 0
	v_mfma_f32_16x16x32_bf16 v[4:7], v[32:35], v[88:91], 0
	v_mfma_f32_16x16x32_bf16 v[8:11], v[32:35], v[96:99], 0
	v_mfma_f32_16x16x32_bf16 v[12:15], v[32:35], v[104:107], 0
	v_mfma_f32_16x16x32_bf16 v[16:19], v[32:35], v[112:115], 0
	v_mfma_f32_16x16x32_bf16 v[20:23], v[32:35], v[120:123], 0
	v_mfma_f32_16x16x32_bf16 v[24:27], v[32:35], v[128:131], 0
	v_mfma_f32_16x16x32_bf16 v[28:31], v[32:35], v[136:139], 0
	v_mfma_f32_16x16x32_bf16 v[0:3], v[36:39], v[84:87], v[0:3]
	v_mfma_f32_16x16x32_bf16 v[4:7], v[36:39], v[92:95], v[4:7]
	v_mfma_f32_16x16x32_bf16 v[8:11], v[36:39], v[100:103], v[8:11]
	v_mfma_f32_16x16x32_bf16 v[12:15], v[36:39], v[108:111], v[12:15]
	v_mfma_f32_16x16x32_bf16 v[16:19], v[36:39], v[116:119], v[16:19]
	v_mfma_f32_16x16x32_bf16 v[20:23], v[36:39], v[124:127], v[20:23]
	v_mfma_f32_16x16x32_bf16 v[24:27], v[36:39], v[132:135], v[24:27]
	v_mfma_f32_16x16x32_bf16 v[28:31], v[36:39], v[228:231], v[28:31]
	s_nop 3
	ds_write2_b32 v237, v0, v4 offset0:0 offset1:16
	ds_write2_b32 v237, v8, v12 offset0:32 offset1:48
	ds_write2_b32 v237, v1, v5 offset0:64 offset1:80
	ds_write2_b32 v237, v9, v13 offset0:96 offset1:112
	ds_write2_b32 v237, v2, v6 offset0:128 offset1:144
	ds_write2_b32 v237, v10, v14 offset0:160 offset1:176
	ds_write2_b32 v237, v3, v7 offset0:192 offset1:208
	ds_write2_b32 v237, v11, v15 offset0:224 offset1:240
	ds_write2_b32 v238, v16, v20 offset0:0 offset1:16
	ds_write2_b32 v238, v24, v28 offset0:32 offset1:48
	ds_write2_b32 v238, v17, v21 offset0:64 offset1:80
	ds_write2_b32 v238, v25, v29 offset0:96 offset1:112
	ds_write2_b32 v238, v18, v22 offset0:128 offset1:144
	ds_write2_b32 v238, v26, v30 offset0:160 offset1:176
	ds_write2_b32 v238, v19, v23 offset0:192 offset1:208
	ds_write2_b32 v238, v27, v31 offset0:224 offset1:240
	s_waitcnt lgkmcnt(0)
; #define LAS __attribute__((address_space(3)))
; #define WAVE_SYNC() asm volatile("s_waitcnt lgkmcnt(0)" ::: "memory")
; __device__ __forceinline__ float sigmoid_f(float x) { return rcpf_(1.f + __expf(-x)); }
; template <bool FINAL, int D>
; __device__ __forceinline__ void rg_dir(PREF p, int l, int h, int ch, int sidx, int rowbase  , LAS bf16_t* sXc, LAS float* stg, int lane) {
;     ...
;         if (FINAL && D == 1) {
; #pragma unroll
;             for (int ti = 0; ti < 16; ++ti) { const size_t row = (size_t)(rowbase + mt * 16 + 15 - ti); grv[ti] = __builtin_bit_cast(float, (unsigned)P[row * PW + 512 + ch]); hfv[ti] = __builtin_bit_cast(float, (unsigned)TMP[row * 512 + ch]); }
;             __builtin_amdgcn_sched_barrier(0);
; #pragma unroll
;             for (int ti = 0; ti < 16; ++ti) { grv[ti] = bf2f(__builtin_bit_cast(unsigned, grv[ti])); hfv[ti] = bf2f(__builtin_bit_cast(unsigned, hfv[ti])); }
;         }
;         const bf16x8 A0 = *(const LAS bf16x8*)(sXc + (mt * 16 + (lane & 15)) * 72 + (lane >> 4) * 8), A1 = *(const LAS bf16x8*)(sXc + (mt * 16 + (lane & 15)) * 72 + 32 + (lane >> 4) * 8);
;         f32x4 ar[4], ai[4];
; #pragma unroll
;         for (int nt = 0; nt < 4; ++nt) { const f32x4 z = {0.f, 0.f, 0.f, 0.f};
;             ar[nt] = mfma16(A0, Br[nt][0], z); ar[nt] = mfma16(A1, Br[nt][1], ar[nt]); ai[nt] = mfma16(A0, Bi[nt][0], z); ai[nt] = mfma16(A1, Bi[nt][1], ai[nt]); }
;         WAVE_SYNC();
; #pragma unroll
;         for (int nt = 0; nt < 4; ++nt)
; #pragma unroll
;             for (int j = 0; j < 4; ++j) { const int o = ((lane >> 4) * 4 + j) * 64 + nt * 16 + (lane & 15); stg[o] = ar[nt][j]; stg[1024 + o] = ai[nt][j]; }
;         WAVE_SYNC();
;         float av[16], iv[16];
; #pragma unroll
;         for (int ti = 0; ti < 16; ++ti) { const int tk = D ? 15 - ti : ti;
;             const float zr = stg[tk * 64 + lane] + ba, zi = stg[1024 + tk * 64 + lane] + bi;
;             const float r = sigmoid_f(zr), ig = sigmoid_f(zi);
;             const float a = __builtin_amdgcn_exp2f(r * sp8);
;             const float xc = bf2f(sXc[(mt * 16 + tk) * 72 + lane]);
;             av[ti] = a; iv[ti] = __builtin_amdgcn_sqrtf(fmaxf(1.f - a * a, 0.f)) * ig * xc;
;             if (FINAL && D == 1) grv[ti] = gelu_tanh_f(grv[ti]);
	ds_read2st64_b32 v[0:1], v239 offset0:36 offset1:37
	ds_read2st64_b32 v[2:3], v239 offset0:38 offset1:39
	ds_read2st64_b32 v[4:5], v239 offset0:40 offset1:41
	ds_read2st64_b32 v[6:7], v239 offset0:42 offset1:43
	ds_read2st64_b32 v[8:9], v239 offset0:44 offset1:45
	ds_read2st64_b32 v[10:11], v239 offset0:46 offset1:47
	ds_read2st64_b32 v[12:13], v239 offset0:48 offset1:49
	ds_read2st64_b32 v[14:15], v239 offset0:50 offset1:51
	ds_read2st64_b32 v[16:17], v239 offset0:52 offset1:53
	ds_read2st64_b32 v[18:19], v239 offset0:54 offset1:55
	ds_read2st64_b32 v[20:21], v239 offset0:56 offset1:57
	ds_read2st64_b32 v[22:23], v239 offset0:58 offset1:59
	ds_read2st64_b32 v[24:25], v239 offset0:60 offset1:61
	ds_read2st64_b32 v[26:27], v239 offset0:62 offset1:63
	ds_read2st64_b32 v[28:29], v239 offset0:64 offset1:65
	ds_read2st64_b32 v[30:31], v239 offset0:66 offset1:67
	ds_read_u16 v48, v240 offset:6912
	ds_read_u16 v49, v240 offset:7056
	ds_read_u16 v50, v240 offset:7200
	ds_read_u16 v51, v240 offset:7344
	ds_read_u16 v52, v240 offset:7488
	ds_read_u16 v53, v240 offset:7632
	ds_read_u16 v54, v240 offset:7776
	ds_read_u16 v55, v240 offset:7920
	ds_read_u16 v56, v240 offset:8064
	ds_read_u16 v57, v240 offset:8208
	ds_read_u16 v58, v240 offset:8352
	ds_read_u16 v59, v240 offset:8496
	ds_read_u16 v60, v240 offset:8640
	ds_read_u16 v61, v240 offset:8784
	ds_read_u16 v62, v240 offset:8928
	ds_read_u16 v63, v240 offset:9072
	v_lshlrev_b32_e32 v206, 16, v190
	v_lshlrev_b32_e32 v207, 16, v191
	v_lshlrev_b32_e32 v208, 16, v192
	v_lshlrev_b32_e32 v209, 16, v193
	v_lshlrev_b32_e32 v210, 16, v194
	v_lshlrev_b32_e32 v211, 16, v195
	v_lshlrev_b32_e32 v212, 16, v196
	v_lshlrev_b32_e32 v213, 16, v197
	v_lshlrev_b32_e32 v214, 16, v198
	v_lshlrev_b32_e32 v215, 16, v199
	v_lshlrev_b32_e32 v216, 16, v200
	v_lshlrev_b32_e32 v217, 16, v201
	v_lshlrev_b32_e32 v218, 16, v202
	v_lshlrev_b32_e32 v219, 16, v203
	v_lshlrev_b32_e32 v222, 16, v204
	v_lshlrev_b32_e32 v223, 16, v205
	v_pk_mul_f32 v[32:33], v[140:141], v[206:207]
	v_pk_mul_f32 v[34:35], v[140:141], v[208:209]
	v_pk_mul_f32 v[36:37], v[140:141], v[210:211]
	v_pk_mul_f32 v[38:39], v[140:141], v[212:213]
	v_pk_mul_f32 v[40:41], v[140:141], v[214:215]
	v_pk_mul_f32 v[42:43], v[140:141], v[216:217]
	v_pk_mul_f32 v[44:45], v[140:141], v[218:219]
	v_pk_mul_f32 v[46:47], v[140:141], v[222:223]
	v_pk_mul_f32 v[32:33], v[32:33], v[206:207]
	v_pk_mul_f32 v[34:35], v[34:35], v[208:209]
	v_pk_mul_f32 v[36:37], v[36:37], v[210:211]
	v_pk_mul_f32 v[38:39], v[38:39], v[212:213]
	v_pk_mul_f32 v[40:41], v[40:41], v[214:215]
	v_pk_mul_f32 v[42:43], v[42:43], v[216:217]
	v_pk_mul_f32 v[44:45], v[44:45], v[218:219]
	v_pk_mul_f32 v[46:47], v[46:47], v[222:223]
	v_fma_f32 v32, v32, v206, v206
	v_fma_f32 v33, v33, v207, v207
	v_fma_f32 v34, v34, v208, v208
	v_fma_f32 v35, v35, v209, v209
	v_fma_f32 v36, v36, v210, v210
	v_fma_f32 v37, v37, v211, v211
	v_fma_f32 v38, v38, v212, v212
	v_fma_f32 v39, v39, v213, v213
	v_fma_f32 v40, v40, v214, v214
	v_fma_f32 v41, v41, v215, v215
	v_fma_f32 v42, v42, v216, v216
	v_fma_f32 v43, v43, v217, v217
	v_fma_f32 v44, v44, v218, v218
	v_fma_f32 v45, v45, v219, v219
	v_fma_f32 v46, v46, v222, v222
	v_fma_f32 v47, v47, v223, v223
	s_mov_b32 s98, 0xc0135761
	v_pk_mul_f32 v[32:33], v[32:33], s[98:99] op_sel_hi:[1,0]
	v_pk_mul_f32 v[34:35], v[34:35], s[98:99] op_sel_hi:[1,0]
	v_pk_mul_f32 v[36:37], v[36:37], s[98:99] op_sel_hi:[1,0]
	v_pk_mul_f32 v[38:39], v[38:39], s[98:99] op_sel_hi:[1,0]
	v_pk_mul_f32 v[40:41], v[40:41], s[98:99] op_sel_hi:[1,0]
	v_pk_mul_f32 v[42:43], v[42:43], s[98:99] op_sel_hi:[1,0]
	v_pk_mul_f32 v[44:45], v[44:45], s[98:99] op_sel_hi:[1,0]
	v_pk_mul_f32 v[46:47], v[46:47], s[98:99] op_sel_hi:[1,0]
	v_exp_f32_e32 v32, v32
	v_exp_f32_e32 v33, v33
	v_exp_f32_e32 v34, v34
	v_exp_f32_e32 v35, v35
	v_exp_f32_e32 v36, v36
	v_exp_f32_e32 v37, v37
	v_exp_f32_e32 v38, v38
	v_exp_f32_e32 v39, v39
	v_exp_f32_e32 v40, v40
	v_exp_f32_e32 v41, v41
	v_exp_f32_e32 v42, v42
	v_exp_f32_e32 v43, v43
	v_exp_f32_e32 v44, v44
	v_exp_f32_e32 v45, v45
	v_exp_f32_e32 v46, v46
	v_exp_f32_e32 v47, v47
	v_pk_add_f32 v[32:33], v[32:33], 1.0 op_sel_hi:[1,0]
	v_pk_add_f32 v[34:35], v[34:35], 1.0 op_sel_hi:[1,0]
	v_pk_add_f32 v[36:37], v[36:37], 1.0 op_sel_hi:[1,0]
	v_pk_add_f32 v[38:39], v[38:39], 1.0 op_sel_hi:[1,0]
	v_pk_add_f32 v[40:41], v[40:41], 1.0 op_sel_hi:[1,0]
	v_pk_add_f32 v[42:43], v[42:43], 1.0 op_sel_hi:[1,0]
	v_pk_add_f32 v[44:45], v[44:45], 1.0 op_sel_hi:[1,0]
	v_pk_add_f32 v[46:47], v[46:47], 1.0 op_sel_hi:[1,0]
	v_rcp_f32_e32 v32, v32
	v_rcp_f32_e32 v33, v33
	v_rcp_f32_e32 v34, v34
	v_rcp_f32_e32 v35, v35
	v_rcp_f32_e32 v36, v36
	v_rcp_f32_e32 v37, v37
	v_rcp_f32_e32 v38, v38
	v_rcp_f32_e32 v39, v39
	v_rcp_f32_e32 v40, v40
	v_rcp_f32_e32 v41, v41
	v_rcp_f32_e32 v42, v42
	v_rcp_f32_e32 v43, v43
	v_rcp_f32_e32 v44, v44
	v_rcp_f32_e32 v45, v45
	v_rcp_f32_e32 v46, v46
	v_rcp_f32_e32 v47, v47
	s_nop 0
	v_pk_mul_f32 v[206:207], v[32:33], v[206:207]
	v_pk_mul_f32 v[208:209], v[34:35], v[208:209]
	v_pk_mul_f32 v[210:211], v[36:37], v[210:211]
	v_pk_mul_f32 v[212:213], v[38:39], v[212:213]
	v_pk_mul_f32 v[214:215], v[40:41], v[214:215]
	v_pk_mul_f32 v[216:217], v[42:43], v[216:217]
	v_pk_mul_f32 v[218:219], v[44:45], v[218:219]
	v_pk_mul_f32 v[222:223], v[46:47], v[222:223]
	s_add_i32 s39, s15, 32
	s_mul_hi_u32 s83, s39, 0x1600
	s_mul_i32 s82, s39, 0x1600
	s_add_u32 s82, s82, s0
	s_addc_u32 s83, s83, s1
	s_add_u32 s82, s82, 0xbc00400
	s_addc_u32 s83, s83, 0
	global_load_ushort v190, v234, s[82:83]
	s_add_u32 s82, s82, 0x1600
	s_addc_u32 s83, s83, 0
	global_load_ushort v191, v234, s[82:83]
	s_add_u32 s82, s82, 0x1600
	s_addc_u32 s83, s83, 0
	global_load_ushort v192, v234, s[82:83]
	s_add_u32 s82, s82, 0x1600
	s_addc_u32 s83, s83, 0
	global_load_ushort v193, v234, s[82:83]
	s_add_u32 s82, s82, 0x1600
	s_addc_u32 s83, s83, 0
	global_load_ushort v194, v234, s[82:83]
	s_add_u32 s82, s82, 0x1600
	s_addc_u32 s83, s83, 0
	global_load_ushort v195, v234, s[82:83]
	s_add_u32 s82, s82, 0x1600
	s_addc_u32 s83, s83, 0
	global_load_ushort v196, v234, s[82:83]
	s_add_u32 s82, s82, 0x1600
	s_addc_u32 s83, s83, 0
	global_load_ushort v197, v234, s[82:83]
	s_add_u32 s82, s82, 0x1600
	s_addc_u32 s83, s83, 0
	global_load_ushort v198, v234, s[82:83]
	s_add_u32 s82, s82, 0x1600
	s_addc_u32 s83, s83, 0
	global_load_ushort v199, v234, s[82:83]
	s_add_u32 s82, s82, 0x1600
	s_addc_u32 s83, s83, 0
	global_load_ushort v200, v234, s[82:83]
	s_add_u32 s82, s82, 0x1600
	s_addc_u32 s83, s83, 0
	global_load_ushort v201, v234, s[82:83]
	s_add_u32 s82, s82, 0x1600
	s_addc_u32 s83, s83, 0
	global_load_ushort v202, v234, s[82:83]
	s_add_u32 s82, s82, 0x1600
	s_addc_u32 s83, s83, 0
	global_load_ushort v203, v234, s[82:83]
	s_add_u32 s82, s82, 0x1600
	s_addc_u32 s83, s83, 0
	global_load_ushort v204, v234, s[82:83]
	s_add_u32 s82, s82, 0x1600
	s_addc_u32 s83, s83, 0
	global_load_ushort v205, v234, s[82:83]
	s_waitcnt lgkmcnt(0)
; __device__ __forceinline__ float sigmoid_f(float x) { return rcpf_(1.f + __expf(-x)); }
; __device__ __forceinline__ float gelu_tanh_f(float x) { const float y = 0.7978845608028654f * (x + 0.044715f * x * x * x); return x * sigmoid_f(2.f * y); }
; template <bool FINAL, int D>
; __device__ __forceinline__ void rg_dir(PREF p, int l, int h, int ch, int sidx, int rowbase  , LAS bf16_t* sXc, LAS float* stg, int lane) {
;     ...
;         float av[16], iv[16];
; #pragma unroll
;         for (int ti = 0; ti < 16; ++ti) { const int tk = D ? 15 - ti : ti;
;             const float zr = stg[tk * 64 + lane] + ba, zi = stg[1024 + tk * 64 + lane] + bi;
;             const float r = sigmoid_f(zr), ig = sigmoid_f(zi);
;             const float a = __builtin_amdgcn_exp2f(r * sp8);
;             const float xc = bf2f(sXc[(mt * 16 + tk) * 72 + lane]);
;             av[ti] = a; iv[ti] = __builtin_amdgcn_sqrtf(fmaxf(1.f - a * a, 0.f)) * ig * xc;
;             if (FINAL && D == 1) grv[ti] = gelu_tanh_f(grv[ti]);
	v_pk_fma_f32 v[0:1], v[0:1], v[248:249], v[242:243]
	v_pk_fma_f32 v[2:3], v[2:3], v[248:249], v[242:243]
	v_pk_fma_f32 v[4:5], v[4:5], v[248:249], v[242:243]
	v_pk_fma_f32 v[6:7], v[6:7], v[248:249], v[242:243]
	v_pk_fma_f32 v[8:9], v[8:9], v[248:249], v[242:243]
	v_pk_fma_f32 v[10:11], v[10:11], v[248:249], v[242:243]
	v_pk_fma_f32 v[12:13], v[12:13], v[248:249], v[242:243]
	v_pk_fma_f32 v[14:15], v[14:15], v[248:249], v[242:243]
	v_pk_fma_f32 v[16:17], v[16:17], v[248:249], v[244:245]
	v_pk_fma_f32 v[18:19], v[18:19], v[248:249], v[244:245]
	v_pk_fma_f32 v[20:21], v[20:21], v[248:249], v[244:245]
	v_pk_fma_f32 v[22:23], v[22:23], v[248:249], v[244:245]
	v_pk_fma_f32 v[24:25], v[24:25], v[248:249], v[244:245]
	v_pk_fma_f32 v[26:27], v[26:27], v[248:249], v[244:245]
	v_pk_fma_f32 v[28:29], v[28:29], v[248:249], v[244:245]
	v_pk_fma_f32 v[30:31], v[30:31], v[248:249], v[244:245]
	v_exp_f32_e32 v0, v0
	v_exp_f32_e32 v1, v1
	v_exp_f32_e32 v2, v2
	v_exp_f32_e32 v3, v3
	v_exp_f32_e32 v4, v4
	v_exp_f32_e32 v5, v5
	v_exp_f32_e32 v6, v6
	v_exp_f32_e32 v7, v7
	v_exp_f32_e32 v8, v8
	v_exp_f32_e32 v9, v9
	v_exp_f32_e32 v10, v10
	v_exp_f32_e32 v11, v11
	v_exp_f32_e32 v12, v12
	v_exp_f32_e32 v13, v13
	v_exp_f32_e32 v14, v14
	v_exp_f32_e32 v15, v15
	v_exp_f32_e32 v16, v16
	v_exp_f32_e32 v17, v17
	v_exp_f32_e32 v18, v18
	v_exp_f32_e32 v19, v19
	v_exp_f32_e32 v20, v20
	v_exp_f32_e32 v21, v21
	v_exp_f32_e32 v22, v22
	v_exp_f32_e32 v23, v23
	v_exp_f32_e32 v24, v24
	v_exp_f32_e32 v25, v25
	v_exp_f32_e32 v26, v26
	v_exp_f32_e32 v27, v27
	v_exp_f32_e32 v28, v28
	v_exp_f32_e32 v29, v29
	v_exp_f32_e32 v30, v30
	v_exp_f32_e32 v31, v31
	v_pk_add_f32 v[0:1], v[0:1], 1.0 op_sel_hi:[1,0]
	v_pk_add_f32 v[2:3], v[2:3], 1.0 op_sel_hi:[1,0]
	v_pk_add_f32 v[4:5], v[4:5], 1.0 op_sel_hi:[1,0]
	v_pk_add_f32 v[6:7], v[6:7], 1.0 op_sel_hi:[1,0]
	v_pk_add_f32 v[8:9], v[8:9], 1.0 op_sel_hi:[1,0]
	v_pk_add_f32 v[10:11], v[10:11], 1.0 op_sel_hi:[1,0]
	v_pk_add_f32 v[12:13], v[12:13], 1.0 op_sel_hi:[1,0]
	v_pk_add_f32 v[14:15], v[14:15], 1.0 op_sel_hi:[1,0]
	v_pk_add_f32 v[16:17], v[16:17], 1.0 op_sel_hi:[1,0]
	v_pk_add_f32 v[18:19], v[18:19], 1.0 op_sel_hi:[1,0]
	v_pk_add_f32 v[20:21], v[20:21], 1.0 op_sel_hi:[1,0]
	v_pk_add_f32 v[22:23], v[22:23], 1.0 op_sel_hi:[1,0]
	v_pk_add_f32 v[24:25], v[24:25], 1.0 op_sel_hi:[1,0]
	v_pk_add_f32 v[26:27], v[26:27], 1.0 op_sel_hi:[1,0]
	v_pk_add_f32 v[28:29], v[28:29], 1.0 op_sel_hi:[1,0]
	v_pk_add_f32 v[30:31], v[30:31], 1.0 op_sel_hi:[1,0]
	v_rcp_f32_e32 v0, v0
	v_rcp_f32_e32 v1, v1
	v_rcp_f32_e32 v2, v2
	v_rcp_f32_e32 v3, v3
	v_rcp_f32_e32 v4, v4
	v_rcp_f32_e32 v5, v5
	v_rcp_f32_e32 v6, v6
	v_rcp_f32_e32 v7, v7
	v_rcp_f32_e32 v8, v8
	v_rcp_f32_e32 v9, v9
	v_rcp_f32_e32 v10, v10
	v_rcp_f32_e32 v11, v11
	v_rcp_f32_e32 v12, v12
	v_rcp_f32_e32 v13, v13
	v_rcp_f32_e32 v14, v14
	v_rcp_f32_e32 v15, v15
	v_rcp_f32_e32 v16, v16
	v_rcp_f32_e32 v17, v17
	v_rcp_f32_e32 v18, v18
	v_rcp_f32_e32 v19, v19
	v_rcp_f32_e32 v20, v20
	v_rcp_f32_e32 v21, v21
	v_rcp_f32_e32 v22, v22
	v_rcp_f32_e32 v23, v23
	v_rcp_f32_e32 v24, v24
	v_rcp_f32_e32 v25, v25
	v_rcp_f32_e32 v26, v26
	v_rcp_f32_e32 v27, v27
	v_rcp_f32_e32 v28, v28
	v_rcp_f32_e32 v29, v29
	v_rcp_f32_e32 v30, v30
	v_rcp_f32_e32 v31, v31
	v_pk_mul_f32 v[0:1], v[246:247], v[0:1]
	v_pk_mul_f32 v[2:3], v[246:247], v[2:3]
	v_pk_mul_f32 v[4:5], v[246:247], v[4:5]
	v_pk_mul_f32 v[6:7], v[246:247], v[6:7]
	v_pk_mul_f32 v[8:9], v[246:247], v[8:9]
	v_pk_mul_f32 v[10:11], v[246:247], v[10:11]
	v_pk_mul_f32 v[12:13], v[246:247], v[12:13]
	v_pk_mul_f32 v[14:15], v[246:247], v[14:15]
	v_lshlrev_b32_e32 v48, 16, v48
	v_lshlrev_b32_e32 v49, 16, v49
	v_lshlrev_b32_e32 v50, 16, v50
	v_lshlrev_b32_e32 v51, 16, v51
	v_lshlrev_b32_e32 v52, 16, v52
	v_lshlrev_b32_e32 v53, 16, v53
	v_lshlrev_b32_e32 v54, 16, v54
	v_lshlrev_b32_e32 v55, 16, v55
	v_lshlrev_b32_e32 v56, 16, v56
	v_lshlrev_b32_e32 v57, 16, v57
	v_lshlrev_b32_e32 v58, 16, v58
	v_lshlrev_b32_e32 v59, 16, v59
	v_lshlrev_b32_e32 v60, 16, v60
	v_lshlrev_b32_e32 v61, 16, v61
	v_lshlrev_b32_e32 v62, 16, v62
	v_lshlrev_b32_e32 v63, 16, v63
	v_exp_f32_e32 v0, v0
	v_exp_f32_e32 v1, v1
	v_exp_f32_e32 v2, v2
	v_exp_f32_e32 v3, v3
	v_exp_f32_e32 v4, v4
	v_exp_f32_e32 v5, v5
	v_exp_f32_e32 v6, v6
	v_exp_f32_e32 v7, v7
	v_exp_f32_e32 v8, v8
	v_exp_f32_e32 v9, v9
	v_exp_f32_e32 v10, v10
	v_exp_f32_e32 v11, v11
	v_exp_f32_e32 v12, v12
	v_exp_f32_e32 v13, v13
	v_exp_f32_e32 v14, v14
	v_exp_f32_e32 v15, v15
	v_fma_f32 v32, -v0, v0, 1.0 clamp
	v_fma_f32 v33, -v1, v1, 1.0 clamp
	v_fma_f32 v34, -v2, v2, 1.0 clamp
	v_fma_f32 v35, -v3, v3, 1.0 clamp
	v_fma_f32 v36, -v4, v4, 1.0 clamp
	v_fma_f32 v37, -v5, v5, 1.0 clamp
	v_fma_f32 v38, -v6, v6, 1.0 clamp
	v_fma_f32 v39, -v7, v7, 1.0 clamp
	v_fma_f32 v40, -v8, v8, 1.0 clamp
	v_fma_f32 v41, -v9, v9, 1.0 clamp
	v_fma_f32 v42, -v10, v10, 1.0 clamp
	v_fma_f32 v43, -v11, v11, 1.0 clamp
	v_fma_f32 v44, -v12, v12, 1.0 clamp
	v_fma_f32 v45, -v13, v13, 1.0 clamp
	v_fma_f32 v46, -v14, v14, 1.0 clamp
	v_fma_f32 v47, -v15, v15, 1.0 clamp
	v_sqrt_f32_e32 v32, v32
	v_sqrt_f32_e32 v33, v33
	v_sqrt_f32_e32 v34, v34
	v_sqrt_f32_e32 v35, v35
	v_sqrt_f32_e32 v36, v36
	v_sqrt_f32_e32 v37, v37
	v_sqrt_f32_e32 v38, v38
	v_sqrt_f32_e32 v39, v39
	v_sqrt_f32_e32 v40, v40
	v_sqrt_f32_e32 v41, v41
	v_sqrt_f32_e32 v42, v42
	v_sqrt_f32_e32 v43, v43
	v_sqrt_f32_e32 v44, v44
	v_sqrt_f32_e32 v45, v45
	v_sqrt_f32_e32 v46, v46
	v_sqrt_f32_e32 v47, v47
	s_nop 0
	v_pk_mul_f32 v[16:17], v[16:17], v[32:33]
	v_pk_mul_f32 v[18:19], v[18:19], v[34:35]
	v_pk_mul_f32 v[20:21], v[20:21], v[36:37]
	v_pk_mul_f32 v[22:23], v[22:23], v[38:39]
	v_pk_mul_f32 v[24:25], v[24:25], v[40:41]
; #define LAS __attribute__((address_space(3)))
; #define WAVE_SYNC() asm volatile("s_waitcnt lgkmcnt(0)" ::: "memory")
; __device__ __forceinline__ unsigned f2bf(float f) { unsigned r; asm("v_cvt_pk_bf16_f32 %0, %1, %1" : "=v"(r) : "v"(f)); return r & 0xffffu; }
; __device__ __forceinline__ float gelu_tanh_f(float x) { const float y = 0.7978845608028654f * (x + 0.044715f * x * x * x); return x * sigmoid_f(2.f * y); }
; __device__ __forceinline__ f32x4 mfma16(bf16x8 a, bf16x8 b, f32x4 c) { return __builtin_amdgcn_mfma_f32_16x16x32_bf16(a, b, c, 0, 0, 0); }
; template <bool FINAL, int D>
; __device__ __forceinline__ void rg_dir(PREF p, int l, int h, int ch, int sidx, int rowbase  , LAS bf16_t* sXc, LAS float* stg, int lane) {
;     ...
;         const bf16x8 A0 = *(const LAS bf16x8*)(sXc + (mt * 16 + (lane & 15)) * 72 + (lane >> 4) * 8), A1 = *(const LAS bf16x8*)(sXc + (mt * 16 + (lane & 15)) * 72 + 32 + (lane >> 4) * 8);
;         f32x4 ar[4], ai[4];
; #pragma unroll
;         for (int nt = 0; nt < 4; ++nt) { const f32x4 z = {0.f, 0.f, 0.f, 0.f};
;             ar[nt] = mfma16(A0, Br[nt][0], z); ar[nt] = mfma16(A1, Br[nt][1], ar[nt]); ai[nt] = mfma16(A0, Bi[nt][0], z); ai[nt] = mfma16(A1, Bi[nt][1], ai[nt]); }
;         WAVE_SYNC();
; #pragma unroll
;         for (int nt = 0; nt < 4; ++nt)
; #pragma unroll
;             for (int j = 0; j < 4; ++j) { const int o = ((lane >> 4) * 4 + j) * 64 + nt * 16 + (lane & 15); stg[o] = ar[nt][j]; stg[1024 + o] = ai[nt][j]; }
;         WAVE_SYNC();
;     ...
;             av[ti] = a; iv[ti] = __builtin_amdgcn_sqrtf(fmaxf(1.f - a * a, 0.f)) * ig * xc;
;             if (FINAL && D == 1) grv[ti] = gelu_tanh_f(grv[ti]);
;         }
; #pragma unroll
;         for (int ti = 0; ti < 16; ++ti) { const int tk = D ? 15 - ti : ti;
;             hc = av[ti] * hc + iv[ti]; Ap *= av[ti];
;             if (FINAL) { const size_t row = (size_t)(rowbase + mt * 16 + tk);
;                 if (D == 0) TMP[row * 512 + ch] = (bf16_t)f2bf(hc);
;                 else MIX[row * DM + ch] = (bf16_t)f2bf(grv[ti] * (hfv[ti] + hc)); }
	v_pk_mul_f32 v[26:27], v[26:27], v[42:43]
	v_pk_mul_f32 v[28:29], v[28:29], v[44:45]
	v_pk_mul_f32 v[30:31], v[30:31], v[46:47]
	v_pk_mul_f32 v[16:17], v[16:17], v[48:49]
	v_pk_mul_f32 v[18:19], v[18:19], v[50:51]
	v_pk_mul_f32 v[20:21], v[20:21], v[52:53]
	v_pk_mul_f32 v[22:23], v[22:23], v[54:55]
	v_pk_mul_f32 v[24:25], v[24:25], v[56:57]
	v_pk_mul_f32 v[26:27], v[26:27], v[58:59]
	v_pk_mul_f32 v[28:29], v[28:29], v[60:61]
	v_pk_mul_f32 v[30:31], v[30:31], v[62:63]
	s_add_i32 s39, s15, 63
	s_lshl_b32 s39, s39, 11
	s_add_u32 s90, s0, 0x7b00000
	s_addc_u32 s91, s1, 0
	s_add_u32 s90, s90, s39
	s_addc_u32 s91, s91, 0
	v_lshlrev_b32_e32 v48, 16, v182
	v_and_b32_e32 v49, 0xffff0000, v182
	v_lshlrev_b32_e32 v50, 16, v183
	v_and_b32_e32 v51, 0xffff0000, v183
	v_lshlrev_b32_e32 v52, 16, v184
	v_and_b32_e32 v53, 0xffff0000, v184
	v_lshlrev_b32_e32 v54, 16, v185
	v_and_b32_e32 v55, 0xffff0000, v185
	v_lshlrev_b32_e32 v56, 16, v186
	v_and_b32_e32 v57, 0xffff0000, v186
	v_lshlrev_b32_e32 v58, 16, v187
	v_and_b32_e32 v59, 0xffff0000, v187
	v_lshlrev_b32_e32 v60, 16, v188
	v_and_b32_e32 v61, 0xffff0000, v188
	v_lshlrev_b32_e32 v62, 16, v189
	v_and_b32_e32 v63, 0xffff0000, v189
	v_fma_f32 v47, v15, v250, v31
	v_fma_f32 v46, v14, v47, v30
	v_fma_f32 v45, v13, v46, v29
	v_fma_f32 v44, v12, v45, v28
	v_fma_f32 v43, v11, v44, v27
	v_fma_f32 v42, v10, v43, v26
	v_fma_f32 v41, v9, v42, v25
	v_fma_f32 v40, v8, v41, v24
	v_fma_f32 v39, v7, v40, v23
	v_fma_f32 v38, v6, v39, v22
	v_fma_f32 v37, v5, v38, v21
	v_fma_f32 v36, v4, v37, v20
	v_fma_f32 v35, v3, v36, v19
	v_fma_f32 v34, v2, v35, v18
	v_fma_f32 v33, v1, v34, v17
	v_fma_f32 v32, v0, v33, v16
	v_mov_b32_e32 v250, v32
	v_pk_add_f32 v[48:49], v[48:49], v[32:33]
	v_pk_add_f32 v[50:51], v[50:51], v[34:35]
	v_pk_add_f32 v[52:53], v[52:53], v[36:37]
	v_pk_add_f32 v[54:55], v[54:55], v[38:39]
	v_pk_add_f32 v[56:57], v[56:57], v[40:41]
	v_pk_add_f32 v[58:59], v[58:59], v[42:43]
	v_pk_add_f32 v[60:61], v[60:61], v[44:45]
	v_pk_add_f32 v[62:63], v[62:63], v[46:47]
	v_pk_mul_f32 v[48:49], v[206:207], v[48:49]
	v_pk_mul_f32 v[50:51], v[208:209], v[50:51]
	v_pk_mul_f32 v[52:53], v[210:211], v[52:53]
	v_pk_mul_f32 v[54:55], v[212:213], v[54:55]
	v_pk_mul_f32 v[56:57], v[214:215], v[56:57]
	v_pk_mul_f32 v[58:59], v[216:217], v[58:59]
	v_pk_mul_f32 v[60:61], v[218:219], v[60:61]
	v_pk_mul_f32 v[62:63], v[222:223], v[62:63]
	v_cvt_pk_bf16_f32 v48, v48, v48
	v_cvt_pk_bf16_f32 v49, v49, v49
	v_cvt_pk_bf16_f32 v50, v50, v50
	v_cvt_pk_bf16_f32 v51, v51, v51
	v_cvt_pk_bf16_f32 v52, v52, v52
	v_cvt_pk_bf16_f32 v53, v53, v53
	v_cvt_pk_bf16_f32 v54, v54, v54
	v_cvt_pk_bf16_f32 v55, v55, v55
	v_cvt_pk_bf16_f32 v56, v56, v56
	v_cvt_pk_bf16_f32 v57, v57, v57
	v_cvt_pk_bf16_f32 v58, v58, v58
	v_cvt_pk_bf16_f32 v59, v59, v59
	v_cvt_pk_bf16_f32 v60, v60, v60
	v_cvt_pk_bf16_f32 v61, v61, v61
	v_cvt_pk_bf16_f32 v62, v62, v62
	v_cvt_pk_bf16_f32 v63, v63, v63
	global_store_short v234, v63, s[90:91]
	s_sub_u32 s90, s90, 0x800
	s_subb_u32 s91, s91, 0
	global_store_short v234, v62, s[90:91]
	s_sub_u32 s90, s90, 0x800
	s_subb_u32 s91, s91, 0
	global_store_short v234, v61, s[90:91]
	s_sub_u32 s90, s90, 0x800
	s_subb_u32 s91, s91, 0
	global_store_short v234, v60, s[90:91]
	s_sub_u32 s90, s90, 0x800
	s_subb_u32 s91, s91, 0
	global_store_short v234, v59, s[90:91]
	s_sub_u32 s90, s90, 0x800
	s_subb_u32 s91, s91, 0
	global_store_short v234, v58, s[90:91]
	s_sub_u32 s90, s90, 0x800
	s_subb_u32 s91, s91, 0
	global_store_short v234, v57, s[90:91]
	s_sub_u32 s90, s90, 0x800
	s_subb_u32 s91, s91, 0
	global_store_short v234, v56, s[90:91]
	s_sub_u32 s90, s90, 0x800
	s_subb_u32 s91, s91, 0
	global_store_short v234, v55, s[90:91]
	s_sub_u32 s90, s90, 0x800
	s_subb_u32 s91, s91, 0
	global_store_short v234, v54, s[90:91]
	s_sub_u32 s90, s90, 0x800
	s_subb_u32 s91, s91, 0
	global_store_short v234, v53, s[90:91]
	s_sub_u32 s90, s90, 0x800
	s_subb_u32 s91, s91, 0
	global_store_short v234, v52, s[90:91]
	s_sub_u32 s90, s90, 0x800
	s_subb_u32 s91, s91, 0
	global_store_short v234, v51, s[90:91]
	s_sub_u32 s90, s90, 0x800
	s_subb_u32 s91, s91, 0
	global_store_short v234, v50, s[90:91]
	s_sub_u32 s90, s90, 0x800
	s_subb_u32 s91, s91, 0
	global_store_short v234, v49, s[90:91]
	s_sub_u32 s90, s90, 0x800
	s_subb_u32 s91, s91, 0
	global_store_short v234, v48, s[90:91]
	ds_read_b128 v[32:35], v236 offset:4608
	ds_read_b128 v[36:39], v236 offset:4672
	s_waitcnt lgkmcnt(0)
	v_mfma_f32_16x16x32_bf16 v[0:3], v[32:35], v[80:83], 0
	v_mfma_f32_16x16x32_bf16 v[4:7], v[32:35], v[88:91], 0
	v_mfma_f32_16x16x32_bf16 v[8:11], v[32:35], v[96:99], 0
	v_mfma_f32_16x16x32_bf16 v[12:15], v[32:35], v[104:107], 0
	v_mfma_f32_16x16x32_bf16 v[16:19], v[32:35], v[112:115], 0
	v_mfma_f32_16x16x32_bf16 v[20:23], v[32:35], v[120:123], 0
	v_mfma_f32_16x16x32_bf16 v[24:27], v[32:35], v[128:131], 0
	v_mfma_f32_16x16x32_bf16 v[28:31], v[32:35], v[136:139], 0
	v_mfma_f32_16x16x32_bf16 v[0:3], v[36:39], v[84:87], v[0:3]
	v_mfma_f32_16x16x32_bf16 v[4:7], v[36:39], v[92:95], v[4:7]
	v_mfma_f32_16x16x32_bf16 v[8:11], v[36:39], v[100:103], v[8:11]
	v_mfma_f32_16x16x32_bf16 v[12:15], v[36:39], v[108:111], v[12:15]
	v_mfma_f32_16x16x32_bf16 v[16:19], v[36:39], v[116:119], v[16:19]
	v_mfma_f32_16x16x32_bf16 v[20:23], v[36:39], v[124:127], v[20:23]
	v_mfma_f32_16x16x32_bf16 v[24:27], v[36:39], v[132:135], v[24:27]
	v_mfma_f32_16x16x32_bf16 v[28:31], v[36:39], v[228:231], v[28:31]
	s_nop 3
	ds_write2_b32 v237, v0, v4 offset0:0 offset1:16
	ds_write2_b32 v237, v8, v12 offset0:32 offset1:48
	ds_write2_b32 v237, v1, v5 offset0:64 offset1:80
	ds_write2_b32 v237, v9, v13 offset0:96 offset1:112
	ds_write2_b32 v237, v2, v6 offset0:128 offset1:144
	ds_write2_b32 v237, v10, v14 offset0:160 offset1:176
	ds_write2_b32 v237, v3, v7 offset0:192 offset1:208
	ds_write2_b32 v237, v11, v15 offset0:224 offset1:240
	ds_write2_b32 v238, v16, v20 offset0:0 offset1:16
	ds_write2_b32 v238, v24, v28 offset0:32 offset1:48
	ds_write2_b32 v238, v17, v21 offset0:64 offset1:80
	ds_write2_b32 v238, v25, v29 offset0:96 offset1:112
	ds_write2_b32 v238, v18, v22 offset0:128 offset1:144
	ds_write2_b32 v238, v26, v30 offset0:160 offset1:176
	ds_write2_b32 v238, v19, v23 offset0:192 offset1:208
	ds_write2_b32 v238, v27, v31 offset0:224 offset1:240
	s_waitcnt lgkmcnt(0)
; #define LAS __attribute__((address_space(3)))
; #define WAVE_SYNC() asm volatile("s_waitcnt lgkmcnt(0)" ::: "memory")
; __device__ __forceinline__ float sigmoid_f(float x) { return rcpf_(1.f + __expf(-x)); }
; template <bool FINAL, int D>
; __device__ __forceinline__ void rg_dir(PREF p, int l, int h, int ch, int sidx, int rowbase  , LAS bf16_t* sXc, LAS float* stg, int lane) {
;     ...
;         if (FINAL && D == 1) {
; #pragma unroll
;             for (int ti = 0; ti < 16; ++ti) { const size_t row = (size_t)(rowbase + mt * 16 + 15 - ti); grv[ti] = __builtin_bit_cast(float, (unsigned)P[row * PW + 512 + ch]); hfv[ti] = __builtin_bit_cast(float, (unsigned)TMP[row * 512 + ch]); }
;             __builtin_amdgcn_sched_barrier(0);
; #pragma unroll
;             for (int ti = 0; ti < 16; ++ti) { grv[ti] = bf2f(__builtin_bit_cast(unsigned, grv[ti])); hfv[ti] = bf2f(__builtin_bit_cast(unsigned, hfv[ti])); }
;         }
;         const bf16x8 A0 = *(const LAS bf16x8*)(sXc + (mt * 16 + (lane & 15)) * 72 + (lane >> 4) * 8), A1 = *(const LAS bf16x8*)(sXc + (mt * 16 + (lane & 15)) * 72 + 32 + (lane >> 4) * 8);
;         f32x4 ar[4], ai[4];
; #pragma unroll
;         for (int nt = 0; nt < 4; ++nt) { const f32x4 z = {0.f, 0.f, 0.f, 0.f};
;             ar[nt] = mfma16(A0, Br[nt][0], z); ar[nt] = mfma16(A1, Br[nt][1], ar[nt]); ai[nt] = mfma16(A0, Bi[nt][0], z); ai[nt] = mfma16(A1, Bi[nt][1], ai[nt]); }
;         WAVE_SYNC();
; #pragma unroll
;         for (int nt = 0; nt < 4; ++nt)
; #pragma unroll
;             for (int j = 0; j < 4; ++j) { const int o = ((lane >> 4) * 4 + j) * 64 + nt * 16 + (lane & 15); stg[o] = ar[nt][j]; stg[1024 + o] = ai[nt][j]; }
;         WAVE_SYNC();
;         float av[16], iv[16];
; #pragma unroll
;         for (int ti = 0; ti < 16; ++ti) { const int tk = D ? 15 - ti : ti;
;             const float zr = stg[tk * 64 + lane] + ba, zi = stg[1024 + tk * 64 + lane] + bi;
;             const float r = sigmoid_f(zr), ig = sigmoid_f(zi);
;             const float a = __builtin_amdgcn_exp2f(r * sp8);
;             const float xc = bf2f(sXc[(mt * 16 + tk) * 72 + lane]);
;             av[ti] = a; iv[ti] = __builtin_amdgcn_sqrtf(fmaxf(1.f - a * a, 0.f)) * ig * xc;
;             if (FINAL && D == 1) grv[ti] = gelu_tanh_f(grv[ti]);
	ds_read2st64_b32 v[0:1], v239 offset0:36 offset1:37
	ds_read2st64_b32 v[2:3], v239 offset0:38 offset1:39
	ds_read2st64_b32 v[4:5], v239 offset0:40 offset1:41
	ds_read2st64_b32 v[6:7], v239 offset0:42 offset1:43
	ds_read2st64_b32 v[8:9], v239 offset0:44 offset1:45
	ds_read2st64_b32 v[10:11], v239 offset0:46 offset1:47
	ds_read2st64_b32 v[12:13], v239 offset0:48 offset1:49
	ds_read2st64_b32 v[14:15], v239 offset0:50 offset1:51
	ds_read2st64_b32 v[16:17], v239 offset0:52 offset1:53
	ds_read2st64_b32 v[18:19], v239 offset0:54 offset1:55
	ds_read2st64_b32 v[20:21], v239 offset0:56 offset1:57
	ds_read2st64_b32 v[22:23], v239 offset0:58 offset1:59
	ds_read2st64_b32 v[24:25], v239 offset0:60 offset1:61
	ds_read2st64_b32 v[26:27], v239 offset0:62 offset1:63
	ds_read2st64_b32 v[28:29], v239 offset0:64 offset1:65
	ds_read2st64_b32 v[30:31], v239 offset0:66 offset1:67
	ds_read_u16 v48, v240 offset:4608
	ds_read_u16 v49, v240 offset:4752
	ds_read_u16 v50, v240 offset:4896
	ds_read_u16 v51, v240 offset:5040
	ds_read_u16 v52, v240 offset:5184
	ds_read_u16 v53, v240 offset:5328
	ds_read_u16 v54, v240 offset:5472
	ds_read_u16 v55, v240 offset:5616
	ds_read_u16 v56, v240 offset:5760
	ds_read_u16 v57, v240 offset:5904
	ds_read_u16 v58, v240 offset:6048
	ds_read_u16 v59, v240 offset:6192
	ds_read_u16 v60, v240 offset:6336
	ds_read_u16 v61, v240 offset:6480
	ds_read_u16 v62, v240 offset:6624
	ds_read_u16 v63, v240 offset:6768
	s_waitcnt vmcnt(16)
	v_lshlrev_b32_e32 v206, 16, v190
	v_lshlrev_b32_e32 v207, 16, v191
	v_lshlrev_b32_e32 v208, 16, v192
	v_lshlrev_b32_e32 v209, 16, v193
	v_lshlrev_b32_e32 v210, 16, v194
	v_lshlrev_b32_e32 v211, 16, v195
	v_lshlrev_b32_e32 v212, 16, v196
	v_lshlrev_b32_e32 v213, 16, v197
	v_lshlrev_b32_e32 v214, 16, v198
	v_lshlrev_b32_e32 v215, 16, v199
	v_lshlrev_b32_e32 v216, 16, v200
	v_lshlrev_b32_e32 v217, 16, v201
	v_lshlrev_b32_e32 v218, 16, v202
	v_lshlrev_b32_e32 v219, 16, v203
	v_lshlrev_b32_e32 v222, 16, v204
	v_lshlrev_b32_e32 v223, 16, v205
	v_pk_mul_f32 v[32:33], v[140:141], v[206:207]
	v_pk_mul_f32 v[34:35], v[140:141], v[208:209]
	v_pk_mul_f32 v[36:37], v[140:141], v[210:211]
	v_pk_mul_f32 v[38:39], v[140:141], v[212:213]
	v_pk_mul_f32 v[40:41], v[140:141], v[214:215]
	v_pk_mul_f32 v[42:43], v[140:141], v[216:217]
	v_pk_mul_f32 v[44:45], v[140:141], v[218:219]
	v_pk_mul_f32 v[46:47], v[140:141], v[222:223]
	v_pk_mul_f32 v[32:33], v[32:33], v[206:207]
	v_pk_mul_f32 v[34:35], v[34:35], v[208:209]
	v_pk_mul_f32 v[36:37], v[36:37], v[210:211]
	v_pk_mul_f32 v[38:39], v[38:39], v[212:213]
	v_pk_mul_f32 v[40:41], v[40:41], v[214:215]
	v_pk_mul_f32 v[42:43], v[42:43], v[216:217]
	v_pk_mul_f32 v[44:45], v[44:45], v[218:219]
	v_pk_mul_f32 v[46:47], v[46:47], v[222:223]
	v_fma_f32 v32, v32, v206, v206
	v_fma_f32 v33, v33, v207, v207
	v_fma_f32 v34, v34, v208, v208
	v_fma_f32 v35, v35, v209, v209
	v_fma_f32 v36, v36, v210, v210
	v_fma_f32 v37, v37, v211, v211
	v_fma_f32 v38, v38, v212, v212
	v_fma_f32 v39, v39, v213, v213
	v_fma_f32 v40, v40, v214, v214
	v_fma_f32 v41, v41, v215, v215
	v_fma_f32 v42, v42, v216, v216
	v_fma_f32 v43, v43, v217, v217
	v_fma_f32 v44, v44, v218, v218
	v_fma_f32 v45, v45, v219, v219
	v_fma_f32 v46, v46, v222, v222
	v_fma_f32 v47, v47, v223, v223
	s_mov_b32 s98, 0xc0135761
	v_pk_mul_f32 v[32:33], v[32:33], s[98:99] op_sel_hi:[1,0]
	v_pk_mul_f32 v[34:35], v[34:35], s[98:99] op_sel_hi:[1,0]
	v_pk_mul_f32 v[36:37], v[36:37], s[98:99] op_sel_hi:[1,0]
	v_pk_mul_f32 v[38:39], v[38:39], s[98:99] op_sel_hi:[1,0]
	v_pk_mul_f32 v[40:41], v[40:41], s[98:99] op_sel_hi:[1,0]
	v_pk_mul_f32 v[42:43], v[42:43], s[98:99] op_sel_hi:[1,0]
	v_pk_mul_f32 v[44:45], v[44:45], s[98:99] op_sel_hi:[1,0]
	v_pk_mul_f32 v[46:47], v[46:47], s[98:99] op_sel_hi:[1,0]
	v_exp_f32_e32 v32, v32
	v_exp_f32_e32 v33, v33
	v_exp_f32_e32 v34, v34
	v_exp_f32_e32 v35, v35
	v_exp_f32_e32 v36, v36
	v_exp_f32_e32 v37, v37
	v_exp_f32_e32 v38, v38
	v_exp_f32_e32 v39, v39
	v_exp_f32_e32 v40, v40
	v_exp_f32_e32 v41, v41
	v_exp_f32_e32 v42, v42
	v_exp_f32_e32 v43, v43
	v_exp_f32_e32 v44, v44
	v_exp_f32_e32 v45, v45
	v_exp_f32_e32 v46, v46
	v_exp_f32_e32 v47, v47
	v_pk_add_f32 v[32:33], v[32:33], 1.0 op_sel_hi:[1,0]
	v_pk_add_f32 v[34:35], v[34:35], 1.0 op_sel_hi:[1,0]
	v_pk_add_f32 v[36:37], v[36:37], 1.0 op_sel_hi:[1,0]
	v_pk_add_f32 v[38:39], v[38:39], 1.0 op_sel_hi:[1,0]
	v_pk_add_f32 v[40:41], v[40:41], 1.0 op_sel_hi:[1,0]
	v_pk_add_f32 v[42:43], v[42:43], 1.0 op_sel_hi:[1,0]
	v_pk_add_f32 v[44:45], v[44:45], 1.0 op_sel_hi:[1,0]
	v_pk_add_f32 v[46:47], v[46:47], 1.0 op_sel_hi:[1,0]
	v_rcp_f32_e32 v32, v32
	v_rcp_f32_e32 v33, v33
	v_rcp_f32_e32 v34, v34
	v_rcp_f32_e32 v35, v35
	v_rcp_f32_e32 v36, v36
	v_rcp_f32_e32 v37, v37
	v_rcp_f32_e32 v38, v38
	v_rcp_f32_e32 v39, v39
	v_rcp_f32_e32 v40, v40
	v_rcp_f32_e32 v41, v41
	v_rcp_f32_e32 v42, v42
	v_rcp_f32_e32 v43, v43
	v_rcp_f32_e32 v44, v44
	v_rcp_f32_e32 v45, v45
	v_rcp_f32_e32 v46, v46
	v_rcp_f32_e32 v47, v47
	s_nop 0
	v_pk_mul_f32 v[206:207], v[32:33], v[206:207]
	v_pk_mul_f32 v[208:209], v[34:35], v[208:209]
	v_pk_mul_f32 v[210:211], v[36:37], v[210:211]
	v_pk_mul_f32 v[212:213], v[38:39], v[212:213]
	v_pk_mul_f32 v[214:215], v[40:41], v[214:215]
	v_pk_mul_f32 v[216:217], v[42:43], v[216:217]
	v_pk_mul_f32 v[218:219], v[44:45], v[218:219]
	v_pk_mul_f32 v[222:223], v[46:47], v[222:223]
	s_add_i32 s39, s15, 16
	s_mul_hi_u32 s83, s39, 0x1600
	s_mul_i32 s82, s39, 0x1600
	s_add_u32 s82, s82, s0
	s_addc_u32 s83, s83, s1
	s_add_u32 s82, s82, 0xbc00400
	s_addc_u32 s83, s83, 0
	global_load_ushort v190, v234, s[82:83]
	s_add_u32 s82, s82, 0x1600
	s_addc_u32 s83, s83, 0
	global_load_ushort v191, v234, s[82:83]
	s_add_u32 s82, s82, 0x1600
	s_addc_u32 s83, s83, 0
	global_load_ushort v192, v234, s[82:83]
	s_add_u32 s82, s82, 0x1600
	s_addc_u32 s83, s83, 0
	global_load_ushort v193, v234, s[82:83]
	s_add_u32 s82, s82, 0x1600
	s_addc_u32 s83, s83, 0
	global_load_ushort v194, v234, s[82:83]
	s_add_u32 s82, s82, 0x1600
	s_addc_u32 s83, s83, 0
	global_load_ushort v195, v234, s[82:83]
	s_add_u32 s82, s82, 0x1600
	s_addc_u32 s83, s83, 0
	global_load_ushort v196, v234, s[82:83]
	s_add_u32 s82, s82, 0x1600
	s_addc_u32 s83, s83, 0
	global_load_ushort v197, v234, s[82:83]
	s_add_u32 s82, s82, 0x1600
	s_addc_u32 s83, s83, 0
	global_load_ushort v198, v234, s[82:83]
	s_add_u32 s82, s82, 0x1600
	s_addc_u32 s83, s83, 0
	global_load_ushort v199, v234, s[82:83]
	s_add_u32 s82, s82, 0x1600
	s_addc_u32 s83, s83, 0
	global_load_ushort v200, v234, s[82:83]
	s_add_u32 s82, s82, 0x1600
	s_addc_u32 s83, s83, 0
	global_load_ushort v201, v234, s[82:83]
	s_add_u32 s82, s82, 0x1600
	s_addc_u32 s83, s83, 0
	global_load_ushort v202, v234, s[82:83]
	s_add_u32 s82, s82, 0x1600
	s_addc_u32 s83, s83, 0
	global_load_ushort v203, v234, s[82:83]
	s_add_u32 s82, s82, 0x1600
	s_addc_u32 s83, s83, 0
	global_load_ushort v204, v234, s[82:83]
	s_add_u32 s82, s82, 0x1600
	s_addc_u32 s83, s83, 0
	global_load_ushort v205, v234, s[82:83]
	s_waitcnt lgkmcnt(0)
; __device__ __forceinline__ float sigmoid_f(float x) { return rcpf_(1.f + __expf(-x)); }
; __device__ __forceinline__ float gelu_tanh_f(float x) { const float y = 0.7978845608028654f * (x + 0.044715f * x * x * x); return x * sigmoid_f(2.f * y); }
; template <bool FINAL, int D>
; __device__ __forceinline__ void rg_dir(PREF p, int l, int h, int ch, int sidx, int rowbase  , LAS bf16_t* sXc, LAS float* stg, int lane) {
;     ...
;         float av[16], iv[16];
; #pragma unroll
;         for (int ti = 0; ti < 16; ++ti) { const int tk = D ? 15 - ti : ti;
;             const float zr = stg[tk * 64 + lane] + ba, zi = stg[1024 + tk * 64 + lane] + bi;
;             const float r = sigmoid_f(zr), ig = sigmoid_f(zi);
;             const float a = __builtin_amdgcn_exp2f(r * sp8);
;             const float xc = bf2f(sXc[(mt * 16 + tk) * 72 + lane]);
;             av[ti] = a; iv[ti] = __builtin_amdgcn_sqrtf(fmaxf(1.f - a * a, 0.f)) * ig * xc;
;             if (FINAL && D == 1) grv[ti] = gelu_tanh_f(grv[ti]);
	v_pk_fma_f32 v[0:1], v[0:1], v[248:249], v[242:243]
	v_pk_fma_f32 v[2:3], v[2:3], v[248:249], v[242:243]
	v_pk_fma_f32 v[4:5], v[4:5], v[248:249], v[242:243]
	v_pk_fma_f32 v[6:7], v[6:7], v[248:249], v[242:243]
	v_pk_fma_f32 v[8:9], v[8:9], v[248:249], v[242:243]
	v_pk_fma_f32 v[10:11], v[10:11], v[248:249], v[242:243]
	v_pk_fma_f32 v[12:13], v[12:13], v[248:249], v[242:243]
	v_pk_fma_f32 v[14:15], v[14:15], v[248:249], v[242:243]
	v_pk_fma_f32 v[16:17], v[16:17], v[248:249], v[244:245]
	v_pk_fma_f32 v[18:19], v[18:19], v[248:249], v[244:245]
	v_pk_fma_f32 v[20:21], v[20:21], v[248:249], v[244:245]
	v_pk_fma_f32 v[22:23], v[22:23], v[248:249], v[244:245]
	v_pk_fma_f32 v[24:25], v[24:25], v[248:249], v[244:245]
	v_pk_fma_f32 v[26:27], v[26:27], v[248:249], v[244:245]
	v_pk_fma_f32 v[28:29], v[28:29], v[248:249], v[244:245]
	v_pk_fma_f32 v[30:31], v[30:31], v[248:249], v[244:245]
	v_exp_f32_e32 v0, v0
	v_exp_f32_e32 v1, v1
	v_exp_f32_e32 v2, v2
	v_exp_f32_e32 v3, v3
	v_exp_f32_e32 v4, v4
	v_exp_f32_e32 v5, v5
	v_exp_f32_e32 v6, v6
	v_exp_f32_e32 v7, v7
	v_exp_f32_e32 v8, v8
	v_exp_f32_e32 v9, v9
	v_exp_f32_e32 v10, v10
	v_exp_f32_e32 v11, v11
	v_exp_f32_e32 v12, v12
	v_exp_f32_e32 v13, v13
	v_exp_f32_e32 v14, v14
	v_exp_f32_e32 v15, v15
	v_exp_f32_e32 v16, v16
	v_exp_f32_e32 v17, v17
	v_exp_f32_e32 v18, v18
	v_exp_f32_e32 v19, v19
	v_exp_f32_e32 v20, v20
	v_exp_f32_e32 v21, v21
	v_exp_f32_e32 v22, v22
	v_exp_f32_e32 v23, v23
	v_exp_f32_e32 v24, v24
	v_exp_f32_e32 v25, v25
	v_exp_f32_e32 v26, v26
	v_exp_f32_e32 v27, v27
	v_exp_f32_e32 v28, v28
	v_exp_f32_e32 v29, v29
	v_exp_f32_e32 v30, v30
	v_exp_f32_e32 v31, v31
	v_pk_add_f32 v[0:1], v[0:1], 1.0 op_sel_hi:[1,0]
	v_pk_add_f32 v[2:3], v[2:3], 1.0 op_sel_hi:[1,0]
	v_pk_add_f32 v[4:5], v[4:5], 1.0 op_sel_hi:[1,0]
	v_pk_add_f32 v[6:7], v[6:7], 1.0 op_sel_hi:[1,0]
	v_pk_add_f32 v[8:9], v[8:9], 1.0 op_sel_hi:[1,0]
	v_pk_add_f32 v[10:11], v[10:11], 1.0 op_sel_hi:[1,0]
	v_pk_add_f32 v[12:13], v[12:13], 1.0 op_sel_hi:[1,0]
	v_pk_add_f32 v[14:15], v[14:15], 1.0 op_sel_hi:[1,0]
	v_pk_add_f32 v[16:17], v[16:17], 1.0 op_sel_hi:[1,0]
	v_pk_add_f32 v[18:19], v[18:19], 1.0 op_sel_hi:[1,0]
	v_pk_add_f32 v[20:21], v[20:21], 1.0 op_sel_hi:[1,0]
	v_pk_add_f32 v[22:23], v[22:23], 1.0 op_sel_hi:[1,0]
	v_pk_add_f32 v[24:25], v[24:25], 1.0 op_sel_hi:[1,0]
	v_pk_add_f32 v[26:27], v[26:27], 1.0 op_sel_hi:[1,0]
	v_pk_add_f32 v[28:29], v[28:29], 1.0 op_sel_hi:[1,0]
	v_pk_add_f32 v[30:31], v[30:31], 1.0 op_sel_hi:[1,0]
	v_rcp_f32_e32 v0, v0
	v_rcp_f32_e32 v1, v1
	v_rcp_f32_e32 v2, v2
	v_rcp_f32_e32 v3, v3
	v_rcp_f32_e32 v4, v4
	v_rcp_f32_e32 v5, v5
	v_rcp_f32_e32 v6, v6
	v_rcp_f32_e32 v7, v7
	v_rcp_f32_e32 v8, v8
	v_rcp_f32_e32 v9, v9
	v_rcp_f32_e32 v10, v10
	v_rcp_f32_e32 v11, v11
	v_rcp_f32_e32 v12, v12
	v_rcp_f32_e32 v13, v13
	v_rcp_f32_e32 v14, v14
	v_rcp_f32_e32 v15, v15
	v_rcp_f32_e32 v16, v16
	v_rcp_f32_e32 v17, v17
	v_rcp_f32_e32 v18, v18
	v_rcp_f32_e32 v19, v19
	v_rcp_f32_e32 v20, v20
	v_rcp_f32_e32 v21, v21
	v_rcp_f32_e32 v22, v22
	v_rcp_f32_e32 v23, v23
	v_rcp_f32_e32 v24, v24
	v_rcp_f32_e32 v25, v25
	v_rcp_f32_e32 v26, v26
	v_rcp_f32_e32 v27, v27
	v_rcp_f32_e32 v28, v28
	v_rcp_f32_e32 v29, v29
	v_rcp_f32_e32 v30, v30
	v_rcp_f32_e32 v31, v31
	v_pk_mul_f32 v[0:1], v[246:247], v[0:1]
	v_pk_mul_f32 v[2:3], v[246:247], v[2:3]
	v_pk_mul_f32 v[4:5], v[246:247], v[4:5]
	v_pk_mul_f32 v[6:7], v[246:247], v[6:7]
	v_pk_mul_f32 v[8:9], v[246:247], v[8:9]
	v_pk_mul_f32 v[10:11], v[246:247], v[10:11]
	v_pk_mul_f32 v[12:13], v[246:247], v[12:13]
	v_pk_mul_f32 v[14:15], v[246:247], v[14:15]
	v_lshlrev_b32_e32 v48, 16, v48
	v_lshlrev_b32_e32 v49, 16, v49
	v_lshlrev_b32_e32 v50, 16, v50
	v_lshlrev_b32_e32 v51, 16, v51
	v_lshlrev_b32_e32 v52, 16, v52
	v_lshlrev_b32_e32 v53, 16, v53
	v_lshlrev_b32_e32 v54, 16, v54
	v_lshlrev_b32_e32 v55, 16, v55
	v_lshlrev_b32_e32 v56, 16, v56
	v_lshlrev_b32_e32 v57, 16, v57
	v_lshlrev_b32_e32 v58, 16, v58
	v_lshlrev_b32_e32 v59, 16, v59
	v_lshlrev_b32_e32 v60, 16, v60
	v_lshlrev_b32_e32 v61, 16, v61
	v_lshlrev_b32_e32 v62, 16, v62
	v_lshlrev_b32_e32 v63, 16, v63
	v_exp_f32_e32 v0, v0
	v_exp_f32_e32 v1, v1
	v_exp_f32_e32 v2, v2
	v_exp_f32_e32 v3, v3
	v_exp_f32_e32 v4, v4
	v_exp_f32_e32 v5, v5
	v_exp_f32_e32 v6, v6
	v_exp_f32_e32 v7, v7
	v_exp_f32_e32 v8, v8
	v_exp_f32_e32 v9, v9
	v_exp_f32_e32 v10, v10
	v_exp_f32_e32 v11, v11
	v_exp_f32_e32 v12, v12
	v_exp_f32_e32 v13, v13
	v_exp_f32_e32 v14, v14
	v_exp_f32_e32 v15, v15
	v_fma_f32 v32, -v0, v0, 1.0 clamp
	v_fma_f32 v33, -v1, v1, 1.0 clamp
	v_fma_f32 v34, -v2, v2, 1.0 clamp
	v_fma_f32 v35, -v3, v3, 1.0 clamp
	v_fma_f32 v36, -v4, v4, 1.0 clamp
	v_fma_f32 v37, -v5, v5, 1.0 clamp
	v_fma_f32 v38, -v6, v6, 1.0 clamp
	v_fma_f32 v39, -v7, v7, 1.0 clamp
	v_fma_f32 v40, -v8, v8, 1.0 clamp
	v_fma_f32 v41, -v9, v9, 1.0 clamp
	v_fma_f32 v42, -v10, v10, 1.0 clamp
	v_fma_f32 v43, -v11, v11, 1.0 clamp
	v_fma_f32 v44, -v12, v12, 1.0 clamp
	v_fma_f32 v45, -v13, v13, 1.0 clamp
	v_fma_f32 v46, -v14, v14, 1.0 clamp
	v_fma_f32 v47, -v15, v15, 1.0 clamp
	v_sqrt_f32_e32 v32, v32
	v_sqrt_f32_e32 v33, v33
	v_sqrt_f32_e32 v34, v34
	v_sqrt_f32_e32 v35, v35
	v_sqrt_f32_e32 v36, v36
	v_sqrt_f32_e32 v37, v37
	v_sqrt_f32_e32 v38, v38
	v_sqrt_f32_e32 v39, v39
	v_sqrt_f32_e32 v40, v40
	v_sqrt_f32_e32 v41, v41
	v_sqrt_f32_e32 v42, v42
	v_sqrt_f32_e32 v43, v43
	v_sqrt_f32_e32 v44, v44
	v_sqrt_f32_e32 v45, v45
	v_sqrt_f32_e32 v46, v46
	v_sqrt_f32_e32 v47, v47
	s_nop 0
	v_pk_mul_f32 v[16:17], v[16:17], v[32:33]
	v_pk_mul_f32 v[18:19], v[18:19], v[34:35]
	v_pk_mul_f32 v[20:21], v[20:21], v[36:37]
	v_pk_mul_f32 v[22:23], v[22:23], v[38:39]
	v_pk_mul_f32 v[24:25], v[24:25], v[40:41]
; #define LAS __attribute__((address_space(3)))
; #define WAVE_SYNC() asm volatile("s_waitcnt lgkmcnt(0)" ::: "memory")
; __device__ __forceinline__ unsigned f2bf(float f) { unsigned r; asm("v_cvt_pk_bf16_f32 %0, %1, %1" : "=v"(r) : "v"(f)); return r & 0xffffu; }
; __device__ __forceinline__ float gelu_tanh_f(float x) { const float y = 0.7978845608028654f * (x + 0.044715f * x * x * x); return x * sigmoid_f(2.f * y); }
; __device__ __forceinline__ f32x4 mfma16(bf16x8 a, bf16x8 b, f32x4 c) { return __builtin_amdgcn_mfma_f32_16x16x32_bf16(a, b, c, 0, 0, 0); }
; template <bool FINAL, int D>
; __device__ __forceinline__ void rg_dir(PREF p, int l, int h, int ch, int sidx, int rowbase  , LAS bf16_t* sXc, LAS float* stg, int lane) {
;     ...
;         const bf16x8 A0 = *(const LAS bf16x8*)(sXc + (mt * 16 + (lane & 15)) * 72 + (lane >> 4) * 8), A1 = *(const LAS bf16x8*)(sXc + (mt * 16 + (lane & 15)) * 72 + 32 + (lane >> 4) * 8);
;         f32x4 ar[4], ai[4];
; #pragma unroll
;         for (int nt = 0; nt < 4; ++nt) { const f32x4 z = {0.f, 0.f, 0.f, 0.f};
;             ar[nt] = mfma16(A0, Br[nt][0], z); ar[nt] = mfma16(A1, Br[nt][1], ar[nt]); ai[nt] = mfma16(A0, Bi[nt][0], z); ai[nt] = mfma16(A1, Bi[nt][1], ai[nt]); }
;         WAVE_SYNC();
; #pragma unroll
;         for (int nt = 0; nt < 4; ++nt)
; #pragma unroll
;             for (int j = 0; j < 4; ++j) { const int o = ((lane >> 4) * 4 + j) * 64 + nt * 16 + (lane & 15); stg[o] = ar[nt][j]; stg[1024 + o] = ai[nt][j]; }
;         WAVE_SYNC();
;     ...
;             av[ti] = a; iv[ti] = __builtin_amdgcn_sqrtf(fmaxf(1.f - a * a, 0.f)) * ig * xc;
;             if (FINAL && D == 1) grv[ti] = gelu_tanh_f(grv[ti]);
;         }
; #pragma unroll
;         for (int ti = 0; ti < 16; ++ti) { const int tk = D ? 15 - ti : ti;
;             hc = av[ti] * hc + iv[ti]; Ap *= av[ti];
;             if (FINAL) { const size_t row = (size_t)(rowbase + mt * 16 + tk);
;                 if (D == 0) TMP[row * 512 + ch] = (bf16_t)f2bf(hc);
;                 else MIX[row * DM + ch] = (bf16_t)f2bf(grv[ti] * (hfv[ti] + hc)); }
	v_pk_mul_f32 v[26:27], v[26:27], v[42:43]
	v_pk_mul_f32 v[28:29], v[28:29], v[44:45]
	v_pk_mul_f32 v[30:31], v[30:31], v[46:47]
	v_pk_mul_f32 v[16:17], v[16:17], v[48:49]
	v_pk_mul_f32 v[18:19], v[18:19], v[50:51]
	v_pk_mul_f32 v[20:21], v[20:21], v[52:53]
	v_pk_mul_f32 v[22:23], v[22:23], v[54:55]
	v_pk_mul_f32 v[24:25], v[24:25], v[56:57]
	v_pk_mul_f32 v[26:27], v[26:27], v[58:59]
	v_pk_mul_f32 v[28:29], v[28:29], v[60:61]
	v_pk_mul_f32 v[30:31], v[30:31], v[62:63]
	s_add_i32 s39, s15, 47
	s_lshl_b32 s39, s39, 11
	s_add_u32 s90, s0, 0x7b00000
	s_addc_u32 s91, s1, 0
	s_add_u32 s90, s90, s39
	s_addc_u32 s91, s91, 0
	v_lshlrev_b32_e32 v48, 16, v174
	v_and_b32_e32 v49, 0xffff0000, v174
	v_lshlrev_b32_e32 v50, 16, v175
	v_and_b32_e32 v51, 0xffff0000, v175
	v_lshlrev_b32_e32 v52, 16, v176
	v_and_b32_e32 v53, 0xffff0000, v176
	v_lshlrev_b32_e32 v54, 16, v177
	v_and_b32_e32 v55, 0xffff0000, v177
	v_lshlrev_b32_e32 v56, 16, v178
	v_and_b32_e32 v57, 0xffff0000, v178
	v_lshlrev_b32_e32 v58, 16, v179
	v_and_b32_e32 v59, 0xffff0000, v179
	v_lshlrev_b32_e32 v60, 16, v180
	v_and_b32_e32 v61, 0xffff0000, v180
	v_lshlrev_b32_e32 v62, 16, v181
	v_and_b32_e32 v63, 0xffff0000, v181
	v_fma_f32 v47, v15, v250, v31
	v_fma_f32 v46, v14, v47, v30
	v_fma_f32 v45, v13, v46, v29
	v_fma_f32 v44, v12, v45, v28
	v_fma_f32 v43, v11, v44, v27
	v_fma_f32 v42, v10, v43, v26
	v_fma_f32 v41, v9, v42, v25
	v_fma_f32 v40, v8, v41, v24
	v_fma_f32 v39, v7, v40, v23
	v_fma_f32 v38, v6, v39, v22
	v_fma_f32 v37, v5, v38, v21
	v_fma_f32 v36, v4, v37, v20
	v_fma_f32 v35, v3, v36, v19
	v_fma_f32 v34, v2, v35, v18
	v_fma_f32 v33, v1, v34, v17
	v_fma_f32 v32, v0, v33, v16
	v_mov_b32_e32 v250, v32
	v_pk_add_f32 v[48:49], v[48:49], v[32:33]
	v_pk_add_f32 v[50:51], v[50:51], v[34:35]
	v_pk_add_f32 v[52:53], v[52:53], v[36:37]
	v_pk_add_f32 v[54:55], v[54:55], v[38:39]
	v_pk_add_f32 v[56:57], v[56:57], v[40:41]
	v_pk_add_f32 v[58:59], v[58:59], v[42:43]
	v_pk_add_f32 v[60:61], v[60:61], v[44:45]
	v_pk_add_f32 v[62:63], v[62:63], v[46:47]
	v_pk_mul_f32 v[48:49], v[206:207], v[48:49]
	v_pk_mul_f32 v[50:51], v[208:209], v[50:51]
	v_pk_mul_f32 v[52:53], v[210:211], v[52:53]
	v_pk_mul_f32 v[54:55], v[212:213], v[54:55]
	v_pk_mul_f32 v[56:57], v[214:215], v[56:57]
	v_pk_mul_f32 v[58:59], v[216:217], v[58:59]
	v_pk_mul_f32 v[60:61], v[218:219], v[60:61]
	v_pk_mul_f32 v[62:63], v[222:223], v[62:63]
	v_cvt_pk_bf16_f32 v48, v48, v48
	v_cvt_pk_bf16_f32 v49, v49, v49
	v_cvt_pk_bf16_f32 v50, v50, v50
	v_cvt_pk_bf16_f32 v51, v51, v51
	v_cvt_pk_bf16_f32 v52, v52, v52
	v_cvt_pk_bf16_f32 v53, v53, v53
	v_cvt_pk_bf16_f32 v54, v54, v54
	v_cvt_pk_bf16_f32 v55, v55, v55
	v_cvt_pk_bf16_f32 v56, v56, v56
	v_cvt_pk_bf16_f32 v57, v57, v57
	v_cvt_pk_bf16_f32 v58, v58, v58
	v_cvt_pk_bf16_f32 v59, v59, v59
	v_cvt_pk_bf16_f32 v60, v60, v60
	v_cvt_pk_bf16_f32 v61, v61, v61
	v_cvt_pk_bf16_f32 v62, v62, v62
	v_cvt_pk_bf16_f32 v63, v63, v63
	global_store_short v234, v63, s[90:91]
	s_sub_u32 s90, s90, 0x800
	s_subb_u32 s91, s91, 0
	global_store_short v234, v62, s[90:91]
	s_sub_u32 s90, s90, 0x800
	s_subb_u32 s91, s91, 0
	global_store_short v234, v61, s[90:91]
	s_sub_u32 s90, s90, 0x800
	s_subb_u32 s91, s91, 0
	global_store_short v234, v60, s[90:91]
	s_sub_u32 s90, s90, 0x800
	s_subb_u32 s91, s91, 0
	global_store_short v234, v59, s[90:91]
	s_sub_u32 s90, s90, 0x800
	s_subb_u32 s91, s91, 0
	global_store_short v234, v58, s[90:91]
	s_sub_u32 s90, s90, 0x800
	s_subb_u32 s91, s91, 0
	global_store_short v234, v57, s[90:91]
	s_sub_u32 s90, s90, 0x800
	s_subb_u32 s91, s91, 0
	global_store_short v234, v56, s[90:91]
	s_sub_u32 s90, s90, 0x800
	s_subb_u32 s91, s91, 0
	global_store_short v234, v55, s[90:91]
	s_sub_u32 s90, s90, 0x800
	s_subb_u32 s91, s91, 0
	global_store_short v234, v54, s[90:91]
	s_sub_u32 s90, s90, 0x800
	s_subb_u32 s91, s91, 0
	global_store_short v234, v53, s[90:91]
	s_sub_u32 s90, s90, 0x800
	s_subb_u32 s91, s91, 0
	global_store_short v234, v52, s[90:91]
	s_sub_u32 s90, s90, 0x800
	s_subb_u32 s91, s91, 0
	global_store_short v234, v51, s[90:91]
	s_sub_u32 s90, s90, 0x800
	s_subb_u32 s91, s91, 0
	global_store_short v234, v50, s[90:91]
	s_sub_u32 s90, s90, 0x800
	s_subb_u32 s91, s91, 0
	global_store_short v234, v49, s[90:91]
	s_sub_u32 s90, s90, 0x800
	s_subb_u32 s91, s91, 0
	global_store_short v234, v48, s[90:91]
	ds_read_b128 v[32:35], v236 offset:2304
	ds_read_b128 v[36:39], v236 offset:2368
	s_waitcnt lgkmcnt(0)
	v_mfma_f32_16x16x32_bf16 v[0:3], v[32:35], v[80:83], 0
	v_mfma_f32_16x16x32_bf16 v[4:7], v[32:35], v[88:91], 0
	v_mfma_f32_16x16x32_bf16 v[8:11], v[32:35], v[96:99], 0
	v_mfma_f32_16x16x32_bf16 v[12:15], v[32:35], v[104:107], 0
	v_mfma_f32_16x16x32_bf16 v[16:19], v[32:35], v[112:115], 0
	v_mfma_f32_16x16x32_bf16 v[20:23], v[32:35], v[120:123], 0
	v_mfma_f32_16x16x32_bf16 v[24:27], v[32:35], v[128:131], 0
	v_mfma_f32_16x16x32_bf16 v[28:31], v[32:35], v[136:139], 0
	v_mfma_f32_16x16x32_bf16 v[0:3], v[36:39], v[84:87], v[0:3]
	v_mfma_f32_16x16x32_bf16 v[4:7], v[36:39], v[92:95], v[4:7]
	v_mfma_f32_16x16x32_bf16 v[8:11], v[36:39], v[100:103], v[8:11]
	v_mfma_f32_16x16x32_bf16 v[12:15], v[36:39], v[108:111], v[12:15]
	v_mfma_f32_16x16x32_bf16 v[16:19], v[36:39], v[116:119], v[16:19]
	v_mfma_f32_16x16x32_bf16 v[20:23], v[36:39], v[124:127], v[20:23]
	v_mfma_f32_16x16x32_bf16 v[24:27], v[36:39], v[132:135], v[24:27]
	v_mfma_f32_16x16x32_bf16 v[28:31], v[36:39], v[228:231], v[28:31]
	s_nop 3
	ds_write2_b32 v237, v0, v4 offset0:0 offset1:16
	ds_write2_b32 v237, v8, v12 offset0:32 offset1:48
	ds_write2_b32 v237, v1, v5 offset0:64 offset1:80
	ds_write2_b32 v237, v9, v13 offset0:96 offset1:112
	ds_write2_b32 v237, v2, v6 offset0:128 offset1:144
	ds_write2_b32 v237, v10, v14 offset0:160 offset1:176
	ds_write2_b32 v237, v3, v7 offset0:192 offset1:208
	ds_write2_b32 v237, v11, v15 offset0:224 offset1:240
	ds_write2_b32 v238, v16, v20 offset0:0 offset1:16
	ds_write2_b32 v238, v24, v28 offset0:32 offset1:48
	ds_write2_b32 v238, v17, v21 offset0:64 offset1:80
	ds_write2_b32 v238, v25, v29 offset0:96 offset1:112
	ds_write2_b32 v238, v18, v22 offset0:128 offset1:144
	ds_write2_b32 v238, v26, v30 offset0:160 offset1:176
	ds_write2_b32 v238, v19, v23 offset0:192 offset1:208
	ds_write2_b32 v238, v27, v31 offset0:224 offset1:240
	s_waitcnt lgkmcnt(0)
; #define LAS __attribute__((address_space(3)))
; #define WAVE_SYNC() asm volatile("s_waitcnt lgkmcnt(0)" ::: "memory")
; __device__ __forceinline__ float sigmoid_f(float x) { return rcpf_(1.f + __expf(-x)); }
; template <bool FINAL, int D>
; __device__ __forceinline__ void rg_dir(PREF p, int l, int h, int ch, int sidx, int rowbase  , LAS bf16_t* sXc, LAS float* stg, int lane) {
;     ...
;         if (FINAL && D == 1) {
; #pragma unroll
;             for (int ti = 0; ti < 16; ++ti) { const size_t row = (size_t)(rowbase + mt * 16 + 15 - ti); grv[ti] = __builtin_bit_cast(float, (unsigned)P[row * PW + 512 + ch]); hfv[ti] = __builtin_bit_cast(float, (unsigned)TMP[row * 512 + ch]); }
;             __builtin_amdgcn_sched_barrier(0);
; #pragma unroll
;             for (int ti = 0; ti < 16; ++ti) { grv[ti] = bf2f(__builtin_bit_cast(unsigned, grv[ti])); hfv[ti] = bf2f(__builtin_bit_cast(unsigned, hfv[ti])); }
;         }
;         const bf16x8 A0 = *(const LAS bf16x8*)(sXc + (mt * 16 + (lane & 15)) * 72 + (lane >> 4) * 8), A1 = *(const LAS bf16x8*)(sXc + (mt * 16 + (lane & 15)) * 72 + 32 + (lane >> 4) * 8);
;         f32x4 ar[4], ai[4];
; #pragma unroll
;         for (int nt = 0; nt < 4; ++nt) { const f32x4 z = {0.f, 0.f, 0.f, 0.f};
;             ar[nt] = mfma16(A0, Br[nt][0], z); ar[nt] = mfma16(A1, Br[nt][1], ar[nt]); ai[nt] = mfma16(A0, Bi[nt][0], z); ai[nt] = mfma16(A1, Bi[nt][1], ai[nt]); }
;         WAVE_SYNC();
; #pragma unroll
;         for (int nt = 0; nt < 4; ++nt)
; #pragma unroll
;             for (int j = 0; j < 4; ++j) { const int o = ((lane >> 4) * 4 + j) * 64 + nt * 16 + (lane & 15); stg[o] = ar[nt][j]; stg[1024 + o] = ai[nt][j]; }
;         WAVE_SYNC();
;         float av[16], iv[16];
; #pragma unroll
;         for (int ti = 0; ti < 16; ++ti) { const int tk = D ? 15 - ti : ti;
;             const float zr = stg[tk * 64 + lane] + ba, zi = stg[1024 + tk * 64 + lane] + bi;
;             const float r = sigmoid_f(zr), ig = sigmoid_f(zi);
;             const float a = __builtin_amdgcn_exp2f(r * sp8);
;             const float xc = bf2f(sXc[(mt * 16 + tk) * 72 + lane]);
;             av[ti] = a; iv[ti] = __builtin_amdgcn_sqrtf(fmaxf(1.f - a * a, 0.f)) * ig * xc;
;             if (FINAL && D == 1) grv[ti] = gelu_tanh_f(grv[ti]);
	ds_read2st64_b32 v[0:1], v239 offset0:36 offset1:37
	ds_read2st64_b32 v[2:3], v239 offset0:38 offset1:39
	ds_read2st64_b32 v[4:5], v239 offset0:40 offset1:41
	ds_read2st64_b32 v[6:7], v239 offset0:42 offset1:43
	ds_read2st64_b32 v[8:9], v239 offset0:44 offset1:45
	ds_read2st64_b32 v[10:11], v239 offset0:46 offset1:47
	ds_read2st64_b32 v[12:13], v239 offset0:48 offset1:49
	ds_read2st64_b32 v[14:15], v239 offset0:50 offset1:51
	ds_read2st64_b32 v[16:17], v239 offset0:52 offset1:53
	ds_read2st64_b32 v[18:19], v239 offset0:54 offset1:55
	ds_read2st64_b32 v[20:21], v239 offset0:56 offset1:57
	ds_read2st64_b32 v[22:23], v239 offset0:58 offset1:59
	ds_read2st64_b32 v[24:25], v239 offset0:60 offset1:61
	ds_read2st64_b32 v[26:27], v239 offset0:62 offset1:63
	ds_read2st64_b32 v[28:29], v239 offset0:64 offset1:65
	ds_read2st64_b32 v[30:31], v239 offset0:66 offset1:67
	ds_read_u16 v48, v240 offset:2304
	ds_read_u16 v49, v240 offset:2448
	ds_read_u16 v50, v240 offset:2592
	ds_read_u16 v51, v240 offset:2736
	ds_read_u16 v52, v240 offset:2880
	ds_read_u16 v53, v240 offset:3024
	ds_read_u16 v54, v240 offset:3168
	ds_read_u16 v55, v240 offset:3312
	ds_read_u16 v56, v240 offset:3456
	ds_read_u16 v57, v240 offset:3600
	ds_read_u16 v58, v240 offset:3744
	ds_read_u16 v59, v240 offset:3888
	ds_read_u16 v60, v240 offset:4032
	ds_read_u16 v61, v240 offset:4176
	ds_read_u16 v62, v240 offset:4320
	ds_read_u16 v63, v240 offset:4464
	s_waitcnt vmcnt(16)
	v_lshlrev_b32_e32 v206, 16, v190
	v_lshlrev_b32_e32 v207, 16, v191
	v_lshlrev_b32_e32 v208, 16, v192
	v_lshlrev_b32_e32 v209, 16, v193
	v_lshlrev_b32_e32 v210, 16, v194
	v_lshlrev_b32_e32 v211, 16, v195
	v_lshlrev_b32_e32 v212, 16, v196
	v_lshlrev_b32_e32 v213, 16, v197
	v_lshlrev_b32_e32 v214, 16, v198
	v_lshlrev_b32_e32 v215, 16, v199
	v_lshlrev_b32_e32 v216, 16, v200
	v_lshlrev_b32_e32 v217, 16, v201
	v_lshlrev_b32_e32 v218, 16, v202
	v_lshlrev_b32_e32 v219, 16, v203
	v_lshlrev_b32_e32 v222, 16, v204
	v_lshlrev_b32_e32 v223, 16, v205
	v_pk_mul_f32 v[32:33], v[140:141], v[206:207]
	v_pk_mul_f32 v[34:35], v[140:141], v[208:209]
	v_pk_mul_f32 v[36:37], v[140:141], v[210:211]
	v_pk_mul_f32 v[38:39], v[140:141], v[212:213]
	v_pk_mul_f32 v[40:41], v[140:141], v[214:215]
	v_pk_mul_f32 v[42:43], v[140:141], v[216:217]
	v_pk_mul_f32 v[44:45], v[140:141], v[218:219]
	v_pk_mul_f32 v[46:47], v[140:141], v[222:223]
	v_pk_mul_f32 v[32:33], v[32:33], v[206:207]
	v_pk_mul_f32 v[34:35], v[34:35], v[208:209]
	v_pk_mul_f32 v[36:37], v[36:37], v[210:211]
	v_pk_mul_f32 v[38:39], v[38:39], v[212:213]
	v_pk_mul_f32 v[40:41], v[40:41], v[214:215]
	v_pk_mul_f32 v[42:43], v[42:43], v[216:217]
	v_pk_mul_f32 v[44:45], v[44:45], v[218:219]
	v_pk_mul_f32 v[46:47], v[46:47], v[222:223]
	v_fma_f32 v32, v32, v206, v206
	v_fma_f32 v33, v33, v207, v207
	v_fma_f32 v34, v34, v208, v208
	v_fma_f32 v35, v35, v209, v209
	v_fma_f32 v36, v36, v210, v210
	v_fma_f32 v37, v37, v211, v211
	v_fma_f32 v38, v38, v212, v212
	v_fma_f32 v39, v39, v213, v213
	v_fma_f32 v40, v40, v214, v214
	v_fma_f32 v41, v41, v215, v215
	v_fma_f32 v42, v42, v216, v216
	v_fma_f32 v43, v43, v217, v217
	v_fma_f32 v44, v44, v218, v218
	v_fma_f32 v45, v45, v219, v219
	v_fma_f32 v46, v46, v222, v222
	v_fma_f32 v47, v47, v223, v223
	s_mov_b32 s98, 0xc0135761
	v_pk_mul_f32 v[32:33], v[32:33], s[98:99] op_sel_hi:[1,0]
	v_pk_mul_f32 v[34:35], v[34:35], s[98:99] op_sel_hi:[1,0]
	v_pk_mul_f32 v[36:37], v[36:37], s[98:99] op_sel_hi:[1,0]
	v_pk_mul_f32 v[38:39], v[38:39], s[98:99] op_sel_hi:[1,0]
	v_pk_mul_f32 v[40:41], v[40:41], s[98:99] op_sel_hi:[1,0]
	v_pk_mul_f32 v[42:43], v[42:43], s[98:99] op_sel_hi:[1,0]
	v_pk_mul_f32 v[44:45], v[44:45], s[98:99] op_sel_hi:[1,0]
	v_pk_mul_f32 v[46:47], v[46:47], s[98:99] op_sel_hi:[1,0]
	v_exp_f32_e32 v32, v32
	v_exp_f32_e32 v33, v33
	v_exp_f32_e32 v34, v34
	v_exp_f32_e32 v35, v35
	v_exp_f32_e32 v36, v36
	v_exp_f32_e32 v37, v37
	v_exp_f32_e32 v38, v38
	v_exp_f32_e32 v39, v39
	v_exp_f32_e32 v40, v40
	v_exp_f32_e32 v41, v41
	v_exp_f32_e32 v42, v42
	v_exp_f32_e32 v43, v43
	v_exp_f32_e32 v44, v44
	v_exp_f32_e32 v45, v45
	v_exp_f32_e32 v46, v46
	v_exp_f32_e32 v47, v47
	v_pk_add_f32 v[32:33], v[32:33], 1.0 op_sel_hi:[1,0]
	v_pk_add_f32 v[34:35], v[34:35], 1.0 op_sel_hi:[1,0]
	v_pk_add_f32 v[36:37], v[36:37], 1.0 op_sel_hi:[1,0]
	v_pk_add_f32 v[38:39], v[38:39], 1.0 op_sel_hi:[1,0]
	v_pk_add_f32 v[40:41], v[40:41], 1.0 op_sel_hi:[1,0]
	v_pk_add_f32 v[42:43], v[42:43], 1.0 op_sel_hi:[1,0]
	v_pk_add_f32 v[44:45], v[44:45], 1.0 op_sel_hi:[1,0]
	v_pk_add_f32 v[46:47], v[46:47], 1.0 op_sel_hi:[1,0]
	v_rcp_f32_e32 v32, v32
	v_rcp_f32_e32 v33, v33
	v_rcp_f32_e32 v34, v34
	v_rcp_f32_e32 v35, v35
	v_rcp_f32_e32 v36, v36
	v_rcp_f32_e32 v37, v37
	v_rcp_f32_e32 v38, v38
	v_rcp_f32_e32 v39, v39
	v_rcp_f32_e32 v40, v40
	v_rcp_f32_e32 v41, v41
	v_rcp_f32_e32 v42, v42
	v_rcp_f32_e32 v43, v43
	v_rcp_f32_e32 v44, v44
	v_rcp_f32_e32 v45, v45
	v_rcp_f32_e32 v46, v46
	v_rcp_f32_e32 v47, v47
	s_nop 0
	v_pk_mul_f32 v[206:207], v[32:33], v[206:207]
	v_pk_mul_f32 v[208:209], v[34:35], v[208:209]
	v_pk_mul_f32 v[210:211], v[36:37], v[210:211]
	v_pk_mul_f32 v[212:213], v[38:39], v[212:213]
	v_pk_mul_f32 v[214:215], v[40:41], v[214:215]
	v_pk_mul_f32 v[216:217], v[42:43], v[216:217]
	v_pk_mul_f32 v[218:219], v[44:45], v[218:219]
	v_pk_mul_f32 v[222:223], v[46:47], v[222:223]
	s_add_i32 s39, s15, 0
	s_mul_hi_u32 s83, s39, 0x1600
	s_mul_i32 s82, s39, 0x1600
	s_add_u32 s82, s82, s0
	s_addc_u32 s83, s83, s1
	s_add_u32 s82, s82, 0xbc00400
	s_addc_u32 s83, s83, 0
	global_load_ushort v190, v234, s[82:83]
	s_add_u32 s82, s82, 0x1600
	s_addc_u32 s83, s83, 0
	global_load_ushort v191, v234, s[82:83]
	s_add_u32 s82, s82, 0x1600
	s_addc_u32 s83, s83, 0
	global_load_ushort v192, v234, s[82:83]
	s_add_u32 s82, s82, 0x1600
	s_addc_u32 s83, s83, 0
	global_load_ushort v193, v234, s[82:83]
	s_add_u32 s82, s82, 0x1600
	s_addc_u32 s83, s83, 0
	global_load_ushort v194, v234, s[82:83]
	s_add_u32 s82, s82, 0x1600
	s_addc_u32 s83, s83, 0
	global_load_ushort v195, v234, s[82:83]
	s_add_u32 s82, s82, 0x1600
	s_addc_u32 s83, s83, 0
	global_load_ushort v196, v234, s[82:83]
	s_add_u32 s82, s82, 0x1600
	s_addc_u32 s83, s83, 0
	global_load_ushort v197, v234, s[82:83]
	s_add_u32 s82, s82, 0x1600
	s_addc_u32 s83, s83, 0
	global_load_ushort v198, v234, s[82:83]
	s_add_u32 s82, s82, 0x1600
	s_addc_u32 s83, s83, 0
	global_load_ushort v199, v234, s[82:83]
	s_add_u32 s82, s82, 0x1600
	s_addc_u32 s83, s83, 0
	global_load_ushort v200, v234, s[82:83]
	s_add_u32 s82, s82, 0x1600
	s_addc_u32 s83, s83, 0
	global_load_ushort v201, v234, s[82:83]
	s_add_u32 s82, s82, 0x1600
	s_addc_u32 s83, s83, 0
	global_load_ushort v202, v234, s[82:83]
	s_add_u32 s82, s82, 0x1600
	s_addc_u32 s83, s83, 0
	global_load_ushort v203, v234, s[82:83]
	s_add_u32 s82, s82, 0x1600
	s_addc_u32 s83, s83, 0
	global_load_ushort v204, v234, s[82:83]
	s_add_u32 s82, s82, 0x1600
	s_addc_u32 s83, s83, 0
	global_load_ushort v205, v234, s[82:83]
	s_waitcnt lgkmcnt(0)
; __device__ __forceinline__ float sigmoid_f(float x) { return rcpf_(1.f + __expf(-x)); }
; __device__ __forceinline__ float gelu_tanh_f(float x) { const float y = 0.7978845608028654f * (x + 0.044715f * x * x * x); return x * sigmoid_f(2.f * y); }
; template <bool FINAL, int D>
; __device__ __forceinline__ void rg_dir(PREF p, int l, int h, int ch, int sidx, int rowbase  , LAS bf16_t* sXc, LAS float* stg, int lane) {
;     ...
;         float av[16], iv[16];
; #pragma unroll
;         for (int ti = 0; ti < 16; ++ti) { const int tk = D ? 15 - ti : ti;
;             const float zr = stg[tk * 64 + lane] + ba, zi = stg[1024 + tk * 64 + lane] + bi;
;             const float r = sigmoid_f(zr), ig = sigmoid_f(zi);
;             const float a = __builtin_amdgcn_exp2f(r * sp8);
;             const float xc = bf2f(sXc[(mt * 16 + tk) * 72 + lane]);
;             av[ti] = a; iv[ti] = __builtin_amdgcn_sqrtf(fmaxf(1.f - a * a, 0.f)) * ig * xc;
;             if (FINAL && D == 1) grv[ti] = gelu_tanh_f(grv[ti]);
	v_pk_fma_f32 v[0:1], v[0:1], v[248:249], v[242:243]
	v_pk_fma_f32 v[2:3], v[2:3], v[248:249], v[242:243]
	v_pk_fma_f32 v[4:5], v[4:5], v[248:249], v[242:243]
	v_pk_fma_f32 v[6:7], v[6:7], v[248:249], v[242:243]
	v_pk_fma_f32 v[8:9], v[8:9], v[248:249], v[242:243]
	v_pk_fma_f32 v[10:11], v[10:11], v[248:249], v[242:243]
	v_pk_fma_f32 v[12:13], v[12:13], v[248:249], v[242:243]
	v_pk_fma_f32 v[14:15], v[14:15], v[248:249], v[242:243]
	v_pk_fma_f32 v[16:17], v[16:17], v[248:249], v[244:245]
	v_pk_fma_f32 v[18:19], v[18:19], v[248:249], v[244:245]
	v_pk_fma_f32 v[20:21], v[20:21], v[248:249], v[244:245]
	v_pk_fma_f32 v[22:23], v[22:23], v[248:249], v[244:245]
	v_pk_fma_f32 v[24:25], v[24:25], v[248:249], v[244:245]
	v_pk_fma_f32 v[26:27], v[26:27], v[248:249], v[244:245]
	v_pk_fma_f32 v[28:29], v[28:29], v[248:249], v[244:245]
	v_pk_fma_f32 v[30:31], v[30:31], v[248:249], v[244:245]
	v_exp_f32_e32 v0, v0
	v_exp_f32_e32 v1, v1
	v_exp_f32_e32 v2, v2
	v_exp_f32_e32 v3, v3
	v_exp_f32_e32 v4, v4
	v_exp_f32_e32 v5, v5
	v_exp_f32_e32 v6, v6
	v_exp_f32_e32 v7, v7
	v_exp_f32_e32 v8, v8
	v_exp_f32_e32 v9, v9
	v_exp_f32_e32 v10, v10
	v_exp_f32_e32 v11, v11
	v_exp_f32_e32 v12, v12
	v_exp_f32_e32 v13, v13
	v_exp_f32_e32 v14, v14
	v_exp_f32_e32 v15, v15
	v_exp_f32_e32 v16, v16
	v_exp_f32_e32 v17, v17
	v_exp_f32_e32 v18, v18
	v_exp_f32_e32 v19, v19
	v_exp_f32_e32 v20, v20
	v_exp_f32_e32 v21, v21
	v_exp_f32_e32 v22, v22
	v_exp_f32_e32 v23, v23
	v_exp_f32_e32 v24, v24
	v_exp_f32_e32 v25, v25
	v_exp_f32_e32 v26, v26
	v_exp_f32_e32 v27, v27
	v_exp_f32_e32 v28, v28
	v_exp_f32_e32 v29, v29
	v_exp_f32_e32 v30, v30
	v_exp_f32_e32 v31, v31
	v_pk_add_f32 v[0:1], v[0:1], 1.0 op_sel_hi:[1,0]
	v_pk_add_f32 v[2:3], v[2:3], 1.0 op_sel_hi:[1,0]
	v_pk_add_f32 v[4:5], v[4:5], 1.0 op_sel_hi:[1,0]
	v_pk_add_f32 v[6:7], v[6:7], 1.0 op_sel_hi:[1,0]
	v_pk_add_f32 v[8:9], v[8:9], 1.0 op_sel_hi:[1,0]
	v_pk_add_f32 v[10:11], v[10:11], 1.0 op_sel_hi:[1,0]
	v_pk_add_f32 v[12:13], v[12:13], 1.0 op_sel_hi:[1,0]
	v_pk_add_f32 v[14:15], v[14:15], 1.0 op_sel_hi:[1,0]
	v_pk_add_f32 v[16:17], v[16:17], 1.0 op_sel_hi:[1,0]
	v_pk_add_f32 v[18:19], v[18:19], 1.0 op_sel_hi:[1,0]
	v_pk_add_f32 v[20:21], v[20:21], 1.0 op_sel_hi:[1,0]
	v_pk_add_f32 v[22:23], v[22:23], 1.0 op_sel_hi:[1,0]
	v_pk_add_f32 v[24:25], v[24:25], 1.0 op_sel_hi:[1,0]
	v_pk_add_f32 v[26:27], v[26:27], 1.0 op_sel_hi:[1,0]
	v_pk_add_f32 v[28:29], v[28:29], 1.0 op_sel_hi:[1,0]
	v_pk_add_f32 v[30:31], v[30:31], 1.0 op_sel_hi:[1,0]
	v_rcp_f32_e32 v0, v0
	v_rcp_f32_e32 v1, v1
	v_rcp_f32_e32 v2, v2
	v_rcp_f32_e32 v3, v3
	v_rcp_f32_e32 v4, v4
	v_rcp_f32_e32 v5, v5
	v_rcp_f32_e32 v6, v6
	v_rcp_f32_e32 v7, v7
	v_rcp_f32_e32 v8, v8
	v_rcp_f32_e32 v9, v9
	v_rcp_f32_e32 v10, v10
	v_rcp_f32_e32 v11, v11
	v_rcp_f32_e32 v12, v12
	v_rcp_f32_e32 v13, v13
	v_rcp_f32_e32 v14, v14
	v_rcp_f32_e32 v15, v15
	v_rcp_f32_e32 v16, v16
	v_rcp_f32_e32 v17, v17
	v_rcp_f32_e32 v18, v18
	v_rcp_f32_e32 v19, v19
	v_rcp_f32_e32 v20, v20
	v_rcp_f32_e32 v21, v21
	v_rcp_f32_e32 v22, v22
	v_rcp_f32_e32 v23, v23
	v_rcp_f32_e32 v24, v24
	v_rcp_f32_e32 v25, v25
	v_rcp_f32_e32 v26, v26
	v_rcp_f32_e32 v27, v27
	v_rcp_f32_e32 v28, v28
	v_rcp_f32_e32 v29, v29
	v_rcp_f32_e32 v30, v30
	v_rcp_f32_e32 v31, v31
	v_pk_mul_f32 v[0:1], v[246:247], v[0:1]
	v_pk_mul_f32 v[2:3], v[246:247], v[2:3]
	v_pk_mul_f32 v[4:5], v[246:247], v[4:5]
	v_pk_mul_f32 v[6:7], v[246:247], v[6:7]
	v_pk_mul_f32 v[8:9], v[246:247], v[8:9]
	v_pk_mul_f32 v[10:11], v[246:247], v[10:11]
	v_pk_mul_f32 v[12:13], v[246:247], v[12:13]
	v_pk_mul_f32 v[14:15], v[246:247], v[14:15]
	v_lshlrev_b32_e32 v48, 16, v48
	v_lshlrev_b32_e32 v49, 16, v49
	v_lshlrev_b32_e32 v50, 16, v50
	v_lshlrev_b32_e32 v51, 16, v51
	v_lshlrev_b32_e32 v52, 16, v52
	v_lshlrev_b32_e32 v53, 16, v53
	v_lshlrev_b32_e32 v54, 16, v54
	v_lshlrev_b32_e32 v55, 16, v55
	v_lshlrev_b32_e32 v56, 16, v56
	v_lshlrev_b32_e32 v57, 16, v57
	v_lshlrev_b32_e32 v58, 16, v58
	v_lshlrev_b32_e32 v59, 16, v59
	v_lshlrev_b32_e32 v60, 16, v60
	v_lshlrev_b32_e32 v61, 16, v61
	v_lshlrev_b32_e32 v62, 16, v62
	v_lshlrev_b32_e32 v63, 16, v63
	v_exp_f32_e32 v0, v0
	v_exp_f32_e32 v1, v1
	v_exp_f32_e32 v2, v2
	v_exp_f32_e32 v3, v3
	v_exp_f32_e32 v4, v4
	v_exp_f32_e32 v5, v5
	v_exp_f32_e32 v6, v6
	v_exp_f32_e32 v7, v7
	v_exp_f32_e32 v8, v8
	v_exp_f32_e32 v9, v9
	v_exp_f32_e32 v10, v10
	v_exp_f32_e32 v11, v11
	v_exp_f32_e32 v12, v12
	v_exp_f32_e32 v13, v13
	v_exp_f32_e32 v14, v14
	v_exp_f32_e32 v15, v15
	v_fma_f32 v32, -v0, v0, 1.0 clamp
	v_fma_f32 v33, -v1, v1, 1.0 clamp
	v_fma_f32 v34, -v2, v2, 1.0 clamp
	v_fma_f32 v35, -v3, v3, 1.0 clamp
	v_fma_f32 v36, -v4, v4, 1.0 clamp
	v_fma_f32 v37, -v5, v5, 1.0 clamp
	v_fma_f32 v38, -v6, v6, 1.0 clamp
	v_fma_f32 v39, -v7, v7, 1.0 clamp
	v_fma_f32 v40, -v8, v8, 1.0 clamp
	v_fma_f32 v41, -v9, v9, 1.0 clamp
	v_fma_f32 v42, -v10, v10, 1.0 clamp
	v_fma_f32 v43, -v11, v11, 1.0 clamp
	v_fma_f32 v44, -v12, v12, 1.0 clamp
	v_fma_f32 v45, -v13, v13, 1.0 clamp
	v_fma_f32 v46, -v14, v14, 1.0 clamp
	v_fma_f32 v47, -v15, v15, 1.0 clamp
	v_sqrt_f32_e32 v32, v32
	v_sqrt_f32_e32 v33, v33
	v_sqrt_f32_e32 v34, v34
	v_sqrt_f32_e32 v35, v35
	v_sqrt_f32_e32 v36, v36
	v_sqrt_f32_e32 v37, v37
	v_sqrt_f32_e32 v38, v38
	v_sqrt_f32_e32 v39, v39
	v_sqrt_f32_e32 v40, v40
	v_sqrt_f32_e32 v41, v41
	v_sqrt_f32_e32 v42, v42
	v_sqrt_f32_e32 v43, v43
	v_sqrt_f32_e32 v44, v44
	v_sqrt_f32_e32 v45, v45
	v_sqrt_f32_e32 v46, v46
	v_sqrt_f32_e32 v47, v47
	s_nop 0
	v_pk_mul_f32 v[16:17], v[16:17], v[32:33]
	v_pk_mul_f32 v[18:19], v[18:19], v[34:35]
	v_pk_mul_f32 v[20:21], v[20:21], v[36:37]
	v_pk_mul_f32 v[22:23], v[22:23], v[38:39]
	v_pk_mul_f32 v[24:25], v[24:25], v[40:41]
; #define LAS __attribute__((address_space(3)))
; #define WAVE_SYNC() asm volatile("s_waitcnt lgkmcnt(0)" ::: "memory")
; __device__ __forceinline__ unsigned f2bf(float f) { unsigned r; asm("v_cvt_pk_bf16_f32 %0, %1, %1" : "=v"(r) : "v"(f)); return r & 0xffffu; }
; __device__ __forceinline__ float gelu_tanh_f(float x) { const float y = 0.7978845608028654f * (x + 0.044715f * x * x * x); return x * sigmoid_f(2.f * y); }
; __device__ __forceinline__ f32x4 mfma16(bf16x8 a, bf16x8 b, f32x4 c) { return __builtin_amdgcn_mfma_f32_16x16x32_bf16(a, b, c, 0, 0, 0); }
; template <bool FINAL, int D>
; __device__ __forceinline__ void rg_dir(PREF p, int l, int h, int ch, int sidx, int rowbase  , LAS bf16_t* sXc, LAS float* stg, int lane) {
;     ...
;         const bf16x8 A0 = *(const LAS bf16x8*)(sXc + (mt * 16 + (lane & 15)) * 72 + (lane >> 4) * 8), A1 = *(const LAS bf16x8*)(sXc + (mt * 16 + (lane & 15)) * 72 + 32 + (lane >> 4) * 8);
;         f32x4 ar[4], ai[4];
; #pragma unroll
;         for (int nt = 0; nt < 4; ++nt) { const f32x4 z = {0.f, 0.f, 0.f, 0.f};
;             ar[nt] = mfma16(A0, Br[nt][0], z); ar[nt] = mfma16(A1, Br[nt][1], ar[nt]); ai[nt] = mfma16(A0, Bi[nt][0], z); ai[nt] = mfma16(A1, Bi[nt][1], ai[nt]); }
;         WAVE_SYNC();
; #pragma unroll
;         for (int nt = 0; nt < 4; ++nt)
; #pragma unroll
;             for (int j = 0; j < 4; ++j) { const int o = ((lane >> 4) * 4 + j) * 64 + nt * 16 + (lane & 15); stg[o] = ar[nt][j]; stg[1024 + o] = ai[nt][j]; }
;         WAVE_SYNC();
;     ...
;             av[ti] = a; iv[ti] = __builtin_amdgcn_sqrtf(fmaxf(1.f - a * a, 0.f)) * ig * xc;
;             if (FINAL && D == 1) grv[ti] = gelu_tanh_f(grv[ti]);
;         }
; #pragma unroll
;         for (int ti = 0; ti < 16; ++ti) { const int tk = D ? 15 - ti : ti;
;             hc = av[ti] * hc + iv[ti]; Ap *= av[ti];
;             if (FINAL) { const size_t row = (size_t)(rowbase + mt * 16 + tk);
;                 if (D == 0) TMP[row * 512 + ch] = (bf16_t)f2bf(hc);
;                 else MIX[row * DM + ch] = (bf16_t)f2bf(grv[ti] * (hfv[ti] + hc)); }
	v_pk_mul_f32 v[26:27], v[26:27], v[42:43]
	v_pk_mul_f32 v[28:29], v[28:29], v[44:45]
	v_pk_mul_f32 v[30:31], v[30:31], v[46:47]
	v_pk_mul_f32 v[16:17], v[16:17], v[48:49]
	v_pk_mul_f32 v[18:19], v[18:19], v[50:51]
	v_pk_mul_f32 v[20:21], v[20:21], v[52:53]
	v_pk_mul_f32 v[22:23], v[22:23], v[54:55]
	v_pk_mul_f32 v[24:25], v[24:25], v[56:57]
	v_pk_mul_f32 v[26:27], v[26:27], v[58:59]
	v_pk_mul_f32 v[28:29], v[28:29], v[60:61]
	v_pk_mul_f32 v[30:31], v[30:31], v[62:63]
	s_add_i32 s39, s15, 31
	s_lshl_b32 s39, s39, 11
	s_add_u32 s90, s0, 0x7b00000
	s_addc_u32 s91, s1, 0
	s_add_u32 s90, s90, s39
	s_addc_u32 s91, s91, 0
	v_lshlrev_b32_e32 v48, 16, v166
	v_and_b32_e32 v49, 0xffff0000, v166
	v_lshlrev_b32_e32 v50, 16, v167
	v_and_b32_e32 v51, 0xffff0000, v167
	v_lshlrev_b32_e32 v52, 16, v168
	v_and_b32_e32 v53, 0xffff0000, v168
	v_lshlrev_b32_e32 v54, 16, v169
	v_and_b32_e32 v55, 0xffff0000, v169
	v_lshlrev_b32_e32 v56, 16, v170
	v_and_b32_e32 v57, 0xffff0000, v170
	v_lshlrev_b32_e32 v58, 16, v171
	v_and_b32_e32 v59, 0xffff0000, v171
	v_lshlrev_b32_e32 v60, 16, v172
	v_and_b32_e32 v61, 0xffff0000, v172
	v_lshlrev_b32_e32 v62, 16, v173
	v_and_b32_e32 v63, 0xffff0000, v173
	v_fma_f32 v47, v15, v250, v31
	v_fma_f32 v46, v14, v47, v30
	v_fma_f32 v45, v13, v46, v29
	v_fma_f32 v44, v12, v45, v28
	v_fma_f32 v43, v11, v44, v27
	v_fma_f32 v42, v10, v43, v26
	v_fma_f32 v41, v9, v42, v25
	v_fma_f32 v40, v8, v41, v24
	v_fma_f32 v39, v7, v40, v23
	v_fma_f32 v38, v6, v39, v22
	v_fma_f32 v37, v5, v38, v21
	v_fma_f32 v36, v4, v37, v20
	v_fma_f32 v35, v3, v36, v19
	v_fma_f32 v34, v2, v35, v18
	v_fma_f32 v33, v1, v34, v17
	v_fma_f32 v32, v0, v33, v16
	v_mov_b32_e32 v250, v32
	v_pk_add_f32 v[48:49], v[48:49], v[32:33]
	v_pk_add_f32 v[50:51], v[50:51], v[34:35]
	v_pk_add_f32 v[52:53], v[52:53], v[36:37]
	v_pk_add_f32 v[54:55], v[54:55], v[38:39]
	v_pk_add_f32 v[56:57], v[56:57], v[40:41]
	v_pk_add_f32 v[58:59], v[58:59], v[42:43]
	v_pk_add_f32 v[60:61], v[60:61], v[44:45]
	v_pk_add_f32 v[62:63], v[62:63], v[46:47]
	v_pk_mul_f32 v[48:49], v[206:207], v[48:49]
	v_pk_mul_f32 v[50:51], v[208:209], v[50:51]
	v_pk_mul_f32 v[52:53], v[210:211], v[52:53]
	v_pk_mul_f32 v[54:55], v[212:213], v[54:55]
	v_pk_mul_f32 v[56:57], v[214:215], v[56:57]
	v_pk_mul_f32 v[58:59], v[216:217], v[58:59]
	v_pk_mul_f32 v[60:61], v[218:219], v[60:61]
	v_pk_mul_f32 v[62:63], v[222:223], v[62:63]
	v_cvt_pk_bf16_f32 v48, v48, v48
	v_cvt_pk_bf16_f32 v49, v49, v49
	v_cvt_pk_bf16_f32 v50, v50, v50
	v_cvt_pk_bf16_f32 v51, v51, v51
	v_cvt_pk_bf16_f32 v52, v52, v52
	v_cvt_pk_bf16_f32 v53, v53, v53
	v_cvt_pk_bf16_f32 v54, v54, v54
	v_cvt_pk_bf16_f32 v55, v55, v55
	v_cvt_pk_bf16_f32 v56, v56, v56
	v_cvt_pk_bf16_f32 v57, v57, v57
	v_cvt_pk_bf16_f32 v58, v58, v58
	v_cvt_pk_bf16_f32 v59, v59, v59
	v_cvt_pk_bf16_f32 v60, v60, v60
	v_cvt_pk_bf16_f32 v61, v61, v61
	v_cvt_pk_bf16_f32 v62, v62, v62
	v_cvt_pk_bf16_f32 v63, v63, v63
	global_store_short v234, v63, s[90:91]
	s_sub_u32 s90, s90, 0x800
	s_subb_u32 s91, s91, 0
	global_store_short v234, v62, s[90:91]
	s_sub_u32 s90, s90, 0x800
	s_subb_u32 s91, s91, 0
	global_store_short v234, v61, s[90:91]
	s_sub_u32 s90, s90, 0x800
	s_subb_u32 s91, s91, 0
	global_store_short v234, v60, s[90:91]
	s_sub_u32 s90, s90, 0x800
	s_subb_u32 s91, s91, 0
	global_store_short v234, v59, s[90:91]
	s_sub_u32 s90, s90, 0x800
	s_subb_u32 s91, s91, 0
	global_store_short v234, v58, s[90:91]
	s_sub_u32 s90, s90, 0x800
	s_subb_u32 s91, s91, 0
	global_store_short v234, v57, s[90:91]
	s_sub_u32 s90, s90, 0x800
	s_subb_u32 s91, s91, 0
	global_store_short v234, v56, s[90:91]
	s_sub_u32 s90, s90, 0x800
	s_subb_u32 s91, s91, 0
	global_store_short v234, v55, s[90:91]
	s_sub_u32 s90, s90, 0x800
	s_subb_u32 s91, s91, 0
	global_store_short v234, v54, s[90:91]
	s_sub_u32 s90, s90, 0x800
	s_subb_u32 s91, s91, 0
	global_store_short v234, v53, s[90:91]
	s_sub_u32 s90, s90, 0x800
	s_subb_u32 s91, s91, 0
	global_store_short v234, v52, s[90:91]
	s_sub_u32 s90, s90, 0x800
	s_subb_u32 s91, s91, 0
	global_store_short v234, v51, s[90:91]
	s_sub_u32 s90, s90, 0x800
	s_subb_u32 s91, s91, 0
	global_store_short v234, v50, s[90:91]
	s_sub_u32 s90, s90, 0x800
	s_subb_u32 s91, s91, 0
	global_store_short v234, v49, s[90:91]
	s_sub_u32 s90, s90, 0x800
	s_subb_u32 s91, s91, 0
	global_store_short v234, v48, s[90:91]
	ds_read_b128 v[32:35], v236 offset:0
	ds_read_b128 v[36:39], v236 offset:64
	s_waitcnt lgkmcnt(0)
	v_mfma_f32_16x16x32_bf16 v[0:3], v[32:35], v[80:83], 0
	v_mfma_f32_16x16x32_bf16 v[4:7], v[32:35], v[88:91], 0
	v_mfma_f32_16x16x32_bf16 v[8:11], v[32:35], v[96:99], 0
	v_mfma_f32_16x16x32_bf16 v[12:15], v[32:35], v[104:107], 0
	v_mfma_f32_16x16x32_bf16 v[16:19], v[32:35], v[112:115], 0
	v_mfma_f32_16x16x32_bf16 v[20:23], v[32:35], v[120:123], 0
	v_mfma_f32_16x16x32_bf16 v[24:27], v[32:35], v[128:131], 0
	v_mfma_f32_16x16x32_bf16 v[28:31], v[32:35], v[136:139], 0
	v_mfma_f32_16x16x32_bf16 v[0:3], v[36:39], v[84:87], v[0:3]
	v_mfma_f32_16x16x32_bf16 v[4:7], v[36:39], v[92:95], v[4:7]
	v_mfma_f32_16x16x32_bf16 v[8:11], v[36:39], v[100:103], v[8:11]
	v_mfma_f32_16x16x32_bf16 v[12:15], v[36:39], v[108:111], v[12:15]
	v_mfma_f32_16x16x32_bf16 v[16:19], v[36:39], v[116:119], v[16:19]
	v_mfma_f32_16x16x32_bf16 v[20:23], v[36:39], v[124:127], v[20:23]
	v_mfma_f32_16x16x32_bf16 v[24:27], v[36:39], v[132:135], v[24:27]
	v_mfma_f32_16x16x32_bf16 v[28:31], v[36:39], v[228:231], v[28:31]
	s_nop 3
	ds_write2_b32 v237, v0, v4 offset0:0 offset1:16
	ds_write2_b32 v237, v8, v12 offset0:32 offset1:48
	ds_write2_b32 v237, v1, v5 offset0:64 offset1:80
	ds_write2_b32 v237, v9, v13 offset0:96 offset1:112
	ds_write2_b32 v237, v2, v6 offset0:128 offset1:144
	ds_write2_b32 v237, v10, v14 offset0:160 offset1:176
	ds_write2_b32 v237, v3, v7 offset0:192 offset1:208
	ds_write2_b32 v237, v11, v15 offset0:224 offset1:240
	ds_write2_b32 v238, v16, v20 offset0:0 offset1:16
	ds_write2_b32 v238, v24, v28 offset0:32 offset1:48
	ds_write2_b32 v238, v17, v21 offset0:64 offset1:80
	ds_write2_b32 v238, v25, v29 offset0:96 offset1:112
	ds_write2_b32 v238, v18, v22 offset0:128 offset1:144
	ds_write2_b32 v238, v26, v30 offset0:160 offset1:176
	ds_write2_b32 v238, v19, v23 offset0:192 offset1:208
	ds_write2_b32 v238, v27, v31 offset0:224 offset1:240
	s_waitcnt lgkmcnt(0)
; #define LAS __attribute__((address_space(3)))
; #define WAVE_SYNC() asm volatile("s_waitcnt lgkmcnt(0)" ::: "memory")
; __device__ __forceinline__ float sigmoid_f(float x) { return rcpf_(1.f + __expf(-x)); }
; template <bool FINAL, int D>
; __device__ __forceinline__ void rg_dir(PREF p, int l, int h, int ch, int sidx, int rowbase  , LAS bf16_t* sXc, LAS float* stg, int lane) {
;     ...
;         if (FINAL && D == 1) {
; #pragma unroll
;             for (int ti = 0; ti < 16; ++ti) { const size_t row = (size_t)(rowbase + mt * 16 + 15 - ti); grv[ti] = __builtin_bit_cast(float, (unsigned)P[row * PW + 512 + ch]); hfv[ti] = __builtin_bit_cast(float, (unsigned)TMP[row * 512 + ch]); }
;             __builtin_amdgcn_sched_barrier(0);
; #pragma unroll
;             for (int ti = 0; ti < 16; ++ti) { grv[ti] = bf2f(__builtin_bit_cast(unsigned, grv[ti])); hfv[ti] = bf2f(__builtin_bit_cast(unsigned, hfv[ti])); }
;         }
;         const bf16x8 A0 = *(const LAS bf16x8*)(sXc + (mt * 16 + (lane & 15)) * 72 + (lane >> 4) * 8), A1 = *(const LAS bf16x8*)(sXc + (mt * 16 + (lane & 15)) * 72 + 32 + (lane >> 4) * 8);
;         f32x4 ar[4], ai[4];
; #pragma unroll
;         for (int nt = 0; nt < 4; ++nt) { const f32x4 z = {0.f, 0.f, 0.f, 0.f};
;             ar[nt] = mfma16(A0, Br[nt][0], z); ar[nt] = mfma16(A1, Br[nt][1], ar[nt]); ai[nt] = mfma16(A0, Bi[nt][0], z); ai[nt] = mfma16(A1, Bi[nt][1], ai[nt]); }
;         WAVE_SYNC();
; #pragma unroll
;         for (int nt = 0; nt < 4; ++nt)
; #pragma unroll
;             for (int j = 0; j < 4; ++j) { const int o = ((lane >> 4) * 4 + j) * 64 + nt * 16 + (lane & 15); stg[o] = ar[nt][j]; stg[1024 + o] = ai[nt][j]; }
;         WAVE_SYNC();
;         float av[16], iv[16];
; #pragma unroll
;         for (int ti = 0; ti < 16; ++ti) { const int tk = D ? 15 - ti : ti;
;             const float zr = stg[tk * 64 + lane] + ba, zi = stg[1024 + tk * 64 + lane] + bi;
;             const float r = sigmoid_f(zr), ig = sigmoid_f(zi);
;             const float a = __builtin_amdgcn_exp2f(r * sp8);
;             const float xc = bf2f(sXc[(mt * 16 + tk) * 72 + lane]);
;             av[ti] = a; iv[ti] = __builtin_amdgcn_sqrtf(fmaxf(1.f - a * a, 0.f)) * ig * xc;
;             if (FINAL && D == 1) grv[ti] = gelu_tanh_f(grv[ti]);
	ds_read2st64_b32 v[0:1], v239 offset0:36 offset1:37
	ds_read2st64_b32 v[2:3], v239 offset0:38 offset1:39
	ds_read2st64_b32 v[4:5], v239 offset0:40 offset1:41
	ds_read2st64_b32 v[6:7], v239 offset0:42 offset1:43
	ds_read2st64_b32 v[8:9], v239 offset0:44 offset1:45
	ds_read2st64_b32 v[10:11], v239 offset0:46 offset1:47
	ds_read2st64_b32 v[12:13], v239 offset0:48 offset1:49
	ds_read2st64_b32 v[14:15], v239 offset0:50 offset1:51
	ds_read2st64_b32 v[16:17], v239 offset0:52 offset1:53
	ds_read2st64_b32 v[18:19], v239 offset0:54 offset1:55
	ds_read2st64_b32 v[20:21], v239 offset0:56 offset1:57
	ds_read2st64_b32 v[22:23], v239 offset0:58 offset1:59
	ds_read2st64_b32 v[24:25], v239 offset0:60 offset1:61
	ds_read2st64_b32 v[26:27], v239 offset0:62 offset1:63
	ds_read2st64_b32 v[28:29], v239 offset0:64 offset1:65
	ds_read2st64_b32 v[30:31], v239 offset0:66 offset1:67
	ds_read_u16 v48, v240 offset:0
	ds_read_u16 v49, v240 offset:144
	ds_read_u16 v50, v240 offset:288
	ds_read_u16 v51, v240 offset:432
	ds_read_u16 v52, v240 offset:576
	ds_read_u16 v53, v240 offset:720
	ds_read_u16 v54, v240 offset:864
	ds_read_u16 v55, v240 offset:1008
	ds_read_u16 v56, v240 offset:1152
	ds_read_u16 v57, v240 offset:1296
	ds_read_u16 v58, v240 offset:1440
	ds_read_u16 v59, v240 offset:1584
	ds_read_u16 v60, v240 offset:1728
	ds_read_u16 v61, v240 offset:1872
	ds_read_u16 v62, v240 offset:2016
	ds_read_u16 v63, v240 offset:2160
	s_waitcnt vmcnt(16)
	v_lshlrev_b32_e32 v206, 16, v190
	v_lshlrev_b32_e32 v207, 16, v191
	v_lshlrev_b32_e32 v208, 16, v192
	v_lshlrev_b32_e32 v209, 16, v193
	v_lshlrev_b32_e32 v210, 16, v194
	v_lshlrev_b32_e32 v211, 16, v195
	v_lshlrev_b32_e32 v212, 16, v196
	v_lshlrev_b32_e32 v213, 16, v197
	v_lshlrev_b32_e32 v214, 16, v198
	v_lshlrev_b32_e32 v215, 16, v199
	v_lshlrev_b32_e32 v216, 16, v200
	v_lshlrev_b32_e32 v217, 16, v201
	v_lshlrev_b32_e32 v218, 16, v202
	v_lshlrev_b32_e32 v219, 16, v203
	v_lshlrev_b32_e32 v222, 16, v204
	v_lshlrev_b32_e32 v223, 16, v205
	v_pk_mul_f32 v[32:33], v[140:141], v[206:207]
	v_pk_mul_f32 v[34:35], v[140:141], v[208:209]
	v_pk_mul_f32 v[36:37], v[140:141], v[210:211]
	v_pk_mul_f32 v[38:39], v[140:141], v[212:213]
	v_pk_mul_f32 v[40:41], v[140:141], v[214:215]
	v_pk_mul_f32 v[42:43], v[140:141], v[216:217]
	v_pk_mul_f32 v[44:45], v[140:141], v[218:219]
	v_pk_mul_f32 v[46:47], v[140:141], v[222:223]
	v_pk_mul_f32 v[32:33], v[32:33], v[206:207]
	v_pk_mul_f32 v[34:35], v[34:35], v[208:209]
	v_pk_mul_f32 v[36:37], v[36:37], v[210:211]
	v_pk_mul_f32 v[38:39], v[38:39], v[212:213]
	v_pk_mul_f32 v[40:41], v[40:41], v[214:215]
	v_pk_mul_f32 v[42:43], v[42:43], v[216:217]
	v_pk_mul_f32 v[44:45], v[44:45], v[218:219]
	v_pk_mul_f32 v[46:47], v[46:47], v[222:223]
	v_fma_f32 v32, v32, v206, v206
	v_fma_f32 v33, v33, v207, v207
	v_fma_f32 v34, v34, v208, v208
	v_fma_f32 v35, v35, v209, v209
	v_fma_f32 v36, v36, v210, v210
	v_fma_f32 v37, v37, v211, v211
	v_fma_f32 v38, v38, v212, v212
	v_fma_f32 v39, v39, v213, v213
	v_fma_f32 v40, v40, v214, v214
	v_fma_f32 v41, v41, v215, v215
	v_fma_f32 v42, v42, v216, v216
	v_fma_f32 v43, v43, v217, v217
	v_fma_f32 v44, v44, v218, v218
	v_fma_f32 v45, v45, v219, v219
	v_fma_f32 v46, v46, v222, v222
	v_fma_f32 v47, v47, v223, v223
	s_mov_b32 s98, 0xc0135761
	v_pk_mul_f32 v[32:33], v[32:33], s[98:99] op_sel_hi:[1,0]
	v_pk_mul_f32 v[34:35], v[34:35], s[98:99] op_sel_hi:[1,0]
	v_pk_mul_f32 v[36:37], v[36:37], s[98:99] op_sel_hi:[1,0]
	v_pk_mul_f32 v[38:39], v[38:39], s[98:99] op_sel_hi:[1,0]
	v_pk_mul_f32 v[40:41], v[40:41], s[98:99] op_sel_hi:[1,0]
	v_pk_mul_f32 v[42:43], v[42:43], s[98:99] op_sel_hi:[1,0]
	v_pk_mul_f32 v[44:45], v[44:45], s[98:99] op_sel_hi:[1,0]
	v_pk_mul_f32 v[46:47], v[46:47], s[98:99] op_sel_hi:[1,0]
	v_exp_f32_e32 v32, v32
	v_exp_f32_e32 v33, v33
	v_exp_f32_e32 v34, v34
	v_exp_f32_e32 v35, v35
	v_exp_f32_e32 v36, v36
	v_exp_f32_e32 v37, v37
	v_exp_f32_e32 v38, v38
	v_exp_f32_e32 v39, v39
	v_exp_f32_e32 v40, v40
	v_exp_f32_e32 v41, v41
	v_exp_f32_e32 v42, v42
	v_exp_f32_e32 v43, v43
	v_exp_f32_e32 v44, v44
	v_exp_f32_e32 v45, v45
	v_exp_f32_e32 v46, v46
	v_exp_f32_e32 v47, v47
	v_pk_add_f32 v[32:33], v[32:33], 1.0 op_sel_hi:[1,0]
	v_pk_add_f32 v[34:35], v[34:35], 1.0 op_sel_hi:[1,0]
	v_pk_add_f32 v[36:37], v[36:37], 1.0 op_sel_hi:[1,0]
	v_pk_add_f32 v[38:39], v[38:39], 1.0 op_sel_hi:[1,0]
	v_pk_add_f32 v[40:41], v[40:41], 1.0 op_sel_hi:[1,0]
	v_pk_add_f32 v[42:43], v[42:43], 1.0 op_sel_hi:[1,0]
	v_pk_add_f32 v[44:45], v[44:45], 1.0 op_sel_hi:[1,0]
	v_pk_add_f32 v[46:47], v[46:47], 1.0 op_sel_hi:[1,0]
	v_rcp_f32_e32 v32, v32
	v_rcp_f32_e32 v33, v33
	v_rcp_f32_e32 v34, v34
	v_rcp_f32_e32 v35, v35
	v_rcp_f32_e32 v36, v36
	v_rcp_f32_e32 v37, v37
	v_rcp_f32_e32 v38, v38
	v_rcp_f32_e32 v39, v39
	v_rcp_f32_e32 v40, v40
	v_rcp_f32_e32 v41, v41
	v_rcp_f32_e32 v42, v42
	v_rcp_f32_e32 v43, v43
	v_rcp_f32_e32 v44, v44
	v_rcp_f32_e32 v45, v45
	v_rcp_f32_e32 v46, v46
	v_rcp_f32_e32 v47, v47
	s_nop 0
	v_pk_mul_f32 v[206:207], v[32:33], v[206:207]
	v_pk_mul_f32 v[208:209], v[34:35], v[208:209]
	v_pk_mul_f32 v[210:211], v[36:37], v[210:211]
	v_pk_mul_f32 v[212:213], v[38:39], v[212:213]
	v_pk_mul_f32 v[214:215], v[40:41], v[214:215]
	v_pk_mul_f32 v[216:217], v[42:43], v[216:217]
	v_pk_mul_f32 v[218:219], v[44:45], v[218:219]
	v_pk_mul_f32 v[222:223], v[46:47], v[222:223]
	s_waitcnt lgkmcnt(0)
; __device__ __forceinline__ float sigmoid_f(float x) { return rcpf_(1.f + __expf(-x)); }
; __device__ __forceinline__ float gelu_tanh_f(float x) { const float y = 0.7978845608028654f * (x + 0.044715f * x * x * x); return x * sigmoid_f(2.f * y); }
; template <bool FINAL, int D>
; __device__ __forceinline__ void rg_dir(PREF p, int l, int h, int ch, int sidx, int rowbase  , LAS bf16_t* sXc, LAS float* stg, int lane) {
;     ...
;         float av[16], iv[16];
; #pragma unroll
;         for (int ti = 0; ti < 16; ++ti) { const int tk = D ? 15 - ti : ti;
;             const float zr = stg[tk * 64 + lane] + ba, zi = stg[1024 + tk * 64 + lane] + bi;
;             const float r = sigmoid_f(zr), ig = sigmoid_f(zi);
;             const float a = __builtin_amdgcn_exp2f(r * sp8);
;             const float xc = bf2f(sXc[(mt * 16 + tk) * 72 + lane]);
;             av[ti] = a; iv[ti] = __builtin_amdgcn_sqrtf(fmaxf(1.f - a * a, 0.f)) * ig * xc;
;             if (FINAL && D == 1) grv[ti] = gelu_tanh_f(grv[ti]);
	v_pk_fma_f32 v[0:1], v[0:1], v[248:249], v[242:243]
	v_pk_fma_f32 v[2:3], v[2:3], v[248:249], v[242:243]
	v_pk_fma_f32 v[4:5], v[4:5], v[248:249], v[242:243]
	v_pk_fma_f32 v[6:7], v[6:7], v[248:249], v[242:243]
	v_pk_fma_f32 v[8:9], v[8:9], v[248:249], v[242:243]
	v_pk_fma_f32 v[10:11], v[10:11], v[248:249], v[242:243]
	v_pk_fma_f32 v[12:13], v[12:13], v[248:249], v[242:243]
	v_pk_fma_f32 v[14:15], v[14:15], v[248:249], v[242:243]
	v_pk_fma_f32 v[16:17], v[16:17], v[248:249], v[244:245]
	v_pk_fma_f32 v[18:19], v[18:19], v[248:249], v[244:245]
	v_pk_fma_f32 v[20:21], v[20:21], v[248:249], v[244:245]
	v_pk_fma_f32 v[22:23], v[22:23], v[248:249], v[244:245]
	v_pk_fma_f32 v[24:25], v[24:25], v[248:249], v[244:245]
	v_pk_fma_f32 v[26:27], v[26:27], v[248:249], v[244:245]
	v_pk_fma_f32 v[28:29], v[28:29], v[248:249], v[244:245]
	v_pk_fma_f32 v[30:31], v[30:31], v[248:249], v[244:245]
	v_exp_f32_e32 v0, v0
	v_exp_f32_e32 v1, v1
	v_exp_f32_e32 v2, v2
	v_exp_f32_e32 v3, v3
	v_exp_f32_e32 v4, v4
	v_exp_f32_e32 v5, v5
	v_exp_f32_e32 v6, v6
	v_exp_f32_e32 v7, v7
	v_exp_f32_e32 v8, v8
	v_exp_f32_e32 v9, v9
	v_exp_f32_e32 v10, v10
	v_exp_f32_e32 v11, v11
	v_exp_f32_e32 v12, v12
	v_exp_f32_e32 v13, v13
	v_exp_f32_e32 v14, v14
	v_exp_f32_e32 v15, v15
	v_exp_f32_e32 v16, v16
	v_exp_f32_e32 v17, v17
	v_exp_f32_e32 v18, v18
	v_exp_f32_e32 v19, v19
	v_exp_f32_e32 v20, v20
	v_exp_f32_e32 v21, v21
	v_exp_f32_e32 v22, v22
	v_exp_f32_e32 v23, v23
	v_exp_f32_e32 v24, v24
	v_exp_f32_e32 v25, v25
	v_exp_f32_e32 v26, v26
	v_exp_f32_e32 v27, v27
	v_exp_f32_e32 v28, v28
	v_exp_f32_e32 v29, v29
	v_exp_f32_e32 v30, v30
	v_exp_f32_e32 v31, v31
	v_pk_add_f32 v[0:1], v[0:1], 1.0 op_sel_hi:[1,0]
	v_pk_add_f32 v[2:3], v[2:3], 1.0 op_sel_hi:[1,0]
	v_pk_add_f32 v[4:5], v[4:5], 1.0 op_sel_hi:[1,0]
	v_pk_add_f32 v[6:7], v[6:7], 1.0 op_sel_hi:[1,0]
	v_pk_add_f32 v[8:9], v[8:9], 1.0 op_sel_hi:[1,0]
	v_pk_add_f32 v[10:11], v[10:11], 1.0 op_sel_hi:[1,0]
	v_pk_add_f32 v[12:13], v[12:13], 1.0 op_sel_hi:[1,0]
	v_pk_add_f32 v[14:15], v[14:15], 1.0 op_sel_hi:[1,0]
	v_pk_add_f32 v[16:17], v[16:17], 1.0 op_sel_hi:[1,0]
	v_pk_add_f32 v[18:19], v[18:19], 1.0 op_sel_hi:[1,0]
	v_pk_add_f32 v[20:21], v[20:21], 1.0 op_sel_hi:[1,0]
	v_pk_add_f32 v[22:23], v[22:23], 1.0 op_sel_hi:[1,0]
	v_pk_add_f32 v[24:25], v[24:25], 1.0 op_sel_hi:[1,0]
	v_pk_add_f32 v[26:27], v[26:27], 1.0 op_sel_hi:[1,0]
	v_pk_add_f32 v[28:29], v[28:29], 1.0 op_sel_hi:[1,0]
	v_pk_add_f32 v[30:31], v[30:31], 1.0 op_sel_hi:[1,0]
	v_rcp_f32_e32 v0, v0
	v_rcp_f32_e32 v1, v1
	v_rcp_f32_e32 v2, v2
	v_rcp_f32_e32 v3, v3
	v_rcp_f32_e32 v4, v4
	v_rcp_f32_e32 v5, v5
	v_rcp_f32_e32 v6, v6
	v_rcp_f32_e32 v7, v7
	v_rcp_f32_e32 v8, v8
	v_rcp_f32_e32 v9, v9
	v_rcp_f32_e32 v10, v10
	v_rcp_f32_e32 v11, v11
	v_rcp_f32_e32 v12, v12
	v_rcp_f32_e32 v13, v13
	v_rcp_f32_e32 v14, v14
	v_rcp_f32_e32 v15, v15
	v_rcp_f32_e32 v16, v16
	v_rcp_f32_e32 v17, v17
	v_rcp_f32_e32 v18, v18
	v_rcp_f32_e32 v19, v19
	v_rcp_f32_e32 v20, v20
	v_rcp_f32_e32 v21, v21
	v_rcp_f32_e32 v22, v22
	v_rcp_f32_e32 v23, v23
	v_rcp_f32_e32 v24, v24
	v_rcp_f32_e32 v25, v25
	v_rcp_f32_e32 v26, v26
	v_rcp_f32_e32 v27, v27
	v_rcp_f32_e32 v28, v28
	v_rcp_f32_e32 v29, v29
	v_rcp_f32_e32 v30, v30
	v_rcp_f32_e32 v31, v31
	v_pk_mul_f32 v[0:1], v[246:247], v[0:1]
	v_pk_mul_f32 v[2:3], v[246:247], v[2:3]
	v_pk_mul_f32 v[4:5], v[246:247], v[4:5]
	v_pk_mul_f32 v[6:7], v[246:247], v[6:7]
	v_pk_mul_f32 v[8:9], v[246:247], v[8:9]
	v_pk_mul_f32 v[10:11], v[246:247], v[10:11]
	v_pk_mul_f32 v[12:13], v[246:247], v[12:13]
	v_pk_mul_f32 v[14:15], v[246:247], v[14:15]
	v_lshlrev_b32_e32 v48, 16, v48
	v_lshlrev_b32_e32 v49, 16, v49
	v_lshlrev_b32_e32 v50, 16, v50
	v_lshlrev_b32_e32 v51, 16, v51
	v_lshlrev_b32_e32 v52, 16, v52
	v_lshlrev_b32_e32 v53, 16, v53
	v_lshlrev_b32_e32 v54, 16, v54
	v_lshlrev_b32_e32 v55, 16, v55
	v_lshlrev_b32_e32 v56, 16, v56
	v_lshlrev_b32_e32 v57, 16, v57
	v_lshlrev_b32_e32 v58, 16, v58
	v_lshlrev_b32_e32 v59, 16, v59
	v_lshlrev_b32_e32 v60, 16, v60
	v_lshlrev_b32_e32 v61, 16, v61
	v_lshlrev_b32_e32 v62, 16, v62
	v_lshlrev_b32_e32 v63, 16, v63
	v_exp_f32_e32 v0, v0
	v_exp_f32_e32 v1, v1
	v_exp_f32_e32 v2, v2
	v_exp_f32_e32 v3, v3
	v_exp_f32_e32 v4, v4
	v_exp_f32_e32 v5, v5
	v_exp_f32_e32 v6, v6
	v_exp_f32_e32 v7, v7
	v_exp_f32_e32 v8, v8
	v_exp_f32_e32 v9, v9
	v_exp_f32_e32 v10, v10
	v_exp_f32_e32 v11, v11
	v_exp_f32_e32 v12, v12
	v_exp_f32_e32 v13, v13
	v_exp_f32_e32 v14, v14
	v_exp_f32_e32 v15, v15
	v_fma_f32 v32, -v0, v0, 1.0 clamp
	v_fma_f32 v33, -v1, v1, 1.0 clamp
	v_fma_f32 v34, -v2, v2, 1.0 clamp
	v_fma_f32 v35, -v3, v3, 1.0 clamp
	v_fma_f32 v36, -v4, v4, 1.0 clamp
	v_fma_f32 v37, -v5, v5, 1.0 clamp
	v_fma_f32 v38, -v6, v6, 1.0 clamp
	v_fma_f32 v39, -v7, v7, 1.0 clamp
	v_fma_f32 v40, -v8, v8, 1.0 clamp
	v_fma_f32 v41, -v9, v9, 1.0 clamp
	v_fma_f32 v42, -v10, v10, 1.0 clamp
	v_fma_f32 v43, -v11, v11, 1.0 clamp
	v_fma_f32 v44, -v12, v12, 1.0 clamp
	v_fma_f32 v45, -v13, v13, 1.0 clamp
	v_fma_f32 v46, -v14, v14, 1.0 clamp
	v_fma_f32 v47, -v15, v15, 1.0 clamp
	v_sqrt_f32_e32 v32, v32
	v_sqrt_f32_e32 v33, v33
	v_sqrt_f32_e32 v34, v34
	v_sqrt_f32_e32 v35, v35
; __device__ __forceinline__ unsigned f2bf(float f) { unsigned r; asm("v_cvt_pk_bf16_f32 %0, %1, %1" : "=v"(r) : "v"(f)); return r & 0xffffu; }
; template <bool FINAL, int D>
; __device__ __forceinline__ void rg_dir(PREF p, int l, int h, int ch, int sidx, int rowbase  , LAS bf16_t* sXc, LAS float* stg, int lane) {
;     ...
; #pragma unroll
;         for (int ti = 0; ti < 16; ++ti) { const int tk = D ? 15 - ti : ti;
;             hc = av[ti] * hc + iv[ti]; Ap *= av[ti];
;             if (FINAL) { const size_t row = (size_t)(rowbase + mt * 16 + tk);
;                 if (D == 0) TMP[row * 512 + ch] = (bf16_t)f2bf(hc);
;                 else MIX[row * DM + ch] = (bf16_t)f2bf(grv[ti] * (hfv[ti] + hc)); }
;         }
; __global__ void __launch_bounds__(NTHREADS, 2) mega_fwd(Params p_arg) {
;     ...
;             for (int item = gw; item < nrg; item += NGW) rg_item<true>(p, l, item, lds + wave * 18432, lane);
	v_sqrt_f32_e32 v36, v36
	v_sqrt_f32_e32 v37, v37
	v_sqrt_f32_e32 v38, v38
	v_sqrt_f32_e32 v39, v39
	v_sqrt_f32_e32 v40, v40
	v_sqrt_f32_e32 v41, v41
	v_sqrt_f32_e32 v42, v42
	v_sqrt_f32_e32 v43, v43
	v_sqrt_f32_e32 v44, v44
	v_sqrt_f32_e32 v45, v45
	v_sqrt_f32_e32 v46, v46
	v_sqrt_f32_e32 v47, v47
	s_nop 0
	v_pk_mul_f32 v[16:17], v[16:17], v[32:33]
	v_pk_mul_f32 v[18:19], v[18:19], v[34:35]
	v_pk_mul_f32 v[20:21], v[20:21], v[36:37]
	v_pk_mul_f32 v[22:23], v[22:23], v[38:39]
	v_pk_mul_f32 v[24:25], v[24:25], v[40:41]
	v_pk_mul_f32 v[26:27], v[26:27], v[42:43]
	v_pk_mul_f32 v[28:29], v[28:29], v[44:45]
	v_pk_mul_f32 v[30:31], v[30:31], v[46:47]
	v_pk_mul_f32 v[16:17], v[16:17], v[48:49]
	v_pk_mul_f32 v[18:19], v[18:19], v[50:51]
	v_pk_mul_f32 v[20:21], v[20:21], v[52:53]
	v_pk_mul_f32 v[22:23], v[22:23], v[54:55]
	v_pk_mul_f32 v[24:25], v[24:25], v[56:57]
	v_pk_mul_f32 v[26:27], v[26:27], v[58:59]
	v_pk_mul_f32 v[28:29], v[28:29], v[60:61]
	v_pk_mul_f32 v[30:31], v[30:31], v[62:63]
	s_add_i32 s39, s15, 15
	s_lshl_b32 s39, s39, 11
	s_add_u32 s90, s0, 0x7b00000
	s_addc_u32 s91, s1, 0
	s_add_u32 s90, s90, s39
	s_addc_u32 s91, s91, 0
	v_lshlrev_b32_e32 v48, 16, v158
	v_and_b32_e32 v49, 0xffff0000, v158
	v_lshlrev_b32_e32 v50, 16, v159
	v_and_b32_e32 v51, 0xffff0000, v159
	v_lshlrev_b32_e32 v52, 16, v160
	v_and_b32_e32 v53, 0xffff0000, v160
	v_lshlrev_b32_e32 v54, 16, v161
	v_and_b32_e32 v55, 0xffff0000, v161
	v_lshlrev_b32_e32 v56, 16, v162
	v_and_b32_e32 v57, 0xffff0000, v162
	v_lshlrev_b32_e32 v58, 16, v163
	v_and_b32_e32 v59, 0xffff0000, v163
	v_lshlrev_b32_e32 v60, 16, v164
	v_and_b32_e32 v61, 0xffff0000, v164
	v_lshlrev_b32_e32 v62, 16, v165
	v_and_b32_e32 v63, 0xffff0000, v165
	v_fma_f32 v47, v15, v250, v31
	v_fma_f32 v46, v14, v47, v30
	v_fma_f32 v45, v13, v46, v29
	v_fma_f32 v44, v12, v45, v28
	v_fma_f32 v43, v11, v44, v27
	v_fma_f32 v42, v10, v43, v26
	v_fma_f32 v41, v9, v42, v25
	v_fma_f32 v40, v8, v41, v24
	v_fma_f32 v39, v7, v40, v23
	v_fma_f32 v38, v6, v39, v22
	v_fma_f32 v37, v5, v38, v21
	v_fma_f32 v36, v4, v37, v20
	v_fma_f32 v35, v3, v36, v19
	v_fma_f32 v34, v2, v35, v18
	v_fma_f32 v33, v1, v34, v17
	v_fma_f32 v32, v0, v33, v16
	v_mov_b32_e32 v250, v32
	v_pk_add_f32 v[48:49], v[48:49], v[32:33]
	v_pk_add_f32 v[50:51], v[50:51], v[34:35]
	v_pk_add_f32 v[52:53], v[52:53], v[36:37]
	v_pk_add_f32 v[54:55], v[54:55], v[38:39]
	v_pk_add_f32 v[56:57], v[56:57], v[40:41]
	v_pk_add_f32 v[58:59], v[58:59], v[42:43]
	v_pk_add_f32 v[60:61], v[60:61], v[44:45]
	v_pk_add_f32 v[62:63], v[62:63], v[46:47]
	v_pk_mul_f32 v[48:49], v[206:207], v[48:49]
	v_pk_mul_f32 v[50:51], v[208:209], v[50:51]
	v_pk_mul_f32 v[52:53], v[210:211], v[52:53]
	v_pk_mul_f32 v[54:55], v[212:213], v[54:55]
	v_pk_mul_f32 v[56:57], v[214:215], v[56:57]
	v_pk_mul_f32 v[58:59], v[216:217], v[58:59]
	v_pk_mul_f32 v[60:61], v[218:219], v[60:61]
	v_pk_mul_f32 v[62:63], v[222:223], v[62:63]
	v_cvt_pk_bf16_f32 v48, v48, v48
	v_cvt_pk_bf16_f32 v49, v49, v49
	v_cvt_pk_bf16_f32 v50, v50, v50
	v_cvt_pk_bf16_f32 v51, v51, v51
	v_cvt_pk_bf16_f32 v52, v52, v52
	v_cvt_pk_bf16_f32 v53, v53, v53
	v_cvt_pk_bf16_f32 v54, v54, v54
	v_cvt_pk_bf16_f32 v55, v55, v55
	v_cvt_pk_bf16_f32 v56, v56, v56
	v_cvt_pk_bf16_f32 v57, v57, v57
	v_cvt_pk_bf16_f32 v58, v58, v58
	v_cvt_pk_bf16_f32 v59, v59, v59
	v_cvt_pk_bf16_f32 v60, v60, v60
	v_cvt_pk_bf16_f32 v61, v61, v61
	v_cvt_pk_bf16_f32 v62, v62, v62
	v_cvt_pk_bf16_f32 v63, v63, v63
	global_store_short v234, v63, s[90:91]
	s_sub_u32 s90, s90, 0x800
	s_subb_u32 s91, s91, 0
	global_store_short v234, v62, s[90:91]
	s_sub_u32 s90, s90, 0x800
	s_subb_u32 s91, s91, 0
	global_store_short v234, v61, s[90:91]
	s_sub_u32 s90, s90, 0x800
	s_subb_u32 s91, s91, 0
	global_store_short v234, v60, s[90:91]
	s_sub_u32 s90, s90, 0x800
	s_subb_u32 s91, s91, 0
	global_store_short v234, v59, s[90:91]
	s_sub_u32 s90, s90, 0x800
	s_subb_u32 s91, s91, 0
	global_store_short v234, v58, s[90:91]
	s_sub_u32 s90, s90, 0x800
	s_subb_u32 s91, s91, 0
	global_store_short v234, v57, s[90:91]
	s_sub_u32 s90, s90, 0x800
	s_subb_u32 s91, s91, 0
	global_store_short v234, v56, s[90:91]
	s_sub_u32 s90, s90, 0x800
	s_subb_u32 s91, s91, 0
	global_store_short v234, v55, s[90:91]
	s_sub_u32 s90, s90, 0x800
	s_subb_u32 s91, s91, 0
	global_store_short v234, v54, s[90:91]
	s_sub_u32 s90, s90, 0x800
	s_subb_u32 s91, s91, 0
	global_store_short v234, v53, s[90:91]
	s_sub_u32 s90, s90, 0x800
	s_subb_u32 s91, s91, 0
	global_store_short v234, v52, s[90:91]
	s_sub_u32 s90, s90, 0x800
	s_subb_u32 s91, s91, 0
	global_store_short v234, v51, s[90:91]
	s_sub_u32 s90, s90, 0x800
	s_subb_u32 s91, s91, 0
	global_store_short v234, v50, s[90:91]
	s_sub_u32 s90, s90, 0x800
	s_subb_u32 s91, s91, 0
	global_store_short v234, v49, s[90:91]
	s_sub_u32 s90, s90, 0x800
	s_subb_u32 s91, s91, 0
	global_store_short v234, v48, s[90:91]
	s_waitcnt lgkmcnt(0)
	v_readlane_b32 s84, v253, 29
	s_add_i32 s12, s12, s84
	s_cmpk_lt_i32 s12, 0x1000
	s_cbranch_scc1 .Lrg7_keep
	s_sub_i32 s0, s12, 0x1000
	s_lshr_b32 s1, s0, 5
	s_and_b32 s0, s0, 31
	s_and_b32 s12, s1, 7
	s_add_i32 s1, s1, 0x1000
	s_cmp_eq_u32 s0, s12
	s_cselect_b32 s12, s1, 0x2000

; #define LAS __attribute__((address_space(3)))
; template <bool FINAL>
; __device__ __forceinline__ void rg_item(PREF p, int l, int item, LAS unsigned char* wl, int lane) {
;     ...
;     const int h = item & 7, rest = item >> 3;
;     const int ci = rest < 512 ? 4 + (rest & 255) : ((rest - 512) & 3), b = rest < 512 ? (rest >> 8) : ((rest - 512) >> 2);
;     const int seq_row0 = ci < 4 ? TL + b * 256 : b * 16384;
;     const int t0 = ci < 4 ? ci * 64 : (ci - 4) * 64;
;     const int seqlen = ci < 4 ? 256 : 16384;
;     const int ch = h * 64 + lane;
;     LAS bf16_t* sXc = (LAS bf16_t*)wl;
;     LAS float* stg = (LAS float*)(wl + 9216);
;     {
;         const float cw0 = p.conv_w[(l * 4 + 0) * 512 + ch], cw1 = p.conv_w[(l * 4 + 1) * 512 + ch], cw2 = p.conv_w[(l * 4 + 2) * 512 + ch], cw3 = p.conv_w[(l * 4 + 3) * 512 + ch];
;         const float cb = p.conv_b[l * 512 + ch];
;         float xv[67]; unsigned xr_[67];
; #pragma unroll
;         for (int i = 0; i < 67; ++i) { const int t = t0 - 2 + i; const int tc = t < 0 ? 0 : (t >= seqlen ? seqlen - 1 : t);
;             xr_[i] = P[(size_t)(seq_row0 + tc) * PW + ch]; }
.Lrg5_dec:
	s_add_i32 s15, s11, s10
	s_mul_i32 s36, s9, 0x104
	s_add_i32 s36, s36, s8
	s_lshl_b32 s36, s36, 12
	s_cmp_eq_u32 s10, 0
	s_cselect_b32 s37, 0, -1
	s_add_i32 s38, s10, 64
	s_cmp_eq_u32 s38, s14
	s_cselect_b32 s38, 0, -1
	s_bfe_u32 s44, s44, 0x30006
	s_mul_i32 s44, s44, 0x4800
	v_lshl_or_b32 v234, s7, 6, v233
	v_lshlrev_b32_e32 v235, 2, v234
	v_lshlrev_b32_e32 v234, 1, v234
	v_and_b32_e32 v236, 15, v233
	v_lshrrev_b32_e32 v241, 4, v233
	s_movk_i32 s39, 0x90
	v_mul_u32_u24_e32 v237, 0x90, v236
	v_lshl_add_u32 v237, v241, 4, v237
	v_lshlrev_b32_e32 v238, 7, v236
	v_lshl_add_u32 v238, v241, 4, v238
	v_lshlrev_b32_e32 v239, 10, v241
	v_lshl_add_u32 v239, v236, 2, v239
	v_mov_b32_e32 v241, v238
	v_add_u32_e32 v236, s44, v237
	s_add_i32 s39, s44, 0x2400
	v_add_u32_e32 v237, s39, v239
	v_add_u32_e32 v238, 0x1000, v237
	v_lshl_add_u32 v239, v233, 2, s44
	v_lshl_add_u32 v240, v233, 1, s44
	s_add_i32 s39, s15, -2
	s_mul_hi_i32 s83, s39, 0x1600
	s_mul_i32 s82, s39, 0x1600
	s_waitcnt lgkmcnt(0)
	s_add_u32 s82, s82, s0
	s_addc_u32 s83, s83, s1
	s_add_u32 s82, s82, 0xbc00000
	s_addc_u32 s83, s83, 0
	global_load_ushort v158, v234, s[82:83]
	s_add_u32 s82, s82, 0x1600
	s_addc_u32 s83, s83, 0
	global_load_ushort v159, v234, s[82:83]
	s_add_u32 s82, s82, 0x1600
	s_addc_u32 s83, s83, 0
	global_load_ushort v160, v234, s[82:83]
	s_add_u32 s82, s82, 0x1600
	s_addc_u32 s83, s83, 0
	global_load_ushort v161, v234, s[82:83]
	s_add_u32 s82, s82, 0x1600
	s_addc_u32 s83, s83, 0
	global_load_ushort v162, v234, s[82:83]
	s_add_u32 s82, s82, 0x1600
	s_addc_u32 s83, s83, 0
	global_load_ushort v163, v234, s[82:83]
	s_add_u32 s82, s82, 0x1600
	s_addc_u32 s83, s83, 0
	global_load_ushort v164, v234, s[82:83]
	s_add_u32 s82, s82, 0x1600
	s_addc_u32 s83, s83, 0
	global_load_ushort v165, v234, s[82:83]
	s_add_u32 s82, s82, 0x1600
	s_addc_u32 s83, s83, 0
	global_load_ushort v166, v234, s[82:83]
	s_add_u32 s82, s82, 0x1600
	s_addc_u32 s83, s83, 0
	global_load_ushort v167, v234, s[82:83]
	s_add_u32 s82, s82, 0x1600
	s_addc_u32 s83, s83, 0
	global_load_ushort v168, v234, s[82:83]
	s_add_u32 s82, s82, 0x1600
	s_addc_u32 s83, s83, 0
	global_load_ushort v169, v234, s[82:83]
	s_add_u32 s82, s82, 0x1600
	s_addc_u32 s83, s83, 0
	global_load_ushort v170, v234, s[82:83]
	s_add_u32 s82, s82, 0x1600
	s_addc_u32 s83, s83, 0
	global_load_ushort v171, v234, s[82:83]
	s_add_u32 s82, s82, 0x1600
	s_addc_u32 s83, s83, 0
	global_load_ushort v172, v234, s[82:83]
	s_add_u32 s82, s82, 0x1600
	s_addc_u32 s83, s83, 0
	global_load_ushort v173, v234, s[82:83]
	s_add_u32 s82, s82, 0x1600
	s_addc_u32 s83, s83, 0
	global_load_ushort v174, v234, s[82:83]
	s_add_u32 s82, s82, 0x1600
	s_addc_u32 s83, s83, 0
	global_load_ushort v175, v234, s[82:83]
	s_add_u32 s82, s82, 0x1600
	s_addc_u32 s83, s83, 0
	global_load_ushort v176, v234, s[82:83]
	s_add_u32 s82, s82, 0x1600
	s_addc_u32 s83, s83, 0
	global_load_ushort v177, v234, s[82:83]
	s_add_u32 s82, s82, 0x1600
	s_addc_u32 s83, s83, 0
	global_load_ushort v178, v234, s[82:83]
	s_add_u32 s82, s82, 0x1600
	s_addc_u32 s83, s83, 0
	global_load_ushort v179, v234, s[82:83]
	s_add_u32 s82, s82, 0x1600
	s_addc_u32 s83, s83, 0
	global_load_ushort v180, v234, s[82:83]
	s_add_u32 s82, s82, 0x1600
	s_addc_u32 s83, s83, 0
	global_load_ushort v181, v234, s[82:83]
	s_add_u32 s82, s82, 0x1600
	s_addc_u32 s83, s83, 0
	global_load_ushort v182, v234, s[82:83]
	s_add_u32 s82, s82, 0x1600
	s_addc_u32 s83, s83, 0
	global_load_ushort v183, v234, s[82:83]
	s_add_u32 s82, s82, 0x1600
	s_addc_u32 s83, s83, 0
	global_load_ushort v184, v234, s[82:83]
	s_add_u32 s82, s82, 0x1600
	s_addc_u32 s83, s83, 0
	global_load_ushort v185, v234, s[82:83]
	s_add_u32 s82, s82, 0x1600
	s_addc_u32 s83, s83, 0
	global_load_ushort v186, v234, s[82:83]
	s_add_u32 s82, s82, 0x1600
	s_addc_u32 s83, s83, 0
	global_load_ushort v187, v234, s[82:83]
	s_add_u32 s82, s82, 0x1600
	s_addc_u32 s83, s83, 0
	global_load_ushort v188, v234, s[82:83]
	s_add_u32 s82, s82, 0x1600
	s_addc_u32 s83, s83, 0
	global_load_ushort v189, v234, s[82:83]
	s_add_u32 s82, s82, 0x1600
	s_addc_u32 s83, s83, 0
	global_load_ushort v190, v234, s[82:83]
	s_add_u32 s82, s82, 0x1600
	s_addc_u32 s83, s83, 0
	global_load_ushort v191, v234, s[82:83]
	s_add_u32 s82, s82, 0x1600
	s_addc_u32 s83, s83, 0
	global_load_ushort v192, v234, s[82:83]
	s_add_u32 s82, s82, 0x1600
	s_addc_u32 s83, s83, 0
	global_load_ushort v193, v234, s[82:83]
	s_add_u32 s82, s82, 0x1600
	s_addc_u32 s83, s83, 0
	global_load_ushort v194, v234, s[82:83]
	s_add_u32 s82, s82, 0x1600
	s_addc_u32 s83, s83, 0
	global_load_ushort v195, v234, s[82:83]
	s_add_u32 s82, s82, 0x1600
	s_addc_u32 s83, s83, 0
	global_load_ushort v196, v234, s[82:83]
	s_add_u32 s82, s82, 0x1600
	s_addc_u32 s83, s83, 0
	global_load_ushort v197, v234, s[82:83]
	s_add_u32 s82, s82, 0x1600
	s_addc_u32 s83, s83, 0
	global_load_ushort v198, v234, s[82:83]
	s_add_u32 s82, s82, 0x1600
	s_addc_u32 s83, s83, 0
	global_load_ushort v199, v234, s[82:83]
	s_add_u32 s82, s82, 0x1600
	s_addc_u32 s83, s83, 0
	global_load_ushort v200, v234, s[82:83]
	s_add_u32 s82, s82, 0x1600
	s_addc_u32 s83, s83, 0
	global_load_ushort v201, v234, s[82:83]
	s_add_u32 s82, s82, 0x1600
	s_addc_u32 s83, s83, 0
	global_load_ushort v202, v234, s[82:83]
	s_add_u32 s82, s82, 0x1600
	s_addc_u32 s83, s83, 0
	global_load_ushort v203, v234, s[82:83]
	s_add_u32 s82, s82, 0x1600
	s_addc_u32 s83, s83, 0
	global_load_ushort v204, v234, s[82:83]
	s_add_u32 s82, s82, 0x1600
	s_addc_u32 s83, s83, 0
	global_load_ushort v205, v234, s[82:83]
	s_add_u32 s82, s82, 0x1600
	s_addc_u32 s83, s83, 0
	global_load_ushort v206, v234, s[82:83]
	s_add_u32 s82, s82, 0x1600
; __device__ __forceinline__ float rcpf_(float x) { return __builtin_amdgcn_rcpf(x); }
; template <bool FINAL, int D>
; __device__ __forceinline__ void rg_dir(PREF p, int l, int h, int ch, int sidx, int rowbase  , LAS bf16_t* sXc, LAS float* stg, int lane) {
;     ...
;     const bf16_t* wr_ = WgT + (size_t)(((l * 2 + D) * 2 + 0) * 8 + h) * 4096; const bf16_t* wi_ = WgT + (size_t)(((l * 2 + D) * 2 + 1) * 8 + h) * 4096;
;     const float ba = p.rg_ba[(l * 2 + D) * 512 + ch], bi = p.rg_bi[(l * 2 + D) * 512 + ch], lam = p.rg_lam[(l * 2 + D) * 512 + ch];
;     const float e_ = __expf(-lam), u_ = 1.f + e_;
;     const float l1p = (u_ == 1.f) ? e_ : __logf(u_) * e_ * rcpf_(u_ - 1.f);
;     const float sp8 = -8.f * 1.4426950408889634f * l1p;
;     float hc = FINAL ? RGC[sidx] : 0.f, Ap = 1.f;
;     bf16x8 Br[4][2], Bi[4][2];
; #pragma unroll
;     for (int nt = 0; nt < 4; ++nt) { const int o0 = (nt * 16 + (lane & 15)) * 64 + (lane >> 4) * 8;
;         Br[nt][0] = *(const bf16x8*)(wr_ + o0); Br[nt][1] = *(const bf16x8*)(wr_ + o0 + 32); Bi[nt][0] = *(const bf16x8*)(wi_ + o0); Bi[nt][1] = *(const bf16x8*)(wi_ + o0 + 32); }
; template <bool FINAL>
; __device__ __forceinline__ void rg_item(PREF p, int l, int item, LAS unsigned char* wl, int lane) {
;     ...
;         const float cw0 = p.conv_w[(l * 4 + 0) * 512 + ch], cw1 = p.conv_w[(l * 4 + 1) * 512 + ch], cw2 = p.conv_w[(l * 4 + 2) * 512 + ch], cw3 = p.conv_w[(l * 4 + 3) * 512 + ch];
;         const float cb = p.conv_b[l * 512 + ch];
;         float xv[67]; unsigned xr_[67];
; #pragma unroll
;         for (int i = 0; i < 67; ++i) { const int t = t0 - 2 + i; const int tc = t < 0 ? 0 : (t >= seqlen ? seqlen - 1 : t);
;             xr_[i] = P[(size_t)(seq_row0 + tc) * PW + ch]; }
;         __builtin_amdgcn_sched_barrier(0);
; #pragma unroll
;         for (int i = 0; i < 67; ++i) { const int t = t0 - 2 + i; const int tc = t < 0 ? 0 : (t >= seqlen ? seqlen - 1 : t); xv[i] = (t == tc) ? bf2f(xr_[i]) : 0.f; }
	s_addc_u32 s83, s83, 0
	global_load_ushort v207, v234, s[82:83]
	s_add_u32 s82, s82, 0x1600
	s_addc_u32 s83, s83, 0
	global_load_ushort v208, v234, s[82:83]
	s_add_u32 s82, s82, 0x1600
	s_addc_u32 s83, s83, 0
	global_load_ushort v209, v234, s[82:83]
	s_add_u32 s82, s82, 0x1600
	s_addc_u32 s83, s83, 0
	global_load_ushort v210, v234, s[82:83]
	s_add_u32 s82, s82, 0x1600
	s_addc_u32 s83, s83, 0
	global_load_ushort v211, v234, s[82:83]
	s_add_u32 s82, s82, 0x1600
	s_addc_u32 s83, s83, 0
	global_load_ushort v212, v234, s[82:83]
	s_add_u32 s82, s82, 0x1600
	s_addc_u32 s83, s83, 0
	global_load_ushort v213, v234, s[82:83]
	s_add_u32 s82, s82, 0x1600
	s_addc_u32 s83, s83, 0
	global_load_ushort v214, v234, s[82:83]
	s_add_u32 s82, s82, 0x1600
	s_addc_u32 s83, s83, 0
	global_load_ushort v215, v234, s[82:83]
	s_add_u32 s82, s82, 0x1600
	s_addc_u32 s83, s83, 0
	global_load_ushort v216, v234, s[82:83]
	s_add_u32 s82, s82, 0x1600
	s_addc_u32 s83, s83, 0
	global_load_ushort v217, v234, s[82:83]
	s_add_u32 s82, s82, 0x1600
	s_addc_u32 s83, s83, 0
	global_load_ushort v218, v234, s[82:83]
	s_add_u32 s82, s82, 0x1600
	s_addc_u32 s83, s83, 0
	global_load_ushort v219, v234, s[82:83]
	s_add_u32 s82, s82, 0x1600
	s_addc_u32 s83, s83, 0
	global_load_ushort v222, v234, s[82:83]
	s_add_u32 s82, s82, 0x1600
	s_addc_u32 s83, s83, 0
	global_load_ushort v223, v234, s[82:83]
	s_add_u32 s82, s82, 0x1600
	s_addc_u32 s83, s83, 0
	global_load_ushort v140, v234, s[82:83]
	s_add_u32 s82, s82, 0x1600
	s_addc_u32 s83, s83, 0
	global_load_ushort v141, v234, s[82:83]
	s_add_u32 s82, s82, 0x1600
	s_addc_u32 s83, s83, 0
	global_load_ushort v232, v234, s[82:83]
	s_lshl_b32 s39, s57, 13
	s_add_u32 s72, s72, s39
	s_addc_u32 s73, s73, 0
	global_load_dword v40, v235, s[72:73]
	global_load_dword v41, v235, s[72:73] offset:2048
	s_add_u32 s72, s72, 0x1000
	s_addc_u32 s73, s73, 0
	global_load_dword v42, v235, s[72:73]
	global_load_dword v43, v235, s[72:73] offset:2048
	s_lshl_b32 s39, s57, 11
	s_add_u32 s74, s74, s39
	s_addc_u32 s75, s75, 0
	global_load_dword v44, v235, s[74:75]
	s_lshl_b32 s39, s57, 12
	s_add_u32 s76, s76, s39
	s_addc_u32 s77, s77, 0
	s_add_u32 s78, s78, s39
	s_addc_u32 s79, s79, 0
	s_add_u32 s80, s80, s39
	s_addc_u32 s81, s81, 0
	s_lshl_b32 s39, s57, 5
	s_add_i32 s39, s39, s7
	s_lshl_b32 s39, s39, 13
	s_add_u32 s92, s0, 0x300000
	s_addc_u32 s93, s1, 0
	s_add_u32 s92, s92, s39
	s_addc_u32 s93, s93, 0
	global_load_dword v45, v235, s[76:77]
	global_load_dword v46, v235, s[78:79]
	global_load_dword v47, v235, s[80:81]
	s_add_u32 s90, s92, 0x0
	s_addc_u32 s91, s93, 0
	global_load_dwordx4 v[80:83], v241, s[90:91]
	global_load_dwordx4 v[84:87], v241, s[90:91] offset:64
	global_load_dwordx4 v[88:91], v241, s[90:91] offset:2048
	global_load_dwordx4 v[92:95], v241, s[90:91] offset:2112
	s_add_u32 s90, s92, 0x1000
	s_addc_u32 s91, s93, 0
	global_load_dwordx4 v[96:99], v241, s[90:91]
	global_load_dwordx4 v[100:103], v241, s[90:91] offset:64
	global_load_dwordx4 v[104:107], v241, s[90:91] offset:2048
	global_load_dwordx4 v[108:111], v241, s[90:91] offset:2112
	s_add_u32 s90, s92, 0x10000
	s_addc_u32 s91, s93, 0
	global_load_dwordx4 v[112:115], v241, s[90:91]
	global_load_dwordx4 v[148:151], v241, s[90:91] offset:64
	global_load_dwordx4 v[120:123], v241, s[90:91] offset:2048
	global_load_dwordx4 v[124:127], v241, s[90:91] offset:2112
	s_add_u32 s90, s92, 0x11000
	s_addc_u32 s91, s93, 0
	global_load_dwordx4 v[128:131], v241, s[90:91]
	global_load_dwordx4 v[132:135], v241, s[90:91] offset:64
	global_load_dwordx4 v[136:139], v241, s[90:91] offset:2048
	global_load_dwordx4 v[228:231], v241, s[90:91] offset:2112
	s_waitcnt vmcnt(19)
	v_lshlrev_b32_e32 v158, 16, v158
	v_lshlrev_b32_e32 v159, 16, v159
	v_lshlrev_b32_e32 v160, 16, v160
	v_lshlrev_b32_e32 v161, 16, v161
	v_lshlrev_b32_e32 v162, 16, v162
	v_lshlrev_b32_e32 v163, 16, v163
	v_lshlrev_b32_e32 v164, 16, v164
	v_lshlrev_b32_e32 v165, 16, v165
	v_lshlrev_b32_e32 v166, 16, v166
	v_lshlrev_b32_e32 v167, 16, v167
	v_lshlrev_b32_e32 v168, 16, v168
	v_lshlrev_b32_e32 v169, 16, v169
	v_lshlrev_b32_e32 v170, 16, v170
	v_lshlrev_b32_e32 v171, 16, v171
	v_lshlrev_b32_e32 v172, 16, v172
	v_lshlrev_b32_e32 v173, 16, v173
	v_lshlrev_b32_e32 v174, 16, v174
	v_lshlrev_b32_e32 v175, 16, v175
	v_lshlrev_b32_e32 v176, 16, v176
	v_lshlrev_b32_e32 v177, 16, v177
	v_lshlrev_b32_e32 v178, 16, v178
	v_lshlrev_b32_e32 v179, 16, v179
	v_lshlrev_b32_e32 v180, 16, v180
	v_lshlrev_b32_e32 v181, 16, v181
	v_lshlrev_b32_e32 v182, 16, v182
	v_lshlrev_b32_e32 v183, 16, v183
	v_lshlrev_b32_e32 v184, 16, v184
	v_lshlrev_b32_e32 v185, 16, v185
	v_lshlrev_b32_e32 v186, 16, v186
	v_lshlrev_b32_e32 v187, 16, v187
	v_lshlrev_b32_e32 v188, 16, v188
	v_lshlrev_b32_e32 v189, 16, v189
	v_lshlrev_b32_e32 v190, 16, v190
	v_lshlrev_b32_e32 v191, 16, v191
	v_lshlrev_b32_e32 v192, 16, v192
	v_lshlrev_b32_e32 v193, 16, v193
	v_lshlrev_b32_e32 v194, 16, v194
	v_lshlrev_b32_e32 v195, 16, v195
	v_lshlrev_b32_e32 v196, 16, v196
	v_lshlrev_b32_e32 v197, 16, v197
	v_lshlrev_b32_e32 v198, 16, v198
	v_lshlrev_b32_e32 v199, 16, v199
	v_lshlrev_b32_e32 v200, 16, v200
	v_lshlrev_b32_e32 v201, 16, v201
	v_lshlrev_b32_e32 v202, 16, v202
	v_lshlrev_b32_e32 v203, 16, v203
	v_lshlrev_b32_e32 v204, 16, v204
	v_lshlrev_b32_e32 v205, 16, v205
	v_lshlrev_b32_e32 v206, 16, v206
	v_lshlrev_b32_e32 v207, 16, v207
	v_lshlrev_b32_e32 v208, 16, v208
	v_lshlrev_b32_e32 v209, 16, v209
	v_lshlrev_b32_e32 v210, 16, v210
	v_lshlrev_b32_e32 v211, 16, v211
	v_lshlrev_b32_e32 v212, 16, v212
	v_lshlrev_b32_e32 v213, 16, v213
	v_lshlrev_b32_e32 v214, 16, v214
	v_lshlrev_b32_e32 v215, 16, v215
	v_lshlrev_b32_e32 v216, 16, v216
; __device__ __forceinline__ unsigned f2bf(float f) { unsigned r; asm("v_cvt_pk_bf16_f32 %0, %1, %1" : "=v"(r) : "v"(f)); return r & 0xffffu; }
; template <bool FINAL>
; __device__ __forceinline__ void rg_item(PREF p, int l, int item, LAS unsigned char* wl, int lane) {
;     ...
;         for (int i = 0; i < 67; ++i) { const int t = t0 - 2 + i; const int tc = t < 0 ? 0 : (t >= seqlen ? seqlen - 1 : t); xv[i] = (t == tc) ? bf2f(xr_[i]) : 0.f; }
; #pragma unroll
;         for (int tt = 0; tt < 64; ++tt) { const float xc = xv[tt] * cw0 + xv[tt + 1] * cw1 + xv[tt + 2] * cw2 + xv[tt + 3] * cw3 + cb; sXc[tt * 72 + lane] = (bf16_t)f2bf(xc); }
	v_lshlrev_b32_e32 v217, 16, v217
	v_lshlrev_b32_e32 v218, 16, v218
	v_lshlrev_b32_e32 v219, 16, v219
	v_lshlrev_b32_e32 v222, 16, v222
	v_lshlrev_b32_e32 v223, 16, v223
	v_lshlrev_b32_e32 v140, 16, v140
	v_lshlrev_b32_e32 v141, 16, v141
	v_lshlrev_b32_e32 v232, 16, v232
	v_and_b32_e32 v158, s37, v158
	v_and_b32_e32 v159, s37, v159
	v_and_b32_e32 v232, s38, v232
	v_mul_f32_e32 v32, v41, v159
	v_mul_f32_e32 v33, v41, v160
	v_mul_f32_e32 v34, v41, v161
	v_mul_f32_e32 v35, v41, v162
	v_mul_f32_e32 v36, v41, v163
	v_mul_f32_e32 v37, v41, v164
	v_mul_f32_e32 v38, v41, v165
	v_mul_f32_e32 v39, v41, v166
	v_fmac_f32_e32 v32, v40, v158
	v_fmac_f32_e32 v33, v40, v159
	v_fmac_f32_e32 v34, v40, v160
	v_fmac_f32_e32 v35, v40, v161
	v_fmac_f32_e32 v36, v40, v162
	v_fmac_f32_e32 v37, v40, v163
	v_fmac_f32_e32 v38, v40, v164
	v_fmac_f32_e32 v39, v40, v165
	v_fmac_f32_e32 v32, v42, v160
	v_fmac_f32_e32 v33, v42, v161
	v_fmac_f32_e32 v34, v42, v162
	v_fmac_f32_e32 v35, v42, v163
	v_fmac_f32_e32 v36, v42, v164
	v_fmac_f32_e32 v37, v42, v165
	v_fmac_f32_e32 v38, v42, v166
	v_fmac_f32_e32 v39, v42, v167
	v_fmac_f32_e32 v32, v43, v161
	v_fmac_f32_e32 v33, v43, v162
	v_fmac_f32_e32 v34, v43, v163
	v_fmac_f32_e32 v35, v43, v164
	v_fmac_f32_e32 v36, v43, v165
	v_fmac_f32_e32 v37, v43, v166
	v_fmac_f32_e32 v38, v43, v167
	v_fmac_f32_e32 v39, v43, v168
	v_add_f32_e32 v32, v44, v32
	v_add_f32_e32 v33, v44, v33
	v_add_f32_e32 v34, v44, v34
	v_add_f32_e32 v35, v44, v35
	v_add_f32_e32 v36, v44, v36
	v_add_f32_e32 v37, v44, v37
	v_add_f32_e32 v38, v44, v38
	v_add_f32_e32 v39, v44, v39
	v_cvt_pk_bf16_f32 v32, v32, v33
	v_cvt_pk_bf16_f32 v34, v34, v35
	v_cvt_pk_bf16_f32 v36, v36, v37
	v_cvt_pk_bf16_f32 v38, v38, v39
	ds_write_b16 v240, v32 offset:0
	ds_write_b16_d16_hi v240, v32 offset:144
	ds_write_b16 v240, v34 offset:288
	ds_write_b16_d16_hi v240, v34 offset:432
	ds_write_b16 v240, v36 offset:576
	ds_write_b16_d16_hi v240, v36 offset:720
	ds_write_b16 v240, v38 offset:864
	ds_write_b16_d16_hi v240, v38 offset:1008
	v_mul_f32_e32 v32, v41, v167
	v_mul_f32_e32 v33, v41, v168
	v_mul_f32_e32 v34, v41, v169
	v_mul_f32_e32 v35, v41, v170
	v_mul_f32_e32 v36, v41, v171
	v_mul_f32_e32 v37, v41, v172
	v_mul_f32_e32 v38, v41, v173
	v_mul_f32_e32 v39, v41, v174
	v_fmac_f32_e32 v32, v40, v166
	v_fmac_f32_e32 v33, v40, v167
	v_fmac_f32_e32 v34, v40, v168
	v_fmac_f32_e32 v35, v40, v169
	v_fmac_f32_e32 v36, v40, v170
	v_fmac_f32_e32 v37, v40, v171
	v_fmac_f32_e32 v38, v40, v172
	v_fmac_f32_e32 v39, v40, v173
	v_fmac_f32_e32 v32, v42, v168
	v_fmac_f32_e32 v33, v42, v169
	v_fmac_f32_e32 v34, v42, v170
	v_fmac_f32_e32 v35, v42, v171
	v_fmac_f32_e32 v36, v42, v172
	v_fmac_f32_e32 v37, v42, v173
	v_fmac_f32_e32 v38, v42, v174
	v_fmac_f32_e32 v39, v42, v175
	v_fmac_f32_e32 v32, v43, v169
	v_fmac_f32_e32 v33, v43, v170
	v_fmac_f32_e32 v34, v43, v171
	v_fmac_f32_e32 v35, v43, v172
	v_fmac_f32_e32 v36, v43, v173
	v_fmac_f32_e32 v37, v43, v174
	v_fmac_f32_e32 v38, v43, v175
	v_fmac_f32_e32 v39, v43, v176
	v_add_f32_e32 v32, v44, v32
	v_add_f32_e32 v33, v44, v33
	v_add_f32_e32 v34, v44, v34
	v_add_f32_e32 v35, v44, v35
	v_add_f32_e32 v36, v44, v36
	v_add_f32_e32 v37, v44, v37
	v_add_f32_e32 v38, v44, v38
	v_add_f32_e32 v39, v44, v39
	v_cvt_pk_bf16_f32 v32, v32, v33
	v_cvt_pk_bf16_f32 v34, v34, v35
	v_cvt_pk_bf16_f32 v36, v36, v37
	v_cvt_pk_bf16_f32 v38, v38, v39
	ds_write_b16 v240, v32 offset:1152
	ds_write_b16_d16_hi v240, v32 offset:1296
	ds_write_b16 v240, v34 offset:1440
	ds_write_b16_d16_hi v240, v34 offset:1584
	ds_write_b16 v240, v36 offset:1728
	ds_write_b16_d16_hi v240, v36 offset:1872
	ds_write_b16 v240, v38 offset:2016
	ds_write_b16_d16_hi v240, v38 offset:2160
	v_mul_f32_e32 v32, v41, v175
	v_mul_f32_e32 v33, v41, v176
	v_mul_f32_e32 v34, v41, v177
	v_mul_f32_e32 v35, v41, v178
	v_mul_f32_e32 v36, v41, v179
	v_mul_f32_e32 v37, v41, v180
	v_mul_f32_e32 v38, v41, v181
	v_mul_f32_e32 v39, v41, v182
	v_fmac_f32_e32 v32, v40, v174
	v_fmac_f32_e32 v33, v40, v175
	v_fmac_f32_e32 v34, v40, v176
	v_fmac_f32_e32 v35, v40, v177
	v_fmac_f32_e32 v36, v40, v178
	v_fmac_f32_e32 v37, v40, v179
	v_fmac_f32_e32 v38, v40, v180
	v_fmac_f32_e32 v39, v40, v181
	v_fmac_f32_e32 v32, v42, v176
	v_fmac_f32_e32 v33, v42, v177
	v_fmac_f32_e32 v34, v42, v178
	v_fmac_f32_e32 v35, v42, v179
	v_fmac_f32_e32 v36, v42, v180
	v_fmac_f32_e32 v37, v42, v181
	v_fmac_f32_e32 v38, v42, v182
	v_fmac_f32_e32 v39, v42, v183
	v_fmac_f32_e32 v32, v43, v177
	v_fmac_f32_e32 v33, v43, v178
	v_fmac_f32_e32 v34, v43, v179
	v_fmac_f32_e32 v35, v43, v180
	v_fmac_f32_e32 v36, v43, v181
	v_fmac_f32_e32 v37, v43, v182
	v_fmac_f32_e32 v38, v43, v183
	v_fmac_f32_e32 v39, v43, v184
	v_add_f32_e32 v32, v44, v32
	v_add_f32_e32 v33, v44, v33
	v_add_f32_e32 v34, v44, v34
	v_add_f32_e32 v35, v44, v35
	v_add_f32_e32 v36, v44, v36
	v_add_f32_e32 v37, v44, v37
	v_add_f32_e32 v38, v44, v38
	v_add_f32_e32 v39, v44, v39
	v_cvt_pk_bf16_f32 v32, v32, v33
	v_cvt_pk_bf16_f32 v34, v34, v35
	v_cvt_pk_bf16_f32 v36, v36, v37
	v_cvt_pk_bf16_f32 v38, v38, v39
	ds_write_b16 v240, v32 offset:2304
	ds_write_b16_d16_hi v240, v32 offset:2448
	ds_write_b16 v240, v34 offset:2592
	ds_write_b16_d16_hi v240, v34 offset:2736
	ds_write_b16 v240, v36 offset:2880
	ds_write_b16_d16_hi v240, v36 offset:3024
	ds_write_b16 v240, v38 offset:3168
	ds_write_b16_d16_hi v240, v38 offset:3312
	v_mul_f32_e32 v32, v41, v183
	v_mul_f32_e32 v33, v41, v184
	v_mul_f32_e32 v34, v41, v185
	v_mul_f32_e32 v35, v41, v186
	v_mul_f32_e32 v36, v41, v187
	v_mul_f32_e32 v37, v41, v188
	v_mul_f32_e32 v38, v41, v189
	v_mul_f32_e32 v39, v41, v190
	v_fmac_f32_e32 v32, v40, v182
	v_fmac_f32_e32 v33, v40, v183
; __device__ __forceinline__ unsigned f2bf(float f) { unsigned r; asm("v_cvt_pk_bf16_f32 %0, %1, %1" : "=v"(r) : "v"(f)); return r & 0xffffu; }
; template <bool FINAL>
; __device__ __forceinline__ void rg_item(PREF p, int l, int item, LAS unsigned char* wl, int lane) {
;     ...
;         for (int i = 0; i < 67; ++i) { const int t = t0 - 2 + i; const int tc = t < 0 ? 0 : (t >= seqlen ? seqlen - 1 : t); xv[i] = (t == tc) ? bf2f(xr_[i]) : 0.f; }
; #pragma unroll
;         for (int tt = 0; tt < 64; ++tt) { const float xc = xv[tt] * cw0 + xv[tt + 1] * cw1 + xv[tt + 2] * cw2 + xv[tt + 3] * cw3 + cb; sXc[tt * 72 + lane] = (bf16_t)f2bf(xc); }
	v_fmac_f32_e32 v34, v40, v184
	v_fmac_f32_e32 v35, v40, v185
	v_fmac_f32_e32 v36, v40, v186
	v_fmac_f32_e32 v37, v40, v187
	v_fmac_f32_e32 v38, v40, v188
	v_fmac_f32_e32 v39, v40, v189
	v_fmac_f32_e32 v32, v42, v184
	v_fmac_f32_e32 v33, v42, v185
	v_fmac_f32_e32 v34, v42, v186
	v_fmac_f32_e32 v35, v42, v187
	v_fmac_f32_e32 v36, v42, v188
	v_fmac_f32_e32 v37, v42, v189
	v_fmac_f32_e32 v38, v42, v190
	v_fmac_f32_e32 v39, v42, v191
	v_fmac_f32_e32 v32, v43, v185
	v_fmac_f32_e32 v33, v43, v186
	v_fmac_f32_e32 v34, v43, v187
	v_fmac_f32_e32 v35, v43, v188
	v_fmac_f32_e32 v36, v43, v189
	v_fmac_f32_e32 v37, v43, v190
	v_fmac_f32_e32 v38, v43, v191
	v_fmac_f32_e32 v39, v43, v192
	v_add_f32_e32 v32, v44, v32
	v_add_f32_e32 v33, v44, v33
	v_add_f32_e32 v34, v44, v34
	v_add_f32_e32 v35, v44, v35
	v_add_f32_e32 v36, v44, v36
	v_add_f32_e32 v37, v44, v37
	v_add_f32_e32 v38, v44, v38
	v_add_f32_e32 v39, v44, v39
	v_cvt_pk_bf16_f32 v32, v32, v33
	v_cvt_pk_bf16_f32 v34, v34, v35
	v_cvt_pk_bf16_f32 v36, v36, v37
	v_cvt_pk_bf16_f32 v38, v38, v39
	ds_write_b16 v240, v32 offset:3456
	ds_write_b16_d16_hi v240, v32 offset:3600
	ds_write_b16 v240, v34 offset:3744
	ds_write_b16_d16_hi v240, v34 offset:3888
	ds_write_b16 v240, v36 offset:4032
	ds_write_b16_d16_hi v240, v36 offset:4176
	ds_write_b16 v240, v38 offset:4320
	ds_write_b16_d16_hi v240, v38 offset:4464
	v_mul_f32_e32 v32, v41, v191
	v_mul_f32_e32 v33, v41, v192
	v_mul_f32_e32 v34, v41, v193
	v_mul_f32_e32 v35, v41, v194
	v_mul_f32_e32 v36, v41, v195
	v_mul_f32_e32 v37, v41, v196
	v_mul_f32_e32 v38, v41, v197
	v_mul_f32_e32 v39, v41, v198
	v_fmac_f32_e32 v32, v40, v190
	v_fmac_f32_e32 v33, v40, v191
	v_fmac_f32_e32 v34, v40, v192
	v_fmac_f32_e32 v35, v40, v193
	v_fmac_f32_e32 v36, v40, v194
	v_fmac_f32_e32 v37, v40, v195
	v_fmac_f32_e32 v38, v40, v196
	v_fmac_f32_e32 v39, v40, v197
	v_fmac_f32_e32 v32, v42, v192
	v_fmac_f32_e32 v33, v42, v193
	v_fmac_f32_e32 v34, v42, v194
	v_fmac_f32_e32 v35, v42, v195
	v_fmac_f32_e32 v36, v42, v196
	v_fmac_f32_e32 v37, v42, v197
	v_fmac_f32_e32 v38, v42, v198
	v_fmac_f32_e32 v39, v42, v199
	v_fmac_f32_e32 v32, v43, v193
	v_fmac_f32_e32 v33, v43, v194
	v_fmac_f32_e32 v34, v43, v195
	v_fmac_f32_e32 v35, v43, v196
	v_fmac_f32_e32 v36, v43, v197
	v_fmac_f32_e32 v37, v43, v198
	v_fmac_f32_e32 v38, v43, v199
	v_fmac_f32_e32 v39, v43, v200
	v_add_f32_e32 v32, v44, v32
	v_add_f32_e32 v33, v44, v33
	v_add_f32_e32 v34, v44, v34
	v_add_f32_e32 v35, v44, v35
	v_add_f32_e32 v36, v44, v36
	v_add_f32_e32 v37, v44, v37
	v_add_f32_e32 v38, v44, v38
	v_add_f32_e32 v39, v44, v39
	v_cvt_pk_bf16_f32 v32, v32, v33
	v_cvt_pk_bf16_f32 v34, v34, v35
	v_cvt_pk_bf16_f32 v36, v36, v37
	v_cvt_pk_bf16_f32 v38, v38, v39
	ds_write_b16 v240, v32 offset:4608
	ds_write_b16_d16_hi v240, v32 offset:4752
	ds_write_b16 v240, v34 offset:4896
	ds_write_b16_d16_hi v240, v34 offset:5040
	ds_write_b16 v240, v36 offset:5184
	ds_write_b16_d16_hi v240, v36 offset:5328
	ds_write_b16 v240, v38 offset:5472
	ds_write_b16_d16_hi v240, v38 offset:5616
	v_mul_f32_e32 v32, v41, v199
	v_mul_f32_e32 v33, v41, v200
	v_mul_f32_e32 v34, v41, v201
	v_mul_f32_e32 v35, v41, v202
	v_mul_f32_e32 v36, v41, v203
	v_mul_f32_e32 v37, v41, v204
	v_mul_f32_e32 v38, v41, v205
	v_mul_f32_e32 v39, v41, v206
	v_fmac_f32_e32 v32, v40, v198
	v_fmac_f32_e32 v33, v40, v199
	v_fmac_f32_e32 v34, v40, v200
	v_fmac_f32_e32 v35, v40, v201
	v_fmac_f32_e32 v36, v40, v202
	v_fmac_f32_e32 v37, v40, v203
	v_fmac_f32_e32 v38, v40, v204
	v_fmac_f32_e32 v39, v40, v205
	v_fmac_f32_e32 v32, v42, v200
	v_fmac_f32_e32 v33, v42, v201
	v_fmac_f32_e32 v34, v42, v202
	v_fmac_f32_e32 v35, v42, v203
	v_fmac_f32_e32 v36, v42, v204
	v_fmac_f32_e32 v37, v42, v205
	v_fmac_f32_e32 v38, v42, v206
	v_fmac_f32_e32 v39, v42, v207
	v_fmac_f32_e32 v32, v43, v201
	v_fmac_f32_e32 v33, v43, v202
	v_fmac_f32_e32 v34, v43, v203
	v_fmac_f32_e32 v35, v43, v204
	v_fmac_f32_e32 v36, v43, v205
	v_fmac_f32_e32 v37, v43, v206
	v_fmac_f32_e32 v38, v43, v207
	v_fmac_f32_e32 v39, v43, v208
	v_add_f32_e32 v32, v44, v32
	v_add_f32_e32 v33, v44, v33
	v_add_f32_e32 v34, v44, v34
	v_add_f32_e32 v35, v44, v35
	v_add_f32_e32 v36, v44, v36
	v_add_f32_e32 v37, v44, v37
	v_add_f32_e32 v38, v44, v38
	v_add_f32_e32 v39, v44, v39
	v_cvt_pk_bf16_f32 v32, v32, v33
	v_cvt_pk_bf16_f32 v34, v34, v35
	v_cvt_pk_bf16_f32 v36, v36, v37
	v_cvt_pk_bf16_f32 v38, v38, v39
	ds_write_b16 v240, v32 offset:5760
	ds_write_b16_d16_hi v240, v32 offset:5904
	ds_write_b16 v240, v34 offset:6048
	ds_write_b16_d16_hi v240, v34 offset:6192
	ds_write_b16 v240, v36 offset:6336
	ds_write_b16_d16_hi v240, v36 offset:6480
	ds_write_b16 v240, v38 offset:6624
	ds_write_b16_d16_hi v240, v38 offset:6768
	v_mul_f32_e32 v32, v41, v207
	v_mul_f32_e32 v33, v41, v208
	v_mul_f32_e32 v34, v41, v209
	v_mul_f32_e32 v35, v41, v210
	v_mul_f32_e32 v36, v41, v211
	v_mul_f32_e32 v37, v41, v212
	v_mul_f32_e32 v38, v41, v213
	v_mul_f32_e32 v39, v41, v214
	v_fmac_f32_e32 v32, v40, v206
	v_fmac_f32_e32 v33, v40, v207
	v_fmac_f32_e32 v34, v40, v208
	v_fmac_f32_e32 v35, v40, v209
	v_fmac_f32_e32 v36, v40, v210
	v_fmac_f32_e32 v37, v40, v211
	v_fmac_f32_e32 v38, v40, v212
	v_fmac_f32_e32 v39, v40, v213
	v_fmac_f32_e32 v32, v42, v208
	v_fmac_f32_e32 v33, v42, v209
	v_fmac_f32_e32 v34, v42, v210
	v_fmac_f32_e32 v35, v42, v211
	v_fmac_f32_e32 v36, v42, v212
	v_fmac_f32_e32 v37, v42, v213
	v_fmac_f32_e32 v38, v42, v214
	v_fmac_f32_e32 v39, v42, v215
	v_fmac_f32_e32 v32, v43, v209
	v_fmac_f32_e32 v33, v43, v210
	v_fmac_f32_e32 v34, v43, v211
	v_fmac_f32_e32 v35, v43, v212
	v_fmac_f32_e32 v36, v43, v213
	v_fmac_f32_e32 v37, v43, v214
	v_fmac_f32_e32 v38, v43, v215
; #define LAS __attribute__((address_space(3)))
; template <bool FINAL, int D>
; __device__ __forceinline__ void rg_dir(PREF p, int l, int h, int ch, int sidx, int rowbase  , LAS bf16_t* sXc, LAS float* stg, int lane) {
;     ...
;     const float ba = p.rg_ba[(l * 2 + D) * 512 + ch], bi = p.rg_bi[(l * 2 + D) * 512 + ch], lam = p.rg_lam[(l * 2 + D) * 512 + ch];
;     const float e_ = __expf(-lam), u_ = 1.f + e_;
;     const float l1p = (u_ == 1.f) ? e_ : __logf(u_) * e_ * rcpf_(u_ - 1.f);
;     const float sp8 = -8.f * 1.4426950408889634f * l1p;
;     float hc = FINAL ? RGC[sidx] : 0.f, Ap = 1.f;
;     bf16x8 Br[4][2], Bi[4][2];
; #pragma unroll
;     for (int nt = 0; nt < 4; ++nt) { const int o0 = (nt * 16 + (lane & 15)) * 64 + (lane >> 4) * 8;
;         Br[nt][0] = *(const bf16x8*)(wr_ + o0); Br[nt][1] = *(const bf16x8*)(wr_ + o0 + 32); Bi[nt][0] = *(const bf16x8*)(wi_ + o0); Bi[nt][1] = *(const bf16x8*)(wi_ + o0 + 32); }
;     if (FINAL && D == 1) asm volatile("s_waitcnt vmcnt(0)" ::: "memory");
; #pragma unroll 1
;     for (int mi = 0; mi < 4; ++mi) { const int mt = D ? 3 - mi : mi;
;         float grv[16], hfv[16];
;         if (FINAL && D == 1) {
; #pragma unroll
;             for (int ti = 0; ti < 16; ++ti) { const size_t row = (size_t)(rowbase + mt * 16 + 15 - ti); grv[ti] = __builtin_bit_cast(float, (unsigned)P[row * PW + 512 + ch]); hfv[ti] = __builtin_bit_cast(float, (unsigned)TMP[row * 512 + ch]); }
;             __builtin_amdgcn_sched_barrier(0);
; #pragma unroll
;             for (int ti = 0; ti < 16; ++ti) { grv[ti] = bf2f(__builtin_bit_cast(unsigned, grv[ti])); hfv[ti] = bf2f(__builtin_bit_cast(unsigned, hfv[ti])); }
;         }
;         const bf16x8 A0 = *(const LAS bf16x8*)(sXc + (mt * 16 + (lane & 15)) * 72 + (lane >> 4) * 8), A1 = *(const LAS bf16x8*)(sXc + (mt * 16 + (lane & 15)) * 72 + 32 + (lane >> 4) * 8);
;         f32x4 ar[4], ai[4];
; #pragma unroll
; template <bool FINAL>
; __device__ __forceinline__ void rg_item(PREF p, int l, int item, LAS unsigned char* wl, int lane) {
;     ...
;         for (int i = 0; i < 67; ++i) { const int t = t0 - 2 + i; const int tc = t < 0 ? 0 : (t >= seqlen ? seqlen - 1 : t); xv[i] = (t == tc) ? bf2f(xr_[i]) : 0.f; }
; #pragma unroll
;         for (int tt = 0; tt < 64; ++tt) { const float xc = xv[tt] * cw0 + xv[tt + 1] * cw1 + xv[tt + 2] * cw2 + xv[tt + 3] * cw3 + cb; sXc[tt * 72 + lane] = (bf16_t)f2bf(xc); }
	v_fmac_f32_e32 v39, v43, v216
	v_add_f32_e32 v32, v44, v32
	v_add_f32_e32 v33, v44, v33
	v_add_f32_e32 v34, v44, v34
	v_add_f32_e32 v35, v44, v35
	v_add_f32_e32 v36, v44, v36
	v_add_f32_e32 v37, v44, v37
	v_add_f32_e32 v38, v44, v38
	v_add_f32_e32 v39, v44, v39
	v_cvt_pk_bf16_f32 v32, v32, v33
	v_cvt_pk_bf16_f32 v34, v34, v35
	v_cvt_pk_bf16_f32 v36, v36, v37
	v_cvt_pk_bf16_f32 v38, v38, v39
	ds_write_b16 v240, v32 offset:6912
	ds_write_b16_d16_hi v240, v32 offset:7056
	ds_write_b16 v240, v34 offset:7200
	ds_write_b16_d16_hi v240, v34 offset:7344
	ds_write_b16 v240, v36 offset:7488
	ds_write_b16_d16_hi v240, v36 offset:7632
	ds_write_b16 v240, v38 offset:7776
	ds_write_b16_d16_hi v240, v38 offset:7920
	v_mul_f32_e32 v32, v41, v215
	v_mul_f32_e32 v33, v41, v216
	v_mul_f32_e32 v34, v41, v217
	v_mul_f32_e32 v35, v41, v218
	v_mul_f32_e32 v36, v41, v219
	v_mul_f32_e32 v37, v41, v222
	v_mul_f32_e32 v38, v41, v223
	v_mul_f32_e32 v39, v41, v140
	v_fmac_f32_e32 v32, v40, v214
	v_fmac_f32_e32 v33, v40, v215
	v_fmac_f32_e32 v34, v40, v216
	v_fmac_f32_e32 v35, v40, v217
	v_fmac_f32_e32 v36, v40, v218
	v_fmac_f32_e32 v37, v40, v219
	v_fmac_f32_e32 v38, v40, v222
	v_fmac_f32_e32 v39, v40, v223
	v_fmac_f32_e32 v32, v42, v216
	v_fmac_f32_e32 v33, v42, v217
	v_fmac_f32_e32 v34, v42, v218
	v_fmac_f32_e32 v35, v42, v219
	v_fmac_f32_e32 v36, v42, v222
	v_fmac_f32_e32 v37, v42, v223
	v_fmac_f32_e32 v38, v42, v140
	v_fmac_f32_e32 v39, v42, v141
	v_fmac_f32_e32 v32, v43, v217
	v_fmac_f32_e32 v33, v43, v218
	v_fmac_f32_e32 v34, v43, v219
	v_fmac_f32_e32 v35, v43, v222
	v_fmac_f32_e32 v36, v43, v223
	v_fmac_f32_e32 v37, v43, v140
	v_fmac_f32_e32 v38, v43, v141
	v_fmac_f32_e32 v39, v43, v232
	v_add_f32_e32 v32, v44, v32
	v_add_f32_e32 v33, v44, v33
	v_add_f32_e32 v34, v44, v34
	v_add_f32_e32 v35, v44, v35
	v_add_f32_e32 v36, v44, v36
	v_add_f32_e32 v37, v44, v37
	v_add_f32_e32 v38, v44, v38
	v_add_f32_e32 v39, v44, v39
	v_cvt_pk_bf16_f32 v32, v32, v33
	v_cvt_pk_bf16_f32 v34, v34, v35
	v_cvt_pk_bf16_f32 v36, v36, v37
	v_cvt_pk_bf16_f32 v38, v38, v39
	ds_write_b16 v240, v32 offset:8064
	ds_write_b16_d16_hi v240, v32 offset:8208
	ds_write_b16 v240, v34 offset:8352
	ds_write_b16_d16_hi v240, v34 offset:8496
	ds_write_b16 v240, v36 offset:8640
	ds_write_b16_d16_hi v240, v36 offset:8784
	ds_write_b16 v240, v38 offset:8928
	ds_write_b16_d16_hi v240, v38 offset:9072
	v_mov_b32_e32 v248, 0xbfb8aa3b
	v_mov_b32_e32 v249, 0xbfb8aa3b
	s_waitcnt vmcnt(16)
	s_mov_b32 s8, 0x800000
	s_mov_b32 s9, 0x3f317217
	s_mov_b32 s14, 0x7f800000
	v_mul_f32_e32 v32, 0xbfb8aa3b, v45
	v_exp_f32_e32 v32, v32
	s_nop 0
	v_add_f32_e32 v33, 1.0, v32
	v_cmp_gt_f32_e32 vcc, s8, v33
	s_nop 1
	v_cndmask_b32_e64 v34, 0, 32, vcc
	v_ldexp_f32 v34, v33, v34
	v_log_f32_e32 v34, v34
	v_cndmask_b32_e32 v36, 0, v226, vcc
	v_cmp_eq_f32_e32 vcc, 1.0, v33
	v_mul_f32_e32 v35, 0x3f317217, v34
	v_fma_f32 v35, v34, s9, -v35
	v_fmac_f32_e32 v35, 0x3377d1cf, v34
	v_fmac_f32_e32 v35, 0x3f317217, v34
	v_cmp_lt_f32_e64 s[10:11], |v34|, s14
	s_nop 1
	v_cndmask_b32_e64 v34, v34, v35, s[10:11]
	v_add_f32_e32 v35, -1.0, v33
	v_rcp_f32_e32 v35, v35
	v_sub_f32_e32 v34, v34, v36
	v_mul_f32_e32 v34, v32, v34
	v_mul_f32_e32 v34, v34, v35
	v_cndmask_b32_e32 v32, v34, v32, vcc
	v_mul_f32_e32 v246, 0xc138aa3b, v32
	v_mov_b32_e32 v247, v246
	v_mul_f32_e32 v242, 0xbfb8aa3b, v46
	v_mul_f32_e32 v244, 0xbfb8aa3b, v47
	v_mov_b32_e32 v243, v242
	v_mov_b32_e32 v245, v244
	v_mov_b32_e32 v250, 0
	v_mov_b32_e32 v232, 1.0
	s_waitcnt vmcnt(0)
	ds_read_b128 v[32:35], v236 offset:0
	ds_read_b128 v[36:39], v236 offset:64
	s_waitcnt lgkmcnt(0)
	v_mfma_f32_16x16x32_bf16 v[0:3], v[32:35], v[80:83], 0
	v_mfma_f32_16x16x32_bf16 v[4:7], v[32:35], v[88:91], 0
	v_mfma_f32_16x16x32_bf16 v[8:11], v[32:35], v[96:99], 0
	v_mfma_f32_16x16x32_bf16 v[12:15], v[32:35], v[104:107], 0
	v_mfma_f32_16x16x32_bf16 v[16:19], v[32:35], v[112:115], 0
	v_mfma_f32_16x16x32_bf16 v[20:23], v[32:35], v[120:123], 0
	v_mfma_f32_16x16x32_bf16 v[24:27], v[32:35], v[128:131], 0
	v_mfma_f32_16x16x32_bf16 v[28:31], v[32:35], v[136:139], 0
	v_mfma_f32_16x16x32_bf16 v[0:3], v[36:39], v[84:87], v[0:3]
	v_mfma_f32_16x16x32_bf16 v[4:7], v[36:39], v[92:95], v[4:7]
	v_mfma_f32_16x16x32_bf16 v[8:11], v[36:39], v[100:103], v[8:11]
	v_mfma_f32_16x16x32_bf16 v[12:15], v[36:39], v[108:111], v[12:15]
	v_mfma_f32_16x16x32_bf16 v[16:19], v[36:39], v[148:151], v[16:19]
	v_mfma_f32_16x16x32_bf16 v[20:23], v[36:39], v[124:127], v[20:23]
	v_mfma_f32_16x16x32_bf16 v[24:27], v[36:39], v[132:135], v[24:27]
	v_mfma_f32_16x16x32_bf16 v[28:31], v[36:39], v[228:231], v[28:31]
	s_nop 3
	ds_write2_b32 v237, v0, v4 offset0:0 offset1:16
	ds_write2_b32 v237, v8, v12 offset0:32 offset1:48
	ds_write2_b32 v237, v1, v5 offset0:64 offset1:80
	ds_write2_b32 v237, v9, v13 offset0:96 offset1:112
	ds_write2_b32 v237, v2, v6 offset0:128 offset1:144
	ds_write2_b32 v237, v10, v14 offset0:160 offset1:176
	ds_write2_b32 v237, v3, v7 offset0:192 offset1:208
	ds_write2_b32 v237, v11, v15 offset0:224 offset1:240
	ds_write2_b32 v238, v16, v20 offset0:0 offset1:16
	ds_write2_b32 v238, v24, v28 offset0:32 offset1:48
	ds_write2_b32 v238, v17, v21 offset0:64 offset1:80
	ds_write2_b32 v238, v25, v29 offset0:96 offset1:112
	ds_write2_b32 v238, v18, v22 offset0:128 offset1:144
	ds_write2_b32 v238, v26, v30 offset0:160 offset1:176
	ds_write2_b32 v238, v19, v23 offset0:192 offset1:208
	ds_write2_b32 v238, v27, v31 offset0:224 offset1:240
	s_waitcnt lgkmcnt(0)
; __device__ __forceinline__ float sigmoid_f(float x) { return rcpf_(1.f + __expf(-x)); }
; template <bool FINAL, int D>
; __device__ __forceinline__ void rg_dir(PREF p, int l, int h, int ch, int sidx, int rowbase  , LAS bf16_t* sXc, LAS float* stg, int lane) {
;     ...
;         float av[16], iv[16];
; #pragma unroll
;         for (int ti = 0; ti < 16; ++ti) { const int tk = D ? 15 - ti : ti;
;             const float zr = stg[tk * 64 + lane] + ba, zi = stg[1024 + tk * 64 + lane] + bi;
;             const float r = sigmoid_f(zr), ig = sigmoid_f(zi);
;             const float a = __builtin_amdgcn_exp2f(r * sp8);
;             const float xc = bf2f(sXc[(mt * 16 + tk) * 72 + lane]);
;             av[ti] = a; iv[ti] = __builtin_amdgcn_sqrtf(fmaxf(1.f - a * a, 0.f)) * ig * xc;
	ds_read2st64_b32 v[0:1], v239 offset0:36 offset1:37
	ds_read2st64_b32 v[2:3], v239 offset0:38 offset1:39
	ds_read2st64_b32 v[4:5], v239 offset0:40 offset1:41
	ds_read2st64_b32 v[6:7], v239 offset0:42 offset1:43
	ds_read2st64_b32 v[8:9], v239 offset0:44 offset1:45
	ds_read2st64_b32 v[10:11], v239 offset0:46 offset1:47
	ds_read2st64_b32 v[12:13], v239 offset0:48 offset1:49
	ds_read2st64_b32 v[14:15], v239 offset0:50 offset1:51
	ds_read2st64_b32 v[16:17], v239 offset0:52 offset1:53
	ds_read2st64_b32 v[18:19], v239 offset0:54 offset1:55
	ds_read2st64_b32 v[20:21], v239 offset0:56 offset1:57
	ds_read2st64_b32 v[22:23], v239 offset0:58 offset1:59
	ds_read2st64_b32 v[24:25], v239 offset0:60 offset1:61
	ds_read2st64_b32 v[26:27], v239 offset0:62 offset1:63
	ds_read2st64_b32 v[28:29], v239 offset0:64 offset1:65
	ds_read2st64_b32 v[30:31], v239 offset0:66 offset1:67
	ds_read_u16 v48, v240 offset:0
	ds_read_u16 v49, v240 offset:144
	ds_read_u16 v50, v240 offset:288
	ds_read_u16 v51, v240 offset:432
	ds_read_u16 v52, v240 offset:576
	ds_read_u16 v53, v240 offset:720
	ds_read_u16 v54, v240 offset:864
	ds_read_u16 v55, v240 offset:1008
	ds_read_u16 v56, v240 offset:1152
	ds_read_u16 v57, v240 offset:1296
	ds_read_u16 v58, v240 offset:1440
	ds_read_u16 v59, v240 offset:1584
	ds_read_u16 v60, v240 offset:1728
	ds_read_u16 v61, v240 offset:1872
	ds_read_u16 v62, v240 offset:2016
	ds_read_u16 v63, v240 offset:2160
	s_waitcnt lgkmcnt(0)
	v_pk_fma_f32 v[0:1], v[0:1], v[248:249], v[242:243]
	v_pk_fma_f32 v[2:3], v[2:3], v[248:249], v[242:243]
	v_pk_fma_f32 v[4:5], v[4:5], v[248:249], v[242:243]
	v_pk_fma_f32 v[6:7], v[6:7], v[248:249], v[242:243]
	v_pk_fma_f32 v[8:9], v[8:9], v[248:249], v[242:243]
	v_pk_fma_f32 v[10:11], v[10:11], v[248:249], v[242:243]
	v_pk_fma_f32 v[12:13], v[12:13], v[248:249], v[242:243]
	v_pk_fma_f32 v[14:15], v[14:15], v[248:249], v[242:243]
	v_pk_fma_f32 v[16:17], v[16:17], v[248:249], v[244:245]
	v_pk_fma_f32 v[18:19], v[18:19], v[248:249], v[244:245]
	v_pk_fma_f32 v[20:21], v[20:21], v[248:249], v[244:245]
	v_pk_fma_f32 v[22:23], v[22:23], v[248:249], v[244:245]
	v_pk_fma_f32 v[24:25], v[24:25], v[248:249], v[244:245]
	v_pk_fma_f32 v[26:27], v[26:27], v[248:249], v[244:245]
	v_pk_fma_f32 v[28:29], v[28:29], v[248:249], v[244:245]
	v_pk_fma_f32 v[30:31], v[30:31], v[248:249], v[244:245]
	v_exp_f32_e32 v0, v0
	v_exp_f32_e32 v1, v1
	v_exp_f32_e32 v2, v2
	v_exp_f32_e32 v3, v3
	v_exp_f32_e32 v4, v4
	v_exp_f32_e32 v5, v5
	v_exp_f32_e32 v6, v6
	v_exp_f32_e32 v7, v7
	v_exp_f32_e32 v8, v8
	v_exp_f32_e32 v9, v9
	v_exp_f32_e32 v10, v10
	v_exp_f32_e32 v11, v11
	v_exp_f32_e32 v12, v12
	v_exp_f32_e32 v13, v13
	v_exp_f32_e32 v14, v14
	v_exp_f32_e32 v15, v15
	v_exp_f32_e32 v16, v16
	v_exp_f32_e32 v17, v17
	v_exp_f32_e32 v18, v18
	v_exp_f32_e32 v19, v19
	v_exp_f32_e32 v20, v20
	v_exp_f32_e32 v21, v21
	v_exp_f32_e32 v22, v22
	v_exp_f32_e32 v23, v23
	v_exp_f32_e32 v24, v24
	v_exp_f32_e32 v25, v25
	v_exp_f32_e32 v26, v26
	v_exp_f32_e32 v27, v27
	v_exp_f32_e32 v28, v28
	v_exp_f32_e32 v29, v29
	v_exp_f32_e32 v30, v30
	v_exp_f32_e32 v31, v31
	v_pk_add_f32 v[0:1], v[0:1], 1.0 op_sel_hi:[1,0]
	v_pk_add_f32 v[2:3], v[2:3], 1.0 op_sel_hi:[1,0]
	v_pk_add_f32 v[4:5], v[4:5], 1.0 op_sel_hi:[1,0]
	v_pk_add_f32 v[6:7], v[6:7], 1.0 op_sel_hi:[1,0]
	v_pk_add_f32 v[8:9], v[8:9], 1.0 op_sel_hi:[1,0]
	v_pk_add_f32 v[10:11], v[10:11], 1.0 op_sel_hi:[1,0]
	v_pk_add_f32 v[12:13], v[12:13], 1.0 op_sel_hi:[1,0]
	v_pk_add_f32 v[14:15], v[14:15], 1.0 op_sel_hi:[1,0]
	v_pk_add_f32 v[16:17], v[16:17], 1.0 op_sel_hi:[1,0]
	v_pk_add_f32 v[18:19], v[18:19], 1.0 op_sel_hi:[1,0]
	v_pk_add_f32 v[20:21], v[20:21], 1.0 op_sel_hi:[1,0]
	v_pk_add_f32 v[22:23], v[22:23], 1.0 op_sel_hi:[1,0]
	v_pk_add_f32 v[24:25], v[24:25], 1.0 op_sel_hi:[1,0]
	v_pk_add_f32 v[26:27], v[26:27], 1.0 op_sel_hi:[1,0]
	v_pk_add_f32 v[28:29], v[28:29], 1.0 op_sel_hi:[1,0]
	v_pk_add_f32 v[30:31], v[30:31], 1.0 op_sel_hi:[1,0]
	v_rcp_f32_e32 v0, v0
	v_rcp_f32_e32 v1, v1
	v_rcp_f32_e32 v2, v2
	v_rcp_f32_e32 v3, v3
	v_rcp_f32_e32 v4, v4
	v_rcp_f32_e32 v5, v5
	v_rcp_f32_e32 v6, v6
	v_rcp_f32_e32 v7, v7
	v_rcp_f32_e32 v8, v8
	v_rcp_f32_e32 v9, v9
	v_rcp_f32_e32 v10, v10
	v_rcp_f32_e32 v11, v11
	v_rcp_f32_e32 v12, v12
	v_rcp_f32_e32 v13, v13
	v_rcp_f32_e32 v14, v14
	v_rcp_f32_e32 v15, v15
	v_rcp_f32_e32 v16, v16
	v_rcp_f32_e32 v17, v17
	v_rcp_f32_e32 v18, v18
	v_rcp_f32_e32 v19, v19
	v_rcp_f32_e32 v20, v20
	v_rcp_f32_e32 v21, v21
	v_rcp_f32_e32 v22, v22
	v_rcp_f32_e32 v23, v23
	v_rcp_f32_e32 v24, v24
	v_rcp_f32_e32 v25, v25
	v_rcp_f32_e32 v26, v26
	v_rcp_f32_e32 v27, v27
	v_rcp_f32_e32 v28, v28
	v_rcp_f32_e32 v29, v29
	v_rcp_f32_e32 v30, v30
	v_rcp_f32_e32 v31, v31
	v_pk_mul_f32 v[0:1], v[246:247], v[0:1]
	v_pk_mul_f32 v[2:3], v[246:247], v[2:3]
	v_pk_mul_f32 v[4:5], v[246:247], v[4:5]
	v_pk_mul_f32 v[6:7], v[246:247], v[6:7]
	v_pk_mul_f32 v[8:9], v[246:247], v[8:9]
	v_pk_mul_f32 v[10:11], v[246:247], v[10:11]
	v_pk_mul_f32 v[12:13], v[246:247], v[12:13]
	v_pk_mul_f32 v[14:15], v[246:247], v[14:15]
	v_lshlrev_b32_e32 v48, 16, v48
	v_lshlrev_b32_e32 v49, 16, v49
	v_lshlrev_b32_e32 v50, 16, v50
	v_lshlrev_b32_e32 v51, 16, v51
	v_lshlrev_b32_e32 v52, 16, v52
	v_lshlrev_b32_e32 v53, 16, v53
	v_lshlrev_b32_e32 v54, 16, v54
	v_lshlrev_b32_e32 v55, 16, v55
	v_lshlrev_b32_e32 v56, 16, v56
	v_lshlrev_b32_e32 v57, 16, v57
	v_lshlrev_b32_e32 v58, 16, v58
	v_lshlrev_b32_e32 v59, 16, v59
	v_lshlrev_b32_e32 v60, 16, v60
	v_lshlrev_b32_e32 v61, 16, v61
	v_lshlrev_b32_e32 v62, 16, v62
	v_lshlrev_b32_e32 v63, 16, v63
	v_exp_f32_e32 v0, v0
	v_exp_f32_e32 v1, v1
	v_exp_f32_e32 v2, v2
	v_exp_f32_e32 v3, v3
	v_exp_f32_e32 v4, v4
; #define LAS __attribute__((address_space(3)))
; #define WAVE_SYNC() asm volatile("s_waitcnt lgkmcnt(0)" ::: "memory")
; __device__ __forceinline__ float sigmoid_f(float x) { return rcpf_(1.f + __expf(-x)); }
; __device__ __forceinline__ float gelu_tanh_f(float x) { const float y = 0.7978845608028654f * (x + 0.044715f * x * x * x); return x * sigmoid_f(2.f * y); }
; __device__ __forceinline__ f32x4 mfma16(bf16x8 a, bf16x8 b, f32x4 c) { return __builtin_amdgcn_mfma_f32_16x16x32_bf16(a, b, c, 0, 0, 0); }
; template <bool FINAL, int D>
; __device__ __forceinline__ void rg_dir(PREF p, int l, int h, int ch, int sidx, int rowbase  , LAS bf16_t* sXc, LAS float* stg, int lane) {
;     ...
;         const bf16x8 A0 = *(const LAS bf16x8*)(sXc + (mt * 16 + (lane & 15)) * 72 + (lane >> 4) * 8), A1 = *(const LAS bf16x8*)(sXc + (mt * 16 + (lane & 15)) * 72 + 32 + (lane >> 4) * 8);
;         f32x4 ar[4], ai[4];
; #pragma unroll
;         for (int nt = 0; nt < 4; ++nt) { const f32x4 z = {0.f, 0.f, 0.f, 0.f};
;             ar[nt] = mfma16(A0, Br[nt][0], z); ar[nt] = mfma16(A1, Br[nt][1], ar[nt]); ai[nt] = mfma16(A0, Bi[nt][0], z); ai[nt] = mfma16(A1, Bi[nt][1], ai[nt]); }
;         WAVE_SYNC();
; #pragma unroll
;         for (int nt = 0; nt < 4; ++nt)
; #pragma unroll
;             for (int j = 0; j < 4; ++j) { const int o = ((lane >> 4) * 4 + j) * 64 + nt * 16 + (lane & 15); stg[o] = ar[nt][j]; stg[1024 + o] = ai[nt][j]; }
;         WAVE_SYNC();
;     ...
;         for (int ti = 0; ti < 16; ++ti) { const int tk = D ? 15 - ti : ti;
;             const float zr = stg[tk * 64 + lane] + ba, zi = stg[1024 + tk * 64 + lane] + bi;
;             const float r = sigmoid_f(zr), ig = sigmoid_f(zi);
;             const float a = __builtin_amdgcn_exp2f(r * sp8);
;             const float xc = bf2f(sXc[(mt * 16 + tk) * 72 + lane]);
;             av[ti] = a; iv[ti] = __builtin_amdgcn_sqrtf(fmaxf(1.f - a * a, 0.f)) * ig * xc;
;             if (FINAL && D == 1) grv[ti] = gelu_tanh_f(grv[ti]);
;         }
; #pragma unroll
;         for (int ti = 0; ti < 16; ++ti) { const int tk = D ? 15 - ti : ti;
;             hc = av[ti] * hc + iv[ti]; Ap *= av[ti];
	v_exp_f32_e32 v5, v5
	v_exp_f32_e32 v6, v6
	v_exp_f32_e32 v7, v7
	v_exp_f32_e32 v8, v8
	v_exp_f32_e32 v9, v9
	v_exp_f32_e32 v10, v10
	v_exp_f32_e32 v11, v11
	v_exp_f32_e32 v12, v12
	v_exp_f32_e32 v13, v13
	v_exp_f32_e32 v14, v14
	v_exp_f32_e32 v15, v15
	v_fma_f32 v32, -v0, v0, 1.0 clamp
	v_fma_f32 v33, -v1, v1, 1.0 clamp
	v_fma_f32 v34, -v2, v2, 1.0 clamp
	v_fma_f32 v35, -v3, v3, 1.0 clamp
	v_fma_f32 v36, -v4, v4, 1.0 clamp
	v_fma_f32 v37, -v5, v5, 1.0 clamp
	v_fma_f32 v38, -v6, v6, 1.0 clamp
	v_fma_f32 v39, -v7, v7, 1.0 clamp
	v_fma_f32 v40, -v8, v8, 1.0 clamp
	v_fma_f32 v41, -v9, v9, 1.0 clamp
	v_fma_f32 v42, -v10, v10, 1.0 clamp
	v_fma_f32 v43, -v11, v11, 1.0 clamp
	v_fma_f32 v44, -v12, v12, 1.0 clamp
	v_fma_f32 v45, -v13, v13, 1.0 clamp
	v_fma_f32 v46, -v14, v14, 1.0 clamp
	v_fma_f32 v47, -v15, v15, 1.0 clamp
	v_sqrt_f32_e32 v32, v32
	v_sqrt_f32_e32 v33, v33
	v_sqrt_f32_e32 v34, v34
	v_sqrt_f32_e32 v35, v35
	v_sqrt_f32_e32 v36, v36
	v_sqrt_f32_e32 v37, v37
	v_sqrt_f32_e32 v38, v38
	v_sqrt_f32_e32 v39, v39
	v_sqrt_f32_e32 v40, v40
	v_sqrt_f32_e32 v41, v41
	v_sqrt_f32_e32 v42, v42
	v_sqrt_f32_e32 v43, v43
	v_sqrt_f32_e32 v44, v44
	v_sqrt_f32_e32 v45, v45
	v_sqrt_f32_e32 v46, v46
	v_sqrt_f32_e32 v47, v47
	s_nop 0
	v_pk_mul_f32 v[16:17], v[16:17], v[32:33]
	v_pk_mul_f32 v[18:19], v[18:19], v[34:35]
	v_pk_mul_f32 v[20:21], v[20:21], v[36:37]
	v_pk_mul_f32 v[22:23], v[22:23], v[38:39]
	v_pk_mul_f32 v[24:25], v[24:25], v[40:41]
	v_pk_mul_f32 v[26:27], v[26:27], v[42:43]
	v_pk_mul_f32 v[28:29], v[28:29], v[44:45]
	v_pk_mul_f32 v[30:31], v[30:31], v[46:47]
	v_pk_mul_f32 v[16:17], v[16:17], v[48:49]
	v_pk_mul_f32 v[18:19], v[18:19], v[50:51]
	v_pk_mul_f32 v[20:21], v[20:21], v[52:53]
	v_pk_mul_f32 v[22:23], v[22:23], v[54:55]
	v_pk_mul_f32 v[24:25], v[24:25], v[56:57]
	v_pk_mul_f32 v[26:27], v[26:27], v[58:59]
	v_pk_mul_f32 v[28:29], v[28:29], v[60:61]
	v_pk_mul_f32 v[30:31], v[30:31], v[62:63]
	v_fma_f32 v32, v0, v250, v16
	v_mul_f32_e32 v232, v232, v0
	v_fma_f32 v250, v1, v32, v17
	v_mul_f32_e32 v232, v232, v1
	v_fma_f32 v32, v2, v250, v18
	v_mul_f32_e32 v232, v232, v2
	v_fma_f32 v250, v3, v32, v19
	v_mul_f32_e32 v232, v232, v3
	v_fma_f32 v32, v4, v250, v20
	v_mul_f32_e32 v232, v232, v4
	v_fma_f32 v250, v5, v32, v21
	v_mul_f32_e32 v232, v232, v5
	v_fma_f32 v32, v6, v250, v22
	v_mul_f32_e32 v232, v232, v6
	v_fma_f32 v250, v7, v32, v23
	v_mul_f32_e32 v232, v232, v7
	v_fma_f32 v32, v8, v250, v24
	v_mul_f32_e32 v232, v232, v8
	v_fma_f32 v250, v9, v32, v25
	v_mul_f32_e32 v232, v232, v9
	v_fma_f32 v32, v10, v250, v26
	v_mul_f32_e32 v232, v232, v10
	v_fma_f32 v250, v11, v32, v27
	v_mul_f32_e32 v232, v232, v11
	v_fma_f32 v32, v12, v250, v28
	v_mul_f32_e32 v232, v232, v12
	v_fma_f32 v250, v13, v32, v29
	v_mul_f32_e32 v232, v232, v13
	v_fma_f32 v32, v14, v250, v30
	v_mul_f32_e32 v232, v232, v14
	v_fma_f32 v250, v15, v32, v31
	v_mul_f32_e32 v232, v232, v15
	ds_read_b128 v[32:35], v236 offset:2304
	ds_read_b128 v[36:39], v236 offset:2368
	s_waitcnt lgkmcnt(0)
	v_mfma_f32_16x16x32_bf16 v[0:3], v[32:35], v[80:83], 0
	v_mfma_f32_16x16x32_bf16 v[4:7], v[32:35], v[88:91], 0
	v_mfma_f32_16x16x32_bf16 v[8:11], v[32:35], v[96:99], 0
	v_mfma_f32_16x16x32_bf16 v[12:15], v[32:35], v[104:107], 0
	v_mfma_f32_16x16x32_bf16 v[16:19], v[32:35], v[112:115], 0
	v_mfma_f32_16x16x32_bf16 v[20:23], v[32:35], v[120:123], 0
	v_mfma_f32_16x16x32_bf16 v[24:27], v[32:35], v[128:131], 0
	v_mfma_f32_16x16x32_bf16 v[28:31], v[32:35], v[136:139], 0
	v_mfma_f32_16x16x32_bf16 v[0:3], v[36:39], v[84:87], v[0:3]
	v_mfma_f32_16x16x32_bf16 v[4:7], v[36:39], v[92:95], v[4:7]
	v_mfma_f32_16x16x32_bf16 v[8:11], v[36:39], v[100:103], v[8:11]
	v_mfma_f32_16x16x32_bf16 v[12:15], v[36:39], v[108:111], v[12:15]
	v_mfma_f32_16x16x32_bf16 v[16:19], v[36:39], v[148:151], v[16:19]
	v_mfma_f32_16x16x32_bf16 v[20:23], v[36:39], v[124:127], v[20:23]
	v_mfma_f32_16x16x32_bf16 v[24:27], v[36:39], v[132:135], v[24:27]
	v_mfma_f32_16x16x32_bf16 v[28:31], v[36:39], v[228:231], v[28:31]
	s_nop 3
	ds_write2_b32 v237, v0, v4 offset0:0 offset1:16
	ds_write2_b32 v237, v8, v12 offset0:32 offset1:48
	ds_write2_b32 v237, v1, v5 offset0:64 offset1:80
	ds_write2_b32 v237, v9, v13 offset0:96 offset1:112
	ds_write2_b32 v237, v2, v6 offset0:128 offset1:144
	ds_write2_b32 v237, v10, v14 offset0:160 offset1:176
	ds_write2_b32 v237, v3, v7 offset0:192 offset1:208
	ds_write2_b32 v237, v11, v15 offset0:224 offset1:240
	ds_write2_b32 v238, v16, v20 offset0:0 offset1:16
	ds_write2_b32 v238, v24, v28 offset0:32 offset1:48
	ds_write2_b32 v238, v17, v21 offset0:64 offset1:80
	ds_write2_b32 v238, v25, v29 offset0:96 offset1:112
	ds_write2_b32 v238, v18, v22 offset0:128 offset1:144
	ds_write2_b32 v238, v26, v30 offset0:160 offset1:176
	ds_write2_b32 v238, v19, v23 offset0:192 offset1:208
	ds_write2_b32 v238, v27, v31 offset0:224 offset1:240
	s_waitcnt lgkmcnt(0)
; __device__ __forceinline__ float sigmoid_f(float x) { return rcpf_(1.f + __expf(-x)); }
; template <bool FINAL, int D>
; __device__ __forceinline__ void rg_dir(PREF p, int l, int h, int ch, int sidx, int rowbase  , LAS bf16_t* sXc, LAS float* stg, int lane) {
;     ...
;         float av[16], iv[16];
; #pragma unroll
;         for (int ti = 0; ti < 16; ++ti) { const int tk = D ? 15 - ti : ti;
;             const float zr = stg[tk * 64 + lane] + ba, zi = stg[1024 + tk * 64 + lane] + bi;
;             const float r = sigmoid_f(zr), ig = sigmoid_f(zi);
;             const float a = __builtin_amdgcn_exp2f(r * sp8);
;             const float xc = bf2f(sXc[(mt * 16 + tk) * 72 + lane]);
;             av[ti] = a; iv[ti] = __builtin_amdgcn_sqrtf(fmaxf(1.f - a * a, 0.f)) * ig * xc;
	ds_read2st64_b32 v[0:1], v239 offset0:36 offset1:37
	ds_read2st64_b32 v[2:3], v239 offset0:38 offset1:39
	ds_read2st64_b32 v[4:5], v239 offset0:40 offset1:41
	ds_read2st64_b32 v[6:7], v239 offset0:42 offset1:43
	ds_read2st64_b32 v[8:9], v239 offset0:44 offset1:45
	ds_read2st64_b32 v[10:11], v239 offset0:46 offset1:47
	ds_read2st64_b32 v[12:13], v239 offset0:48 offset1:49
	ds_read2st64_b32 v[14:15], v239 offset0:50 offset1:51
	ds_read2st64_b32 v[16:17], v239 offset0:52 offset1:53
	ds_read2st64_b32 v[18:19], v239 offset0:54 offset1:55
	ds_read2st64_b32 v[20:21], v239 offset0:56 offset1:57
	ds_read2st64_b32 v[22:23], v239 offset0:58 offset1:59
	ds_read2st64_b32 v[24:25], v239 offset0:60 offset1:61
	ds_read2st64_b32 v[26:27], v239 offset0:62 offset1:63
	ds_read2st64_b32 v[28:29], v239 offset0:64 offset1:65
	ds_read2st64_b32 v[30:31], v239 offset0:66 offset1:67
	ds_read_u16_d16_hi v48, v240 offset:2304
	ds_read_u16_d16_hi v49, v240 offset:2448
	ds_read_u16_d16_hi v50, v240 offset:2592
	ds_read_u16_d16_hi v51, v240 offset:2736
	ds_read_u16_d16_hi v52, v240 offset:2880
	ds_read_u16_d16_hi v53, v240 offset:3024
	ds_read_u16_d16_hi v54, v240 offset:3168
	ds_read_u16_d16_hi v55, v240 offset:3312
	ds_read_u16_d16_hi v56, v240 offset:3456
	ds_read_u16_d16_hi v57, v240 offset:3600
	ds_read_u16_d16_hi v58, v240 offset:3744
	ds_read_u16_d16_hi v59, v240 offset:3888
	ds_read_u16_d16_hi v60, v240 offset:4032
	ds_read_u16_d16_hi v61, v240 offset:4176
	ds_read_u16_d16_hi v62, v240 offset:4320
	ds_read_u16_d16_hi v63, v240 offset:4464
	s_waitcnt lgkmcnt(0)
	v_pk_fma_f32 v[0:1], v[0:1], v[248:249], v[242:243]
	v_pk_fma_f32 v[2:3], v[2:3], v[248:249], v[242:243]
	v_pk_fma_f32 v[4:5], v[4:5], v[248:249], v[242:243]
	v_pk_fma_f32 v[6:7], v[6:7], v[248:249], v[242:243]
	v_pk_fma_f32 v[8:9], v[8:9], v[248:249], v[242:243]
	v_pk_fma_f32 v[10:11], v[10:11], v[248:249], v[242:243]
	v_pk_fma_f32 v[12:13], v[12:13], v[248:249], v[242:243]
	v_pk_fma_f32 v[14:15], v[14:15], v[248:249], v[242:243]
	v_pk_fma_f32 v[16:17], v[16:17], v[248:249], v[244:245]
	v_pk_fma_f32 v[18:19], v[18:19], v[248:249], v[244:245]
	v_pk_fma_f32 v[20:21], v[20:21], v[248:249], v[244:245]
	v_pk_fma_f32 v[22:23], v[22:23], v[248:249], v[244:245]
	v_pk_fma_f32 v[24:25], v[24:25], v[248:249], v[244:245]
	v_pk_fma_f32 v[26:27], v[26:27], v[248:249], v[244:245]
	v_pk_fma_f32 v[28:29], v[28:29], v[248:249], v[244:245]
	v_pk_fma_f32 v[30:31], v[30:31], v[248:249], v[244:245]
	v_exp_f32_e32 v0, v0
	v_exp_f32_e32 v1, v1
	v_exp_f32_e32 v2, v2
	v_exp_f32_e32 v3, v3
	v_exp_f32_e32 v4, v4
	v_exp_f32_e32 v5, v5
	v_exp_f32_e32 v6, v6
	v_exp_f32_e32 v7, v7
	v_exp_f32_e32 v8, v8
	v_exp_f32_e32 v9, v9
	v_exp_f32_e32 v10, v10
	v_exp_f32_e32 v11, v11
	v_exp_f32_e32 v12, v12
	v_exp_f32_e32 v13, v13
	v_exp_f32_e32 v14, v14
	v_exp_f32_e32 v15, v15
	v_exp_f32_e32 v16, v16
	v_exp_f32_e32 v17, v17
	v_exp_f32_e32 v18, v18
	v_exp_f32_e32 v19, v19
	v_exp_f32_e32 v20, v20
	v_exp_f32_e32 v21, v21
	v_exp_f32_e32 v22, v22
	v_exp_f32_e32 v23, v23
	v_exp_f32_e32 v24, v24
	v_exp_f32_e32 v25, v25
	v_exp_f32_e32 v26, v26
	v_exp_f32_e32 v27, v27
	v_exp_f32_e32 v28, v28
	v_exp_f32_e32 v29, v29
	v_exp_f32_e32 v30, v30
	v_exp_f32_e32 v31, v31
	v_pk_add_f32 v[0:1], v[0:1], 1.0 op_sel_hi:[1,0]
	v_pk_add_f32 v[2:3], v[2:3], 1.0 op_sel_hi:[1,0]
	v_pk_add_f32 v[4:5], v[4:5], 1.0 op_sel_hi:[1,0]
	v_pk_add_f32 v[6:7], v[6:7], 1.0 op_sel_hi:[1,0]
	v_pk_add_f32 v[8:9], v[8:9], 1.0 op_sel_hi:[1,0]
	v_pk_add_f32 v[10:11], v[10:11], 1.0 op_sel_hi:[1,0]
	v_pk_add_f32 v[12:13], v[12:13], 1.0 op_sel_hi:[1,0]
	v_pk_add_f32 v[14:15], v[14:15], 1.0 op_sel_hi:[1,0]
	v_pk_add_f32 v[16:17], v[16:17], 1.0 op_sel_hi:[1,0]
	v_pk_add_f32 v[18:19], v[18:19], 1.0 op_sel_hi:[1,0]
	v_pk_add_f32 v[20:21], v[20:21], 1.0 op_sel_hi:[1,0]
	v_pk_add_f32 v[22:23], v[22:23], 1.0 op_sel_hi:[1,0]
	v_pk_add_f32 v[24:25], v[24:25], 1.0 op_sel_hi:[1,0]
	v_pk_add_f32 v[26:27], v[26:27], 1.0 op_sel_hi:[1,0]
	v_pk_add_f32 v[28:29], v[28:29], 1.0 op_sel_hi:[1,0]
	v_pk_add_f32 v[30:31], v[30:31], 1.0 op_sel_hi:[1,0]
	v_rcp_f32_e32 v0, v0
	v_rcp_f32_e32 v1, v1
	v_rcp_f32_e32 v2, v2
	v_rcp_f32_e32 v3, v3
	v_rcp_f32_e32 v4, v4
	v_rcp_f32_e32 v5, v5
	v_rcp_f32_e32 v6, v6
	v_rcp_f32_e32 v7, v7
	v_rcp_f32_e32 v8, v8
	v_rcp_f32_e32 v9, v9
	v_rcp_f32_e32 v10, v10
	v_rcp_f32_e32 v11, v11
	v_rcp_f32_e32 v12, v12
	v_rcp_f32_e32 v13, v13
	v_rcp_f32_e32 v14, v14
	v_rcp_f32_e32 v15, v15
	v_rcp_f32_e32 v16, v16
	v_rcp_f32_e32 v17, v17
	v_rcp_f32_e32 v18, v18
	v_rcp_f32_e32 v19, v19
	v_rcp_f32_e32 v20, v20
	v_rcp_f32_e32 v21, v21
	v_rcp_f32_e32 v22, v22
	v_rcp_f32_e32 v23, v23
	v_rcp_f32_e32 v24, v24
	v_rcp_f32_e32 v25, v25
	v_rcp_f32_e32 v26, v26
	v_rcp_f32_e32 v27, v27
	v_rcp_f32_e32 v28, v28
	v_rcp_f32_e32 v29, v29
	v_rcp_f32_e32 v30, v30
	v_rcp_f32_e32 v31, v31
	v_pk_mul_f32 v[0:1], v[246:247], v[0:1]
	v_pk_mul_f32 v[2:3], v[246:247], v[2:3]
	v_pk_mul_f32 v[4:5], v[246:247], v[4:5]
	v_pk_mul_f32 v[6:7], v[246:247], v[6:7]
	v_pk_mul_f32 v[8:9], v[246:247], v[8:9]
	v_pk_mul_f32 v[10:11], v[246:247], v[10:11]
	v_pk_mul_f32 v[12:13], v[246:247], v[12:13]
	v_pk_mul_f32 v[14:15], v[246:247], v[14:15]
	v_exp_f32_e32 v0, v0
	v_exp_f32_e32 v1, v1
	v_exp_f32_e32 v2, v2
	v_exp_f32_e32 v3, v3
	v_exp_f32_e32 v4, v4
	v_exp_f32_e32 v5, v5
	v_exp_f32_e32 v6, v6
	v_exp_f32_e32 v7, v7
	v_exp_f32_e32 v8, v8
	v_exp_f32_e32 v9, v9
	v_exp_f32_e32 v10, v10
	v_exp_f32_e32 v11, v11
	v_exp_f32_e32 v12, v12
	v_exp_f32_e32 v13, v13
	v_exp_f32_e32 v14, v14
	v_exp_f32_e32 v15, v15
	v_fma_f32 v32, -v0, v0, 1.0 clamp
	v_fma_f32 v33, -v1, v1, 1.0 clamp
	v_fma_f32 v34, -v2, v2, 1.0 clamp
	v_fma_f32 v35, -v3, v3, 1.0 clamp
; __device__ __forceinline__ float sigmoid_f(float x) { return rcpf_(1.f + __expf(-x)); }
; __device__ __forceinline__ float gelu_tanh_f(float x) { const float y = 0.7978845608028654f * (x + 0.044715f * x * x * x); return x * sigmoid_f(2.f * y); }
; template <bool FINAL, int D>
; __device__ __forceinline__ void rg_dir(PREF p, int l, int h, int ch, int sidx, int rowbase  , LAS bf16_t* sXc, LAS float* stg, int lane) {
;     ...
;         for (int ti = 0; ti < 16; ++ti) { const int tk = D ? 15 - ti : ti;
;             const float zr = stg[tk * 64 + lane] + ba, zi = stg[1024 + tk * 64 + lane] + bi;
;             const float r = sigmoid_f(zr), ig = sigmoid_f(zi);
;             const float a = __builtin_amdgcn_exp2f(r * sp8);
;             const float xc = bf2f(sXc[(mt * 16 + tk) * 72 + lane]);
;             av[ti] = a; iv[ti] = __builtin_amdgcn_sqrtf(fmaxf(1.f - a * a, 0.f)) * ig * xc;
;             if (FINAL && D == 1) grv[ti] = gelu_tanh_f(grv[ti]);
;         }
; #pragma unroll
;         for (int ti = 0; ti < 16; ++ti) { const int tk = D ? 15 - ti : ti;
;             hc = av[ti] * hc + iv[ti]; Ap *= av[ti];
	v_fma_f32 v36, -v4, v4, 1.0 clamp
	v_fma_f32 v37, -v5, v5, 1.0 clamp
	v_fma_f32 v38, -v6, v6, 1.0 clamp
	v_fma_f32 v39, -v7, v7, 1.0 clamp
	v_fma_f32 v40, -v8, v8, 1.0 clamp
	v_fma_f32 v41, -v9, v9, 1.0 clamp
	v_fma_f32 v42, -v10, v10, 1.0 clamp
	v_fma_f32 v43, -v11, v11, 1.0 clamp
	v_fma_f32 v44, -v12, v12, 1.0 clamp
	v_fma_f32 v45, -v13, v13, 1.0 clamp
	v_fma_f32 v46, -v14, v14, 1.0 clamp
	v_fma_f32 v47, -v15, v15, 1.0 clamp
	v_sqrt_f32_e32 v32, v32
	v_sqrt_f32_e32 v33, v33
	v_sqrt_f32_e32 v34, v34
	v_sqrt_f32_e32 v35, v35
	v_sqrt_f32_e32 v36, v36
	v_sqrt_f32_e32 v37, v37
	v_sqrt_f32_e32 v38, v38
	v_sqrt_f32_e32 v39, v39
	v_sqrt_f32_e32 v40, v40
	v_sqrt_f32_e32 v41, v41
	v_sqrt_f32_e32 v42, v42
	v_sqrt_f32_e32 v43, v43
	v_sqrt_f32_e32 v44, v44
	v_sqrt_f32_e32 v45, v45
	v_sqrt_f32_e32 v46, v46
	v_sqrt_f32_e32 v47, v47
	s_nop 0
	v_pk_mul_f32 v[16:17], v[16:17], v[32:33]
	v_pk_mul_f32 v[18:19], v[18:19], v[34:35]
	v_pk_mul_f32 v[20:21], v[20:21], v[36:37]
	v_pk_mul_f32 v[22:23], v[22:23], v[38:39]
	v_pk_mul_f32 v[24:25], v[24:25], v[40:41]
	v_pk_mul_f32 v[26:27], v[26:27], v[42:43]
	v_pk_mul_f32 v[28:29], v[28:29], v[44:45]
	v_pk_mul_f32 v[30:31], v[30:31], v[46:47]
	v_pk_mul_f32 v[16:17], v[16:17], v[48:49]
	v_pk_mul_f32 v[18:19], v[18:19], v[50:51]
	v_pk_mul_f32 v[20:21], v[20:21], v[52:53]
	v_pk_mul_f32 v[22:23], v[22:23], v[54:55]
	v_pk_mul_f32 v[24:25], v[24:25], v[56:57]
	v_pk_mul_f32 v[26:27], v[26:27], v[58:59]
	v_pk_mul_f32 v[28:29], v[28:29], v[60:61]
	v_pk_mul_f32 v[30:31], v[30:31], v[62:63]
	v_fma_f32 v32, v0, v250, v16
	v_mul_f32_e32 v232, v232, v0
	v_fma_f32 v250, v1, v32, v17
	v_mul_f32_e32 v232, v232, v1
	v_fma_f32 v32, v2, v250, v18
	v_mul_f32_e32 v232, v232, v2
	v_fma_f32 v250, v3, v32, v19
	v_mul_f32_e32 v232, v232, v3
	v_fma_f32 v32, v4, v250, v20
	v_mul_f32_e32 v232, v232, v4
	v_fma_f32 v250, v5, v32, v21
	v_mul_f32_e32 v232, v232, v5
	v_fma_f32 v32, v6, v250, v22
	v_mul_f32_e32 v232, v232, v6
	v_fma_f32 v250, v7, v32, v23
	v_mul_f32_e32 v232, v232, v7
	v_fma_f32 v32, v8, v250, v24
	v_mul_f32_e32 v232, v232, v8
	v_fma_f32 v250, v9, v32, v25
	v_mul_f32_e32 v232, v232, v9
	v_fma_f32 v32, v10, v250, v26
	v_mul_f32_e32 v232, v232, v10
	v_fma_f32 v250, v11, v32, v27
	v_mul_f32_e32 v232, v232, v11
	v_fma_f32 v32, v12, v250, v28
	v_mul_f32_e32 v232, v232, v12
	v_fma_f32 v250, v13, v32, v29
	v_mul_f32_e32 v232, v232, v13
	v_fma_f32 v32, v14, v250, v30
	v_mul_f32_e32 v232, v232, v14
	v_fma_f32 v250, v15, v32, v31
	v_mul_f32_e32 v232, v232, v15
	ds_read_b128 v[32:35], v236 offset:4608
	ds_read_b128 v[36:39], v236 offset:4672
	s_waitcnt lgkmcnt(0)
	v_mfma_f32_16x16x32_bf16 v[0:3], v[32:35], v[80:83], 0
	v_mfma_f32_16x16x32_bf16 v[4:7], v[32:35], v[88:91], 0
	v_mfma_f32_16x16x32_bf16 v[8:11], v[32:35], v[96:99], 0
	v_mfma_f32_16x16x32_bf16 v[12:15], v[32:35], v[104:107], 0
	v_mfma_f32_16x16x32_bf16 v[16:19], v[32:35], v[112:115], 0
	v_mfma_f32_16x16x32_bf16 v[20:23], v[32:35], v[120:123], 0
	v_mfma_f32_16x16x32_bf16 v[24:27], v[32:35], v[128:131], 0
	v_mfma_f32_16x16x32_bf16 v[28:31], v[32:35], v[136:139], 0
	v_mfma_f32_16x16x32_bf16 v[0:3], v[36:39], v[84:87], v[0:3]
	v_mfma_f32_16x16x32_bf16 v[4:7], v[36:39], v[92:95], v[4:7]
	v_mfma_f32_16x16x32_bf16 v[8:11], v[36:39], v[100:103], v[8:11]
	v_mfma_f32_16x16x32_bf16 v[12:15], v[36:39], v[108:111], v[12:15]
	v_mfma_f32_16x16x32_bf16 v[16:19], v[36:39], v[148:151], v[16:19]
	v_mfma_f32_16x16x32_bf16 v[20:23], v[36:39], v[124:127], v[20:23]
	v_mfma_f32_16x16x32_bf16 v[24:27], v[36:39], v[132:135], v[24:27]
	v_mfma_f32_16x16x32_bf16 v[28:31], v[36:39], v[228:231], v[28:31]
	s_nop 3
	ds_write2_b32 v237, v0, v4 offset0:0 offset1:16
	ds_write2_b32 v237, v8, v12 offset0:32 offset1:48
	ds_write2_b32 v237, v1, v5 offset0:64 offset1:80
	ds_write2_b32 v237, v9, v13 offset0:96 offset1:112
	ds_write2_b32 v237, v2, v6 offset0:128 offset1:144
	ds_write2_b32 v237, v10, v14 offset0:160 offset1:176
	ds_write2_b32 v237, v3, v7 offset0:192 offset1:208
	ds_write2_b32 v237, v11, v15 offset0:224 offset1:240
	ds_write2_b32 v238, v16, v20 offset0:0 offset1:16
	ds_write2_b32 v238, v24, v28 offset0:32 offset1:48
	ds_write2_b32 v238, v17, v21 offset0:64 offset1:80
	ds_write2_b32 v238, v25, v29 offset0:96 offset1:112
	ds_write2_b32 v238, v18, v22 offset0:128 offset1:144
	ds_write2_b32 v238, v26, v30 offset0:160 offset1:176
	ds_write2_b32 v238, v19, v23 offset0:192 offset1:208
	ds_write2_b32 v238, v27, v31 offset0:224 offset1:240
	s_waitcnt lgkmcnt(0)
	ds_read2st64_b32 v[0:1], v239 offset0:36 offset1:37
	ds_read2st64_b32 v[2:3], v239 offset0:38 offset1:39
	ds_read2st64_b32 v[4:5], v239 offset0:40 offset1:41
	ds_read2st64_b32 v[6:7], v239 offset0:42 offset1:43
	ds_read2st64_b32 v[8:9], v239 offset0:44 offset1:45
	ds_read2st64_b32 v[10:11], v239 offset0:46 offset1:47
	ds_read2st64_b32 v[12:13], v239 offset0:48 offset1:49
	ds_read2st64_b32 v[14:15], v239 offset0:50 offset1:51
	ds_read2st64_b32 v[16:17], v239 offset0:52 offset1:53
	ds_read2st64_b32 v[18:19], v239 offset0:54 offset1:55
	ds_read2st64_b32 v[20:21], v239 offset0:56 offset1:57
	ds_read2st64_b32 v[22:23], v239 offset0:58 offset1:59
	ds_read2st64_b32 v[24:25], v239 offset0:60 offset1:61
	ds_read2st64_b32 v[26:27], v239 offset0:62 offset1:63
	ds_read2st64_b32 v[28:29], v239 offset0:64 offset1:65
	ds_read2st64_b32 v[30:31], v239 offset0:66 offset1:67
	ds_read_u16_d16_hi v48, v240 offset:4608
	ds_read_u16_d16_hi v49, v240 offset:4752
	ds_read_u16_d16_hi v50, v240 offset:4896
	ds_read_u16_d16_hi v51, v240 offset:5040
	ds_read_u16_d16_hi v52, v240 offset:5184
	ds_read_u16_d16_hi v53, v240 offset:5328
	ds_read_u16_d16_hi v54, v240 offset:5472
	ds_read_u16_d16_hi v55, v240 offset:5616
	ds_read_u16_d16_hi v56, v240 offset:5760
	ds_read_u16_d16_hi v57, v240 offset:5904
	ds_read_u16_d16_hi v58, v240 offset:6048
	ds_read_u16_d16_hi v59, v240 offset:6192
	ds_read_u16_d16_hi v60, v240 offset:6336
	ds_read_u16_d16_hi v61, v240 offset:6480
	ds_read_u16_d16_hi v62, v240 offset:6624
	ds_read_u16_d16_hi v63, v240 offset:6768
	s_waitcnt lgkmcnt(0)
; #define LAS __attribute__((address_space(3)))
; #define WAVE_SYNC() asm volatile("s_waitcnt lgkmcnt(0)" ::: "memory")
; __device__ __forceinline__ float sigmoid_f(float x) { return rcpf_(1.f + __expf(-x)); }
; __device__ __forceinline__ float gelu_tanh_f(float x) { const float y = 0.7978845608028654f * (x + 0.044715f * x * x * x); return x * sigmoid_f(2.f * y); }
; __device__ __forceinline__ f32x4 mfma16(bf16x8 a, bf16x8 b, f32x4 c) { return __builtin_amdgcn_mfma_f32_16x16x32_bf16(a, b, c, 0, 0, 0); }
; template <bool FINAL, int D>
; __device__ __forceinline__ void rg_dir(PREF p, int l, int h, int ch, int sidx, int rowbase  , LAS bf16_t* sXc, LAS float* stg, int lane) {
;     ...
;         const bf16x8 A0 = *(const LAS bf16x8*)(sXc + (mt * 16 + (lane & 15)) * 72 + (lane >> 4) * 8), A1 = *(const LAS bf16x8*)(sXc + (mt * 16 + (lane & 15)) * 72 + 32 + (lane >> 4) * 8);
;         f32x4 ar[4], ai[4];
; #pragma unroll
;         for (int nt = 0; nt < 4; ++nt) { const f32x4 z = {0.f, 0.f, 0.f, 0.f};
;             ar[nt] = mfma16(A0, Br[nt][0], z); ar[nt] = mfma16(A1, Br[nt][1], ar[nt]); ai[nt] = mfma16(A0, Bi[nt][0], z); ai[nt] = mfma16(A1, Bi[nt][1], ai[nt]); }
;         WAVE_SYNC();
; #pragma unroll
;         for (int nt = 0; nt < 4; ++nt)
; #pragma unroll
;             for (int j = 0; j < 4; ++j) { const int o = ((lane >> 4) * 4 + j) * 64 + nt * 16 + (lane & 15); stg[o] = ar[nt][j]; stg[1024 + o] = ai[nt][j]; }
;         WAVE_SYNC();
;         float av[16], iv[16];
; #pragma unroll
;         for (int ti = 0; ti < 16; ++ti) { const int tk = D ? 15 - ti : ti;
;             const float zr = stg[tk * 64 + lane] + ba, zi = stg[1024 + tk * 64 + lane] + bi;
;             const float r = sigmoid_f(zr), ig = sigmoid_f(zi);
;             const float a = __builtin_amdgcn_exp2f(r * sp8);
;             const float xc = bf2f(sXc[(mt * 16 + tk) * 72 + lane]);
;             av[ti] = a; iv[ti] = __builtin_amdgcn_sqrtf(fmaxf(1.f - a * a, 0.f)) * ig * xc;
;             if (FINAL && D == 1) grv[ti] = gelu_tanh_f(grv[ti]);
;         }
; #pragma unroll
;         for (int ti = 0; ti < 16; ++ti) { const int tk = D ? 15 - ti : ti;
;             hc = av[ti] * hc + iv[ti]; Ap *= av[ti];
	v_pk_fma_f32 v[0:1], v[0:1], v[248:249], v[242:243]
	v_pk_fma_f32 v[2:3], v[2:3], v[248:249], v[242:243]
	v_pk_fma_f32 v[4:5], v[4:5], v[248:249], v[242:243]
	v_pk_fma_f32 v[6:7], v[6:7], v[248:249], v[242:243]
	v_pk_fma_f32 v[8:9], v[8:9], v[248:249], v[242:243]
	v_pk_fma_f32 v[10:11], v[10:11], v[248:249], v[242:243]
	v_pk_fma_f32 v[12:13], v[12:13], v[248:249], v[242:243]
	v_pk_fma_f32 v[14:15], v[14:15], v[248:249], v[242:243]
	v_pk_fma_f32 v[16:17], v[16:17], v[248:249], v[244:245]
	v_pk_fma_f32 v[18:19], v[18:19], v[248:249], v[244:245]
	v_pk_fma_f32 v[20:21], v[20:21], v[248:249], v[244:245]
	v_pk_fma_f32 v[22:23], v[22:23], v[248:249], v[244:245]
	v_pk_fma_f32 v[24:25], v[24:25], v[248:249], v[244:245]
	v_pk_fma_f32 v[26:27], v[26:27], v[248:249], v[244:245]
	v_pk_fma_f32 v[28:29], v[28:29], v[248:249], v[244:245]
	v_pk_fma_f32 v[30:31], v[30:31], v[248:249], v[244:245]
	v_exp_f32_e32 v0, v0
	v_exp_f32_e32 v1, v1
	v_exp_f32_e32 v2, v2
	v_exp_f32_e32 v3, v3
	v_exp_f32_e32 v4, v4
	v_exp_f32_e32 v5, v5
	v_exp_f32_e32 v6, v6
	v_exp_f32_e32 v7, v7
	v_exp_f32_e32 v8, v8
	v_exp_f32_e32 v9, v9
	v_exp_f32_e32 v10, v10
	v_exp_f32_e32 v11, v11
	v_exp_f32_e32 v12, v12
	v_exp_f32_e32 v13, v13
	v_exp_f32_e32 v14, v14
	v_exp_f32_e32 v15, v15
	v_exp_f32_e32 v16, v16
	v_exp_f32_e32 v17, v17
	v_exp_f32_e32 v18, v18
	v_exp_f32_e32 v19, v19
	v_exp_f32_e32 v20, v20
	v_exp_f32_e32 v21, v21
	v_exp_f32_e32 v22, v22
	v_exp_f32_e32 v23, v23
	v_exp_f32_e32 v24, v24
	v_exp_f32_e32 v25, v25
	v_exp_f32_e32 v26, v26
	v_exp_f32_e32 v27, v27
	v_exp_f32_e32 v28, v28
	v_exp_f32_e32 v29, v29
	v_exp_f32_e32 v30, v30
	v_exp_f32_e32 v31, v31
	v_pk_add_f32 v[0:1], v[0:1], 1.0 op_sel_hi:[1,0]
	v_pk_add_f32 v[2:3], v[2:3], 1.0 op_sel_hi:[1,0]
	v_pk_add_f32 v[4:5], v[4:5], 1.0 op_sel_hi:[1,0]
	v_pk_add_f32 v[6:7], v[6:7], 1.0 op_sel_hi:[1,0]
	v_pk_add_f32 v[8:9], v[8:9], 1.0 op_sel_hi:[1,0]
	v_pk_add_f32 v[10:11], v[10:11], 1.0 op_sel_hi:[1,0]
	v_pk_add_f32 v[12:13], v[12:13], 1.0 op_sel_hi:[1,0]
	v_pk_add_f32 v[14:15], v[14:15], 1.0 op_sel_hi:[1,0]
	v_pk_add_f32 v[16:17], v[16:17], 1.0 op_sel_hi:[1,0]
	v_pk_add_f32 v[18:19], v[18:19], 1.0 op_sel_hi:[1,0]
	v_pk_add_f32 v[20:21], v[20:21], 1.0 op_sel_hi:[1,0]
	v_pk_add_f32 v[22:23], v[22:23], 1.0 op_sel_hi:[1,0]
	v_pk_add_f32 v[24:25], v[24:25], 1.0 op_sel_hi:[1,0]
	v_pk_add_f32 v[26:27], v[26:27], 1.0 op_sel_hi:[1,0]
	v_pk_add_f32 v[28:29], v[28:29], 1.0 op_sel_hi:[1,0]
	v_pk_add_f32 v[30:31], v[30:31], 1.0 op_sel_hi:[1,0]
	v_rcp_f32_e32 v0, v0
	v_rcp_f32_e32 v1, v1
	v_rcp_f32_e32 v2, v2
	v_rcp_f32_e32 v3, v3
	v_rcp_f32_e32 v4, v4
	v_rcp_f32_e32 v5, v5
	v_rcp_f32_e32 v6, v6
	v_rcp_f32_e32 v7, v7
	v_rcp_f32_e32 v8, v8
	v_rcp_f32_e32 v9, v9
	v_rcp_f32_e32 v10, v10
	v_rcp_f32_e32 v11, v11
	v_rcp_f32_e32 v12, v12
	v_rcp_f32_e32 v13, v13
	v_rcp_f32_e32 v14, v14
	v_rcp_f32_e32 v15, v15
	v_rcp_f32_e32 v16, v16
	v_rcp_f32_e32 v17, v17
	v_rcp_f32_e32 v18, v18
	v_rcp_f32_e32 v19, v19
	v_rcp_f32_e32 v20, v20
	v_rcp_f32_e32 v21, v21
	v_rcp_f32_e32 v22, v22
	v_rcp_f32_e32 v23, v23
	v_rcp_f32_e32 v24, v24
	v_rcp_f32_e32 v25, v25
	v_rcp_f32_e32 v26, v26
	v_rcp_f32_e32 v27, v27
	v_rcp_f32_e32 v28, v28
	v_rcp_f32_e32 v29, v29
	v_rcp_f32_e32 v30, v30
	v_rcp_f32_e32 v31, v31
	v_pk_mul_f32 v[0:1], v[246:247], v[0:1]
	v_pk_mul_f32 v[2:3], v[246:247], v[2:3]
	v_pk_mul_f32 v[4:5], v[246:247], v[4:5]
	v_pk_mul_f32 v[6:7], v[246:247], v[6:7]
	v_pk_mul_f32 v[8:9], v[246:247], v[8:9]
	v_pk_mul_f32 v[10:11], v[246:247], v[10:11]
	v_pk_mul_f32 v[12:13], v[246:247], v[12:13]
	v_pk_mul_f32 v[14:15], v[246:247], v[14:15]
	v_exp_f32_e32 v0, v0
	v_exp_f32_e32 v1, v1
	v_exp_f32_e32 v2, v2
	v_exp_f32_e32 v3, v3
	v_exp_f32_e32 v4, v4
	v_exp_f32_e32 v5, v5
	v_exp_f32_e32 v6, v6
	v_exp_f32_e32 v7, v7
	v_exp_f32_e32 v8, v8
	v_exp_f32_e32 v9, v9
	v_exp_f32_e32 v10, v10
	v_exp_f32_e32 v11, v11
	v_exp_f32_e32 v12, v12
	v_exp_f32_e32 v13, v13
	v_exp_f32_e32 v14, v14
	v_exp_f32_e32 v15, v15
	v_fma_f32 v32, -v0, v0, 1.0 clamp
	v_fma_f32 v33, -v1, v1, 1.0 clamp
	v_fma_f32 v34, -v2, v2, 1.0 clamp
	v_fma_f32 v35, -v3, v3, 1.0 clamp
	v_fma_f32 v36, -v4, v4, 1.0 clamp
	v_fma_f32 v37, -v5, v5, 1.0 clamp
	v_fma_f32 v38, -v6, v6, 1.0 clamp
	v_fma_f32 v39, -v7, v7, 1.0 clamp
	v_fma_f32 v40, -v8, v8, 1.0 clamp
	v_fma_f32 v41, -v9, v9, 1.0 clamp
	v_fma_f32 v42, -v10, v10, 1.0 clamp
	v_fma_f32 v43, -v11, v11, 1.0 clamp
	v_fma_f32 v44, -v12, v12, 1.0 clamp
	v_fma_f32 v45, -v13, v13, 1.0 clamp
	v_fma_f32 v46, -v14, v14, 1.0 clamp
	v_fma_f32 v47, -v15, v15, 1.0 clamp
	v_sqrt_f32_e32 v32, v32
	v_sqrt_f32_e32 v33, v33
	v_sqrt_f32_e32 v34, v34
	v_sqrt_f32_e32 v35, v35
	v_sqrt_f32_e32 v36, v36
	v_sqrt_f32_e32 v37, v37
	v_sqrt_f32_e32 v38, v38
	v_sqrt_f32_e32 v39, v39
	v_sqrt_f32_e32 v40, v40
	v_sqrt_f32_e32 v41, v41
	v_sqrt_f32_e32 v42, v42
	v_sqrt_f32_e32 v43, v43
	v_sqrt_f32_e32 v44, v44
	v_sqrt_f32_e32 v45, v45
	v_sqrt_f32_e32 v46, v46
	v_sqrt_f32_e32 v47, v47
	s_nop 0
	v_pk_mul_f32 v[16:17], v[16:17], v[32:33]
	v_pk_mul_f32 v[18:19], v[18:19], v[34:35]
	v_pk_mul_f32 v[20:21], v[20:21], v[36:37]
	v_pk_mul_f32 v[22:23], v[22:23], v[38:39]
	v_pk_mul_f32 v[24:25], v[24:25], v[40:41]
	v_pk_mul_f32 v[26:27], v[26:27], v[42:43]
	v_pk_mul_f32 v[28:29], v[28:29], v[44:45]
	v_pk_mul_f32 v[30:31], v[30:31], v[46:47]
	v_pk_mul_f32 v[16:17], v[16:17], v[48:49]
	v_pk_mul_f32 v[18:19], v[18:19], v[50:51]
	v_pk_mul_f32 v[20:21], v[20:21], v[52:53]
	v_pk_mul_f32 v[22:23], v[22:23], v[54:55]
	v_pk_mul_f32 v[24:25], v[24:25], v[56:57]
	v_pk_mul_f32 v[26:27], v[26:27], v[58:59]
	v_pk_mul_f32 v[28:29], v[28:29], v[60:61]
	v_pk_mul_f32 v[30:31], v[30:31], v[62:63]
	v_fma_f32 v32, v0, v250, v16
	v_mul_f32_e32 v232, v232, v0
	v_fma_f32 v250, v1, v32, v17
	v_mul_f32_e32 v232, v232, v1
	v_fma_f32 v32, v2, v250, v18
	v_mul_f32_e32 v232, v232, v2
	v_fma_f32 v250, v3, v32, v19
	v_mul_f32_e32 v232, v232, v3
	v_fma_f32 v32, v4, v250, v20
	v_mul_f32_e32 v232, v232, v4
	v_fma_f32 v250, v5, v32, v21
	v_mul_f32_e32 v232, v232, v5
	v_fma_f32 v32, v6, v250, v22
	v_mul_f32_e32 v232, v232, v6
	v_fma_f32 v250, v7, v32, v23
	v_mul_f32_e32 v232, v232, v7
	v_fma_f32 v32, v8, v250, v24
	v_mul_f32_e32 v232, v232, v8
	v_fma_f32 v250, v9, v32, v25
	v_mul_f32_e32 v232, v232, v9
	v_fma_f32 v32, v10, v250, v26
	v_mul_f32_e32 v232, v232, v10
	v_fma_f32 v250, v11, v32, v27
	v_mul_f32_e32 v232, v232, v11
	v_fma_f32 v32, v12, v250, v28
	v_mul_f32_e32 v232, v232, v12
	v_fma_f32 v250, v13, v32, v29
	v_mul_f32_e32 v232, v232, v13
	v_fma_f32 v32, v14, v250, v30
	v_mul_f32_e32 v232, v232, v14
	v_fma_f32 v250, v15, v32, v31
	v_mul_f32_e32 v232, v232, v15
	ds_read_b128 v[32:35], v236 offset:6912
	ds_read_b128 v[36:39], v236 offset:6976
	s_waitcnt lgkmcnt(0)
; #define LAS __attribute__((address_space(3)))
; #define WAVE_SYNC() asm volatile("s_waitcnt lgkmcnt(0)" ::: "memory")
; __device__ __forceinline__ f32x4 mfma16(bf16x8 a, bf16x8 b, f32x4 c) { return __builtin_amdgcn_mfma_f32_16x16x32_bf16(a, b, c, 0, 0, 0); }
; template <bool FINAL, int D>
; __device__ __forceinline__ void rg_dir(PREF p, int l, int h, int ch, int sidx, int rowbase  , LAS bf16_t* sXc, LAS float* stg, int lane) {
;     ...
;     for (int nt = 0; nt < 4; ++nt) { const int o0 = (nt * 16 + (lane & 15)) * 64 + (lane >> 4) * 8;
;         Br[nt][0] = *(const bf16x8*)(wr_ + o0); Br[nt][1] = *(const bf16x8*)(wr_ + o0 + 32); Bi[nt][0] = *(const bf16x8*)(wi_ + o0); Bi[nt][1] = *(const bf16x8*)(wi_ + o0 + 32); }
;     ...
;         const bf16x8 A0 = *(const LAS bf16x8*)(sXc + (mt * 16 + (lane & 15)) * 72 + (lane >> 4) * 8), A1 = *(const LAS bf16x8*)(sXc + (mt * 16 + (lane & 15)) * 72 + 32 + (lane >> 4) * 8);
;         f32x4 ar[4], ai[4];
; #pragma unroll
;         for (int nt = 0; nt < 4; ++nt) { const f32x4 z = {0.f, 0.f, 0.f, 0.f};
;             ar[nt] = mfma16(A0, Br[nt][0], z); ar[nt] = mfma16(A1, Br[nt][1], ar[nt]); ai[nt] = mfma16(A0, Bi[nt][0], z); ai[nt] = mfma16(A1, Bi[nt][1], ai[nt]); }
;         WAVE_SYNC();
; #pragma unroll
;         for (int nt = 0; nt < 4; ++nt)
; #pragma unroll
;             for (int j = 0; j < 4; ++j) { const int o = ((lane >> 4) * 4 + j) * 64 + nt * 16 + (lane & 15); stg[o] = ar[nt][j]; stg[1024 + o] = ai[nt][j]; }
;         WAVE_SYNC();
	v_mfma_f32_16x16x32_bf16 v[0:3], v[32:35], v[80:83], 0
	v_mfma_f32_16x16x32_bf16 v[4:7], v[32:35], v[88:91], 0
	v_mfma_f32_16x16x32_bf16 v[8:11], v[32:35], v[96:99], 0
	v_mfma_f32_16x16x32_bf16 v[12:15], v[32:35], v[104:107], 0
	v_mfma_f32_16x16x32_bf16 v[16:19], v[32:35], v[112:115], 0
	v_mfma_f32_16x16x32_bf16 v[20:23], v[32:35], v[120:123], 0
	v_mfma_f32_16x16x32_bf16 v[24:27], v[32:35], v[128:131], 0
	v_mfma_f32_16x16x32_bf16 v[28:31], v[32:35], v[136:139], 0
	v_mfma_f32_16x16x32_bf16 v[0:3], v[36:39], v[84:87], v[0:3]
	v_mfma_f32_16x16x32_bf16 v[4:7], v[36:39], v[92:95], v[4:7]
	v_mfma_f32_16x16x32_bf16 v[8:11], v[36:39], v[100:103], v[8:11]
	v_mfma_f32_16x16x32_bf16 v[12:15], v[36:39], v[108:111], v[12:15]
	v_mfma_f32_16x16x32_bf16 v[16:19], v[36:39], v[148:151], v[16:19]
	v_mfma_f32_16x16x32_bf16 v[20:23], v[36:39], v[124:127], v[20:23]
	v_mfma_f32_16x16x32_bf16 v[24:27], v[36:39], v[132:135], v[24:27]
	v_mfma_f32_16x16x32_bf16 v[28:31], v[36:39], v[228:231], v[28:31]
	s_nop 3
	ds_write2_b32 v237, v0, v4 offset0:0 offset1:16
	ds_write2_b32 v237, v8, v12 offset0:32 offset1:48
	ds_write2_b32 v237, v1, v5 offset0:64 offset1:80
	ds_write2_b32 v237, v9, v13 offset0:96 offset1:112
	ds_write2_b32 v237, v2, v6 offset0:128 offset1:144
	ds_write2_b32 v237, v10, v14 offset0:160 offset1:176
	ds_write2_b32 v237, v3, v7 offset0:192 offset1:208
	ds_write2_b32 v237, v11, v15 offset0:224 offset1:240
	ds_write2_b32 v238, v16, v20 offset0:0 offset1:16
	ds_write2_b32 v238, v24, v28 offset0:32 offset1:48
	ds_write2_b32 v238, v17, v21 offset0:64 offset1:80
	ds_write2_b32 v238, v25, v29 offset0:96 offset1:112
	ds_write2_b32 v238, v18, v22 offset0:128 offset1:144
	ds_write2_b32 v238, v26, v30 offset0:160 offset1:176
	ds_write2_b32 v238, v19, v23 offset0:192 offset1:208
	ds_write2_b32 v238, v27, v31 offset0:224 offset1:240
	s_waitcnt lgkmcnt(0)
	ds_read2st64_b32 v[0:1], v239 offset0:36 offset1:37
	ds_read2st64_b32 v[2:3], v239 offset0:38 offset1:39
	ds_read2st64_b32 v[4:5], v239 offset0:40 offset1:41
	ds_read2st64_b32 v[6:7], v239 offset0:42 offset1:43
	ds_read2st64_b32 v[8:9], v239 offset0:44 offset1:45
	ds_read2st64_b32 v[10:11], v239 offset0:46 offset1:47
	ds_read2st64_b32 v[12:13], v239 offset0:48 offset1:49
	ds_read2st64_b32 v[14:15], v239 offset0:50 offset1:51
	ds_read2st64_b32 v[16:17], v239 offset0:52 offset1:53
	ds_read2st64_b32 v[18:19], v239 offset0:54 offset1:55
	ds_read2st64_b32 v[20:21], v239 offset0:56 offset1:57
	ds_read2st64_b32 v[22:23], v239 offset0:58 offset1:59
	ds_read2st64_b32 v[24:25], v239 offset0:60 offset1:61
	ds_read2st64_b32 v[26:27], v239 offset0:62 offset1:63
	ds_read2st64_b32 v[28:29], v239 offset0:64 offset1:65
	ds_read2st64_b32 v[30:31], v239 offset0:66 offset1:67
	ds_read_u16_d16_hi v48, v240 offset:6912
	ds_read_u16_d16_hi v49, v240 offset:7056
	ds_read_u16_d16_hi v50, v240 offset:7200
	ds_read_u16_d16_hi v51, v240 offset:7344
	ds_read_u16_d16_hi v52, v240 offset:7488
	ds_read_u16_d16_hi v53, v240 offset:7632
	ds_read_u16_d16_hi v54, v240 offset:7776
	ds_read_u16_d16_hi v55, v240 offset:7920
	ds_read_u16_d16_hi v56, v240 offset:8064
	ds_read_u16_d16_hi v57, v240 offset:8208
	ds_read_u16_d16_hi v58, v240 offset:8352
	ds_read_u16_d16_hi v59, v240 offset:8496
	ds_read_u16_d16_hi v60, v240 offset:8640
	ds_read_u16_d16_hi v61, v240 offset:8784
	ds_read_u16_d16_hi v62, v240 offset:8928
	ds_read_u16_d16_hi v63, v240 offset:9072
	s_add_u32 s90, s92, 0x20000
	s_addc_u32 s91, s93, 0
	global_load_dwordx4 v[80:83], v241, s[90:91]
	global_load_dwordx4 v[84:87], v241, s[90:91] offset:64
	global_load_dwordx4 v[88:91], v241, s[90:91] offset:2048
	global_load_dwordx4 v[92:95], v241, s[90:91] offset:2112
	s_add_u32 s90, s92, 0x21000
	s_addc_u32 s91, s93, 0
	global_load_dwordx4 v[96:99], v241, s[90:91]
	global_load_dwordx4 v[100:103], v241, s[90:91] offset:64
	global_load_dwordx4 v[104:107], v241, s[90:91] offset:2048
	global_load_dwordx4 v[108:111], v241, s[90:91] offset:2112
	s_add_u32 s90, s92, 0x30000
	s_addc_u32 s91, s93, 0
	global_load_dwordx4 v[112:115], v241, s[90:91]
	global_load_dwordx4 v[148:151], v241, s[90:91] offset:64
	global_load_dwordx4 v[120:123], v241, s[90:91] offset:2048
	global_load_dwordx4 v[124:127], v241, s[90:91] offset:2112
	s_add_u32 s90, s92, 0x31000
	s_addc_u32 s91, s93, 0
	global_load_dwordx4 v[128:131], v241, s[90:91]
	global_load_dwordx4 v[132:135], v241, s[90:91] offset:64
	global_load_dwordx4 v[136:139], v241, s[90:91] offset:2048
	global_load_dwordx4 v[228:231], v241, s[90:91] offset:2112
	s_waitcnt lgkmcnt(0)
; __device__ __forceinline__ unsigned f2bf(float f) { unsigned r; asm("v_cvt_pk_bf16_f32 %0, %1, %1" : "=v"(r) : "v"(f)); return r & 0xffffu; }
; __device__ __forceinline__ float rcpf_(float x) { return __builtin_amdgcn_rcpf(x); }
; __device__ __forceinline__ float sigmoid_f(float x) { return rcpf_(1.f + __expf(-x)); }
; __device__ __forceinline__ float gelu_tanh_f(float x) { const float y = 0.7978845608028654f * (x + 0.044715f * x * x * x); return x * sigmoid_f(2.f * y); }
; template <bool FINAL, int D>
; __device__ __forceinline__ void rg_dir(PREF p, int l, int h, int ch, int sidx, int rowbase  , LAS bf16_t* sXc, LAS float* stg, int lane) {
;     ...
;     const float ba = p.rg_ba[(l * 2 + D) * 512 + ch], bi = p.rg_bi[(l * 2 + D) * 512 + ch], lam = p.rg_lam[(l * 2 + D) * 512 + ch];
;     const float e_ = __expf(-lam), u_ = 1.f + e_;
;     const float l1p = (u_ == 1.f) ? e_ : __logf(u_) * e_ * rcpf_(u_ - 1.f);
;     ...
;         for (int ti = 0; ti < 16; ++ti) { const int tk = D ? 15 - ti : ti;
;             const float zr = stg[tk * 64 + lane] + ba, zi = stg[1024 + tk * 64 + lane] + bi;
;             const float r = sigmoid_f(zr), ig = sigmoid_f(zi);
;             const float a = __builtin_amdgcn_exp2f(r * sp8);
;             const float xc = bf2f(sXc[(mt * 16 + tk) * 72 + lane]);
;             av[ti] = a; iv[ti] = __builtin_amdgcn_sqrtf(fmaxf(1.f - a * a, 0.f)) * ig * xc;
;             if (FINAL && D == 1) grv[ti] = gelu_tanh_f(grv[ti]);
;         }
; #pragma unroll
;         for (int ti = 0; ti < 16; ++ti) { const int tk = D ? 15 - ti : ti;
;             hc = av[ti] * hc + iv[ti]; Ap *= av[ti];
;             if (FINAL) { const size_t row = (size_t)(rowbase + mt * 16 + tk);
;                 if (D == 0) TMP[row * 512 + ch] = (bf16_t)f2bf(hc);
;                 else MIX[row * DM + ch] = (bf16_t)f2bf(grv[ti] * (hfv[ti] + hc)); }
;         }
;     }
;     if (!FINAL) { RGA[sidx] = Ap; RGH[sidx] = hc; }
	v_pk_fma_f32 v[0:1], v[0:1], v[248:249], v[242:243]
	v_pk_fma_f32 v[2:3], v[2:3], v[248:249], v[242:243]
	v_pk_fma_f32 v[4:5], v[4:5], v[248:249], v[242:243]
	v_pk_fma_f32 v[6:7], v[6:7], v[248:249], v[242:243]
	v_pk_fma_f32 v[8:9], v[8:9], v[248:249], v[242:243]
	v_pk_fma_f32 v[10:11], v[10:11], v[248:249], v[242:243]
	v_pk_fma_f32 v[12:13], v[12:13], v[248:249], v[242:243]
	v_pk_fma_f32 v[14:15], v[14:15], v[248:249], v[242:243]
	v_pk_fma_f32 v[16:17], v[16:17], v[248:249], v[244:245]
	v_pk_fma_f32 v[18:19], v[18:19], v[248:249], v[244:245]
	v_pk_fma_f32 v[20:21], v[20:21], v[248:249], v[244:245]
	v_pk_fma_f32 v[22:23], v[22:23], v[248:249], v[244:245]
	v_pk_fma_f32 v[24:25], v[24:25], v[248:249], v[244:245]
	v_pk_fma_f32 v[26:27], v[26:27], v[248:249], v[244:245]
	v_pk_fma_f32 v[28:29], v[28:29], v[248:249], v[244:245]
	v_pk_fma_f32 v[30:31], v[30:31], v[248:249], v[244:245]
	v_exp_f32_e32 v0, v0
	v_exp_f32_e32 v1, v1
	v_exp_f32_e32 v2, v2
	v_exp_f32_e32 v3, v3
	v_exp_f32_e32 v4, v4
	v_exp_f32_e32 v5, v5
	v_exp_f32_e32 v6, v6
	v_exp_f32_e32 v7, v7
	v_exp_f32_e32 v8, v8
	v_exp_f32_e32 v9, v9
	v_exp_f32_e32 v10, v10
	v_exp_f32_e32 v11, v11
	v_exp_f32_e32 v12, v12
	v_exp_f32_e32 v13, v13
	v_exp_f32_e32 v14, v14
	v_exp_f32_e32 v15, v15
	v_exp_f32_e32 v16, v16
	v_exp_f32_e32 v17, v17
	v_exp_f32_e32 v18, v18
	v_exp_f32_e32 v19, v19
	v_exp_f32_e32 v20, v20
	v_exp_f32_e32 v21, v21
	v_exp_f32_e32 v22, v22
	v_exp_f32_e32 v23, v23
	v_exp_f32_e32 v24, v24
	v_exp_f32_e32 v25, v25
	v_exp_f32_e32 v26, v26
	v_exp_f32_e32 v27, v27
	v_exp_f32_e32 v28, v28
	v_exp_f32_e32 v29, v29
	v_exp_f32_e32 v30, v30
	v_exp_f32_e32 v31, v31
	v_pk_add_f32 v[0:1], v[0:1], 1.0 op_sel_hi:[1,0]
	v_pk_add_f32 v[2:3], v[2:3], 1.0 op_sel_hi:[1,0]
	v_pk_add_f32 v[4:5], v[4:5], 1.0 op_sel_hi:[1,0]
	v_pk_add_f32 v[6:7], v[6:7], 1.0 op_sel_hi:[1,0]
	v_pk_add_f32 v[8:9], v[8:9], 1.0 op_sel_hi:[1,0]
	v_pk_add_f32 v[10:11], v[10:11], 1.0 op_sel_hi:[1,0]
	v_pk_add_f32 v[12:13], v[12:13], 1.0 op_sel_hi:[1,0]
	v_pk_add_f32 v[14:15], v[14:15], 1.0 op_sel_hi:[1,0]
	v_pk_add_f32 v[16:17], v[16:17], 1.0 op_sel_hi:[1,0]
	v_pk_add_f32 v[18:19], v[18:19], 1.0 op_sel_hi:[1,0]
	v_pk_add_f32 v[20:21], v[20:21], 1.0 op_sel_hi:[1,0]
	v_pk_add_f32 v[22:23], v[22:23], 1.0 op_sel_hi:[1,0]
	v_pk_add_f32 v[24:25], v[24:25], 1.0 op_sel_hi:[1,0]
	v_pk_add_f32 v[26:27], v[26:27], 1.0 op_sel_hi:[1,0]
	v_pk_add_f32 v[28:29], v[28:29], 1.0 op_sel_hi:[1,0]
	v_pk_add_f32 v[30:31], v[30:31], 1.0 op_sel_hi:[1,0]
	v_rcp_f32_e32 v0, v0
	v_rcp_f32_e32 v1, v1
	v_rcp_f32_e32 v2, v2
	v_rcp_f32_e32 v3, v3
	v_rcp_f32_e32 v4, v4
	v_rcp_f32_e32 v5, v5
	v_rcp_f32_e32 v6, v6
	v_rcp_f32_e32 v7, v7
	v_rcp_f32_e32 v8, v8
	v_rcp_f32_e32 v9, v9
	v_rcp_f32_e32 v10, v10
	v_rcp_f32_e32 v11, v11
	v_rcp_f32_e32 v12, v12
	v_rcp_f32_e32 v13, v13
	v_rcp_f32_e32 v14, v14
	v_rcp_f32_e32 v15, v15
	v_rcp_f32_e32 v16, v16
	v_rcp_f32_e32 v17, v17
	v_rcp_f32_e32 v18, v18
	v_rcp_f32_e32 v19, v19
	v_rcp_f32_e32 v20, v20
	v_rcp_f32_e32 v21, v21
	v_rcp_f32_e32 v22, v22
	v_rcp_f32_e32 v23, v23
	v_rcp_f32_e32 v24, v24
	v_rcp_f32_e32 v25, v25
	v_rcp_f32_e32 v26, v26
	v_rcp_f32_e32 v27, v27
	v_rcp_f32_e32 v28, v28
	v_rcp_f32_e32 v29, v29
	v_rcp_f32_e32 v30, v30
	v_rcp_f32_e32 v31, v31
	v_pk_mul_f32 v[0:1], v[246:247], v[0:1]
	v_pk_mul_f32 v[2:3], v[246:247], v[2:3]
	v_pk_mul_f32 v[4:5], v[246:247], v[4:5]
	v_pk_mul_f32 v[6:7], v[246:247], v[6:7]
	v_pk_mul_f32 v[8:9], v[246:247], v[8:9]
	v_pk_mul_f32 v[10:11], v[246:247], v[10:11]
	v_pk_mul_f32 v[12:13], v[246:247], v[12:13]
	v_pk_mul_f32 v[14:15], v[246:247], v[14:15]
	v_exp_f32_e32 v0, v0
	v_exp_f32_e32 v1, v1
	v_exp_f32_e32 v2, v2
	v_exp_f32_e32 v3, v3
	v_exp_f32_e32 v4, v4
	v_exp_f32_e32 v5, v5
	v_exp_f32_e32 v6, v6
	v_exp_f32_e32 v7, v7
	v_exp_f32_e32 v8, v8
	v_exp_f32_e32 v9, v9
	v_exp_f32_e32 v10, v10
	v_exp_f32_e32 v11, v11
	v_exp_f32_e32 v12, v12
	v_exp_f32_e32 v13, v13
	v_exp_f32_e32 v14, v14
	v_exp_f32_e32 v15, v15
	v_fma_f32 v32, -v0, v0, 1.0 clamp
	v_fma_f32 v33, -v1, v1, 1.0 clamp
	v_fma_f32 v34, -v2, v2, 1.0 clamp
	v_fma_f32 v35, -v3, v3, 1.0 clamp
	v_fma_f32 v36, -v4, v4, 1.0 clamp
	v_fma_f32 v37, -v5, v5, 1.0 clamp
	v_fma_f32 v38, -v6, v6, 1.0 clamp
	v_fma_f32 v39, -v7, v7, 1.0 clamp
	v_fma_f32 v40, -v8, v8, 1.0 clamp
	v_fma_f32 v41, -v9, v9, 1.0 clamp
	v_fma_f32 v42, -v10, v10, 1.0 clamp
	v_fma_f32 v43, -v11, v11, 1.0 clamp
	v_fma_f32 v44, -v12, v12, 1.0 clamp
	v_fma_f32 v45, -v13, v13, 1.0 clamp
	v_fma_f32 v46, -v14, v14, 1.0 clamp
	v_fma_f32 v47, -v15, v15, 1.0 clamp
	v_sqrt_f32_e32 v32, v32
	v_sqrt_f32_e32 v33, v33
	v_sqrt_f32_e32 v34, v34
	v_sqrt_f32_e32 v35, v35
	v_sqrt_f32_e32 v36, v36
	v_sqrt_f32_e32 v37, v37
	v_sqrt_f32_e32 v38, v38
	v_sqrt_f32_e32 v39, v39
	v_sqrt_f32_e32 v40, v40
	v_sqrt_f32_e32 v41, v41
	v_sqrt_f32_e32 v42, v42
	v_sqrt_f32_e32 v43, v43
	v_sqrt_f32_e32 v44, v44
	v_sqrt_f32_e32 v45, v45
	v_sqrt_f32_e32 v46, v46
	v_sqrt_f32_e32 v47, v47
	s_nop 0
	v_pk_mul_f32 v[16:17], v[16:17], v[32:33]
	v_pk_mul_f32 v[18:19], v[18:19], v[34:35]
	v_pk_mul_f32 v[20:21], v[20:21], v[36:37]
	v_pk_mul_f32 v[22:23], v[22:23], v[38:39]
	v_pk_mul_f32 v[24:25], v[24:25], v[40:41]
	v_pk_mul_f32 v[26:27], v[26:27], v[42:43]
	v_pk_mul_f32 v[28:29], v[28:29], v[44:45]
	v_pk_mul_f32 v[30:31], v[30:31], v[46:47]
	v_pk_mul_f32 v[16:17], v[16:17], v[48:49]
	v_pk_mul_f32 v[18:19], v[18:19], v[50:51]
	v_pk_mul_f32 v[20:21], v[20:21], v[52:53]
	v_pk_mul_f32 v[22:23], v[22:23], v[54:55]
	v_pk_mul_f32 v[24:25], v[24:25], v[56:57]
	v_pk_mul_f32 v[26:27], v[26:27], v[58:59]
	v_pk_mul_f32 v[28:29], v[28:29], v[60:61]
	v_pk_mul_f32 v[30:31], v[30:31], v[62:63]
	v_fma_f32 v32, v0, v250, v16
	v_mul_f32_e32 v232, v232, v0
	v_fma_f32 v250, v1, v32, v17
	v_mul_f32_e32 v232, v232, v1
	v_fma_f32 v32, v2, v250, v18
	v_mul_f32_e32 v232, v232, v2
	v_fma_f32 v250, v3, v32, v19
	v_mul_f32_e32 v232, v232, v3
	v_fma_f32 v32, v4, v250, v20
	v_mul_f32_e32 v232, v232, v4
	v_fma_f32 v250, v5, v32, v21
	v_mul_f32_e32 v232, v232, v5
	v_fma_f32 v32, v6, v250, v22
	v_mul_f32_e32 v232, v232, v6
	v_fma_f32 v250, v7, v32, v23
	v_mul_f32_e32 v232, v232, v7
	v_fma_f32 v32, v8, v250, v24
	v_mul_f32_e32 v232, v232, v8
	v_fma_f32 v250, v9, v32, v25
	v_mul_f32_e32 v232, v232, v9
	v_fma_f32 v32, v10, v250, v26
	v_mul_f32_e32 v232, v232, v10
	v_fma_f32 v250, v11, v32, v27
	v_mul_f32_e32 v232, v232, v11
	v_fma_f32 v32, v12, v250, v28
	v_mul_f32_e32 v232, v232, v12
	v_fma_f32 v250, v13, v32, v29
	v_mul_f32_e32 v232, v232, v13
	v_fma_f32 v32, v14, v250, v30
	v_mul_f32_e32 v232, v232, v14
	v_fma_f32 v250, v15, v32, v31
	v_mul_f32_e32 v232, v232, v15
	s_add_u32 s96, s0, 0x400000
	s_addc_u32 s97, s1, 0
	s_add_u32 s96, s96, s36
	s_addc_u32 s97, s97, 0
	global_store_dword v235, v232, s[96:97]
	s_add_u32 s96, s96, 0x300000
	s_addc_u32 s97, s97, 0
	global_store_dword v235, v250, s[96:97]
	global_load_dword v45, v235, s[76:77] offset:2048
	global_load_dword v46, v235, s[78:79] offset:2048
	global_load_dword v47, v235, s[80:81] offset:2048
	s_waitcnt vmcnt(0)
; #define LAS __attribute__((address_space(3)))
; #define WAVE_SYNC() asm volatile("s_waitcnt lgkmcnt(0)" ::: "memory")
; __device__ __forceinline__ float rcpf_(float x) { return __builtin_amdgcn_rcpf(x); }
; __device__ __forceinline__ f32x4 mfma16(bf16x8 a, bf16x8 b, f32x4 c) { return __builtin_amdgcn_mfma_f32_16x16x32_bf16(a, b, c, 0, 0, 0); }
; template <bool FINAL, int D>
; __device__ __forceinline__ void rg_dir(PREF p, int l, int h, int ch, int sidx, int rowbase  , LAS bf16_t* sXc, LAS float* stg, int lane) {
;     ...
;     const float ba = p.rg_ba[(l * 2 + D) * 512 + ch], bi = p.rg_bi[(l * 2 + D) * 512 + ch], lam = p.rg_lam[(l * 2 + D) * 512 + ch];
;     const float e_ = __expf(-lam), u_ = 1.f + e_;
;     const float l1p = (u_ == 1.f) ? e_ : __logf(u_) * e_ * rcpf_(u_ - 1.f);
;     const float sp8 = -8.f * 1.4426950408889634f * l1p;
;     float hc = FINAL ? RGC[sidx] : 0.f, Ap = 1.f;
;     ...
;         const bf16x8 A0 = *(const LAS bf16x8*)(sXc + (mt * 16 + (lane & 15)) * 72 + (lane >> 4) * 8), A1 = *(const LAS bf16x8*)(sXc + (mt * 16 + (lane & 15)) * 72 + 32 + (lane >> 4) * 8);
;         f32x4 ar[4], ai[4];
; #pragma unroll
;         for (int nt = 0; nt < 4; ++nt) { const f32x4 z = {0.f, 0.f, 0.f, 0.f};
;             ar[nt] = mfma16(A0, Br[nt][0], z); ar[nt] = mfma16(A1, Br[nt][1], ar[nt]); ai[nt] = mfma16(A0, Bi[nt][0], z); ai[nt] = mfma16(A1, Bi[nt][1], ai[nt]); }
;         WAVE_SYNC();
; #pragma unroll
;         for (int nt = 0; nt < 4; ++nt)
; #pragma unroll
;             for (int j = 0; j < 4; ++j) { const int o = ((lane >> 4) * 4 + j) * 64 + nt * 16 + (lane & 15); stg[o] = ar[nt][j]; stg[1024 + o] = ai[nt][j]; }
;         WAVE_SYNC();
	s_mov_b32 s8, 0x800000
	s_mov_b32 s9, 0x3f317217
	s_mov_b32 s14, 0x7f800000
	v_mul_f32_e32 v32, 0xbfb8aa3b, v45
	v_exp_f32_e32 v32, v32
	s_nop 0
	v_add_f32_e32 v33, 1.0, v32
	v_cmp_gt_f32_e32 vcc, s8, v33
	s_nop 1
	v_cndmask_b32_e64 v34, 0, 32, vcc
	v_ldexp_f32 v34, v33, v34
	v_log_f32_e32 v34, v34
	v_cndmask_b32_e32 v36, 0, v226, vcc
	v_cmp_eq_f32_e32 vcc, 1.0, v33
	v_mul_f32_e32 v35, 0x3f317217, v34
	v_fma_f32 v35, v34, s9, -v35
	v_fmac_f32_e32 v35, 0x3377d1cf, v34
	v_fmac_f32_e32 v35, 0x3f317217, v34
	v_cmp_lt_f32_e64 s[10:11], |v34|, s14
	s_nop 1
	v_cndmask_b32_e64 v34, v34, v35, s[10:11]
	v_add_f32_e32 v35, -1.0, v33
	v_rcp_f32_e32 v35, v35
	v_sub_f32_e32 v34, v34, v36
	v_mul_f32_e32 v34, v32, v34
	v_mul_f32_e32 v34, v34, v35
	v_cndmask_b32_e32 v32, v34, v32, vcc
	v_mul_f32_e32 v246, 0xc138aa3b, v32
	v_mov_b32_e32 v247, v246
	v_mul_f32_e32 v242, 0xbfb8aa3b, v46
	v_mul_f32_e32 v244, 0xbfb8aa3b, v47
	v_mov_b32_e32 v243, v242
	v_mov_b32_e32 v245, v244
	v_mov_b32_e32 v250, 0
	v_mov_b32_e32 v232, 1.0
	ds_read_b128 v[32:35], v236 offset:6912
	ds_read_b128 v[36:39], v236 offset:6976
	s_waitcnt lgkmcnt(0)
	v_mfma_f32_16x16x32_bf16 v[0:3], v[32:35], v[80:83], 0
	v_mfma_f32_16x16x32_bf16 v[4:7], v[32:35], v[88:91], 0
	v_mfma_f32_16x16x32_bf16 v[8:11], v[32:35], v[96:99], 0
	v_mfma_f32_16x16x32_bf16 v[12:15], v[32:35], v[104:107], 0
	v_mfma_f32_16x16x32_bf16 v[16:19], v[32:35], v[112:115], 0
	v_mfma_f32_16x16x32_bf16 v[20:23], v[32:35], v[120:123], 0
	v_mfma_f32_16x16x32_bf16 v[24:27], v[32:35], v[128:131], 0
	v_mfma_f32_16x16x32_bf16 v[28:31], v[32:35], v[136:139], 0
	v_mfma_f32_16x16x32_bf16 v[0:3], v[36:39], v[84:87], v[0:3]
	v_mfma_f32_16x16x32_bf16 v[4:7], v[36:39], v[92:95], v[4:7]
	v_mfma_f32_16x16x32_bf16 v[8:11], v[36:39], v[100:103], v[8:11]
	v_mfma_f32_16x16x32_bf16 v[12:15], v[36:39], v[108:111], v[12:15]
	v_mfma_f32_16x16x32_bf16 v[16:19], v[36:39], v[148:151], v[16:19]
	v_mfma_f32_16x16x32_bf16 v[20:23], v[36:39], v[124:127], v[20:23]
	v_mfma_f32_16x16x32_bf16 v[24:27], v[36:39], v[132:135], v[24:27]
	v_mfma_f32_16x16x32_bf16 v[28:31], v[36:39], v[228:231], v[28:31]
	s_nop 3
	ds_write2_b32 v237, v0, v4 offset0:0 offset1:16
	ds_write2_b32 v237, v8, v12 offset0:32 offset1:48
	ds_write2_b32 v237, v1, v5 offset0:64 offset1:80
	ds_write2_b32 v237, v9, v13 offset0:96 offset1:112
	ds_write2_b32 v237, v2, v6 offset0:128 offset1:144
	ds_write2_b32 v237, v10, v14 offset0:160 offset1:176
	ds_write2_b32 v237, v3, v7 offset0:192 offset1:208
	ds_write2_b32 v237, v11, v15 offset0:224 offset1:240
	ds_write2_b32 v238, v16, v20 offset0:0 offset1:16
	ds_write2_b32 v238, v24, v28 offset0:32 offset1:48
	ds_write2_b32 v238, v17, v21 offset0:64 offset1:80
	ds_write2_b32 v238, v25, v29 offset0:96 offset1:112
	ds_write2_b32 v238, v18, v22 offset0:128 offset1:144
	ds_write2_b32 v238, v26, v30 offset0:160 offset1:176
	ds_write2_b32 v238, v19, v23 offset0:192 offset1:208
	ds_write2_b32 v238, v27, v31 offset0:224 offset1:240
	s_waitcnt lgkmcnt(0)
	ds_read2st64_b32 v[0:1], v239 offset0:36 offset1:37
	ds_read2st64_b32 v[2:3], v239 offset0:38 offset1:39
	ds_read2st64_b32 v[4:5], v239 offset0:40 offset1:41
	ds_read2st64_b32 v[6:7], v239 offset0:42 offset1:43
	ds_read2st64_b32 v[8:9], v239 offset0:44 offset1:45
	ds_read2st64_b32 v[10:11], v239 offset0:46 offset1:47
	ds_read2st64_b32 v[12:13], v239 offset0:48 offset1:49
	ds_read2st64_b32 v[14:15], v239 offset0:50 offset1:51
	ds_read2st64_b32 v[16:17], v239 offset0:52 offset1:53
	ds_read2st64_b32 v[18:19], v239 offset0:54 offset1:55
	ds_read2st64_b32 v[20:21], v239 offset0:56 offset1:57
	ds_read2st64_b32 v[22:23], v239 offset0:58 offset1:59
	ds_read2st64_b32 v[24:25], v239 offset0:60 offset1:61
	ds_read2st64_b32 v[26:27], v239 offset0:62 offset1:63
	ds_read2st64_b32 v[28:29], v239 offset0:64 offset1:65
	ds_read2st64_b32 v[30:31], v239 offset0:66 offset1:67
	ds_read_u16_d16_hi v48, v240 offset:6912
	ds_read_u16_d16_hi v49, v240 offset:7056
	ds_read_u16_d16_hi v50, v240 offset:7200
	ds_read_u16_d16_hi v51, v240 offset:7344
	ds_read_u16_d16_hi v52, v240 offset:7488
	ds_read_u16_d16_hi v53, v240 offset:7632
	ds_read_u16_d16_hi v54, v240 offset:7776
	ds_read_u16_d16_hi v55, v240 offset:7920
	ds_read_u16_d16_hi v56, v240 offset:8064
	ds_read_u16_d16_hi v57, v240 offset:8208
	ds_read_u16_d16_hi v58, v240 offset:8352
	ds_read_u16_d16_hi v59, v240 offset:8496
	ds_read_u16_d16_hi v60, v240 offset:8640
	ds_read_u16_d16_hi v61, v240 offset:8784
	ds_read_u16_d16_hi v62, v240 offset:8928
	ds_read_u16_d16_hi v63, v240 offset:9072
	s_waitcnt lgkmcnt(0)
; __device__ __forceinline__ float sigmoid_f(float x) { return rcpf_(1.f + __expf(-x)); }
; __device__ __forceinline__ float gelu_tanh_f(float x) { const float y = 0.7978845608028654f * (x + 0.044715f * x * x * x); return x * sigmoid_f(2.f * y); }
; template <bool FINAL, int D>
; __device__ __forceinline__ void rg_dir(PREF p, int l, int h, int ch, int sidx, int rowbase  , LAS bf16_t* sXc, LAS float* stg, int lane) {
;     ...
;         for (int ti = 0; ti < 16; ++ti) { const int tk = D ? 15 - ti : ti;
;             const float zr = stg[tk * 64 + lane] + ba, zi = stg[1024 + tk * 64 + lane] + bi;
;             const float r = sigmoid_f(zr), ig = sigmoid_f(zi);
;             const float a = __builtin_amdgcn_exp2f(r * sp8);
;             const float xc = bf2f(sXc[(mt * 16 + tk) * 72 + lane]);
;             av[ti] = a; iv[ti] = __builtin_amdgcn_sqrtf(fmaxf(1.f - a * a, 0.f)) * ig * xc;
;             if (FINAL && D == 1) grv[ti] = gelu_tanh_f(grv[ti]);
;         }
; #pragma unroll
;         for (int ti = 0; ti < 16; ++ti) { const int tk = D ? 15 - ti : ti;
;             hc = av[ti] * hc + iv[ti]; Ap *= av[ti];
	v_pk_fma_f32 v[0:1], v[0:1], v[248:249], v[242:243]
	v_pk_fma_f32 v[2:3], v[2:3], v[248:249], v[242:243]
	v_pk_fma_f32 v[4:5], v[4:5], v[248:249], v[242:243]
	v_pk_fma_f32 v[6:7], v[6:7], v[248:249], v[242:243]
	v_pk_fma_f32 v[8:9], v[8:9], v[248:249], v[242:243]
	v_pk_fma_f32 v[10:11], v[10:11], v[248:249], v[242:243]
	v_pk_fma_f32 v[12:13], v[12:13], v[248:249], v[242:243]
	v_pk_fma_f32 v[14:15], v[14:15], v[248:249], v[242:243]
	v_pk_fma_f32 v[16:17], v[16:17], v[248:249], v[244:245]
	v_pk_fma_f32 v[18:19], v[18:19], v[248:249], v[244:245]
	v_pk_fma_f32 v[20:21], v[20:21], v[248:249], v[244:245]
	v_pk_fma_f32 v[22:23], v[22:23], v[248:249], v[244:245]
	v_pk_fma_f32 v[24:25], v[24:25], v[248:249], v[244:245]
	v_pk_fma_f32 v[26:27], v[26:27], v[248:249], v[244:245]
	v_pk_fma_f32 v[28:29], v[28:29], v[248:249], v[244:245]
	v_pk_fma_f32 v[30:31], v[30:31], v[248:249], v[244:245]
	v_exp_f32_e32 v0, v0
	v_exp_f32_e32 v1, v1
	v_exp_f32_e32 v2, v2
	v_exp_f32_e32 v3, v3
	v_exp_f32_e32 v4, v4
	v_exp_f32_e32 v5, v5
	v_exp_f32_e32 v6, v6
	v_exp_f32_e32 v7, v7
	v_exp_f32_e32 v8, v8
	v_exp_f32_e32 v9, v9
	v_exp_f32_e32 v10, v10
	v_exp_f32_e32 v11, v11
	v_exp_f32_e32 v12, v12
	v_exp_f32_e32 v13, v13
	v_exp_f32_e32 v14, v14
	v_exp_f32_e32 v15, v15
	v_exp_f32_e32 v16, v16
	v_exp_f32_e32 v17, v17
	v_exp_f32_e32 v18, v18
	v_exp_f32_e32 v19, v19
	v_exp_f32_e32 v20, v20
	v_exp_f32_e32 v21, v21
	v_exp_f32_e32 v22, v22
	v_exp_f32_e32 v23, v23
	v_exp_f32_e32 v24, v24
	v_exp_f32_e32 v25, v25
	v_exp_f32_e32 v26, v26
	v_exp_f32_e32 v27, v27
	v_exp_f32_e32 v28, v28
	v_exp_f32_e32 v29, v29
	v_exp_f32_e32 v30, v30
	v_exp_f32_e32 v31, v31
	v_pk_add_f32 v[0:1], v[0:1], 1.0 op_sel_hi:[1,0]
	v_pk_add_f32 v[2:3], v[2:3], 1.0 op_sel_hi:[1,0]
	v_pk_add_f32 v[4:5], v[4:5], 1.0 op_sel_hi:[1,0]
	v_pk_add_f32 v[6:7], v[6:7], 1.0 op_sel_hi:[1,0]
	v_pk_add_f32 v[8:9], v[8:9], 1.0 op_sel_hi:[1,0]
	v_pk_add_f32 v[10:11], v[10:11], 1.0 op_sel_hi:[1,0]
	v_pk_add_f32 v[12:13], v[12:13], 1.0 op_sel_hi:[1,0]
	v_pk_add_f32 v[14:15], v[14:15], 1.0 op_sel_hi:[1,0]
	v_pk_add_f32 v[16:17], v[16:17], 1.0 op_sel_hi:[1,0]
	v_pk_add_f32 v[18:19], v[18:19], 1.0 op_sel_hi:[1,0]
	v_pk_add_f32 v[20:21], v[20:21], 1.0 op_sel_hi:[1,0]
	v_pk_add_f32 v[22:23], v[22:23], 1.0 op_sel_hi:[1,0]
	v_pk_add_f32 v[24:25], v[24:25], 1.0 op_sel_hi:[1,0]
	v_pk_add_f32 v[26:27], v[26:27], 1.0 op_sel_hi:[1,0]
	v_pk_add_f32 v[28:29], v[28:29], 1.0 op_sel_hi:[1,0]
	v_pk_add_f32 v[30:31], v[30:31], 1.0 op_sel_hi:[1,0]
	v_rcp_f32_e32 v0, v0
	v_rcp_f32_e32 v1, v1
	v_rcp_f32_e32 v2, v2
	v_rcp_f32_e32 v3, v3
	v_rcp_f32_e32 v4, v4
	v_rcp_f32_e32 v5, v5
	v_rcp_f32_e32 v6, v6
	v_rcp_f32_e32 v7, v7
	v_rcp_f32_e32 v8, v8
	v_rcp_f32_e32 v9, v9
	v_rcp_f32_e32 v10, v10
	v_rcp_f32_e32 v11, v11
	v_rcp_f32_e32 v12, v12
	v_rcp_f32_e32 v13, v13
	v_rcp_f32_e32 v14, v14
	v_rcp_f32_e32 v15, v15
	v_rcp_f32_e32 v16, v16
	v_rcp_f32_e32 v17, v17
	v_rcp_f32_e32 v18, v18
	v_rcp_f32_e32 v19, v19
	v_rcp_f32_e32 v20, v20
	v_rcp_f32_e32 v21, v21
	v_rcp_f32_e32 v22, v22
	v_rcp_f32_e32 v23, v23
	v_rcp_f32_e32 v24, v24
	v_rcp_f32_e32 v25, v25
	v_rcp_f32_e32 v26, v26
	v_rcp_f32_e32 v27, v27
	v_rcp_f32_e32 v28, v28
	v_rcp_f32_e32 v29, v29
	v_rcp_f32_e32 v30, v30
	v_rcp_f32_e32 v31, v31
	v_pk_mul_f32 v[0:1], v[246:247], v[0:1]
	v_pk_mul_f32 v[2:3], v[246:247], v[2:3]
	v_pk_mul_f32 v[4:5], v[246:247], v[4:5]
	v_pk_mul_f32 v[6:7], v[246:247], v[6:7]
	v_pk_mul_f32 v[8:9], v[246:247], v[8:9]
	v_pk_mul_f32 v[10:11], v[246:247], v[10:11]
	v_pk_mul_f32 v[12:13], v[246:247], v[12:13]
	v_pk_mul_f32 v[14:15], v[246:247], v[14:15]
	v_exp_f32_e32 v0, v0
	v_exp_f32_e32 v1, v1
	v_exp_f32_e32 v2, v2
	v_exp_f32_e32 v3, v3
	v_exp_f32_e32 v4, v4
	v_exp_f32_e32 v5, v5
	v_exp_f32_e32 v6, v6
	v_exp_f32_e32 v7, v7
	v_exp_f32_e32 v8, v8
	v_exp_f32_e32 v9, v9
	v_exp_f32_e32 v10, v10
	v_exp_f32_e32 v11, v11
	v_exp_f32_e32 v12, v12
	v_exp_f32_e32 v13, v13
	v_exp_f32_e32 v14, v14
	v_exp_f32_e32 v15, v15
	v_fma_f32 v32, -v0, v0, 1.0 clamp
	v_fma_f32 v33, -v1, v1, 1.0 clamp
	v_fma_f32 v34, -v2, v2, 1.0 clamp
	v_fma_f32 v35, -v3, v3, 1.0 clamp
	v_fma_f32 v36, -v4, v4, 1.0 clamp
	v_fma_f32 v37, -v5, v5, 1.0 clamp
	v_fma_f32 v38, -v6, v6, 1.0 clamp
	v_fma_f32 v39, -v7, v7, 1.0 clamp
	v_fma_f32 v40, -v8, v8, 1.0 clamp
	v_fma_f32 v41, -v9, v9, 1.0 clamp
	v_fma_f32 v42, -v10, v10, 1.0 clamp
	v_fma_f32 v43, -v11, v11, 1.0 clamp
	v_fma_f32 v44, -v12, v12, 1.0 clamp
	v_fma_f32 v45, -v13, v13, 1.0 clamp
	v_fma_f32 v46, -v14, v14, 1.0 clamp
	v_fma_f32 v47, -v15, v15, 1.0 clamp
	v_sqrt_f32_e32 v32, v32
	v_sqrt_f32_e32 v33, v33
	v_sqrt_f32_e32 v34, v34
	v_sqrt_f32_e32 v35, v35
	v_sqrt_f32_e32 v36, v36
	v_sqrt_f32_e32 v37, v37
	v_sqrt_f32_e32 v38, v38
	v_sqrt_f32_e32 v39, v39
	v_sqrt_f32_e32 v40, v40
	v_sqrt_f32_e32 v41, v41
	v_sqrt_f32_e32 v42, v42
	v_sqrt_f32_e32 v43, v43
	v_sqrt_f32_e32 v44, v44
	v_sqrt_f32_e32 v45, v45
	v_sqrt_f32_e32 v46, v46
	v_sqrt_f32_e32 v47, v47
	s_nop 0
	v_pk_mul_f32 v[16:17], v[16:17], v[32:33]
	v_pk_mul_f32 v[18:19], v[18:19], v[34:35]
	v_pk_mul_f32 v[20:21], v[20:21], v[36:37]
	v_pk_mul_f32 v[22:23], v[22:23], v[38:39]
	v_pk_mul_f32 v[24:25], v[24:25], v[40:41]
	v_pk_mul_f32 v[26:27], v[26:27], v[42:43]
	v_pk_mul_f32 v[28:29], v[28:29], v[44:45]
	v_pk_mul_f32 v[30:31], v[30:31], v[46:47]
	v_pk_mul_f32 v[16:17], v[16:17], v[48:49]
	v_pk_mul_f32 v[18:19], v[18:19], v[50:51]
	v_pk_mul_f32 v[20:21], v[20:21], v[52:53]
	v_pk_mul_f32 v[22:23], v[22:23], v[54:55]
	v_pk_mul_f32 v[24:25], v[24:25], v[56:57]
	v_pk_mul_f32 v[26:27], v[26:27], v[58:59]
	v_pk_mul_f32 v[28:29], v[28:29], v[60:61]
	v_pk_mul_f32 v[30:31], v[30:31], v[62:63]
	v_fma_f32 v250, v15, v250, v31
	v_mul_f32_e32 v232, v232, v15
	v_fma_f32 v250, v14, v250, v30
	v_mul_f32_e32 v232, v232, v14
	v_fma_f32 v250, v13, v250, v29
	v_mul_f32_e32 v232, v232, v13
	v_fma_f32 v250, v12, v250, v28
	v_mul_f32_e32 v232, v232, v12
	v_fma_f32 v250, v11, v250, v27
	v_mul_f32_e32 v232, v232, v11
	v_fma_f32 v250, v10, v250, v26
	v_mul_f32_e32 v232, v232, v10
	v_fma_f32 v250, v9, v250, v25
	v_mul_f32_e32 v232, v232, v9
	v_fma_f32 v250, v8, v250, v24
	v_mul_f32_e32 v232, v232, v8
	v_fma_f32 v250, v7, v250, v23
	v_mul_f32_e32 v232, v232, v7
	v_fma_f32 v250, v6, v250, v22
	v_mul_f32_e32 v232, v232, v6
	v_fma_f32 v250, v5, v250, v21
	v_mul_f32_e32 v232, v232, v5
	v_fma_f32 v250, v4, v250, v20
	v_mul_f32_e32 v232, v232, v4
	v_fma_f32 v250, v3, v250, v19
	v_mul_f32_e32 v232, v232, v3
	v_fma_f32 v250, v2, v250, v18
	v_mul_f32_e32 v232, v232, v2
	v_fma_f32 v250, v1, v250, v17
	v_mul_f32_e32 v232, v232, v1
	v_fma_f32 v250, v0, v250, v16
	v_mul_f32_e32 v232, v232, v0
	ds_read_b128 v[32:35], v236 offset:4608
	ds_read_b128 v[36:39], v236 offset:4672
	s_waitcnt lgkmcnt(0)
; #define LAS __attribute__((address_space(3)))
; #define WAVE_SYNC() asm volatile("s_waitcnt lgkmcnt(0)" ::: "memory")
; __device__ __forceinline__ float sigmoid_f(float x) { return rcpf_(1.f + __expf(-x)); }
; __device__ __forceinline__ f32x4 mfma16(bf16x8 a, bf16x8 b, f32x4 c) { return __builtin_amdgcn_mfma_f32_16x16x32_bf16(a, b, c, 0, 0, 0); }
; template <bool FINAL, int D>
; __device__ __forceinline__ void rg_dir(PREF p, int l, int h, int ch, int sidx, int rowbase  , LAS bf16_t* sXc, LAS float* stg, int lane) {
;     ...
;         const bf16x8 A0 = *(const LAS bf16x8*)(sXc + (mt * 16 + (lane & 15)) * 72 + (lane >> 4) * 8), A1 = *(const LAS bf16x8*)(sXc + (mt * 16 + (lane & 15)) * 72 + 32 + (lane >> 4) * 8);
;         f32x4 ar[4], ai[4];
; #pragma unroll
;         for (int nt = 0; nt < 4; ++nt) { const f32x4 z = {0.f, 0.f, 0.f, 0.f};
;             ar[nt] = mfma16(A0, Br[nt][0], z); ar[nt] = mfma16(A1, Br[nt][1], ar[nt]); ai[nt] = mfma16(A0, Bi[nt][0], z); ai[nt] = mfma16(A1, Bi[nt][1], ai[nt]); }
;         WAVE_SYNC();
; #pragma unroll
;         for (int nt = 0; nt < 4; ++nt)
; #pragma unroll
;             for (int j = 0; j < 4; ++j) { const int o = ((lane >> 4) * 4 + j) * 64 + nt * 16 + (lane & 15); stg[o] = ar[nt][j]; stg[1024 + o] = ai[nt][j]; }
;         WAVE_SYNC();
;         float av[16], iv[16];
; #pragma unroll
;         for (int ti = 0; ti < 16; ++ti) { const int tk = D ? 15 - ti : ti;
;             const float zr = stg[tk * 64 + lane] + ba, zi = stg[1024 + tk * 64 + lane] + bi;
;             const float r = sigmoid_f(zr), ig = sigmoid_f(zi);
	v_mfma_f32_16x16x32_bf16 v[0:3], v[32:35], v[80:83], 0
	v_mfma_f32_16x16x32_bf16 v[4:7], v[32:35], v[88:91], 0
	v_mfma_f32_16x16x32_bf16 v[8:11], v[32:35], v[96:99], 0
	v_mfma_f32_16x16x32_bf16 v[12:15], v[32:35], v[104:107], 0
	v_mfma_f32_16x16x32_bf16 v[16:19], v[32:35], v[112:115], 0
	v_mfma_f32_16x16x32_bf16 v[20:23], v[32:35], v[120:123], 0
	v_mfma_f32_16x16x32_bf16 v[24:27], v[32:35], v[128:131], 0
	v_mfma_f32_16x16x32_bf16 v[28:31], v[32:35], v[136:139], 0
	v_mfma_f32_16x16x32_bf16 v[0:3], v[36:39], v[84:87], v[0:3]
	v_mfma_f32_16x16x32_bf16 v[4:7], v[36:39], v[92:95], v[4:7]
	v_mfma_f32_16x16x32_bf16 v[8:11], v[36:39], v[100:103], v[8:11]
	v_mfma_f32_16x16x32_bf16 v[12:15], v[36:39], v[108:111], v[12:15]
	v_mfma_f32_16x16x32_bf16 v[16:19], v[36:39], v[148:151], v[16:19]
	v_mfma_f32_16x16x32_bf16 v[20:23], v[36:39], v[124:127], v[20:23]
	v_mfma_f32_16x16x32_bf16 v[24:27], v[36:39], v[132:135], v[24:27]
	v_mfma_f32_16x16x32_bf16 v[28:31], v[36:39], v[228:231], v[28:31]
	s_nop 3
	ds_write2_b32 v237, v0, v4 offset0:0 offset1:16
	ds_write2_b32 v237, v8, v12 offset0:32 offset1:48
	ds_write2_b32 v237, v1, v5 offset0:64 offset1:80
	ds_write2_b32 v237, v9, v13 offset0:96 offset1:112
	ds_write2_b32 v237, v2, v6 offset0:128 offset1:144
	ds_write2_b32 v237, v10, v14 offset0:160 offset1:176
	ds_write2_b32 v237, v3, v7 offset0:192 offset1:208
	ds_write2_b32 v237, v11, v15 offset0:224 offset1:240
	ds_write2_b32 v238, v16, v20 offset0:0 offset1:16
	ds_write2_b32 v238, v24, v28 offset0:32 offset1:48
	ds_write2_b32 v238, v17, v21 offset0:64 offset1:80
	ds_write2_b32 v238, v25, v29 offset0:96 offset1:112
	ds_write2_b32 v238, v18, v22 offset0:128 offset1:144
	ds_write2_b32 v238, v26, v30 offset0:160 offset1:176
	ds_write2_b32 v238, v19, v23 offset0:192 offset1:208
	ds_write2_b32 v238, v27, v31 offset0:224 offset1:240
	s_waitcnt lgkmcnt(0)
	ds_read2st64_b32 v[0:1], v239 offset0:36 offset1:37
	ds_read2st64_b32 v[2:3], v239 offset0:38 offset1:39
	ds_read2st64_b32 v[4:5], v239 offset0:40 offset1:41
	ds_read2st64_b32 v[6:7], v239 offset0:42 offset1:43
	ds_read2st64_b32 v[8:9], v239 offset0:44 offset1:45
	ds_read2st64_b32 v[10:11], v239 offset0:46 offset1:47
	ds_read2st64_b32 v[12:13], v239 offset0:48 offset1:49
	ds_read2st64_b32 v[14:15], v239 offset0:50 offset1:51
	ds_read2st64_b32 v[16:17], v239 offset0:52 offset1:53
	ds_read2st64_b32 v[18:19], v239 offset0:54 offset1:55
	ds_read2st64_b32 v[20:21], v239 offset0:56 offset1:57
	ds_read2st64_b32 v[22:23], v239 offset0:58 offset1:59
	ds_read2st64_b32 v[24:25], v239 offset0:60 offset1:61
	ds_read2st64_b32 v[26:27], v239 offset0:62 offset1:63
	ds_read2st64_b32 v[28:29], v239 offset0:64 offset1:65
	ds_read2st64_b32 v[30:31], v239 offset0:66 offset1:67
	ds_read_u16_d16_hi v48, v240 offset:4608
	ds_read_u16_d16_hi v49, v240 offset:4752
	ds_read_u16_d16_hi v50, v240 offset:4896
	ds_read_u16_d16_hi v51, v240 offset:5040
	ds_read_u16_d16_hi v52, v240 offset:5184
	ds_read_u16_d16_hi v53, v240 offset:5328
	ds_read_u16_d16_hi v54, v240 offset:5472
	ds_read_u16_d16_hi v55, v240 offset:5616
	ds_read_u16_d16_hi v56, v240 offset:5760
	ds_read_u16_d16_hi v57, v240 offset:5904
	ds_read_u16_d16_hi v58, v240 offset:6048
	ds_read_u16_d16_hi v59, v240 offset:6192
	ds_read_u16_d16_hi v60, v240 offset:6336
	ds_read_u16_d16_hi v61, v240 offset:6480
	ds_read_u16_d16_hi v62, v240 offset:6624
	ds_read_u16_d16_hi v63, v240 offset:6768
	s_waitcnt lgkmcnt(0)
	v_pk_fma_f32 v[0:1], v[0:1], v[248:249], v[242:243]
	v_pk_fma_f32 v[2:3], v[2:3], v[248:249], v[242:243]
	v_pk_fma_f32 v[4:5], v[4:5], v[248:249], v[242:243]
	v_pk_fma_f32 v[6:7], v[6:7], v[248:249], v[242:243]
	v_pk_fma_f32 v[8:9], v[8:9], v[248:249], v[242:243]
	v_pk_fma_f32 v[10:11], v[10:11], v[248:249], v[242:243]
	v_pk_fma_f32 v[12:13], v[12:13], v[248:249], v[242:243]
	v_pk_fma_f32 v[14:15], v[14:15], v[248:249], v[242:243]
	v_pk_fma_f32 v[16:17], v[16:17], v[248:249], v[244:245]
	v_pk_fma_f32 v[18:19], v[18:19], v[248:249], v[244:245]
	v_pk_fma_f32 v[20:21], v[20:21], v[248:249], v[244:245]
	v_pk_fma_f32 v[22:23], v[22:23], v[248:249], v[244:245]
	v_pk_fma_f32 v[24:25], v[24:25], v[248:249], v[244:245]
	v_pk_fma_f32 v[26:27], v[26:27], v[248:249], v[244:245]
	v_pk_fma_f32 v[28:29], v[28:29], v[248:249], v[244:245]
	v_pk_fma_f32 v[30:31], v[30:31], v[248:249], v[244:245]
	v_exp_f32_e32 v0, v0
	v_exp_f32_e32 v1, v1
	v_exp_f32_e32 v2, v2
	v_exp_f32_e32 v3, v3
	v_exp_f32_e32 v4, v4
	v_exp_f32_e32 v5, v5
	v_exp_f32_e32 v6, v6
	v_exp_f32_e32 v7, v7
	v_exp_f32_e32 v8, v8
	v_exp_f32_e32 v9, v9
	v_exp_f32_e32 v10, v10
	v_exp_f32_e32 v11, v11
	v_exp_f32_e32 v12, v12
	v_exp_f32_e32 v13, v13
	v_exp_f32_e32 v14, v14
	v_exp_f32_e32 v15, v15
	v_exp_f32_e32 v16, v16
	v_exp_f32_e32 v17, v17
	v_exp_f32_e32 v18, v18
	v_exp_f32_e32 v19, v19
	v_exp_f32_e32 v20, v20
	v_exp_f32_e32 v21, v21
	v_exp_f32_e32 v22, v22
	v_exp_f32_e32 v23, v23
	v_exp_f32_e32 v24, v24
	v_exp_f32_e32 v25, v25
	v_exp_f32_e32 v26, v26
	v_exp_f32_e32 v27, v27
	v_exp_f32_e32 v28, v28
	v_exp_f32_e32 v29, v29
	v_exp_f32_e32 v30, v30
	v_exp_f32_e32 v31, v31
	v_pk_add_f32 v[0:1], v[0:1], 1.0 op_sel_hi:[1,0]
	v_pk_add_f32 v[2:3], v[2:3], 1.0 op_sel_hi:[1,0]
	v_pk_add_f32 v[4:5], v[4:5], 1.0 op_sel_hi:[1,0]
	v_pk_add_f32 v[6:7], v[6:7], 1.0 op_sel_hi:[1,0]
	v_pk_add_f32 v[8:9], v[8:9], 1.0 op_sel_hi:[1,0]
	v_pk_add_f32 v[10:11], v[10:11], 1.0 op_sel_hi:[1,0]
	v_pk_add_f32 v[12:13], v[12:13], 1.0 op_sel_hi:[1,0]
	v_pk_add_f32 v[14:15], v[14:15], 1.0 op_sel_hi:[1,0]
	v_pk_add_f32 v[16:17], v[16:17], 1.0 op_sel_hi:[1,0]
	v_pk_add_f32 v[18:19], v[18:19], 1.0 op_sel_hi:[1,0]
	v_pk_add_f32 v[20:21], v[20:21], 1.0 op_sel_hi:[1,0]
; #define LAS __attribute__((address_space(3)))
; #define WAVE_SYNC() asm volatile("s_waitcnt lgkmcnt(0)" ::: "memory")
; __device__ __forceinline__ float sigmoid_f(float x) { return rcpf_(1.f + __expf(-x)); }
; __device__ __forceinline__ float gelu_tanh_f(float x) { const float y = 0.7978845608028654f * (x + 0.044715f * x * x * x); return x * sigmoid_f(2.f * y); }
; __device__ __forceinline__ f32x4 mfma16(bf16x8 a, bf16x8 b, f32x4 c) { return __builtin_amdgcn_mfma_f32_16x16x32_bf16(a, b, c, 0, 0, 0); }
; template <bool FINAL, int D>
; __device__ __forceinline__ void rg_dir(PREF p, int l, int h, int ch, int sidx, int rowbase  , LAS bf16_t* sXc, LAS float* stg, int lane) {
;     ...
;         const bf16x8 A0 = *(const LAS bf16x8*)(sXc + (mt * 16 + (lane & 15)) * 72 + (lane >> 4) * 8), A1 = *(const LAS bf16x8*)(sXc + (mt * 16 + (lane & 15)) * 72 + 32 + (lane >> 4) * 8);
;         f32x4 ar[4], ai[4];
; #pragma unroll
;         for (int nt = 0; nt < 4; ++nt) { const f32x4 z = {0.f, 0.f, 0.f, 0.f};
;             ar[nt] = mfma16(A0, Br[nt][0], z); ar[nt] = mfma16(A1, Br[nt][1], ar[nt]); ai[nt] = mfma16(A0, Bi[nt][0], z); ai[nt] = mfma16(A1, Bi[nt][1], ai[nt]); }
;         WAVE_SYNC();
; #pragma unroll
;         for (int nt = 0; nt < 4; ++nt)
; #pragma unroll
;             for (int j = 0; j < 4; ++j) { const int o = ((lane >> 4) * 4 + j) * 64 + nt * 16 + (lane & 15); stg[o] = ar[nt][j]; stg[1024 + o] = ai[nt][j]; }
;     ...
;         for (int ti = 0; ti < 16; ++ti) { const int tk = D ? 15 - ti : ti;
;             const float zr = stg[tk * 64 + lane] + ba, zi = stg[1024 + tk * 64 + lane] + bi;
;             const float r = sigmoid_f(zr), ig = sigmoid_f(zi);
;             const float a = __builtin_amdgcn_exp2f(r * sp8);
;             const float xc = bf2f(sXc[(mt * 16 + tk) * 72 + lane]);
;             av[ti] = a; iv[ti] = __builtin_amdgcn_sqrtf(fmaxf(1.f - a * a, 0.f)) * ig * xc;
;             if (FINAL && D == 1) grv[ti] = gelu_tanh_f(grv[ti]);
;         }
; #pragma unroll
;         for (int ti = 0; ti < 16; ++ti) { const int tk = D ? 15 - ti : ti;
;             hc = av[ti] * hc + iv[ti]; Ap *= av[ti];
	v_pk_add_f32 v[22:23], v[22:23], 1.0 op_sel_hi:[1,0]
	v_pk_add_f32 v[24:25], v[24:25], 1.0 op_sel_hi:[1,0]
	v_pk_add_f32 v[26:27], v[26:27], 1.0 op_sel_hi:[1,0]
	v_pk_add_f32 v[28:29], v[28:29], 1.0 op_sel_hi:[1,0]
	v_pk_add_f32 v[30:31], v[30:31], 1.0 op_sel_hi:[1,0]
	v_rcp_f32_e32 v0, v0
	v_rcp_f32_e32 v1, v1
	v_rcp_f32_e32 v2, v2
	v_rcp_f32_e32 v3, v3
	v_rcp_f32_e32 v4, v4
	v_rcp_f32_e32 v5, v5
	v_rcp_f32_e32 v6, v6
	v_rcp_f32_e32 v7, v7
	v_rcp_f32_e32 v8, v8
	v_rcp_f32_e32 v9, v9
	v_rcp_f32_e32 v10, v10
	v_rcp_f32_e32 v11, v11
	v_rcp_f32_e32 v12, v12
	v_rcp_f32_e32 v13, v13
	v_rcp_f32_e32 v14, v14
	v_rcp_f32_e32 v15, v15
	v_rcp_f32_e32 v16, v16
	v_rcp_f32_e32 v17, v17
	v_rcp_f32_e32 v18, v18
	v_rcp_f32_e32 v19, v19
	v_rcp_f32_e32 v20, v20
	v_rcp_f32_e32 v21, v21
	v_rcp_f32_e32 v22, v22
	v_rcp_f32_e32 v23, v23
	v_rcp_f32_e32 v24, v24
	v_rcp_f32_e32 v25, v25
	v_rcp_f32_e32 v26, v26
	v_rcp_f32_e32 v27, v27
	v_rcp_f32_e32 v28, v28
	v_rcp_f32_e32 v29, v29
	v_rcp_f32_e32 v30, v30
	v_rcp_f32_e32 v31, v31
	v_pk_mul_f32 v[0:1], v[246:247], v[0:1]
	v_pk_mul_f32 v[2:3], v[246:247], v[2:3]
	v_pk_mul_f32 v[4:5], v[246:247], v[4:5]
	v_pk_mul_f32 v[6:7], v[246:247], v[6:7]
	v_pk_mul_f32 v[8:9], v[246:247], v[8:9]
	v_pk_mul_f32 v[10:11], v[246:247], v[10:11]
	v_pk_mul_f32 v[12:13], v[246:247], v[12:13]
	v_pk_mul_f32 v[14:15], v[246:247], v[14:15]
	v_exp_f32_e32 v0, v0
	v_exp_f32_e32 v1, v1
	v_exp_f32_e32 v2, v2
	v_exp_f32_e32 v3, v3
	v_exp_f32_e32 v4, v4
	v_exp_f32_e32 v5, v5
	v_exp_f32_e32 v6, v6
	v_exp_f32_e32 v7, v7
	v_exp_f32_e32 v8, v8
	v_exp_f32_e32 v9, v9
	v_exp_f32_e32 v10, v10
	v_exp_f32_e32 v11, v11
	v_exp_f32_e32 v12, v12
	v_exp_f32_e32 v13, v13
	v_exp_f32_e32 v14, v14
	v_exp_f32_e32 v15, v15
	v_fma_f32 v32, -v0, v0, 1.0 clamp
	v_fma_f32 v33, -v1, v1, 1.0 clamp
	v_fma_f32 v34, -v2, v2, 1.0 clamp
	v_fma_f32 v35, -v3, v3, 1.0 clamp
	v_fma_f32 v36, -v4, v4, 1.0 clamp
	v_fma_f32 v37, -v5, v5, 1.0 clamp
	v_fma_f32 v38, -v6, v6, 1.0 clamp
	v_fma_f32 v39, -v7, v7, 1.0 clamp
	v_fma_f32 v40, -v8, v8, 1.0 clamp
	v_fma_f32 v41, -v9, v9, 1.0 clamp
	v_fma_f32 v42, -v10, v10, 1.0 clamp
	v_fma_f32 v43, -v11, v11, 1.0 clamp
	v_fma_f32 v44, -v12, v12, 1.0 clamp
	v_fma_f32 v45, -v13, v13, 1.0 clamp
	v_fma_f32 v46, -v14, v14, 1.0 clamp
	v_fma_f32 v47, -v15, v15, 1.0 clamp
	v_sqrt_f32_e32 v32, v32
	v_sqrt_f32_e32 v33, v33
	v_sqrt_f32_e32 v34, v34
	v_sqrt_f32_e32 v35, v35
	v_sqrt_f32_e32 v36, v36
	v_sqrt_f32_e32 v37, v37
	v_sqrt_f32_e32 v38, v38
	v_sqrt_f32_e32 v39, v39
	v_sqrt_f32_e32 v40, v40
	v_sqrt_f32_e32 v41, v41
	v_sqrt_f32_e32 v42, v42
	v_sqrt_f32_e32 v43, v43
	v_sqrt_f32_e32 v44, v44
	v_sqrt_f32_e32 v45, v45
	v_sqrt_f32_e32 v46, v46
	v_sqrt_f32_e32 v47, v47
	s_nop 0
	v_pk_mul_f32 v[16:17], v[16:17], v[32:33]
	v_pk_mul_f32 v[18:19], v[18:19], v[34:35]
	v_pk_mul_f32 v[20:21], v[20:21], v[36:37]
	v_pk_mul_f32 v[22:23], v[22:23], v[38:39]
	v_pk_mul_f32 v[24:25], v[24:25], v[40:41]
	v_pk_mul_f32 v[26:27], v[26:27], v[42:43]
	v_pk_mul_f32 v[28:29], v[28:29], v[44:45]
	v_pk_mul_f32 v[30:31], v[30:31], v[46:47]
	v_pk_mul_f32 v[16:17], v[16:17], v[48:49]
	v_pk_mul_f32 v[18:19], v[18:19], v[50:51]
	v_pk_mul_f32 v[20:21], v[20:21], v[52:53]
	v_pk_mul_f32 v[22:23], v[22:23], v[54:55]
	v_pk_mul_f32 v[24:25], v[24:25], v[56:57]
	v_pk_mul_f32 v[26:27], v[26:27], v[58:59]
	v_pk_mul_f32 v[28:29], v[28:29], v[60:61]
	v_pk_mul_f32 v[30:31], v[30:31], v[62:63]
	v_fma_f32 v250, v15, v250, v31
	v_mul_f32_e32 v232, v232, v15
	v_fma_f32 v250, v14, v250, v30
	v_mul_f32_e32 v232, v232, v14
	v_fma_f32 v250, v13, v250, v29
	v_mul_f32_e32 v232, v232, v13
	v_fma_f32 v250, v12, v250, v28
	v_mul_f32_e32 v232, v232, v12
	v_fma_f32 v250, v11, v250, v27
	v_mul_f32_e32 v232, v232, v11
	v_fma_f32 v250, v10, v250, v26
	v_mul_f32_e32 v232, v232, v10
	v_fma_f32 v250, v9, v250, v25
	v_mul_f32_e32 v232, v232, v9
	v_fma_f32 v250, v8, v250, v24
	v_mul_f32_e32 v232, v232, v8
	v_fma_f32 v250, v7, v250, v23
	v_mul_f32_e32 v232, v232, v7
	v_fma_f32 v250, v6, v250, v22
	v_mul_f32_e32 v232, v232, v6
	v_fma_f32 v250, v5, v250, v21
	v_mul_f32_e32 v232, v232, v5
	v_fma_f32 v250, v4, v250, v20
	v_mul_f32_e32 v232, v232, v4
	v_fma_f32 v250, v3, v250, v19
	v_mul_f32_e32 v232, v232, v3
	v_fma_f32 v250, v2, v250, v18
	v_mul_f32_e32 v232, v232, v2
	v_fma_f32 v250, v1, v250, v17
	v_mul_f32_e32 v232, v232, v1
	v_fma_f32 v250, v0, v250, v16
	v_mul_f32_e32 v232, v232, v0
	ds_read_b128 v[32:35], v236 offset:2304
	ds_read_b128 v[36:39], v236 offset:2368
	s_waitcnt lgkmcnt(0)
	v_mfma_f32_16x16x32_bf16 v[0:3], v[32:35], v[80:83], 0
	v_mfma_f32_16x16x32_bf16 v[4:7], v[32:35], v[88:91], 0
	v_mfma_f32_16x16x32_bf16 v[8:11], v[32:35], v[96:99], 0
	v_mfma_f32_16x16x32_bf16 v[12:15], v[32:35], v[104:107], 0
	v_mfma_f32_16x16x32_bf16 v[16:19], v[32:35], v[112:115], 0
	v_mfma_f32_16x16x32_bf16 v[20:23], v[32:35], v[120:123], 0
	v_mfma_f32_16x16x32_bf16 v[24:27], v[32:35], v[128:131], 0
	v_mfma_f32_16x16x32_bf16 v[28:31], v[32:35], v[136:139], 0
	v_mfma_f32_16x16x32_bf16 v[0:3], v[36:39], v[84:87], v[0:3]
	v_mfma_f32_16x16x32_bf16 v[4:7], v[36:39], v[92:95], v[4:7]
	v_mfma_f32_16x16x32_bf16 v[8:11], v[36:39], v[100:103], v[8:11]
	v_mfma_f32_16x16x32_bf16 v[12:15], v[36:39], v[108:111], v[12:15]
	v_mfma_f32_16x16x32_bf16 v[16:19], v[36:39], v[148:151], v[16:19]
	v_mfma_f32_16x16x32_bf16 v[20:23], v[36:39], v[124:127], v[20:23]
	v_mfma_f32_16x16x32_bf16 v[24:27], v[36:39], v[132:135], v[24:27]
	v_mfma_f32_16x16x32_bf16 v[28:31], v[36:39], v[228:231], v[28:31]
	s_nop 3
	ds_write2_b32 v237, v0, v4 offset0:0 offset1:16
	ds_write2_b32 v237, v8, v12 offset0:32 offset1:48
	ds_write2_b32 v237, v1, v5 offset0:64 offset1:80
	ds_write2_b32 v237, v9, v13 offset0:96 offset1:112
	ds_write2_b32 v237, v2, v6 offset0:128 offset1:144
	ds_write2_b32 v237, v10, v14 offset0:160 offset1:176
	ds_write2_b32 v237, v3, v7 offset0:192 offset1:208
	ds_write2_b32 v237, v11, v15 offset0:224 offset1:240
	ds_write2_b32 v238, v16, v20 offset0:0 offset1:16
	ds_write2_b32 v238, v24, v28 offset0:32 offset1:48
	ds_write2_b32 v238, v17, v21 offset0:64 offset1:80
	ds_write2_b32 v238, v25, v29 offset0:96 offset1:112
	ds_write2_b32 v238, v18, v22 offset0:128 offset1:144
	ds_write2_b32 v238, v26, v30 offset0:160 offset1:176
	ds_write2_b32 v238, v19, v23 offset0:192 offset1:208
	ds_write2_b32 v238, v27, v31 offset0:224 offset1:240
	s_waitcnt lgkmcnt(0)
; __device__ __forceinline__ float sigmoid_f(float x) { return rcpf_(1.f + __expf(-x)); }
; template <bool FINAL, int D>
; __device__ __forceinline__ void rg_dir(PREF p, int l, int h, int ch, int sidx, int rowbase  , LAS bf16_t* sXc, LAS float* stg, int lane) {
;     ...
;         float av[16], iv[16];
; #pragma unroll
;         for (int ti = 0; ti < 16; ++ti) { const int tk = D ? 15 - ti : ti;
;             const float zr = stg[tk * 64 + lane] + ba, zi = stg[1024 + tk * 64 + lane] + bi;
;             const float r = sigmoid_f(zr), ig = sigmoid_f(zi);
;             const float a = __builtin_amdgcn_exp2f(r * sp8);
;             const float xc = bf2f(sXc[(mt * 16 + tk) * 72 + lane]);
;             av[ti] = a; iv[ti] = __builtin_amdgcn_sqrtf(fmaxf(1.f - a * a, 0.f)) * ig * xc;
	ds_read2st64_b32 v[0:1], v239 offset0:36 offset1:37
	ds_read2st64_b32 v[2:3], v239 offset0:38 offset1:39
	ds_read2st64_b32 v[4:5], v239 offset0:40 offset1:41
	ds_read2st64_b32 v[6:7], v239 offset0:42 offset1:43
	ds_read2st64_b32 v[8:9], v239 offset0:44 offset1:45
	ds_read2st64_b32 v[10:11], v239 offset0:46 offset1:47
	ds_read2st64_b32 v[12:13], v239 offset0:48 offset1:49
	ds_read2st64_b32 v[14:15], v239 offset0:50 offset1:51
	ds_read2st64_b32 v[16:17], v239 offset0:52 offset1:53
	ds_read2st64_b32 v[18:19], v239 offset0:54 offset1:55
	ds_read2st64_b32 v[20:21], v239 offset0:56 offset1:57
	ds_read2st64_b32 v[22:23], v239 offset0:58 offset1:59
	ds_read2st64_b32 v[24:25], v239 offset0:60 offset1:61
	ds_read2st64_b32 v[26:27], v239 offset0:62 offset1:63
	ds_read2st64_b32 v[28:29], v239 offset0:64 offset1:65
	ds_read2st64_b32 v[30:31], v239 offset0:66 offset1:67
	ds_read_u16_d16_hi v48, v240 offset:2304
	ds_read_u16_d16_hi v49, v240 offset:2448
	ds_read_u16_d16_hi v50, v240 offset:2592
	ds_read_u16_d16_hi v51, v240 offset:2736
	ds_read_u16_d16_hi v52, v240 offset:2880
	ds_read_u16_d16_hi v53, v240 offset:3024
	ds_read_u16_d16_hi v54, v240 offset:3168
	ds_read_u16_d16_hi v55, v240 offset:3312
	ds_read_u16_d16_hi v56, v240 offset:3456
	ds_read_u16_d16_hi v57, v240 offset:3600
	ds_read_u16_d16_hi v58, v240 offset:3744
	ds_read_u16_d16_hi v59, v240 offset:3888
	ds_read_u16_d16_hi v60, v240 offset:4032
	ds_read_u16_d16_hi v61, v240 offset:4176
	ds_read_u16_d16_hi v62, v240 offset:4320
	ds_read_u16_d16_hi v63, v240 offset:4464
	s_waitcnt lgkmcnt(0)
	v_pk_fma_f32 v[0:1], v[0:1], v[248:249], v[242:243]
	v_pk_fma_f32 v[2:3], v[2:3], v[248:249], v[242:243]
	v_pk_fma_f32 v[4:5], v[4:5], v[248:249], v[242:243]
	v_pk_fma_f32 v[6:7], v[6:7], v[248:249], v[242:243]
	v_pk_fma_f32 v[8:9], v[8:9], v[248:249], v[242:243]
	v_pk_fma_f32 v[10:11], v[10:11], v[248:249], v[242:243]
	v_pk_fma_f32 v[12:13], v[12:13], v[248:249], v[242:243]
	v_pk_fma_f32 v[14:15], v[14:15], v[248:249], v[242:243]
	v_pk_fma_f32 v[16:17], v[16:17], v[248:249], v[244:245]
	v_pk_fma_f32 v[18:19], v[18:19], v[248:249], v[244:245]
	v_pk_fma_f32 v[20:21], v[20:21], v[248:249], v[244:245]
	v_pk_fma_f32 v[22:23], v[22:23], v[248:249], v[244:245]
	v_pk_fma_f32 v[24:25], v[24:25], v[248:249], v[244:245]
	v_pk_fma_f32 v[26:27], v[26:27], v[248:249], v[244:245]
	v_pk_fma_f32 v[28:29], v[28:29], v[248:249], v[244:245]
	v_pk_fma_f32 v[30:31], v[30:31], v[248:249], v[244:245]
	v_exp_f32_e32 v0, v0
	v_exp_f32_e32 v1, v1
	v_exp_f32_e32 v2, v2
	v_exp_f32_e32 v3, v3
	v_exp_f32_e32 v4, v4
	v_exp_f32_e32 v5, v5
	v_exp_f32_e32 v6, v6
	v_exp_f32_e32 v7, v7
	v_exp_f32_e32 v8, v8
	v_exp_f32_e32 v9, v9
	v_exp_f32_e32 v10, v10
	v_exp_f32_e32 v11, v11
	v_exp_f32_e32 v12, v12
	v_exp_f32_e32 v13, v13
	v_exp_f32_e32 v14, v14
	v_exp_f32_e32 v15, v15
	v_exp_f32_e32 v16, v16
	v_exp_f32_e32 v17, v17
	v_exp_f32_e32 v18, v18
	v_exp_f32_e32 v19, v19
	v_exp_f32_e32 v20, v20
	v_exp_f32_e32 v21, v21
	v_exp_f32_e32 v22, v22
	v_exp_f32_e32 v23, v23
	v_exp_f32_e32 v24, v24
	v_exp_f32_e32 v25, v25
	v_exp_f32_e32 v26, v26
	v_exp_f32_e32 v27, v27
	v_exp_f32_e32 v28, v28
	v_exp_f32_e32 v29, v29
	v_exp_f32_e32 v30, v30
	v_exp_f32_e32 v31, v31
	v_pk_add_f32 v[0:1], v[0:1], 1.0 op_sel_hi:[1,0]
	v_pk_add_f32 v[2:3], v[2:3], 1.0 op_sel_hi:[1,0]
	v_pk_add_f32 v[4:5], v[4:5], 1.0 op_sel_hi:[1,0]
	v_pk_add_f32 v[6:7], v[6:7], 1.0 op_sel_hi:[1,0]
	v_pk_add_f32 v[8:9], v[8:9], 1.0 op_sel_hi:[1,0]
	v_pk_add_f32 v[10:11], v[10:11], 1.0 op_sel_hi:[1,0]
	v_pk_add_f32 v[12:13], v[12:13], 1.0 op_sel_hi:[1,0]
	v_pk_add_f32 v[14:15], v[14:15], 1.0 op_sel_hi:[1,0]
	v_pk_add_f32 v[16:17], v[16:17], 1.0 op_sel_hi:[1,0]
	v_pk_add_f32 v[18:19], v[18:19], 1.0 op_sel_hi:[1,0]
	v_pk_add_f32 v[20:21], v[20:21], 1.0 op_sel_hi:[1,0]
	v_pk_add_f32 v[22:23], v[22:23], 1.0 op_sel_hi:[1,0]
	v_pk_add_f32 v[24:25], v[24:25], 1.0 op_sel_hi:[1,0]
	v_pk_add_f32 v[26:27], v[26:27], 1.0 op_sel_hi:[1,0]
	v_pk_add_f32 v[28:29], v[28:29], 1.0 op_sel_hi:[1,0]
	v_pk_add_f32 v[30:31], v[30:31], 1.0 op_sel_hi:[1,0]
	v_rcp_f32_e32 v0, v0
	v_rcp_f32_e32 v1, v1
	v_rcp_f32_e32 v2, v2
	v_rcp_f32_e32 v3, v3
	v_rcp_f32_e32 v4, v4
	v_rcp_f32_e32 v5, v5
	v_rcp_f32_e32 v6, v6
	v_rcp_f32_e32 v7, v7
	v_rcp_f32_e32 v8, v8
	v_rcp_f32_e32 v9, v9
	v_rcp_f32_e32 v10, v10
	v_rcp_f32_e32 v11, v11
	v_rcp_f32_e32 v12, v12
	v_rcp_f32_e32 v13, v13
	v_rcp_f32_e32 v14, v14
	v_rcp_f32_e32 v15, v15
	v_rcp_f32_e32 v16, v16
	v_rcp_f32_e32 v17, v17
	v_rcp_f32_e32 v18, v18
	v_rcp_f32_e32 v19, v19
	v_rcp_f32_e32 v20, v20
	v_rcp_f32_e32 v21, v21
	v_rcp_f32_e32 v22, v22
	v_rcp_f32_e32 v23, v23
	v_rcp_f32_e32 v24, v24
	v_rcp_f32_e32 v25, v25
	v_rcp_f32_e32 v26, v26
	v_rcp_f32_e32 v27, v27
	v_rcp_f32_e32 v28, v28
	v_rcp_f32_e32 v29, v29
	v_rcp_f32_e32 v30, v30
	v_rcp_f32_e32 v31, v31
	v_pk_mul_f32 v[0:1], v[246:247], v[0:1]
	v_pk_mul_f32 v[2:3], v[246:247], v[2:3]
	v_pk_mul_f32 v[4:5], v[246:247], v[4:5]
	v_pk_mul_f32 v[6:7], v[246:247], v[6:7]
	v_pk_mul_f32 v[8:9], v[246:247], v[8:9]
	v_pk_mul_f32 v[10:11], v[246:247], v[10:11]
	v_pk_mul_f32 v[12:13], v[246:247], v[12:13]
	v_pk_mul_f32 v[14:15], v[246:247], v[14:15]
	v_exp_f32_e32 v0, v0
	v_exp_f32_e32 v1, v1
	v_exp_f32_e32 v2, v2
	v_exp_f32_e32 v3, v3
	v_exp_f32_e32 v4, v4
	v_exp_f32_e32 v5, v5
	v_exp_f32_e32 v6, v6
	v_exp_f32_e32 v7, v7
	v_exp_f32_e32 v8, v8
	v_exp_f32_e32 v9, v9
	v_exp_f32_e32 v10, v10
	v_exp_f32_e32 v11, v11
	v_exp_f32_e32 v12, v12
	v_exp_f32_e32 v13, v13
	v_exp_f32_e32 v14, v14
	v_exp_f32_e32 v15, v15
	v_fma_f32 v32, -v0, v0, 1.0 clamp
	v_fma_f32 v33, -v1, v1, 1.0 clamp
	v_fma_f32 v34, -v2, v2, 1.0 clamp
	v_fma_f32 v35, -v3, v3, 1.0 clamp
; #define LAS __attribute__((address_space(3)))
; #define WAVE_SYNC() asm volatile("s_waitcnt lgkmcnt(0)" ::: "memory")
; __device__ __forceinline__ float gelu_tanh_f(float x) { const float y = 0.7978845608028654f * (x + 0.044715f * x * x * x); return x * sigmoid_f(2.f * y); }
; __device__ __forceinline__ f32x4 mfma16(bf16x8 a, bf16x8 b, f32x4 c) { return __builtin_amdgcn_mfma_f32_16x16x32_bf16(a, b, c, 0, 0, 0); }
; template <bool FINAL, int D>
; __device__ __forceinline__ void rg_dir(PREF p, int l, int h, int ch, int sidx, int rowbase  , LAS bf16_t* sXc, LAS float* stg, int lane) {
;     ...
;         const bf16x8 A0 = *(const LAS bf16x8*)(sXc + (mt * 16 + (lane & 15)) * 72 + (lane >> 4) * 8), A1 = *(const LAS bf16x8*)(sXc + (mt * 16 + (lane & 15)) * 72 + 32 + (lane >> 4) * 8);
;         f32x4 ar[4], ai[4];
; #pragma unroll
;         for (int nt = 0; nt < 4; ++nt) { const f32x4 z = {0.f, 0.f, 0.f, 0.f};
;             ar[nt] = mfma16(A0, Br[nt][0], z); ar[nt] = mfma16(A1, Br[nt][1], ar[nt]); ai[nt] = mfma16(A0, Bi[nt][0], z); ai[nt] = mfma16(A1, Bi[nt][1], ai[nt]); }
;         WAVE_SYNC();
; #pragma unroll
;         for (int nt = 0; nt < 4; ++nt)
; #pragma unroll
;             for (int j = 0; j < 4; ++j) { const int o = ((lane >> 4) * 4 + j) * 64 + nt * 16 + (lane & 15); stg[o] = ar[nt][j]; stg[1024 + o] = ai[nt][j]; }
;     ...
;             av[ti] = a; iv[ti] = __builtin_amdgcn_sqrtf(fmaxf(1.f - a * a, 0.f)) * ig * xc;
;             if (FINAL && D == 1) grv[ti] = gelu_tanh_f(grv[ti]);
;         }
; #pragma unroll
;         for (int ti = 0; ti < 16; ++ti) { const int tk = D ? 15 - ti : ti;
;             hc = av[ti] * hc + iv[ti]; Ap *= av[ti];
	v_fma_f32 v36, -v4, v4, 1.0 clamp
	v_fma_f32 v37, -v5, v5, 1.0 clamp
	v_fma_f32 v38, -v6, v6, 1.0 clamp
	v_fma_f32 v39, -v7, v7, 1.0 clamp
	v_fma_f32 v40, -v8, v8, 1.0 clamp
	v_fma_f32 v41, -v9, v9, 1.0 clamp
	v_fma_f32 v42, -v10, v10, 1.0 clamp
	v_fma_f32 v43, -v11, v11, 1.0 clamp
	v_fma_f32 v44, -v12, v12, 1.0 clamp
	v_fma_f32 v45, -v13, v13, 1.0 clamp
	v_fma_f32 v46, -v14, v14, 1.0 clamp
	v_fma_f32 v47, -v15, v15, 1.0 clamp
	v_sqrt_f32_e32 v32, v32
	v_sqrt_f32_e32 v33, v33
	v_sqrt_f32_e32 v34, v34
	v_sqrt_f32_e32 v35, v35
	v_sqrt_f32_e32 v36, v36
	v_sqrt_f32_e32 v37, v37
	v_sqrt_f32_e32 v38, v38
	v_sqrt_f32_e32 v39, v39
	v_sqrt_f32_e32 v40, v40
	v_sqrt_f32_e32 v41, v41
	v_sqrt_f32_e32 v42, v42
	v_sqrt_f32_e32 v43, v43
	v_sqrt_f32_e32 v44, v44
	v_sqrt_f32_e32 v45, v45
	v_sqrt_f32_e32 v46, v46
	v_sqrt_f32_e32 v47, v47
	s_nop 0
	v_pk_mul_f32 v[16:17], v[16:17], v[32:33]
	v_pk_mul_f32 v[18:19], v[18:19], v[34:35]
	v_pk_mul_f32 v[20:21], v[20:21], v[36:37]
	v_pk_mul_f32 v[22:23], v[22:23], v[38:39]
	v_pk_mul_f32 v[24:25], v[24:25], v[40:41]
	v_pk_mul_f32 v[26:27], v[26:27], v[42:43]
	v_pk_mul_f32 v[28:29], v[28:29], v[44:45]
	v_pk_mul_f32 v[30:31], v[30:31], v[46:47]
	v_pk_mul_f32 v[16:17], v[16:17], v[48:49]
	v_pk_mul_f32 v[18:19], v[18:19], v[50:51]
	v_pk_mul_f32 v[20:21], v[20:21], v[52:53]
	v_pk_mul_f32 v[22:23], v[22:23], v[54:55]
	v_pk_mul_f32 v[24:25], v[24:25], v[56:57]
	v_pk_mul_f32 v[26:27], v[26:27], v[58:59]
	v_pk_mul_f32 v[28:29], v[28:29], v[60:61]
	v_pk_mul_f32 v[30:31], v[30:31], v[62:63]
	v_fma_f32 v250, v15, v250, v31
	v_mul_f32_e32 v232, v232, v15
	v_fma_f32 v250, v14, v250, v30
	v_mul_f32_e32 v232, v232, v14
	v_fma_f32 v250, v13, v250, v29
	v_mul_f32_e32 v232, v232, v13
	v_fma_f32 v250, v12, v250, v28
	v_mul_f32_e32 v232, v232, v12
	v_fma_f32 v250, v11, v250, v27
	v_mul_f32_e32 v232, v232, v11
	v_fma_f32 v250, v10, v250, v26
	v_mul_f32_e32 v232, v232, v10
	v_fma_f32 v250, v9, v250, v25
	v_mul_f32_e32 v232, v232, v9
	v_fma_f32 v250, v8, v250, v24
	v_mul_f32_e32 v232, v232, v8
	v_fma_f32 v250, v7, v250, v23
	v_mul_f32_e32 v232, v232, v7
	v_fma_f32 v250, v6, v250, v22
	v_mul_f32_e32 v232, v232, v6
	v_fma_f32 v250, v5, v250, v21
	v_mul_f32_e32 v232, v232, v5
	v_fma_f32 v250, v4, v250, v20
	v_mul_f32_e32 v232, v232, v4
	v_fma_f32 v250, v3, v250, v19
	v_mul_f32_e32 v232, v232, v3
	v_fma_f32 v250, v2, v250, v18
	v_mul_f32_e32 v232, v232, v2
	v_fma_f32 v250, v1, v250, v17
	v_mul_f32_e32 v232, v232, v1
	v_fma_f32 v250, v0, v250, v16
	v_mul_f32_e32 v232, v232, v0
	ds_read_b128 v[32:35], v236 offset:0
	ds_read_b128 v[36:39], v236 offset:64
	s_waitcnt lgkmcnt(0)
	v_mfma_f32_16x16x32_bf16 v[0:3], v[32:35], v[80:83], 0
	v_mfma_f32_16x16x32_bf16 v[4:7], v[32:35], v[88:91], 0
	v_mfma_f32_16x16x32_bf16 v[8:11], v[32:35], v[96:99], 0
	v_mfma_f32_16x16x32_bf16 v[12:15], v[32:35], v[104:107], 0
	v_mfma_f32_16x16x32_bf16 v[16:19], v[32:35], v[112:115], 0
	v_mfma_f32_16x16x32_bf16 v[20:23], v[32:35], v[120:123], 0
	v_mfma_f32_16x16x32_bf16 v[24:27], v[32:35], v[128:131], 0
	v_mfma_f32_16x16x32_bf16 v[28:31], v[32:35], v[136:139], 0
	v_mfma_f32_16x16x32_bf16 v[0:3], v[36:39], v[84:87], v[0:3]
	v_mfma_f32_16x16x32_bf16 v[4:7], v[36:39], v[92:95], v[4:7]
	v_mfma_f32_16x16x32_bf16 v[8:11], v[36:39], v[100:103], v[8:11]
	v_mfma_f32_16x16x32_bf16 v[12:15], v[36:39], v[108:111], v[12:15]
	v_mfma_f32_16x16x32_bf16 v[16:19], v[36:39], v[148:151], v[16:19]
	v_mfma_f32_16x16x32_bf16 v[20:23], v[36:39], v[124:127], v[20:23]
	v_mfma_f32_16x16x32_bf16 v[24:27], v[36:39], v[132:135], v[24:27]
	v_mfma_f32_16x16x32_bf16 v[28:31], v[36:39], v[228:231], v[28:31]
	s_nop 3
	ds_write2_b32 v237, v0, v4 offset0:0 offset1:16
	ds_write2_b32 v237, v8, v12 offset0:32 offset1:48
	ds_write2_b32 v237, v1, v5 offset0:64 offset1:80
	ds_write2_b32 v237, v9, v13 offset0:96 offset1:112
	ds_write2_b32 v237, v2, v6 offset0:128 offset1:144
	ds_write2_b32 v237, v10, v14 offset0:160 offset1:176
	ds_write2_b32 v237, v3, v7 offset0:192 offset1:208
	ds_write2_b32 v237, v11, v15 offset0:224 offset1:240
	ds_write2_b32 v238, v16, v20 offset0:0 offset1:16
	ds_write2_b32 v238, v24, v28 offset0:32 offset1:48
	ds_write2_b32 v238, v17, v21 offset0:64 offset1:80
	ds_write2_b32 v238, v25, v29 offset0:96 offset1:112
	ds_write2_b32 v238, v18, v22 offset0:128 offset1:144
	ds_write2_b32 v238, v26, v30 offset0:160 offset1:176
	ds_write2_b32 v238, v19, v23 offset0:192 offset1:208
	ds_write2_b32 v238, v27, v31 offset0:224 offset1:240
	s_waitcnt lgkmcnt(0)
	ds_read2st64_b32 v[0:1], v239 offset0:36 offset1:37
	ds_read2st64_b32 v[2:3], v239 offset0:38 offset1:39
	ds_read2st64_b32 v[4:5], v239 offset0:40 offset1:41
	ds_read2st64_b32 v[6:7], v239 offset0:42 offset1:43
	ds_read2st64_b32 v[8:9], v239 offset0:44 offset1:45
	ds_read2st64_b32 v[10:11], v239 offset0:46 offset1:47
	ds_read2st64_b32 v[12:13], v239 offset0:48 offset1:49
	ds_read2st64_b32 v[14:15], v239 offset0:50 offset1:51
	ds_read2st64_b32 v[16:17], v239 offset0:52 offset1:53
	ds_read2st64_b32 v[18:19], v239 offset0:54 offset1:55
	ds_read2st64_b32 v[20:21], v239 offset0:56 offset1:57
	ds_read2st64_b32 v[22:23], v239 offset0:58 offset1:59
	ds_read2st64_b32 v[24:25], v239 offset0:60 offset1:61
	ds_read2st64_b32 v[26:27], v239 offset0:62 offset1:63
	ds_read2st64_b32 v[28:29], v239 offset0:64 offset1:65
	ds_read2st64_b32 v[30:31], v239 offset0:66 offset1:67
	ds_read_u16_d16_hi v48, v240 offset:0
	ds_read_u16_d16_hi v49, v240 offset:144
	ds_read_u16_d16_hi v50, v240 offset:288
	ds_read_u16_d16_hi v51, v240 offset:432
	ds_read_u16_d16_hi v52, v240 offset:576
	ds_read_u16_d16_hi v53, v240 offset:720
	ds_read_u16_d16_hi v54, v240 offset:864
	ds_read_u16_d16_hi v55, v240 offset:1008
	ds_read_u16_d16_hi v56, v240 offset:1152
	ds_read_u16_d16_hi v57, v240 offset:1296
	ds_read_u16_d16_hi v58, v240 offset:1440
	ds_read_u16_d16_hi v59, v240 offset:1584
	ds_read_u16_d16_hi v60, v240 offset:1728
	ds_read_u16_d16_hi v61, v240 offset:1872
	ds_read_u16_d16_hi v62, v240 offset:2016
	ds_read_u16_d16_hi v63, v240 offset:2160
	s_waitcnt lgkmcnt(0)
; __device__ __forceinline__ unsigned f2bf(float f) { unsigned r; asm("v_cvt_pk_bf16_f32 %0, %1, %1" : "=v"(r) : "v"(f)); return r & 0xffffu; }
; __device__ __forceinline__ float sigmoid_f(float x) { return rcpf_(1.f + __expf(-x)); }
; __device__ __forceinline__ float gelu_tanh_f(float x) { const float y = 0.7978845608028654f * (x + 0.044715f * x * x * x); return x * sigmoid_f(2.f * y); }
; template <bool FINAL, int D>
; __device__ __forceinline__ void rg_dir(PREF p, int l, int h, int ch, int sidx, int rowbase  , LAS bf16_t* sXc, LAS float* stg, int lane) {
;     ...
;         float av[16], iv[16];
; #pragma unroll
;         for (int ti = 0; ti < 16; ++ti) { const int tk = D ? 15 - ti : ti;
;             const float zr = stg[tk * 64 + lane] + ba, zi = stg[1024 + tk * 64 + lane] + bi;
;             const float r = sigmoid_f(zr), ig = sigmoid_f(zi);
;             const float a = __builtin_amdgcn_exp2f(r * sp8);
;             const float xc = bf2f(sXc[(mt * 16 + tk) * 72 + lane]);
;             av[ti] = a; iv[ti] = __builtin_amdgcn_sqrtf(fmaxf(1.f - a * a, 0.f)) * ig * xc;
;             if (FINAL && D == 1) grv[ti] = gelu_tanh_f(grv[ti]);
;         }
; #pragma unroll
;         for (int ti = 0; ti < 16; ++ti) { const int tk = D ? 15 - ti : ti;
;             hc = av[ti] * hc + iv[ti]; Ap *= av[ti];
;             if (FINAL) { const size_t row = (size_t)(rowbase + mt * 16 + tk);
;                 if (D == 0) TMP[row * 512 + ch] = (bf16_t)f2bf(hc);
;                 else MIX[row * DM + ch] = (bf16_t)f2bf(grv[ti] * (hfv[ti] + hc)); }
;         }
;     }
;     if (!FINAL) { RGA[sidx] = Ap; RGH[sidx] = hc; }
	v_pk_fma_f32 v[0:1], v[0:1], v[248:249], v[242:243]
	v_pk_fma_f32 v[2:3], v[2:3], v[248:249], v[242:243]
	v_pk_fma_f32 v[4:5], v[4:5], v[248:249], v[242:243]
	v_pk_fma_f32 v[6:7], v[6:7], v[248:249], v[242:243]
	v_pk_fma_f32 v[8:9], v[8:9], v[248:249], v[242:243]
	v_pk_fma_f32 v[10:11], v[10:11], v[248:249], v[242:243]
	v_pk_fma_f32 v[12:13], v[12:13], v[248:249], v[242:243]
	v_pk_fma_f32 v[14:15], v[14:15], v[248:249], v[242:243]
	v_pk_fma_f32 v[16:17], v[16:17], v[248:249], v[244:245]
	v_pk_fma_f32 v[18:19], v[18:19], v[248:249], v[244:245]
	v_pk_fma_f32 v[20:21], v[20:21], v[248:249], v[244:245]
	v_pk_fma_f32 v[22:23], v[22:23], v[248:249], v[244:245]
	v_pk_fma_f32 v[24:25], v[24:25], v[248:249], v[244:245]
	v_pk_fma_f32 v[26:27], v[26:27], v[248:249], v[244:245]
	v_pk_fma_f32 v[28:29], v[28:29], v[248:249], v[244:245]
	v_pk_fma_f32 v[30:31], v[30:31], v[248:249], v[244:245]
	v_exp_f32_e32 v0, v0
	v_exp_f32_e32 v1, v1
	v_exp_f32_e32 v2, v2
	v_exp_f32_e32 v3, v3
	v_exp_f32_e32 v4, v4
	v_exp_f32_e32 v5, v5
	v_exp_f32_e32 v6, v6
	v_exp_f32_e32 v7, v7
	v_exp_f32_e32 v8, v8
	v_exp_f32_e32 v9, v9
	v_exp_f32_e32 v10, v10
	v_exp_f32_e32 v11, v11
	v_exp_f32_e32 v12, v12
	v_exp_f32_e32 v13, v13
	v_exp_f32_e32 v14, v14
	v_exp_f32_e32 v15, v15
	v_exp_f32_e32 v16, v16
	v_exp_f32_e32 v17, v17
	v_exp_f32_e32 v18, v18
	v_exp_f32_e32 v19, v19
	v_exp_f32_e32 v20, v20
	v_exp_f32_e32 v21, v21
	v_exp_f32_e32 v22, v22
	v_exp_f32_e32 v23, v23
	v_exp_f32_e32 v24, v24
	v_exp_f32_e32 v25, v25
	v_exp_f32_e32 v26, v26
	v_exp_f32_e32 v27, v27
	v_exp_f32_e32 v28, v28
	v_exp_f32_e32 v29, v29
	v_exp_f32_e32 v30, v30
	v_exp_f32_e32 v31, v31
	v_pk_add_f32 v[0:1], v[0:1], 1.0 op_sel_hi:[1,0]
	v_pk_add_f32 v[2:3], v[2:3], 1.0 op_sel_hi:[1,0]
	v_pk_add_f32 v[4:5], v[4:5], 1.0 op_sel_hi:[1,0]
	v_pk_add_f32 v[6:7], v[6:7], 1.0 op_sel_hi:[1,0]
	v_pk_add_f32 v[8:9], v[8:9], 1.0 op_sel_hi:[1,0]
	v_pk_add_f32 v[10:11], v[10:11], 1.0 op_sel_hi:[1,0]
	v_pk_add_f32 v[12:13], v[12:13], 1.0 op_sel_hi:[1,0]
	v_pk_add_f32 v[14:15], v[14:15], 1.0 op_sel_hi:[1,0]
	v_pk_add_f32 v[16:17], v[16:17], 1.0 op_sel_hi:[1,0]
	v_pk_add_f32 v[18:19], v[18:19], 1.0 op_sel_hi:[1,0]
	v_pk_add_f32 v[20:21], v[20:21], 1.0 op_sel_hi:[1,0]
	v_pk_add_f32 v[22:23], v[22:23], 1.0 op_sel_hi:[1,0]
	v_pk_add_f32 v[24:25], v[24:25], 1.0 op_sel_hi:[1,0]
	v_pk_add_f32 v[26:27], v[26:27], 1.0 op_sel_hi:[1,0]
	v_pk_add_f32 v[28:29], v[28:29], 1.0 op_sel_hi:[1,0]
	v_pk_add_f32 v[30:31], v[30:31], 1.0 op_sel_hi:[1,0]
	v_rcp_f32_e32 v0, v0
	v_rcp_f32_e32 v1, v1
	v_rcp_f32_e32 v2, v2
	v_rcp_f32_e32 v3, v3
	v_rcp_f32_e32 v4, v4
	v_rcp_f32_e32 v5, v5
	v_rcp_f32_e32 v6, v6
	v_rcp_f32_e32 v7, v7
	v_rcp_f32_e32 v8, v8
	v_rcp_f32_e32 v9, v9
	v_rcp_f32_e32 v10, v10
	v_rcp_f32_e32 v11, v11
	v_rcp_f32_e32 v12, v12
	v_rcp_f32_e32 v13, v13
	v_rcp_f32_e32 v14, v14
	v_rcp_f32_e32 v15, v15
	v_rcp_f32_e32 v16, v16
	v_rcp_f32_e32 v17, v17
	v_rcp_f32_e32 v18, v18
	v_rcp_f32_e32 v19, v19
	v_rcp_f32_e32 v20, v20
	v_rcp_f32_e32 v21, v21
	v_rcp_f32_e32 v22, v22
	v_rcp_f32_e32 v23, v23
	v_rcp_f32_e32 v24, v24
	v_rcp_f32_e32 v25, v25
	v_rcp_f32_e32 v26, v26
	v_rcp_f32_e32 v27, v27
	v_rcp_f32_e32 v28, v28
	v_rcp_f32_e32 v29, v29
	v_rcp_f32_e32 v30, v30
	v_rcp_f32_e32 v31, v31
	v_pk_mul_f32 v[0:1], v[246:247], v[0:1]
	v_pk_mul_f32 v[2:3], v[246:247], v[2:3]
	v_pk_mul_f32 v[4:5], v[246:247], v[4:5]
	v_pk_mul_f32 v[6:7], v[246:247], v[6:7]
	v_pk_mul_f32 v[8:9], v[246:247], v[8:9]
	v_pk_mul_f32 v[10:11], v[246:247], v[10:11]
	v_pk_mul_f32 v[12:13], v[246:247], v[12:13]
	v_pk_mul_f32 v[14:15], v[246:247], v[14:15]
	v_exp_f32_e32 v0, v0
	v_exp_f32_e32 v1, v1
	v_exp_f32_e32 v2, v2
	v_exp_f32_e32 v3, v3
	v_exp_f32_e32 v4, v4
	v_exp_f32_e32 v5, v5
	v_exp_f32_e32 v6, v6
	v_exp_f32_e32 v7, v7
	v_exp_f32_e32 v8, v8
	v_exp_f32_e32 v9, v9
	v_exp_f32_e32 v10, v10
	v_exp_f32_e32 v11, v11
	v_exp_f32_e32 v12, v12
	v_exp_f32_e32 v13, v13
	v_exp_f32_e32 v14, v14
	v_exp_f32_e32 v15, v15
	v_fma_f32 v32, -v0, v0, 1.0 clamp
	v_fma_f32 v33, -v1, v1, 1.0 clamp
	v_fma_f32 v34, -v2, v2, 1.0 clamp
	v_fma_f32 v35, -v3, v3, 1.0 clamp
	v_fma_f32 v36, -v4, v4, 1.0 clamp
	v_fma_f32 v37, -v5, v5, 1.0 clamp
	v_fma_f32 v38, -v6, v6, 1.0 clamp
	v_fma_f32 v39, -v7, v7, 1.0 clamp
	v_fma_f32 v40, -v8, v8, 1.0 clamp
	v_fma_f32 v41, -v9, v9, 1.0 clamp
	v_fma_f32 v42, -v10, v10, 1.0 clamp
	v_fma_f32 v43, -v11, v11, 1.0 clamp
	v_fma_f32 v44, -v12, v12, 1.0 clamp
	v_fma_f32 v45, -v13, v13, 1.0 clamp
	v_fma_f32 v46, -v14, v14, 1.0 clamp
	v_fma_f32 v47, -v15, v15, 1.0 clamp
	v_sqrt_f32_e32 v32, v32
	v_sqrt_f32_e32 v33, v33
	v_sqrt_f32_e32 v34, v34
	v_sqrt_f32_e32 v35, v35
	v_sqrt_f32_e32 v36, v36
	v_sqrt_f32_e32 v37, v37
	v_sqrt_f32_e32 v38, v38
	v_sqrt_f32_e32 v39, v39
	v_sqrt_f32_e32 v40, v40
	v_sqrt_f32_e32 v41, v41
	v_sqrt_f32_e32 v42, v42
	v_sqrt_f32_e32 v43, v43
	v_sqrt_f32_e32 v44, v44
	v_sqrt_f32_e32 v45, v45
	v_sqrt_f32_e32 v46, v46
	v_sqrt_f32_e32 v47, v47
	s_nop 0
	v_pk_mul_f32 v[16:17], v[16:17], v[32:33]
	v_pk_mul_f32 v[18:19], v[18:19], v[34:35]
	v_pk_mul_f32 v[20:21], v[20:21], v[36:37]
	v_pk_mul_f32 v[22:23], v[22:23], v[38:39]
	v_pk_mul_f32 v[24:25], v[24:25], v[40:41]
	v_pk_mul_f32 v[26:27], v[26:27], v[42:43]
	v_pk_mul_f32 v[28:29], v[28:29], v[44:45]
	v_pk_mul_f32 v[30:31], v[30:31], v[46:47]
	v_pk_mul_f32 v[16:17], v[16:17], v[48:49]
	v_pk_mul_f32 v[18:19], v[18:19], v[50:51]
	v_pk_mul_f32 v[20:21], v[20:21], v[52:53]
	v_pk_mul_f32 v[22:23], v[22:23], v[54:55]
	v_pk_mul_f32 v[24:25], v[24:25], v[56:57]
	v_pk_mul_f32 v[26:27], v[26:27], v[58:59]
	v_pk_mul_f32 v[28:29], v[28:29], v[60:61]
	v_pk_mul_f32 v[30:31], v[30:31], v[62:63]
	v_fma_f32 v250, v15, v250, v31
	v_mul_f32_e32 v232, v232, v15
	v_fma_f32 v250, v14, v250, v30
	v_mul_f32_e32 v232, v232, v14
	v_fma_f32 v250, v13, v250, v29
	v_mul_f32_e32 v232, v232, v13
	v_fma_f32 v250, v12, v250, v28
	v_mul_f32_e32 v232, v232, v12
	v_fma_f32 v250, v11, v250, v27
	v_mul_f32_e32 v232, v232, v11
	v_fma_f32 v250, v10, v250, v26
	v_mul_f32_e32 v232, v232, v10
	v_fma_f32 v250, v9, v250, v25
	v_mul_f32_e32 v232, v232, v9
	v_fma_f32 v250, v8, v250, v24
	v_mul_f32_e32 v232, v232, v8
	v_fma_f32 v250, v7, v250, v23
	v_mul_f32_e32 v232, v232, v7
	v_fma_f32 v250, v6, v250, v22
	v_mul_f32_e32 v232, v232, v6
	v_fma_f32 v250, v5, v250, v21
	v_mul_f32_e32 v232, v232, v5
	v_fma_f32 v250, v4, v250, v20
	v_mul_f32_e32 v232, v232, v4
	v_fma_f32 v250, v3, v250, v19
	v_mul_f32_e32 v232, v232, v3
	v_fma_f32 v250, v2, v250, v18
	v_mul_f32_e32 v232, v232, v2
	v_fma_f32 v250, v1, v250, v17
	v_mul_f32_e32 v232, v232, v1
	v_fma_f32 v250, v0, v250, v16
	v_mul_f32_e32 v232, v232, v0
	s_add_u32 s96, s0, 0x400800
	s_addc_u32 s97, s1, 0
	s_add_u32 s96, s96, s36
	s_addc_u32 s97, s97, 0
	global_store_dword v235, v232, s[96:97]
	s_add_u32 s96, s96, 0x300000
	s_addc_u32 s97, s97, 0
	global_store_dword v235, v250, s[96:97]
	s_waitcnt lgkmcnt(0)
	v_readlane_b32 s84, v253, 29
	s_add_i32 s12, s12, s84
	s_cmpk_lt_i32 s12, 0x1000
	s_cbranch_scc1 .Lrg5_keep
; __global__ void __launch_bounds__(NTHREADS, 2) mega_fwd(Params p_arg) {
;     ...
;             for (int item = gw; item < 2 * NCH * 8; item += NGW) rg_item<false>(p, l, item, lds + wave * 18432, lane);
	s_sub_i32 s0, s12, 0x1000
	s_lshr_b32 s1, s0, 5
	s_and_b32 s0, s0, 31
	s_and_b32 s12, s1, 7
	s_add_i32 s1, s1, 0x1000
	s_cmp_eq_u32 s0, s12
	s_cselect_b32 s12, s1, 0x2000
